# epilogue bias hoist + attention loop copy elimination + gMLP stats/mt prefetch + latent-pass load hoist (bit-identical numerics)
# speedup vs baseline: 1.0406x; 1.0406x over previous
; __device__ __forceinline__ float sigmoidf_(float x) { return __builtin_amdgcn_rcpf(1.f + __builtin_amdgcn_exp2f(-1.4426950408889634f * x)); }
; __device__ __forceinline__ float gelu_t(float x) { const float u = x * (-2.3022081986f - 0.1029432404f * x * x); return x * __builtin_amdgcn_rcpf(1.f + __builtin_amdgcn_exp2f(u)); }
;     __device__ __forceinline__ void operator()(const f32x4 (&acc)[2][2][4][2], const Unit& u, int wr, int wc, int fr, int fq) const {
;         const int pn = u.pn; const int act = (pn < 4 || pn == 8 || pn == 9) ? 1 : (pn >= 10 ? 2 : 0);
;         EPI_LOOP_BEGIN
;             const int col = pn * BM + cl; const f32x4 b0 = *(const f32x4*)(bias + col), b1 = *(const f32x4*)(bias + col + 4);
;             v0 = v0 + b0; v1 = v1 + b1;
;             if (act == 1) {
; #pragma unroll
;                 for (int e = 0; e < 4; ++e) { v0[e] = gelu_t(v0[e]); v1[e] = gelu_t(v1[e]); }
;             } else if (act == 2) {
; #pragma unroll
;                 for (int e = 0; e < 4; ++e) { v0[e] = sigmoidf_(v0[e]); v1[e] = sigmoidf_(v1[e]); }
.LBB0_214:
	v_lshl_or_b32 v144, s28, 8, v150
	v_ashrrev_i32_e32 v145, 31, v144
	v_lshl_add_u64 v[146:147], v[144:145], 2, s[8:9]
	global_load_dwordx4 v[200:203], v[146:147], off
	global_load_dwordx4 v[204:207], v[146:147], off offset:16
	global_load_dwordx4 v[208:211], v[146:147], off offset:512
	global_load_dwordx4 v[212:215], v[146:147], off offset:528
	s_cmp_lt_i32 s28, 4
	s_cselect_b64 s[6:7], -1, 0
	s_and_b32 s17, s28, -2
	s_cmp_eq_u32 s17, 8
	s_cselect_b64 s[24:25], -1, 0
	s_or_b64 s[6:7], s[6:7], s[24:25]
	s_cmp_gt_i32 s28, 9
	s_cselect_b32 s17, 2, 0
	s_and_b64 s[6:7], s[6:7], exec
	s_cselect_b32 s17, 1, s17
	s_cmp_gt_i32 s17, 1
	s_mov_b64 s[6:7], -1
	s_waitcnt vmcnt(0)
	v_pk_add_f32 v[126:127], v[126:127], v[202:203]
	v_pk_add_f32 v[124:125], v[124:125], v[200:201]
	v_pk_add_f32 v[122:123], v[122:123], v[206:207]
	v_pk_add_f32 v[120:121], v[120:121], v[204:205]
	s_cbranch_scc0 .LBB0_216
	v_mul_f32_e32 v160, 0xbfb8aa3b, v127
	v_mul_f32_e32 v154, 0xbfb8aa3b, v124
	v_mul_f32_e32 v155, 0xbfb8aa3b, v120
	v_mul_f32_e32 v156, 0xbfb8aa3b, v125
	v_mul_f32_e32 v157, 0xbfb8aa3b, v121
	v_mul_f32_e32 v158, 0xbfb8aa3b, v126
	v_mul_f32_e32 v159, 0xbfb8aa3b, v122
	v_exp_f32_e32 v160, v160
	v_mul_f32_e32 v161, 0xbfb8aa3b, v123
	v_exp_f32_e32 v154, v154
	v_exp_f32_e32 v155, v155
	v_exp_f32_e32 v156, v156
	v_exp_f32_e32 v157, v157
	v_exp_f32_e32 v158, v158
	v_exp_f32_e32 v159, v159
	v_exp_f32_e32 v162, v161
	v_add_f32_e32 v160, 1.0, v160
	v_add_f32_e32 v154, 1.0, v154
	v_add_f32_e32 v155, 1.0, v155
	v_add_f32_e32 v156, 1.0, v156
	v_add_f32_e32 v157, 1.0, v157
	v_add_f32_e32 v158, 1.0, v158
	v_add_f32_e32 v159, 1.0, v159
	v_rcp_f32_e32 v161, v160
	v_add_f32_e32 v160, 1.0, v162
	v_rcp_f32_e32 v154, v154
	v_rcp_f32_e32 v155, v155
	v_rcp_f32_e32 v156, v156
	v_rcp_f32_e32 v157, v157
	v_rcp_f32_e32 v158, v158
	v_rcp_f32_e32 v159, v159
	v_rcp_f32_e32 v160, v160
	s_mov_b64 s[6:7], 0

; __device__ __forceinline__ float sigmoidf_(float x) { return __builtin_amdgcn_rcpf(1.f + __builtin_amdgcn_exp2f(-1.4426950408889634f * x)); }
; __device__ __forceinline__ float gelu_t(float x) { const float u = x * (-2.3022081986f - 0.1029432404f * x * x); return x * __builtin_amdgcn_rcpf(1.f + __builtin_amdgcn_exp2f(u)); }
; __device__ __forceinline__ unsigned cvt_pk_bf16(float lo, float hi) { unsigned r; asm volatile("v_cvt_pk_bf16_f32 %0, %1, %2" : "=v"(r) : "v"(lo), "v"(hi)); return r; }
;     __device__ __forceinline__ void operator()(const f32x4 (&acc)[2][2][4][2], const Unit& u, int wr, int wc, int fr, int fq) const {
;     ...
;             const int col = pn * BM + cl; const f32x4 b0 = *(const f32x4*)(bias + col), b1 = *(const f32x4*)(bias + col + 4);
;             v0 = v0 + b0; v1 = v1 + b1;
;             if (act == 1) {
; #pragma unroll
;                 for (int e = 0; e < 4; ++e) { v0[e] = gelu_t(v0[e]); v1[e] = gelu_t(v1[e]); }
;             } else if (act == 2) {
; #pragma unroll
;                 for (int e = 0; e < 4; ++e) { v0[e] = sigmoidf_(v0[e]); v1[e] = sigmoidf_(v1[e]); }
;             }
;             u32x4 w; w.x = cvt_pk_bf16(v0[0], v0[1]); w.y = cvt_pk_bf16(v0[2], v0[3]); w.z = cvt_pk_bf16(v1[0], v1[1]); w.w = cvt_pk_bf16(v1[2], v1[3]);
;             *(u32x4*)(Z + (size_t)row * ZP + col) = w;
.LBB0_220:
	v_lshl_add_u32 v124, s26, 8, v148
	v_mov_b64_e32 v[120:121], s[4:5]
	v_mad_i64_i32 v[120:121], s[6:7], v124, s65, v[120:121]
	v_lshl_add_u64 v[122:123], v[144:145], 1, v[120:121]
	v_or_b32_e32 v120, 0x80, v144
	v_ashrrev_i32_e32 v121, 31, v120
	v_cvt_pk_bf16_f32 v162, v154, v156
	v_cvt_pk_bf16_f32 v163, v158, v161
	v_cvt_pk_bf16_f32 v164, v155, v157
	v_cvt_pk_bf16_f32 v165, v159, v160
	global_store_dwordx4 v[122:123], v[162:165], off
	v_lshl_add_u64 v[120:121], v[120:121], 2, s[8:9]
	s_cmp_gt_i32 s17, 1
	s_mov_b64 s[6:7], -1
	v_pk_add_f32 v[118:119], v[118:119], v[210:211]
	v_pk_add_f32 v[116:117], v[116:117], v[208:209]
	v_pk_add_f32 v[114:115], v[114:115], v[214:215]
	v_pk_add_f32 v[112:113], v[112:113], v[212:213]
	s_cbranch_scc0 .LBB0_222
	v_mul_f32_e32 v157, 0xbfb8aa3b, v119
	v_mul_f32_e32 v125, 0xbfb8aa3b, v116
	v_mul_f32_e32 v126, 0xbfb8aa3b, v112
	v_mul_f32_e32 v127, 0xbfb8aa3b, v117
	v_mul_f32_e32 v154, 0xbfb8aa3b, v113
	v_mul_f32_e32 v155, 0xbfb8aa3b, v118
	v_mul_f32_e32 v156, 0xbfb8aa3b, v114
	v_exp_f32_e32 v157, v157
	v_mul_f32_e32 v158, 0xbfb8aa3b, v115
	v_exp_f32_e32 v125, v125
	v_exp_f32_e32 v126, v126
	v_exp_f32_e32 v127, v127
	v_exp_f32_e32 v154, v154
	v_exp_f32_e32 v155, v155
	v_exp_f32_e32 v156, v156
	v_exp_f32_e32 v159, v158
	v_add_f32_e32 v157, 1.0, v157
	v_add_f32_e32 v125, 1.0, v125
	v_add_f32_e32 v126, 1.0, v126
	v_add_f32_e32 v127, 1.0, v127
	v_add_f32_e32 v154, 1.0, v154
	v_add_f32_e32 v155, 1.0, v155
	v_add_f32_e32 v156, 1.0, v156
	v_rcp_f32_e32 v158, v157
	v_add_f32_e32 v157, 1.0, v159
	v_rcp_f32_e32 v125, v125
	v_rcp_f32_e32 v126, v126
	v_rcp_f32_e32 v127, v127
	v_rcp_f32_e32 v154, v154
	v_rcp_f32_e32 v155, v155
	v_rcp_f32_e32 v156, v156
	v_rcp_f32_e32 v157, v157
	s_mov_b64 s[6:7], 0

; __device__ __forceinline__ float sigmoidf_(float x) { return __builtin_amdgcn_rcpf(1.f + __builtin_amdgcn_exp2f(-1.4426950408889634f * x)); }
; __device__ __forceinline__ float gelu_t(float x) { const float u = x * (-2.3022081986f - 0.1029432404f * x * x); return x * __builtin_amdgcn_rcpf(1.f + __builtin_amdgcn_exp2f(u)); }
; __device__ __forceinline__ unsigned cvt_pk_bf16(float lo, float hi) { unsigned r; asm volatile("v_cvt_pk_bf16_f32 %0, %1, %2" : "=v"(r) : "v"(lo), "v"(hi)); return r; }
;     __device__ __forceinline__ void operator()(const f32x4 (&acc)[2][2][4][2], const Unit& u, int wr, int wc, int fr, int fq) const {
;     ...
;             const int col = pn * BM + cl; const f32x4 b0 = *(const f32x4*)(bias + col), b1 = *(const f32x4*)(bias + col + 4);
;             v0 = v0 + b0; v1 = v1 + b1;
;             if (act == 1) {
; #pragma unroll
;                 for (int e = 0; e < 4; ++e) { v0[e] = gelu_t(v0[e]); v1[e] = gelu_t(v1[e]); }
;             } else if (act == 2) {
; #pragma unroll
;                 for (int e = 0; e < 4; ++e) { v0[e] = sigmoidf_(v0[e]); v1[e] = sigmoidf_(v1[e]); }
;             }
;             u32x4 w; w.x = cvt_pk_bf16(v0[0], v0[1]); w.y = cvt_pk_bf16(v0[2], v0[3]); w.z = cvt_pk_bf16(v1[0], v1[1]); w.w = cvt_pk_bf16(v1[2], v1[3]);
;             *(u32x4*)(Z + (size_t)row * ZP + col) = w;
.LBB0_226:
	v_cvt_pk_bf16_f32 v112, v125, v127
	v_cvt_pk_bf16_f32 v113, v155, v158
	v_cvt_pk_bf16_f32 v114, v126, v154
	v_cvt_pk_bf16_f32 v115, v156, v157
	global_store_dwordx4 v[122:123], v[112:115], off offset:256
	s_cmp_gt_i32 s17, 1
	s_mov_b64 s[6:7], -1
	v_pk_add_f32 v[110:111], v[110:111], v[202:203]
	v_pk_add_f32 v[108:109], v[108:109], v[200:201]
	v_pk_add_f32 v[106:107], v[106:107], v[206:207]
	v_pk_add_f32 v[104:105], v[104:105], v[204:205]
	s_cbranch_scc0 .LBB0_228
	v_mul_f32_e32 v118, 0xbfb8aa3b, v111
	v_mul_f32_e32 v112, 0xbfb8aa3b, v108
	v_mul_f32_e32 v113, 0xbfb8aa3b, v104
	v_mul_f32_e32 v114, 0xbfb8aa3b, v109
	v_mul_f32_e32 v115, 0xbfb8aa3b, v105
	v_mul_f32_e32 v116, 0xbfb8aa3b, v110
	v_mul_f32_e32 v117, 0xbfb8aa3b, v106
	v_exp_f32_e32 v118, v118
	v_mul_f32_e32 v119, 0xbfb8aa3b, v107
	v_exp_f32_e32 v112, v112
	v_exp_f32_e32 v113, v113
	v_exp_f32_e32 v114, v114
	v_exp_f32_e32 v115, v115
	v_exp_f32_e32 v116, v116
	v_exp_f32_e32 v117, v117
	v_exp_f32_e32 v122, v119
	v_add_f32_e32 v118, 1.0, v118
	v_add_f32_e32 v112, 1.0, v112
	v_add_f32_e32 v113, 1.0, v113
	v_add_f32_e32 v114, 1.0, v114
	v_add_f32_e32 v115, 1.0, v115
	v_add_f32_e32 v116, 1.0, v116
	v_add_f32_e32 v117, 1.0, v117
	v_rcp_f32_e32 v119, v118
	v_add_f32_e32 v118, 1.0, v122
	v_rcp_f32_e32 v112, v112
	v_rcp_f32_e32 v113, v113
	v_rcp_f32_e32 v114, v114
	v_rcp_f32_e32 v115, v115
	v_rcp_f32_e32 v116, v116
	v_rcp_f32_e32 v117, v117
	v_rcp_f32_e32 v118, v118
	s_mov_b64 s[6:7], 0

; __device__ __forceinline__ float sigmoidf_(float x) { return __builtin_amdgcn_rcpf(1.f + __builtin_amdgcn_exp2f(-1.4426950408889634f * x)); }
; __device__ __forceinline__ float gelu_t(float x) { const float u = x * (-2.3022081986f - 0.1029432404f * x * x); return x * __builtin_amdgcn_rcpf(1.f + __builtin_amdgcn_exp2f(u)); }
; __device__ __forceinline__ unsigned cvt_pk_bf16(float lo, float hi) { unsigned r; asm volatile("v_cvt_pk_bf16_f32 %0, %1, %2" : "=v"(r) : "v"(lo), "v"(hi)); return r; }
;     __device__ __forceinline__ void operator()(const f32x4 (&acc)[2][2][4][2], const Unit& u, int wr, int wc, int fr, int fq) const {
;     ...
;             const int col = pn * BM + cl; const f32x4 b0 = *(const f32x4*)(bias + col), b1 = *(const f32x4*)(bias + col + 4);
;             v0 = v0 + b0; v1 = v1 + b1;
;             if (act == 1) {
; #pragma unroll
;                 for (int e = 0; e < 4; ++e) { v0[e] = gelu_t(v0[e]); v1[e] = gelu_t(v1[e]); }
;             } else if (act == 2) {
; #pragma unroll
;                 for (int e = 0; e < 4; ++e) { v0[e] = sigmoidf_(v0[e]); v1[e] = sigmoidf_(v1[e]); }
;             }
;             u32x4 w; w.x = cvt_pk_bf16(v0[0], v0[1]); w.y = cvt_pk_bf16(v0[2], v0[3]); w.z = cvt_pk_bf16(v1[0], v1[1]); w.w = cvt_pk_bf16(v1[2], v1[3]);
;             *(u32x4*)(Z + (size_t)row * ZP + col) = w;
.LBB0_232:
	v_or_b32_e32 v110, 16, v124
	v_mov_b64_e32 v[104:105], s[4:5]
	v_mad_i64_i32 v[104:105], s[6:7], v110, s65, v[104:105]
	v_lshl_add_u64 v[104:105], v[144:145], 1, v[104:105]
	v_cvt_pk_bf16_f32 v106, v112, v114
	v_cvt_pk_bf16_f32 v107, v116, v119
	v_cvt_pk_bf16_f32 v108, v113, v115
	v_cvt_pk_bf16_f32 v109, v117, v118
	global_store_dwordx4 v[104:105], v[106:109], off
	s_cmp_gt_i32 s17, 1
	s_mov_b64 s[6:7], -1
	v_pk_add_f32 v[102:103], v[102:103], v[210:211]
	v_pk_add_f32 v[100:101], v[100:101], v[208:209]
	v_pk_add_f32 v[98:99], v[98:99], v[214:215]
	v_pk_add_f32 v[96:97], v[96:97], v[212:213]
	s_cbranch_scc0 .LBB0_234
	v_mul_f32_e32 v112, 0xbfb8aa3b, v103
	v_mul_f32_e32 v106, 0xbfb8aa3b, v100
	v_mul_f32_e32 v107, 0xbfb8aa3b, v96
	v_mul_f32_e32 v108, 0xbfb8aa3b, v101
	v_mul_f32_e32 v109, 0xbfb8aa3b, v97
	v_mul_f32_e32 v110, 0xbfb8aa3b, v102
	v_mul_f32_e32 v111, 0xbfb8aa3b, v98
	v_exp_f32_e32 v112, v112
	v_mul_f32_e32 v113, 0xbfb8aa3b, v99
	v_exp_f32_e32 v106, v106
	v_exp_f32_e32 v107, v107
	v_exp_f32_e32 v108, v108
	v_exp_f32_e32 v109, v109
	v_exp_f32_e32 v110, v110
	v_exp_f32_e32 v111, v111
	v_exp_f32_e32 v114, v113
	v_add_f32_e32 v112, 1.0, v112
	v_add_f32_e32 v106, 1.0, v106
	v_add_f32_e32 v107, 1.0, v107
	v_add_f32_e32 v108, 1.0, v108
	v_add_f32_e32 v109, 1.0, v109
	v_add_f32_e32 v110, 1.0, v110
	v_add_f32_e32 v111, 1.0, v111
	v_rcp_f32_e32 v113, v112
	v_add_f32_e32 v112, 1.0, v114
	v_rcp_f32_e32 v106, v106
	v_rcp_f32_e32 v107, v107
	v_rcp_f32_e32 v108, v108
	v_rcp_f32_e32 v109, v109
	v_rcp_f32_e32 v110, v110
	v_rcp_f32_e32 v111, v111
	v_rcp_f32_e32 v112, v112
	s_mov_b64 s[6:7], 0

; __device__ __forceinline__ float sigmoidf_(float x) { return __builtin_amdgcn_rcpf(1.f + __builtin_amdgcn_exp2f(-1.4426950408889634f * x)); }
; __device__ __forceinline__ float gelu_t(float x) { const float u = x * (-2.3022081986f - 0.1029432404f * x * x); return x * __builtin_amdgcn_rcpf(1.f + __builtin_amdgcn_exp2f(u)); }
; __device__ __forceinline__ unsigned cvt_pk_bf16(float lo, float hi) { unsigned r; asm volatile("v_cvt_pk_bf16_f32 %0, %1, %2" : "=v"(r) : "v"(lo), "v"(hi)); return r; }
;     __device__ __forceinline__ void operator()(const f32x4 (&acc)[2][2][4][2], const Unit& u, int wr, int wc, int fr, int fq) const {
;     ...
;             const int col = pn * BM + cl; const f32x4 b0 = *(const f32x4*)(bias + col), b1 = *(const f32x4*)(bias + col + 4);
;             v0 = v0 + b0; v1 = v1 + b1;
;             if (act == 1) {
; #pragma unroll
;                 for (int e = 0; e < 4; ++e) { v0[e] = gelu_t(v0[e]); v1[e] = gelu_t(v1[e]); }
;             } else if (act == 2) {
; #pragma unroll
;                 for (int e = 0; e < 4; ++e) { v0[e] = sigmoidf_(v0[e]); v1[e] = sigmoidf_(v1[e]); }
;             }
;             u32x4 w; w.x = cvt_pk_bf16(v0[0], v0[1]); w.y = cvt_pk_bf16(v0[2], v0[3]); w.z = cvt_pk_bf16(v1[0], v1[1]); w.w = cvt_pk_bf16(v1[2], v1[3]);
;             *(u32x4*)(Z + (size_t)row * ZP + col) = w;
.LBB0_238:
	v_cvt_pk_bf16_f32 v96, v106, v108
	v_cvt_pk_bf16_f32 v97, v110, v113
	v_cvt_pk_bf16_f32 v98, v107, v109
	v_cvt_pk_bf16_f32 v99, v111, v112
	global_store_dwordx4 v[104:105], v[96:99], off offset:256
	s_cmp_gt_i32 s17, 1
	s_mov_b64 s[6:7], -1
	v_pk_add_f32 v[94:95], v[94:95], v[202:203]
	v_pk_add_f32 v[92:93], v[92:93], v[200:201]
	v_pk_add_f32 v[90:91], v[90:91], v[206:207]
	v_pk_add_f32 v[88:89], v[88:89], v[204:205]
	s_cbranch_scc0 .LBB0_240
	v_mul_f32_e32 v102, 0xbfb8aa3b, v95
	v_mul_f32_e32 v96, 0xbfb8aa3b, v92
	v_mul_f32_e32 v97, 0xbfb8aa3b, v88
	v_mul_f32_e32 v98, 0xbfb8aa3b, v93
	v_mul_f32_e32 v99, 0xbfb8aa3b, v89
	v_mul_f32_e32 v100, 0xbfb8aa3b, v94
	v_mul_f32_e32 v101, 0xbfb8aa3b, v90
	v_exp_f32_e32 v102, v102
	v_mul_f32_e32 v103, 0xbfb8aa3b, v91
	v_exp_f32_e32 v96, v96
	v_exp_f32_e32 v97, v97
	v_exp_f32_e32 v98, v98
	v_exp_f32_e32 v99, v99
	v_exp_f32_e32 v100, v100
	v_exp_f32_e32 v101, v101
	v_exp_f32_e32 v104, v103
	v_add_f32_e32 v102, 1.0, v102
	v_add_f32_e32 v96, 1.0, v96
	v_add_f32_e32 v97, 1.0, v97
	v_add_f32_e32 v98, 1.0, v98
	v_add_f32_e32 v99, 1.0, v99
	v_add_f32_e32 v100, 1.0, v100
	v_add_f32_e32 v101, 1.0, v101
	v_rcp_f32_e32 v103, v102
	v_add_f32_e32 v102, 1.0, v104
	v_rcp_f32_e32 v96, v96
	v_rcp_f32_e32 v97, v97
	v_rcp_f32_e32 v98, v98
	v_rcp_f32_e32 v99, v99
	v_rcp_f32_e32 v100, v100
	v_rcp_f32_e32 v101, v101
	v_rcp_f32_e32 v102, v102
	s_mov_b64 s[6:7], 0

; __device__ __forceinline__ float sigmoidf_(float x) { return __builtin_amdgcn_rcpf(1.f + __builtin_amdgcn_exp2f(-1.4426950408889634f * x)); }
; __device__ __forceinline__ float gelu_t(float x) { const float u = x * (-2.3022081986f - 0.1029432404f * x * x); return x * __builtin_amdgcn_rcpf(1.f + __builtin_amdgcn_exp2f(u)); }
; __device__ __forceinline__ unsigned cvt_pk_bf16(float lo, float hi) { unsigned r; asm volatile("v_cvt_pk_bf16_f32 %0, %1, %2" : "=v"(r) : "v"(lo), "v"(hi)); return r; }
;     __device__ __forceinline__ void operator()(const f32x4 (&acc)[2][2][4][2], const Unit& u, int wr, int wc, int fr, int fq) const {
;     ...
;             const int col = pn * BM + cl; const f32x4 b0 = *(const f32x4*)(bias + col), b1 = *(const f32x4*)(bias + col + 4);
;             v0 = v0 + b0; v1 = v1 + b1;
;             if (act == 1) {
; #pragma unroll
;                 for (int e = 0; e < 4; ++e) { v0[e] = gelu_t(v0[e]); v1[e] = gelu_t(v1[e]); }
;             } else if (act == 2) {
; #pragma unroll
;                 for (int e = 0; e < 4; ++e) { v0[e] = sigmoidf_(v0[e]); v1[e] = sigmoidf_(v1[e]); }
;             }
;             u32x4 w; w.x = cvt_pk_bf16(v0[0], v0[1]); w.y = cvt_pk_bf16(v0[2], v0[3]); w.z = cvt_pk_bf16(v1[0], v1[1]); w.w = cvt_pk_bf16(v1[2], v1[3]);
;             *(u32x4*)(Z + (size_t)row * ZP + col) = w;
.LBB0_244:
	v_or_b32_e32 v94, 32, v124
	v_mov_b64_e32 v[88:89], s[4:5]
	v_mad_i64_i32 v[88:89], s[6:7], v94, s65, v[88:89]
	v_lshl_add_u64 v[88:89], v[144:145], 1, v[88:89]
	v_cvt_pk_bf16_f32 v90, v96, v98
	v_cvt_pk_bf16_f32 v91, v100, v103
	v_cvt_pk_bf16_f32 v92, v97, v99
	v_cvt_pk_bf16_f32 v93, v101, v102
	global_store_dwordx4 v[88:89], v[90:93], off
	s_cmp_gt_i32 s17, 1
	s_mov_b64 s[6:7], -1
	v_pk_add_f32 v[86:87], v[86:87], v[210:211]
	v_pk_add_f32 v[84:85], v[84:85], v[208:209]
	v_pk_add_f32 v[82:83], v[82:83], v[214:215]
	v_pk_add_f32 v[80:81], v[80:81], v[212:213]
	s_cbranch_scc0 .LBB0_246
	v_mul_f32_e32 v96, 0xbfb8aa3b, v87
	v_mul_f32_e32 v90, 0xbfb8aa3b, v84
	v_mul_f32_e32 v91, 0xbfb8aa3b, v80
	v_mul_f32_e32 v92, 0xbfb8aa3b, v85
	v_mul_f32_e32 v93, 0xbfb8aa3b, v81
	v_mul_f32_e32 v94, 0xbfb8aa3b, v86
	v_mul_f32_e32 v95, 0xbfb8aa3b, v82
	v_exp_f32_e32 v96, v96
	v_mul_f32_e32 v97, 0xbfb8aa3b, v83
	v_exp_f32_e32 v90, v90
	v_exp_f32_e32 v91, v91
	v_exp_f32_e32 v92, v92
	v_exp_f32_e32 v93, v93
	v_exp_f32_e32 v94, v94
	v_exp_f32_e32 v95, v95
	v_exp_f32_e32 v98, v97
	v_add_f32_e32 v96, 1.0, v96
	v_add_f32_e32 v90, 1.0, v90
	v_add_f32_e32 v91, 1.0, v91
	v_add_f32_e32 v92, 1.0, v92
	v_add_f32_e32 v93, 1.0, v93
	v_add_f32_e32 v94, 1.0, v94
	v_add_f32_e32 v95, 1.0, v95
	v_rcp_f32_e32 v97, v96
	v_add_f32_e32 v96, 1.0, v98
	v_rcp_f32_e32 v90, v90
	v_rcp_f32_e32 v91, v91
	v_rcp_f32_e32 v92, v92
	v_rcp_f32_e32 v93, v93
	v_rcp_f32_e32 v94, v94
	v_rcp_f32_e32 v95, v95
	v_rcp_f32_e32 v96, v96
	s_mov_b64 s[6:7], 0

; __device__ __forceinline__ float sigmoidf_(float x) { return __builtin_amdgcn_rcpf(1.f + __builtin_amdgcn_exp2f(-1.4426950408889634f * x)); }
; __device__ __forceinline__ float gelu_t(float x) { const float u = x * (-2.3022081986f - 0.1029432404f * x * x); return x * __builtin_amdgcn_rcpf(1.f + __builtin_amdgcn_exp2f(u)); }
; __device__ __forceinline__ unsigned cvt_pk_bf16(float lo, float hi) { unsigned r; asm volatile("v_cvt_pk_bf16_f32 %0, %1, %2" : "=v"(r) : "v"(lo), "v"(hi)); return r; }
;     __device__ __forceinline__ void operator()(const f32x4 (&acc)[2][2][4][2], const Unit& u, int wr, int wc, int fr, int fq) const {
;     ...
;             const int col = pn * BM + cl; const f32x4 b0 = *(const f32x4*)(bias + col), b1 = *(const f32x4*)(bias + col + 4);
;             v0 = v0 + b0; v1 = v1 + b1;
;             if (act == 1) {
; #pragma unroll
;                 for (int e = 0; e < 4; ++e) { v0[e] = gelu_t(v0[e]); v1[e] = gelu_t(v1[e]); }
;             } else if (act == 2) {
; #pragma unroll
;                 for (int e = 0; e < 4; ++e) { v0[e] = sigmoidf_(v0[e]); v1[e] = sigmoidf_(v1[e]); }
;             }
;             u32x4 w; w.x = cvt_pk_bf16(v0[0], v0[1]); w.y = cvt_pk_bf16(v0[2], v0[3]); w.z = cvt_pk_bf16(v1[0], v1[1]); w.w = cvt_pk_bf16(v1[2], v1[3]);
;             *(u32x4*)(Z + (size_t)row * ZP + col) = w;
.LBB0_250:
	v_cvt_pk_bf16_f32 v80, v90, v92
	v_cvt_pk_bf16_f32 v81, v94, v97
	v_cvt_pk_bf16_f32 v82, v91, v93
	v_cvt_pk_bf16_f32 v83, v95, v96
	global_store_dwordx4 v[88:89], v[80:83], off offset:256
	s_cmp_gt_i32 s17, 1
	s_mov_b64 s[6:7], -1
	v_pk_add_f32 v[78:79], v[78:79], v[202:203]
	v_pk_add_f32 v[76:77], v[76:77], v[200:201]
	v_pk_add_f32 v[74:75], v[74:75], v[206:207]
	v_pk_add_f32 v[72:73], v[72:73], v[204:205]
	s_cbranch_scc0 .LBB0_252
	v_mul_f32_e32 v86, 0xbfb8aa3b, v79
	v_mul_f32_e32 v80, 0xbfb8aa3b, v76
	v_mul_f32_e32 v81, 0xbfb8aa3b, v72
	v_mul_f32_e32 v82, 0xbfb8aa3b, v77
	v_mul_f32_e32 v83, 0xbfb8aa3b, v73
	v_mul_f32_e32 v84, 0xbfb8aa3b, v78
	v_mul_f32_e32 v85, 0xbfb8aa3b, v74
	v_exp_f32_e32 v86, v86
	v_mul_f32_e32 v87, 0xbfb8aa3b, v75
	v_exp_f32_e32 v80, v80
	v_exp_f32_e32 v81, v81
	v_exp_f32_e32 v82, v82
	v_exp_f32_e32 v83, v83
	v_exp_f32_e32 v84, v84
	v_exp_f32_e32 v85, v85
	v_exp_f32_e32 v88, v87
	v_add_f32_e32 v86, 1.0, v86
	v_add_f32_e32 v80, 1.0, v80
	v_add_f32_e32 v81, 1.0, v81
	v_add_f32_e32 v82, 1.0, v82
	v_add_f32_e32 v83, 1.0, v83
	v_add_f32_e32 v84, 1.0, v84
	v_add_f32_e32 v85, 1.0, v85
	v_rcp_f32_e32 v87, v86
	v_add_f32_e32 v86, 1.0, v88
	v_rcp_f32_e32 v80, v80
	v_rcp_f32_e32 v81, v81
	v_rcp_f32_e32 v82, v82
	v_rcp_f32_e32 v83, v83
	v_rcp_f32_e32 v84, v84
	v_rcp_f32_e32 v85, v85
	v_rcp_f32_e32 v86, v86
	s_mov_b64 s[6:7], 0

; __device__ __forceinline__ float sigmoidf_(float x) { return __builtin_amdgcn_rcpf(1.f + __builtin_amdgcn_exp2f(-1.4426950408889634f * x)); }
; __device__ __forceinline__ float gelu_t(float x) { const float u = x * (-2.3022081986f - 0.1029432404f * x * x); return x * __builtin_amdgcn_rcpf(1.f + __builtin_amdgcn_exp2f(u)); }
; __device__ __forceinline__ unsigned cvt_pk_bf16(float lo, float hi) { unsigned r; asm volatile("v_cvt_pk_bf16_f32 %0, %1, %2" : "=v"(r) : "v"(lo), "v"(hi)); return r; }
;     __device__ __forceinline__ void operator()(const f32x4 (&acc)[2][2][4][2], const Unit& u, int wr, int wc, int fr, int fq) const {
;     ...
;             const int col = pn * BM + cl; const f32x4 b0 = *(const f32x4*)(bias + col), b1 = *(const f32x4*)(bias + col + 4);
;             v0 = v0 + b0; v1 = v1 + b1;
;             if (act == 1) {
; #pragma unroll
;                 for (int e = 0; e < 4; ++e) { v0[e] = gelu_t(v0[e]); v1[e] = gelu_t(v1[e]); }
;             } else if (act == 2) {
; #pragma unroll
;                 for (int e = 0; e < 4; ++e) { v0[e] = sigmoidf_(v0[e]); v1[e] = sigmoidf_(v1[e]); }
;             }
;             u32x4 w; w.x = cvt_pk_bf16(v0[0], v0[1]); w.y = cvt_pk_bf16(v0[2], v0[3]); w.z = cvt_pk_bf16(v1[0], v1[1]); w.w = cvt_pk_bf16(v1[2], v1[3]);
;             *(u32x4*)(Z + (size_t)row * ZP + col) = w;
.LBB0_256:
	v_or_b32_e32 v78, 48, v124
	v_mov_b64_e32 v[72:73], s[4:5]
	v_mad_i64_i32 v[72:73], s[6:7], v78, s65, v[72:73]
	v_lshl_add_u64 v[72:73], v[144:145], 1, v[72:73]
	v_cvt_pk_bf16_f32 v74, v80, v82
	v_cvt_pk_bf16_f32 v75, v84, v87
	v_cvt_pk_bf16_f32 v76, v81, v83
	v_cvt_pk_bf16_f32 v77, v85, v86
	global_store_dwordx4 v[72:73], v[74:77], off
	s_cmp_gt_i32 s17, 1
	s_mov_b64 s[6:7], -1
	v_pk_add_f32 v[70:71], v[70:71], v[210:211]
	v_pk_add_f32 v[68:69], v[68:69], v[208:209]
	v_pk_add_f32 v[66:67], v[66:67], v[214:215]
	v_pk_add_f32 v[64:65], v[64:65], v[212:213]
	s_cbranch_scc0 .LBB0_258
	v_mul_f32_e32 v80, 0xbfb8aa3b, v71
	v_mul_f32_e32 v74, 0xbfb8aa3b, v68
	v_mul_f32_e32 v75, 0xbfb8aa3b, v64
	v_mul_f32_e32 v76, 0xbfb8aa3b, v69
	v_mul_f32_e32 v77, 0xbfb8aa3b, v65
	v_mul_f32_e32 v78, 0xbfb8aa3b, v70
	v_mul_f32_e32 v79, 0xbfb8aa3b, v66
	v_exp_f32_e32 v80, v80
	v_mul_f32_e32 v81, 0xbfb8aa3b, v67
	v_exp_f32_e32 v74, v74
	v_exp_f32_e32 v75, v75
	v_exp_f32_e32 v76, v76
	v_exp_f32_e32 v77, v77
	v_exp_f32_e32 v78, v78
	v_exp_f32_e32 v79, v79
	v_exp_f32_e32 v82, v81
	v_add_f32_e32 v80, 1.0, v80
	v_add_f32_e32 v74, 1.0, v74
	v_add_f32_e32 v75, 1.0, v75
	v_add_f32_e32 v76, 1.0, v76
	v_add_f32_e32 v77, 1.0, v77
	v_add_f32_e32 v78, 1.0, v78
	v_add_f32_e32 v79, 1.0, v79
	v_rcp_f32_e32 v81, v80
	v_add_f32_e32 v80, 1.0, v82
	v_rcp_f32_e32 v74, v74
	v_rcp_f32_e32 v75, v75
	v_rcp_f32_e32 v76, v76
	v_rcp_f32_e32 v77, v77
	v_rcp_f32_e32 v78, v78
	v_rcp_f32_e32 v79, v79
	v_rcp_f32_e32 v80, v80
	s_mov_b64 s[6:7], 0

; __device__ __forceinline__ float sigmoidf_(float x) { return __builtin_amdgcn_rcpf(1.f + __builtin_amdgcn_exp2f(-1.4426950408889634f * x)); }
; __device__ __forceinline__ float gelu_t(float x) { const float u = x * (-2.3022081986f - 0.1029432404f * x * x); return x * __builtin_amdgcn_rcpf(1.f + __builtin_amdgcn_exp2f(u)); }
; __device__ __forceinline__ unsigned cvt_pk_bf16(float lo, float hi) { unsigned r; asm volatile("v_cvt_pk_bf16_f32 %0, %1, %2" : "=v"(r) : "v"(lo), "v"(hi)); return r; }
;     __device__ __forceinline__ void operator()(const f32x4 (&acc)[2][2][4][2], const Unit& u, int wr, int wc, int fr, int fq) const {
;     ...
;             const int col = pn * BM + cl; const f32x4 b0 = *(const f32x4*)(bias + col), b1 = *(const f32x4*)(bias + col + 4);
;             v0 = v0 + b0; v1 = v1 + b1;
;             if (act == 1) {
; #pragma unroll
;                 for (int e = 0; e < 4; ++e) { v0[e] = gelu_t(v0[e]); v1[e] = gelu_t(v1[e]); }
;             } else if (act == 2) {
; #pragma unroll
;                 for (int e = 0; e < 4; ++e) { v0[e] = sigmoidf_(v0[e]); v1[e] = sigmoidf_(v1[e]); }
;             }
;             u32x4 w; w.x = cvt_pk_bf16(v0[0], v0[1]); w.y = cvt_pk_bf16(v0[2], v0[3]); w.z = cvt_pk_bf16(v1[0], v1[1]); w.w = cvt_pk_bf16(v1[2], v1[3]);
;             *(u32x4*)(Z + (size_t)row * ZP + col) = w;
.LBB0_262:
	v_cvt_pk_bf16_f32 v64, v74, v76
	v_cvt_pk_bf16_f32 v65, v78, v81
	v_cvt_pk_bf16_f32 v66, v75, v77
	v_cvt_pk_bf16_f32 v67, v79, v80
	global_store_dwordx4 v[72:73], v[64:67], off offset:256
	s_cmp_gt_i32 s17, 1
	s_mov_b64 s[6:7], -1
	v_pk_add_f32 v[62:63], v[62:63], v[202:203]
	v_pk_add_f32 v[60:61], v[60:61], v[200:201]
	v_pk_add_f32 v[58:59], v[58:59], v[206:207]
	v_pk_add_f32 v[56:57], v[56:57], v[204:205]
	s_cbranch_scc0 .LBB0_264
	v_mul_f32_e32 v70, 0xbfb8aa3b, v63
	v_mul_f32_e32 v64, 0xbfb8aa3b, v60
	v_mul_f32_e32 v65, 0xbfb8aa3b, v56
	v_mul_f32_e32 v66, 0xbfb8aa3b, v61
	v_mul_f32_e32 v67, 0xbfb8aa3b, v57
	v_mul_f32_e32 v68, 0xbfb8aa3b, v62
	v_mul_f32_e32 v69, 0xbfb8aa3b, v58
	v_exp_f32_e32 v70, v70
	v_mul_f32_e32 v71, 0xbfb8aa3b, v59
	v_exp_f32_e32 v64, v64
	v_exp_f32_e32 v65, v65
	v_exp_f32_e32 v66, v66
	v_exp_f32_e32 v67, v67
	v_exp_f32_e32 v68, v68
	v_exp_f32_e32 v69, v69
	v_exp_f32_e32 v72, v71
	v_add_f32_e32 v70, 1.0, v70
	v_add_f32_e32 v64, 1.0, v64
	v_add_f32_e32 v65, 1.0, v65
	v_add_f32_e32 v66, 1.0, v66
	v_add_f32_e32 v67, 1.0, v67
	v_add_f32_e32 v68, 1.0, v68
	v_add_f32_e32 v69, 1.0, v69
	v_rcp_f32_e32 v71, v70
	v_add_f32_e32 v70, 1.0, v72
	v_rcp_f32_e32 v64, v64
	v_rcp_f32_e32 v65, v65
	v_rcp_f32_e32 v66, v66
	v_rcp_f32_e32 v67, v67
	v_rcp_f32_e32 v68, v68
	v_rcp_f32_e32 v69, v69
	v_rcp_f32_e32 v70, v70
	s_mov_b64 s[6:7], 0

; __device__ __forceinline__ float sigmoidf_(float x) { return __builtin_amdgcn_rcpf(1.f + __builtin_amdgcn_exp2f(-1.4426950408889634f * x)); }
; __device__ __forceinline__ float gelu_t(float x) { const float u = x * (-2.3022081986f - 0.1029432404f * x * x); return x * __builtin_amdgcn_rcpf(1.f + __builtin_amdgcn_exp2f(u)); }
; __device__ __forceinline__ unsigned cvt_pk_bf16(float lo, float hi) { unsigned r; asm volatile("v_cvt_pk_bf16_f32 %0, %1, %2" : "=v"(r) : "v"(lo), "v"(hi)); return r; }
;     __device__ __forceinline__ void operator()(const f32x4 (&acc)[2][2][4][2], const Unit& u, int wr, int wc, int fr, int fq) const {
;     ...
;             const int col = pn * BM + cl; const f32x4 b0 = *(const f32x4*)(bias + col), b1 = *(const f32x4*)(bias + col + 4);
;             v0 = v0 + b0; v1 = v1 + b1;
;             if (act == 1) {
; #pragma unroll
;                 for (int e = 0; e < 4; ++e) { v0[e] = gelu_t(v0[e]); v1[e] = gelu_t(v1[e]); }
;             } else if (act == 2) {
; #pragma unroll
;                 for (int e = 0; e < 4; ++e) { v0[e] = sigmoidf_(v0[e]); v1[e] = sigmoidf_(v1[e]); }
;             }
;             u32x4 w; w.x = cvt_pk_bf16(v0[0], v0[1]); w.y = cvt_pk_bf16(v0[2], v0[3]); w.z = cvt_pk_bf16(v1[0], v1[1]); w.w = cvt_pk_bf16(v1[2], v1[3]);
;             *(u32x4*)(Z + (size_t)row * ZP + col) = w;
.LBB0_268:
	v_add_u32_e32 v62, 0x80, v124
	v_mov_b64_e32 v[56:57], s[4:5]
	v_mad_i64_i32 v[56:57], s[6:7], v62, s65, v[56:57]
	v_lshl_add_u64 v[56:57], v[144:145], 1, v[56:57]
	v_cvt_pk_bf16_f32 v58, v64, v66
	v_cvt_pk_bf16_f32 v59, v68, v71
	v_cvt_pk_bf16_f32 v60, v65, v67
	v_cvt_pk_bf16_f32 v61, v69, v70
	global_store_dwordx4 v[56:57], v[58:61], off
	s_cmp_gt_i32 s17, 1
	s_mov_b64 s[6:7], -1
	v_pk_add_f32 v[54:55], v[54:55], v[210:211]
	v_pk_add_f32 v[52:53], v[52:53], v[208:209]
	v_pk_add_f32 v[50:51], v[50:51], v[214:215]
	v_pk_add_f32 v[48:49], v[48:49], v[212:213]
	s_cbranch_scc0 .LBB0_270
	v_mul_f32_e32 v64, 0xbfb8aa3b, v55
	v_mul_f32_e32 v58, 0xbfb8aa3b, v52
	v_mul_f32_e32 v59, 0xbfb8aa3b, v48
	v_mul_f32_e32 v60, 0xbfb8aa3b, v53
	v_mul_f32_e32 v61, 0xbfb8aa3b, v49
	v_mul_f32_e32 v62, 0xbfb8aa3b, v54
	v_mul_f32_e32 v63, 0xbfb8aa3b, v50
	v_exp_f32_e32 v64, v64
	v_mul_f32_e32 v65, 0xbfb8aa3b, v51
	v_exp_f32_e32 v58, v58
	v_exp_f32_e32 v59, v59
	v_exp_f32_e32 v60, v60
	v_exp_f32_e32 v61, v61
	v_exp_f32_e32 v62, v62
	v_exp_f32_e32 v63, v63
	v_exp_f32_e32 v66, v65
	v_add_f32_e32 v64, 1.0, v64
	v_add_f32_e32 v58, 1.0, v58
	v_add_f32_e32 v59, 1.0, v59
	v_add_f32_e32 v60, 1.0, v60
	v_add_f32_e32 v61, 1.0, v61
	v_add_f32_e32 v62, 1.0, v62
	v_add_f32_e32 v63, 1.0, v63
	v_rcp_f32_e32 v65, v64
	v_add_f32_e32 v64, 1.0, v66
	v_rcp_f32_e32 v58, v58
	v_rcp_f32_e32 v59, v59
	v_rcp_f32_e32 v60, v60
	v_rcp_f32_e32 v61, v61
	v_rcp_f32_e32 v62, v62
	v_rcp_f32_e32 v63, v63
	v_rcp_f32_e32 v64, v64
	s_mov_b64 s[6:7], 0

; __device__ __forceinline__ float sigmoidf_(float x) { return __builtin_amdgcn_rcpf(1.f + __builtin_amdgcn_exp2f(-1.4426950408889634f * x)); }
; __device__ __forceinline__ float gelu_t(float x) { const float u = x * (-2.3022081986f - 0.1029432404f * x * x); return x * __builtin_amdgcn_rcpf(1.f + __builtin_amdgcn_exp2f(u)); }
; __device__ __forceinline__ unsigned cvt_pk_bf16(float lo, float hi) { unsigned r; asm volatile("v_cvt_pk_bf16_f32 %0, %1, %2" : "=v"(r) : "v"(lo), "v"(hi)); return r; }
;     __device__ __forceinline__ void operator()(const f32x4 (&acc)[2][2][4][2], const Unit& u, int wr, int wc, int fr, int fq) const {
;     ...
;             const int col = pn * BM + cl; const f32x4 b0 = *(const f32x4*)(bias + col), b1 = *(const f32x4*)(bias + col + 4);
;             v0 = v0 + b0; v1 = v1 + b1;
;             if (act == 1) {
; #pragma unroll
;                 for (int e = 0; e < 4; ++e) { v0[e] = gelu_t(v0[e]); v1[e] = gelu_t(v1[e]); }
;             } else if (act == 2) {
; #pragma unroll
;                 for (int e = 0; e < 4; ++e) { v0[e] = sigmoidf_(v0[e]); v1[e] = sigmoidf_(v1[e]); }
;             }
;             u32x4 w; w.x = cvt_pk_bf16(v0[0], v0[1]); w.y = cvt_pk_bf16(v0[2], v0[3]); w.z = cvt_pk_bf16(v1[0], v1[1]); w.w = cvt_pk_bf16(v1[2], v1[3]);
;             *(u32x4*)(Z + (size_t)row * ZP + col) = w;
.LBB0_274:
	v_cvt_pk_bf16_f32 v48, v58, v60
	v_cvt_pk_bf16_f32 v49, v62, v65
	v_cvt_pk_bf16_f32 v50, v59, v61
	v_cvt_pk_bf16_f32 v51, v63, v64
	global_store_dwordx4 v[56:57], v[48:51], off offset:256
	s_cmp_gt_i32 s17, 1
	s_mov_b64 s[6:7], -1
	v_pk_add_f32 v[46:47], v[46:47], v[202:203]
	v_pk_add_f32 v[44:45], v[44:45], v[200:201]
	v_pk_add_f32 v[42:43], v[42:43], v[206:207]
	v_pk_add_f32 v[40:41], v[40:41], v[204:205]
	s_cbranch_scc0 .LBB0_276
	v_mul_f32_e32 v54, 0xbfb8aa3b, v47
	v_mul_f32_e32 v48, 0xbfb8aa3b, v44
	v_mul_f32_e32 v49, 0xbfb8aa3b, v40
	v_mul_f32_e32 v50, 0xbfb8aa3b, v45
	v_mul_f32_e32 v51, 0xbfb8aa3b, v41
	v_mul_f32_e32 v52, 0xbfb8aa3b, v46
	v_mul_f32_e32 v53, 0xbfb8aa3b, v42
	v_exp_f32_e32 v54, v54
	v_mul_f32_e32 v55, 0xbfb8aa3b, v43
	v_exp_f32_e32 v48, v48
	v_exp_f32_e32 v49, v49
	v_exp_f32_e32 v50, v50
	v_exp_f32_e32 v51, v51
	v_exp_f32_e32 v52, v52
	v_exp_f32_e32 v53, v53
	v_exp_f32_e32 v56, v55
	v_add_f32_e32 v54, 1.0, v54
	v_add_f32_e32 v48, 1.0, v48
	v_add_f32_e32 v49, 1.0, v49
	v_add_f32_e32 v50, 1.0, v50
	v_add_f32_e32 v51, 1.0, v51
	v_add_f32_e32 v52, 1.0, v52
	v_add_f32_e32 v53, 1.0, v53
	v_rcp_f32_e32 v55, v54
	v_add_f32_e32 v54, 1.0, v56
	v_rcp_f32_e32 v48, v48
	v_rcp_f32_e32 v49, v49
	v_rcp_f32_e32 v50, v50
	v_rcp_f32_e32 v51, v51
	v_rcp_f32_e32 v52, v52
	v_rcp_f32_e32 v53, v53
	v_rcp_f32_e32 v54, v54
	s_mov_b64 s[6:7], 0

; __device__ __forceinline__ float sigmoidf_(float x) { return __builtin_amdgcn_rcpf(1.f + __builtin_amdgcn_exp2f(-1.4426950408889634f * x)); }
; __device__ __forceinline__ float gelu_t(float x) { const float u = x * (-2.3022081986f - 0.1029432404f * x * x); return x * __builtin_amdgcn_rcpf(1.f + __builtin_amdgcn_exp2f(u)); }
; __device__ __forceinline__ unsigned cvt_pk_bf16(float lo, float hi) { unsigned r; asm volatile("v_cvt_pk_bf16_f32 %0, %1, %2" : "=v"(r) : "v"(lo), "v"(hi)); return r; }
;     __device__ __forceinline__ void operator()(const f32x4 (&acc)[2][2][4][2], const Unit& u, int wr, int wc, int fr, int fq) const {
;     ...
;             const int col = pn * BM + cl; const f32x4 b0 = *(const f32x4*)(bias + col), b1 = *(const f32x4*)(bias + col + 4);
;             v0 = v0 + b0; v1 = v1 + b1;
;             if (act == 1) {
; #pragma unroll
;                 for (int e = 0; e < 4; ++e) { v0[e] = gelu_t(v0[e]); v1[e] = gelu_t(v1[e]); }
;             } else if (act == 2) {
; #pragma unroll
;                 for (int e = 0; e < 4; ++e) { v0[e] = sigmoidf_(v0[e]); v1[e] = sigmoidf_(v1[e]); }
;             }
;             u32x4 w; w.x = cvt_pk_bf16(v0[0], v0[1]); w.y = cvt_pk_bf16(v0[2], v0[3]); w.z = cvt_pk_bf16(v1[0], v1[1]); w.w = cvt_pk_bf16(v1[2], v1[3]);
;             *(u32x4*)(Z + (size_t)row * ZP + col) = w;
.LBB0_280:
	v_add_u32_e32 v46, 0x90, v124
	v_mov_b64_e32 v[40:41], s[4:5]
	v_mad_i64_i32 v[40:41], s[6:7], v46, s65, v[40:41]
	v_lshl_add_u64 v[40:41], v[144:145], 1, v[40:41]
	v_cvt_pk_bf16_f32 v42, v48, v50
	v_cvt_pk_bf16_f32 v43, v52, v55
	v_cvt_pk_bf16_f32 v44, v49, v51
	v_cvt_pk_bf16_f32 v45, v53, v54
	global_store_dwordx4 v[40:41], v[42:45], off
	s_cmp_gt_i32 s17, 1
	s_mov_b64 s[6:7], -1
	v_pk_add_f32 v[38:39], v[38:39], v[210:211]
	v_pk_add_f32 v[36:37], v[36:37], v[208:209]
	v_pk_add_f32 v[34:35], v[34:35], v[214:215]
	v_pk_add_f32 v[32:33], v[32:33], v[212:213]
	s_cbranch_scc0 .LBB0_282
	v_mul_f32_e32 v48, 0xbfb8aa3b, v39
	v_mul_f32_e32 v42, 0xbfb8aa3b, v36
	v_mul_f32_e32 v43, 0xbfb8aa3b, v32
	v_mul_f32_e32 v44, 0xbfb8aa3b, v37
	v_mul_f32_e32 v45, 0xbfb8aa3b, v33
	v_mul_f32_e32 v46, 0xbfb8aa3b, v38
	v_mul_f32_e32 v47, 0xbfb8aa3b, v34
	v_exp_f32_e32 v48, v48
	v_mul_f32_e32 v49, 0xbfb8aa3b, v35
	v_exp_f32_e32 v42, v42
	v_exp_f32_e32 v43, v43
	v_exp_f32_e32 v44, v44
	v_exp_f32_e32 v45, v45
	v_exp_f32_e32 v46, v46
	v_exp_f32_e32 v47, v47
	v_exp_f32_e32 v50, v49
	v_add_f32_e32 v48, 1.0, v48
	v_add_f32_e32 v42, 1.0, v42
	v_add_f32_e32 v43, 1.0, v43
	v_add_f32_e32 v44, 1.0, v44
	v_add_f32_e32 v45, 1.0, v45
	v_add_f32_e32 v46, 1.0, v46
	v_add_f32_e32 v47, 1.0, v47
	v_rcp_f32_e32 v49, v48
	v_add_f32_e32 v48, 1.0, v50
	v_rcp_f32_e32 v42, v42
	v_rcp_f32_e32 v43, v43
	v_rcp_f32_e32 v44, v44
	v_rcp_f32_e32 v45, v45
	v_rcp_f32_e32 v46, v46
	v_rcp_f32_e32 v47, v47
	v_rcp_f32_e32 v48, v48
	s_mov_b64 s[6:7], 0

; __device__ __forceinline__ float sigmoidf_(float x) { return __builtin_amdgcn_rcpf(1.f + __builtin_amdgcn_exp2f(-1.4426950408889634f * x)); }
; __device__ __forceinline__ float gelu_t(float x) { const float u = x * (-2.3022081986f - 0.1029432404f * x * x); return x * __builtin_amdgcn_rcpf(1.f + __builtin_amdgcn_exp2f(u)); }
; __device__ __forceinline__ unsigned cvt_pk_bf16(float lo, float hi) { unsigned r; asm volatile("v_cvt_pk_bf16_f32 %0, %1, %2" : "=v"(r) : "v"(lo), "v"(hi)); return r; }
;     __device__ __forceinline__ void operator()(const f32x4 (&acc)[2][2][4][2], const Unit& u, int wr, int wc, int fr, int fq) const {
;     ...
;             const int col = pn * BM + cl; const f32x4 b0 = *(const f32x4*)(bias + col), b1 = *(const f32x4*)(bias + col + 4);
;             v0 = v0 + b0; v1 = v1 + b1;
;             if (act == 1) {
; #pragma unroll
;                 for (int e = 0; e < 4; ++e) { v0[e] = gelu_t(v0[e]); v1[e] = gelu_t(v1[e]); }
;             } else if (act == 2) {
; #pragma unroll
;                 for (int e = 0; e < 4; ++e) { v0[e] = sigmoidf_(v0[e]); v1[e] = sigmoidf_(v1[e]); }
;             }
;             u32x4 w; w.x = cvt_pk_bf16(v0[0], v0[1]); w.y = cvt_pk_bf16(v0[2], v0[3]); w.z = cvt_pk_bf16(v1[0], v1[1]); w.w = cvt_pk_bf16(v1[2], v1[3]);
;             *(u32x4*)(Z + (size_t)row * ZP + col) = w;
.LBB0_286:
	v_cvt_pk_bf16_f32 v32, v42, v44
	v_cvt_pk_bf16_f32 v33, v46, v49
	v_cvt_pk_bf16_f32 v34, v43, v45
	v_cvt_pk_bf16_f32 v35, v47, v48
	global_store_dwordx4 v[40:41], v[32:35], off offset:256
	s_cmp_gt_i32 s17, 1
	s_mov_b64 s[6:7], -1
	v_pk_add_f32 v[30:31], v[30:31], v[202:203]
	v_pk_add_f32 v[28:29], v[28:29], v[200:201]
	v_pk_add_f32 v[26:27], v[26:27], v[206:207]
	v_pk_add_f32 v[24:25], v[24:25], v[204:205]
	s_cbranch_scc0 .LBB0_288
	v_mul_f32_e32 v38, 0xbfb8aa3b, v31
	v_mul_f32_e32 v32, 0xbfb8aa3b, v28
	v_mul_f32_e32 v33, 0xbfb8aa3b, v24
	v_mul_f32_e32 v34, 0xbfb8aa3b, v29
	v_mul_f32_e32 v35, 0xbfb8aa3b, v25
	v_mul_f32_e32 v36, 0xbfb8aa3b, v30
	v_mul_f32_e32 v37, 0xbfb8aa3b, v26
	v_exp_f32_e32 v38, v38
	v_mul_f32_e32 v39, 0xbfb8aa3b, v27
	v_exp_f32_e32 v32, v32
	v_exp_f32_e32 v33, v33
	v_exp_f32_e32 v34, v34
	v_exp_f32_e32 v35, v35
	v_exp_f32_e32 v36, v36
	v_exp_f32_e32 v37, v37
	v_exp_f32_e32 v40, v39
	v_add_f32_e32 v38, 1.0, v38
	v_add_f32_e32 v32, 1.0, v32
	v_add_f32_e32 v33, 1.0, v33
	v_add_f32_e32 v34, 1.0, v34
	v_add_f32_e32 v35, 1.0, v35
	v_add_f32_e32 v36, 1.0, v36
	v_add_f32_e32 v37, 1.0, v37
	v_rcp_f32_e32 v39, v38
	v_add_f32_e32 v38, 1.0, v40
	v_rcp_f32_e32 v32, v32
	v_rcp_f32_e32 v33, v33
	v_rcp_f32_e32 v34, v34
	v_rcp_f32_e32 v35, v35
	v_rcp_f32_e32 v36, v36
	v_rcp_f32_e32 v37, v37
	v_rcp_f32_e32 v38, v38
	s_mov_b64 s[6:7], 0

; __device__ __forceinline__ float sigmoidf_(float x) { return __builtin_amdgcn_rcpf(1.f + __builtin_amdgcn_exp2f(-1.4426950408889634f * x)); }
; __device__ __forceinline__ float gelu_t(float x) { const float u = x * (-2.3022081986f - 0.1029432404f * x * x); return x * __builtin_amdgcn_rcpf(1.f + __builtin_amdgcn_exp2f(u)); }
; __device__ __forceinline__ unsigned cvt_pk_bf16(float lo, float hi) { unsigned r; asm volatile("v_cvt_pk_bf16_f32 %0, %1, %2" : "=v"(r) : "v"(lo), "v"(hi)); return r; }
;     __device__ __forceinline__ void operator()(const f32x4 (&acc)[2][2][4][2], const Unit& u, int wr, int wc, int fr, int fq) const {
;     ...
;             const int col = pn * BM + cl; const f32x4 b0 = *(const f32x4*)(bias + col), b1 = *(const f32x4*)(bias + col + 4);
;             v0 = v0 + b0; v1 = v1 + b1;
;             if (act == 1) {
; #pragma unroll
;                 for (int e = 0; e < 4; ++e) { v0[e] = gelu_t(v0[e]); v1[e] = gelu_t(v1[e]); }
;             } else if (act == 2) {
; #pragma unroll
;                 for (int e = 0; e < 4; ++e) { v0[e] = sigmoidf_(v0[e]); v1[e] = sigmoidf_(v1[e]); }
;             }
;             u32x4 w; w.x = cvt_pk_bf16(v0[0], v0[1]); w.y = cvt_pk_bf16(v0[2], v0[3]); w.z = cvt_pk_bf16(v1[0], v1[1]); w.w = cvt_pk_bf16(v1[2], v1[3]);
;             *(u32x4*)(Z + (size_t)row * ZP + col) = w;
.LBB0_292:
	v_add_u32_e32 v30, 0xa0, v124
	v_mov_b64_e32 v[24:25], s[4:5]
	v_mad_i64_i32 v[24:25], s[6:7], v30, s65, v[24:25]
	v_lshl_add_u64 v[24:25], v[144:145], 1, v[24:25]
	v_cvt_pk_bf16_f32 v26, v32, v34
	v_cvt_pk_bf16_f32 v27, v36, v39
	v_cvt_pk_bf16_f32 v28, v33, v35
	v_cvt_pk_bf16_f32 v29, v37, v38
	global_store_dwordx4 v[24:25], v[26:29], off
	s_cmp_gt_i32 s17, 1
	s_mov_b64 s[6:7], -1
	v_pk_add_f32 v[22:23], v[22:23], v[210:211]
	v_pk_add_f32 v[20:21], v[20:21], v[208:209]
	v_pk_add_f32 v[18:19], v[18:19], v[214:215]
	v_pk_add_f32 v[16:17], v[16:17], v[212:213]
	s_cbranch_scc0 .LBB0_294
	v_mul_f32_e32 v32, 0xbfb8aa3b, v23
	v_mul_f32_e32 v26, 0xbfb8aa3b, v20
	v_mul_f32_e32 v27, 0xbfb8aa3b, v16
	v_mul_f32_e32 v28, 0xbfb8aa3b, v21
	v_mul_f32_e32 v29, 0xbfb8aa3b, v17
	v_mul_f32_e32 v30, 0xbfb8aa3b, v22
	v_mul_f32_e32 v31, 0xbfb8aa3b, v18
	v_exp_f32_e32 v32, v32
	v_mul_f32_e32 v33, 0xbfb8aa3b, v19
	v_exp_f32_e32 v26, v26
	v_exp_f32_e32 v27, v27
	v_exp_f32_e32 v28, v28
	v_exp_f32_e32 v29, v29
	v_exp_f32_e32 v30, v30
	v_exp_f32_e32 v31, v31
	v_exp_f32_e32 v34, v33
	v_add_f32_e32 v32, 1.0, v32
	v_add_f32_e32 v26, 1.0, v26
	v_add_f32_e32 v27, 1.0, v27
	v_add_f32_e32 v28, 1.0, v28
	v_add_f32_e32 v29, 1.0, v29
	v_add_f32_e32 v30, 1.0, v30
	v_add_f32_e32 v31, 1.0, v31
	v_rcp_f32_e32 v33, v32
	v_add_f32_e32 v32, 1.0, v34
	v_rcp_f32_e32 v26, v26
	v_rcp_f32_e32 v27, v27
	v_rcp_f32_e32 v28, v28
	v_rcp_f32_e32 v29, v29
	v_rcp_f32_e32 v30, v30
	v_rcp_f32_e32 v31, v31
	v_rcp_f32_e32 v32, v32
	s_mov_b64 s[6:7], 0

; __device__ __forceinline__ float sigmoidf_(float x) { return __builtin_amdgcn_rcpf(1.f + __builtin_amdgcn_exp2f(-1.4426950408889634f * x)); }
; __device__ __forceinline__ float gelu_t(float x) { const float u = x * (-2.3022081986f - 0.1029432404f * x * x); return x * __builtin_amdgcn_rcpf(1.f + __builtin_amdgcn_exp2f(u)); }
; __device__ __forceinline__ unsigned cvt_pk_bf16(float lo, float hi) { unsigned r; asm volatile("v_cvt_pk_bf16_f32 %0, %1, %2" : "=v"(r) : "v"(lo), "v"(hi)); return r; }
;     __device__ __forceinline__ void operator()(const f32x4 (&acc)[2][2][4][2], const Unit& u, int wr, int wc, int fr, int fq) const {
;     ...
;             const int col = pn * BM + cl; const f32x4 b0 = *(const f32x4*)(bias + col), b1 = *(const f32x4*)(bias + col + 4);
;             v0 = v0 + b0; v1 = v1 + b1;
;             if (act == 1) {
; #pragma unroll
;                 for (int e = 0; e < 4; ++e) { v0[e] = gelu_t(v0[e]); v1[e] = gelu_t(v1[e]); }
;             } else if (act == 2) {
; #pragma unroll
;                 for (int e = 0; e < 4; ++e) { v0[e] = sigmoidf_(v0[e]); v1[e] = sigmoidf_(v1[e]); }
;             }
;             u32x4 w; w.x = cvt_pk_bf16(v0[0], v0[1]); w.y = cvt_pk_bf16(v0[2], v0[3]); w.z = cvt_pk_bf16(v1[0], v1[1]); w.w = cvt_pk_bf16(v1[2], v1[3]);
;             *(u32x4*)(Z + (size_t)row * ZP + col) = w;
.LBB0_298:
	v_cvt_pk_bf16_f32 v16, v26, v28
	v_cvt_pk_bf16_f32 v17, v30, v33
	v_cvt_pk_bf16_f32 v18, v27, v29
	v_cvt_pk_bf16_f32 v19, v31, v32
	global_store_dwordx4 v[24:25], v[16:19], off offset:256
	s_cmp_gt_i32 s17, 1
	s_mov_b64 s[6:7], -1
	v_pk_add_f32 v[14:15], v[14:15], v[202:203]
	v_pk_add_f32 v[12:13], v[12:13], v[200:201]
	v_pk_add_f32 v[10:11], v[10:11], v[206:207]
	v_pk_add_f32 v[8:9], v[8:9], v[204:205]
	s_cbranch_scc0 .LBB0_300
	v_mul_f32_e32 v22, 0xbfb8aa3b, v15
	v_mul_f32_e32 v16, 0xbfb8aa3b, v12
	v_mul_f32_e32 v17, 0xbfb8aa3b, v8
	v_mul_f32_e32 v18, 0xbfb8aa3b, v13
	v_mul_f32_e32 v19, 0xbfb8aa3b, v9
	v_mul_f32_e32 v20, 0xbfb8aa3b, v14
	v_mul_f32_e32 v21, 0xbfb8aa3b, v10
	v_exp_f32_e32 v22, v22
	v_mul_f32_e32 v23, 0xbfb8aa3b, v11
	v_exp_f32_e32 v16, v16
	v_exp_f32_e32 v17, v17
	v_exp_f32_e32 v18, v18
	v_exp_f32_e32 v19, v19
	v_exp_f32_e32 v20, v20
	v_exp_f32_e32 v21, v21
	v_exp_f32_e32 v24, v23
	v_add_f32_e32 v22, 1.0, v22
	v_add_f32_e32 v16, 1.0, v16
	v_add_f32_e32 v17, 1.0, v17
	v_add_f32_e32 v18, 1.0, v18
	v_add_f32_e32 v19, 1.0, v19
	v_add_f32_e32 v20, 1.0, v20
	v_add_f32_e32 v21, 1.0, v21
	v_rcp_f32_e32 v23, v22
	v_add_f32_e32 v22, 1.0, v24
	v_rcp_f32_e32 v16, v16
	v_rcp_f32_e32 v17, v17
	v_rcp_f32_e32 v18, v18
	v_rcp_f32_e32 v19, v19
	v_rcp_f32_e32 v20, v20
	v_rcp_f32_e32 v21, v21
	v_rcp_f32_e32 v22, v22
	s_mov_b64 s[6:7], 0

; __device__ __forceinline__ float sigmoidf_(float x) { return __builtin_amdgcn_rcpf(1.f + __builtin_amdgcn_exp2f(-1.4426950408889634f * x)); }
; __device__ __forceinline__ float gelu_t(float x) { const float u = x * (-2.3022081986f - 0.1029432404f * x * x); return x * __builtin_amdgcn_rcpf(1.f + __builtin_amdgcn_exp2f(u)); }
; __device__ __forceinline__ unsigned cvt_pk_bf16(float lo, float hi) { unsigned r; asm volatile("v_cvt_pk_bf16_f32 %0, %1, %2" : "=v"(r) : "v"(lo), "v"(hi)); return r; }
;     __device__ __forceinline__ void operator()(const f32x4 (&acc)[2][2][4][2], const Unit& u, int wr, int wc, int fr, int fq) const {
;     ...
;             const int col = pn * BM + cl; const f32x4 b0 = *(const f32x4*)(bias + col), b1 = *(const f32x4*)(bias + col + 4);
;             v0 = v0 + b0; v1 = v1 + b1;
;             if (act == 1) {
; #pragma unroll
;                 for (int e = 0; e < 4; ++e) { v0[e] = gelu_t(v0[e]); v1[e] = gelu_t(v1[e]); }
;             } else if (act == 2) {
; #pragma unroll
;                 for (int e = 0; e < 4; ++e) { v0[e] = sigmoidf_(v0[e]); v1[e] = sigmoidf_(v1[e]); }
;             }
;             u32x4 w; w.x = cvt_pk_bf16(v0[0], v0[1]); w.y = cvt_pk_bf16(v0[2], v0[3]); w.z = cvt_pk_bf16(v1[0], v1[1]); w.w = cvt_pk_bf16(v1[2], v1[3]);
;             *(u32x4*)(Z + (size_t)row * ZP + col) = w;
.LBB0_304:
	v_add_u32_e32 v14, 0xb0, v124
	v_mov_b64_e32 v[8:9], s[4:5]
	v_mad_i64_i32 v[8:9], s[6:7], v14, s65, v[8:9]
	v_lshl_add_u64 v[8:9], v[144:145], 1, v[8:9]
	v_cvt_pk_bf16_f32 v10, v16, v18
	v_cvt_pk_bf16_f32 v11, v20, v23
	v_cvt_pk_bf16_f32 v12, v17, v19
	v_cvt_pk_bf16_f32 v13, v21, v22
	global_store_dwordx4 v[8:9], v[10:13], off
	s_cmp_gt_i32 s17, 1
	s_mov_b64 s[6:7], -1
	v_pk_add_f32 v[6:7], v[6:7], v[210:211]
	v_pk_add_f32 v[4:5], v[4:5], v[208:209]
	v_pk_add_f32 v[2:3], v[2:3], v[214:215]
	v_pk_add_f32 v[0:1], v[0:1], v[212:213]
	s_cbranch_scc0 .LBB0_306
	v_mul_f32_e32 v16, 0xbfb8aa3b, v7
	v_mul_f32_e32 v10, 0xbfb8aa3b, v4
	v_mul_f32_e32 v11, 0xbfb8aa3b, v0
	v_mul_f32_e32 v12, 0xbfb8aa3b, v5
	v_mul_f32_e32 v13, 0xbfb8aa3b, v1
	v_mul_f32_e32 v14, 0xbfb8aa3b, v6
	v_mul_f32_e32 v15, 0xbfb8aa3b, v2
	v_exp_f32_e32 v16, v16
	v_mul_f32_e32 v17, 0xbfb8aa3b, v3
	v_exp_f32_e32 v10, v10
	v_exp_f32_e32 v11, v11
	v_exp_f32_e32 v12, v12
	v_exp_f32_e32 v13, v13
	v_exp_f32_e32 v14, v14
	v_exp_f32_e32 v15, v15
	v_exp_f32_e32 v18, v17
	v_add_f32_e32 v16, 1.0, v16
	v_add_f32_e32 v10, 1.0, v10
	v_add_f32_e32 v11, 1.0, v11
	v_add_f32_e32 v12, 1.0, v12
	v_add_f32_e32 v13, 1.0, v13
	v_add_f32_e32 v14, 1.0, v14
	v_add_f32_e32 v15, 1.0, v15
	v_rcp_f32_e32 v17, v16
	v_add_f32_e32 v16, 1.0, v18
	v_rcp_f32_e32 v10, v10
	v_rcp_f32_e32 v11, v11
	v_rcp_f32_e32 v12, v12
	v_rcp_f32_e32 v13, v13
	v_rcp_f32_e32 v14, v14
	v_rcp_f32_e32 v15, v15
	v_rcp_f32_e32 v16, v16
	s_mov_b64 s[6:7], 0

; __device__ __forceinline__ void gmlp_mfma_unit(const Params& p, int l, bf16_t* Z, LAS unsigned char* lds, int nb) {
;     ...
;     for (int i = 0; i < 16; ++i) { const int tok = wave * 16 + i;
;         const u32x4 raw = *(const u32x4*)(Z + (size_t)(row0 + tok) * ZP + ZC_V + lane * 8);
;         const float x[8] = {bflo(raw.x), bfhi(raw.x), bflo(raw.y), bfhi(raw.y), bflo(raw.z), bfhi(raw.z), bflo(raw.w), bfhi(raw.w)};
;         float s = 0.f;
; #pragma unroll
;         for (int e = 0; e < 8; ++e) s += x[e];
;         const float mean = wave_sum(s) * (1.f / 512.f); float s2 = 0.f;
; #pragma unroll
;         for (int e = 0; e < 8; ++e) { const float d = x[e] - mean; s2 += d * d; }
;         const float rstd = 1.f / sqrtf(wave_sum(s2) * (1.f / 512.f) + 1e-5f);
;         if (lane == 0) { st[tok] = mean; st[128 + tok] = rstd; } }
.LBB0_334:
	v_lshl_add_u64 v[160:161], v[0:1], 0, 0
	global_load_dwordx4 v[96:99], v[160:161], off
	v_lshl_add_u64 v[160:161], v[160:161], 0, s[18:19]
	global_load_dwordx4 v[100:103], v[160:161], off
	v_lshl_add_u64 v[160:161], v[160:161], 0, s[18:19]
	global_load_dwordx4 v[104:107], v[160:161], off
	v_lshl_add_u64 v[160:161], v[160:161], 0, s[18:19]
	global_load_dwordx4 v[108:111], v[160:161], off
	v_lshl_add_u64 v[160:161], v[160:161], 0, s[18:19]
	global_load_dwordx4 v[112:115], v[160:161], off
	v_lshl_add_u64 v[160:161], v[160:161], 0, s[18:19]
	global_load_dwordx4 v[116:119], v[160:161], off
	v_lshl_add_u64 v[160:161], v[160:161], 0, s[18:19]
	global_load_dwordx4 v[120:123], v[160:161], off
	v_lshl_add_u64 v[160:161], v[160:161], 0, s[18:19]
	global_load_dwordx4 v[124:127], v[160:161], off
	v_lshl_add_u64 v[160:161], v[160:161], 0, s[18:19]
	global_load_dwordx4 v[128:131], v[160:161], off
	v_lshl_add_u64 v[160:161], v[160:161], 0, s[18:19]
	global_load_dwordx4 v[132:135], v[160:161], off
	v_lshl_add_u64 v[160:161], v[160:161], 0, s[18:19]
	global_load_dwordx4 v[136:139], v[160:161], off
	v_lshl_add_u64 v[160:161], v[160:161], 0, s[18:19]
	global_load_dwordx4 v[140:143], v[160:161], off
	v_lshl_add_u64 v[160:161], v[160:161], 0, s[18:19]
	global_load_dwordx4 v[144:147], v[160:161], off
	v_lshl_add_u64 v[160:161], v[160:161], 0, s[18:19]
	global_load_dwordx4 v[148:151], v[160:161], off
	v_lshl_add_u64 v[160:161], v[160:161], 0, s[18:19]
	global_load_dwordx4 v[152:155], v[160:161], off
	v_lshl_add_u64 v[160:161], v[160:161], 0, s[18:19]
	global_load_dwordx4 v[156:159], v[160:161], off
	s_waitcnt vmcnt(0)
	v_mov_b64_e32 v[2:3], v[96:97]
	v_mov_b64_e32 v[4:5], v[98:99]
	v_lshlrev_b32_e32 v6, 16, v2
	v_and_b32_e32 v7, 0xffff0000, v2
	v_add_f32_e32 v2, 0, v6
	v_lshlrev_b32_e32 v8, 16, v3
	v_add_f32_e32 v2, v2, v7
	v_and_b32_e32 v3, 0xffff0000, v3
	v_add_f32_e32 v2, v2, v8
	v_lshlrev_b32_e32 v9, 16, v4
	v_add_f32_e32 v2, v2, v3
	v_and_b32_e32 v4, 0xffff0000, v4
	v_add_f32_e32 v2, v2, v9
	v_lshlrev_b32_e32 v10, 16, v5
	v_add_f32_e32 v2, v2, v4
	v_and_b32_e32 v5, 0xffff0000, v5
	v_add_f32_e32 v2, v2, v10
	v_add_f32_e32 v2, v2, v5
	v_mov_b32_e32 v11, v2
	s_nop 1
	v_mov_b32_dpp v11, v11 quad_perm:[1,0,3,2] row_mask:0xf bank_mask:0xf
	v_add_f32_e32 v2, v2, v11
	v_mov_b32_e32 v11, v2
	s_nop 1
	v_mov_b32_dpp v11, v11 quad_perm:[2,3,0,1] row_mask:0xf bank_mask:0xf
	v_add_f32_e32 v2, v2, v11
	v_mov_b32_e32 v11, v2
	s_nop 1
	v_mov_b32_dpp v11, v11 row_half_mirror row_mask:0xf bank_mask:0xf
	v_add_f32_e32 v2, v2, v11
	v_mov_b32_e32 v11, v2
	s_nop 1
	v_mov_b32_dpp v11, v11 row_mirror row_mask:0xf bank_mask:0xf
	v_add_f32_e32 v2, v2, v11
	s_nop 0
	v_readlane_b32 s1, v2, 16
	v_readlane_b32 s5, v2, 48
	v_readlane_b32 s0, v2, 0
	v_readlane_b32 s4, v2, 32
	v_mov_b32_e32 v2, s1
	v_mov_b32_e32 v11, s5
	v_add_f32_e32 v2, s0, v2
	v_add_f32_e32 v11, s4, v11
	v_add_f32_e32 v2, v2, v11
	v_fmac_f32_e32 v7, 0xbb000000, v2
	v_fmac_f32_e32 v6, 0xbb000000, v2
	v_mul_f32_e32 v7, v7, v7
	v_fmac_f32_e32 v8, 0xbb000000, v2
	v_fmac_f32_e32 v7, v6, v6
	v_fmac_f32_e32 v3, 0xbb000000, v2
	v_fmac_f32_e32 v7, v8, v8
	v_fmac_f32_e32 v9, 0xbb000000, v2
	v_fmac_f32_e32 v7, v3, v3
	v_fmac_f32_e32 v4, 0xbb000000, v2
	v_fmac_f32_e32 v7, v9, v9
	v_fmac_f32_e32 v10, 0xbb000000, v2
	v_fmac_f32_e32 v7, v4, v4
	v_fmac_f32_e32 v5, 0xbb000000, v2
	v_fmac_f32_e32 v7, v10, v10
	v_fmac_f32_e32 v7, v5, v5
	v_mov_b32_e32 v3, v7
	s_nop 1
	v_mov_b32_dpp v3, v3 quad_perm:[1,0,3,2] row_mask:0xf bank_mask:0xf
	v_add_f32_e32 v3, v7, v3
	v_mov_b32_e32 v4, v3
	s_nop 1
	v_mov_b32_dpp v4, v4 quad_perm:[2,3,0,1] row_mask:0xf bank_mask:0xf
	v_add_f32_e32 v3, v3, v4
	v_mov_b32_e32 v4, v3
	s_nop 1
	v_mov_b32_dpp v4, v4 row_half_mirror row_mask:0xf bank_mask:0xf
	v_add_f32_e32 v3, v3, v4
	v_mov_b32_e32 v4, v3
	s_nop 1
	v_mov_b32_dpp v4, v4 row_mirror row_mask:0xf bank_mask:0xf
	v_add_f32_e32 v3, v3, v4
	s_nop 0
	v_readlane_b32 s0, v3, 0
	v_readlane_b32 s26, v3, 16
	v_readlane_b32 s1, v3, 32
	v_readlane_b32 s27, v3, 48
	s_and_saveexec_b64 s[4:5], s[2:3]
	s_cbranch_execz .Lgst_0_0
	v_mov_b32_e32 v3, s26
	v_mov_b32_e32 v4, s27
	v_add_f32_e32 v3, s0, v3
	v_add_f32_e32 v4, s1, v4
	v_add_f32_e32 v3, v3, v4
	v_fmamk_f32 v3, v3, 0x3b000000, v59
	v_mul_f32_e32 v4, 0x4f800000, v3
	v_cmp_gt_f32_e32 vcc, s13, v3
	v_mul_f32_e32 v2, 0x3b000000, v2
	s_nop 0
	v_cndmask_b32_e32 v3, v3, v4, vcc
	v_sqrt_f32_e32 v4, v3
	s_nop 0
	v_add_u32_e32 v5, -1, v4
	v_fma_f32 v6, -v5, v4, v3
	v_cmp_ge_f32_e64 s[0:1], 0, v6
	v_add_u32_e32 v6, 1, v4
	s_nop 0
	v_cndmask_b32_e64 v5, v4, v5, s[0:1]
	v_fma_f32 v4, -v6, v4, v3
	v_cmp_lt_f32_e64 s[0:1], 0, v4
	s_nop 1
	v_cndmask_b32_e64 v4, v5, v6, s[0:1]
	v_mul_f32_e32 v5, 0x37800000, v4
	v_cndmask_b32_e32 v4, v4, v5, vcc
	v_cmp_class_f32_e32 vcc, v3, v60
	s_nop 1
	v_cndmask_b32_e32 v3, v4, v3, vcc
	v_div_scale_f32 v4, s[0:1], v3, v3, 1.0
	v_rcp_f32_e32 v5, v4
	s_add_i32 s0, s24, s25
	v_fma_f32 v6, -v4, v5, 1.0
	v_fmac_f32_e32 v5, v6, v5
	v_div_scale_f32 v6, vcc, 1.0, v3, 1.0
	v_mul_f32_e32 v7, v6, v5
	v_fma_f32 v8, -v4, v7, v6
	v_fmac_f32_e32 v7, v8, v5
	v_fma_f32 v4, -v4, v7, v6
	v_div_fmas_f32 v4, v4, v5, v7
	v_div_fixup_f32 v3, v4, v3, 1.0
	v_mov_b32_e32 v4, s0
	ds_write2st64_b32 v4, v2, v3 offset1:2
; __device__ __forceinline__ void gmlp_mfma_unit(const Params& p, int l, bf16_t* Z, LAS unsigned char* lds, int nb) {
;     ...
;     for (int i = 0; i < 16; ++i) { const int tok = wave * 16 + i;
;         const u32x4 raw = *(const u32x4*)(Z + (size_t)(row0 + tok) * ZP + ZC_V + lane * 8);
;         const float x[8] = {bflo(raw.x), bfhi(raw.x), bflo(raw.y), bfhi(raw.y), bflo(raw.z), bfhi(raw.z), bflo(raw.w), bfhi(raw.w)};
;         float s = 0.f;
; #pragma unroll
;         for (int e = 0; e < 8; ++e) s += x[e];
;         const float mean = wave_sum(s) * (1.f / 512.f); float s2 = 0.f;
; #pragma unroll
;         for (int e = 0; e < 8; ++e) { const float d = x[e] - mean; s2 += d * d; }
;         const float rstd = 1.f / sqrtf(wave_sum(s2) * (1.f / 512.f) + 1e-5f);
;         if (lane == 0) { st[tok] = mean; st[128 + tok] = rstd; } }
.Lgst_0_0:
	s_or_b64 exec, exec, s[4:5]
	s_add_i32 s25, s25, 4
	v_mov_b64_e32 v[2:3], v[100:101]
	v_mov_b64_e32 v[4:5], v[102:103]
	v_lshlrev_b32_e32 v6, 16, v2
	v_and_b32_e32 v7, 0xffff0000, v2
	v_add_f32_e32 v2, 0, v6
	v_lshlrev_b32_e32 v8, 16, v3
	v_add_f32_e32 v2, v2, v7
	v_and_b32_e32 v3, 0xffff0000, v3
	v_add_f32_e32 v2, v2, v8
	v_lshlrev_b32_e32 v9, 16, v4
	v_add_f32_e32 v2, v2, v3
	v_and_b32_e32 v4, 0xffff0000, v4
	v_add_f32_e32 v2, v2, v9
	v_lshlrev_b32_e32 v10, 16, v5
	v_add_f32_e32 v2, v2, v4
	v_and_b32_e32 v5, 0xffff0000, v5
	v_add_f32_e32 v2, v2, v10
	v_add_f32_e32 v2, v2, v5
	v_mov_b32_e32 v11, v2
	s_nop 1
	v_mov_b32_dpp v11, v11 quad_perm:[1,0,3,2] row_mask:0xf bank_mask:0xf
	v_add_f32_e32 v2, v2, v11
	v_mov_b32_e32 v11, v2
	s_nop 1
	v_mov_b32_dpp v11, v11 quad_perm:[2,3,0,1] row_mask:0xf bank_mask:0xf
	v_add_f32_e32 v2, v2, v11
	v_mov_b32_e32 v11, v2
	s_nop 1
	v_mov_b32_dpp v11, v11 row_half_mirror row_mask:0xf bank_mask:0xf
	v_add_f32_e32 v2, v2, v11
	v_mov_b32_e32 v11, v2
	s_nop 1
	v_mov_b32_dpp v11, v11 row_mirror row_mask:0xf bank_mask:0xf
	v_add_f32_e32 v2, v2, v11
	s_nop 0
	v_readlane_b32 s1, v2, 16
	v_readlane_b32 s5, v2, 48
	v_readlane_b32 s0, v2, 0
	v_readlane_b32 s4, v2, 32
	v_mov_b32_e32 v2, s1
	v_mov_b32_e32 v11, s5
	v_add_f32_e32 v2, s0, v2
	v_add_f32_e32 v11, s4, v11
	v_add_f32_e32 v2, v2, v11
	v_fmac_f32_e32 v7, 0xbb000000, v2
	v_fmac_f32_e32 v6, 0xbb000000, v2
	v_mul_f32_e32 v7, v7, v7
	v_fmac_f32_e32 v8, 0xbb000000, v2
	v_fmac_f32_e32 v7, v6, v6
	v_fmac_f32_e32 v3, 0xbb000000, v2
	v_fmac_f32_e32 v7, v8, v8
	v_fmac_f32_e32 v9, 0xbb000000, v2
	v_fmac_f32_e32 v7, v3, v3
	v_fmac_f32_e32 v4, 0xbb000000, v2
	v_fmac_f32_e32 v7, v9, v9
	v_fmac_f32_e32 v10, 0xbb000000, v2
	v_fmac_f32_e32 v7, v4, v4
	v_fmac_f32_e32 v5, 0xbb000000, v2
	v_fmac_f32_e32 v7, v10, v10
	v_fmac_f32_e32 v7, v5, v5
	v_mov_b32_e32 v3, v7
	s_nop 1
	v_mov_b32_dpp v3, v3 quad_perm:[1,0,3,2] row_mask:0xf bank_mask:0xf
	v_add_f32_e32 v3, v7, v3
	v_mov_b32_e32 v4, v3
	s_nop 1
	v_mov_b32_dpp v4, v4 quad_perm:[2,3,0,1] row_mask:0xf bank_mask:0xf
	v_add_f32_e32 v3, v3, v4
	v_mov_b32_e32 v4, v3
	s_nop 1
	v_mov_b32_dpp v4, v4 row_half_mirror row_mask:0xf bank_mask:0xf
	v_add_f32_e32 v3, v3, v4
	v_mov_b32_e32 v4, v3
	s_nop 1
	v_mov_b32_dpp v4, v4 row_mirror row_mask:0xf bank_mask:0xf
	v_add_f32_e32 v3, v3, v4
	s_nop 0
	v_readlane_b32 s0, v3, 0
	v_readlane_b32 s26, v3, 16
	v_readlane_b32 s1, v3, 32
	v_readlane_b32 s27, v3, 48
	s_and_saveexec_b64 s[4:5], s[2:3]
	s_cbranch_execz .Lgst_0_1
	v_mov_b32_e32 v3, s26
	v_mov_b32_e32 v4, s27
	v_add_f32_e32 v3, s0, v3
	v_add_f32_e32 v4, s1, v4
	v_add_f32_e32 v3, v3, v4
	v_fmamk_f32 v3, v3, 0x3b000000, v59
	v_mul_f32_e32 v4, 0x4f800000, v3
	v_cmp_gt_f32_e32 vcc, s13, v3
	v_mul_f32_e32 v2, 0x3b000000, v2
	s_nop 0
	v_cndmask_b32_e32 v3, v3, v4, vcc
	v_sqrt_f32_e32 v4, v3
	s_nop 0
	v_add_u32_e32 v5, -1, v4
	v_fma_f32 v6, -v5, v4, v3
	v_cmp_ge_f32_e64 s[0:1], 0, v6
	v_add_u32_e32 v6, 1, v4
	s_nop 0
	v_cndmask_b32_e64 v5, v4, v5, s[0:1]
	v_fma_f32 v4, -v6, v4, v3
	v_cmp_lt_f32_e64 s[0:1], 0, v4
	s_nop 1
	v_cndmask_b32_e64 v4, v5, v6, s[0:1]
	v_mul_f32_e32 v5, 0x37800000, v4
	v_cndmask_b32_e32 v4, v4, v5, vcc
	v_cmp_class_f32_e32 vcc, v3, v60
	s_nop 1
	v_cndmask_b32_e32 v3, v4, v3, vcc
	v_div_scale_f32 v4, s[0:1], v3, v3, 1.0
	v_rcp_f32_e32 v5, v4
	s_add_i32 s0, s24, s25
	v_fma_f32 v6, -v4, v5, 1.0
	v_fmac_f32_e32 v5, v6, v5
	v_div_scale_f32 v6, vcc, 1.0, v3, 1.0
	v_mul_f32_e32 v7, v6, v5
	v_fma_f32 v8, -v4, v7, v6
	v_fmac_f32_e32 v7, v8, v5
	v_fma_f32 v4, -v4, v7, v6
	v_div_fmas_f32 v4, v4, v5, v7
	v_div_fixup_f32 v3, v4, v3, 1.0
	v_mov_b32_e32 v4, s0
	ds_write2st64_b32 v4, v2, v3 offset1:2
.Lgst_0_1:
	s_or_b64 exec, exec, s[4:5]
	s_add_i32 s25, s25, 4
	v_mov_b64_e32 v[2:3], v[104:105]
	v_mov_b64_e32 v[4:5], v[106:107]
	v_lshlrev_b32_e32 v6, 16, v2
	v_and_b32_e32 v7, 0xffff0000, v2
	v_add_f32_e32 v2, 0, v6
	v_lshlrev_b32_e32 v8, 16, v3
	v_add_f32_e32 v2, v2, v7
	v_and_b32_e32 v3, 0xffff0000, v3
	v_add_f32_e32 v2, v2, v8
	v_lshlrev_b32_e32 v9, 16, v4
	v_add_f32_e32 v2, v2, v3
	v_and_b32_e32 v4, 0xffff0000, v4
	v_add_f32_e32 v2, v2, v9
	v_lshlrev_b32_e32 v10, 16, v5
	v_add_f32_e32 v2, v2, v4
	v_and_b32_e32 v5, 0xffff0000, v5
	v_add_f32_e32 v2, v2, v10
	v_add_f32_e32 v2, v2, v5
	v_mov_b32_e32 v11, v2
	s_nop 1
	v_mov_b32_dpp v11, v11 quad_perm:[1,0,3,2] row_mask:0xf bank_mask:0xf
	v_add_f32_e32 v2, v2, v11
	v_mov_b32_e32 v11, v2
	s_nop 1
	v_mov_b32_dpp v11, v11 quad_perm:[2,3,0,1] row_mask:0xf bank_mask:0xf
	v_add_f32_e32 v2, v2, v11
	v_mov_b32_e32 v11, v2
	s_nop 1
	v_mov_b32_dpp v11, v11 row_half_mirror row_mask:0xf bank_mask:0xf
	v_add_f32_e32 v2, v2, v11
	v_mov_b32_e32 v11, v2
	s_nop 1
	v_mov_b32_dpp v11, v11 row_mirror row_mask:0xf bank_mask:0xf
	v_add_f32_e32 v2, v2, v11
	s_nop 0
	v_readlane_b32 s1, v2, 16
	v_readlane_b32 s5, v2, 48
	v_readlane_b32 s0, v2, 0
	v_readlane_b32 s4, v2, 32
	v_mov_b32_e32 v2, s1
	v_mov_b32_e32 v11, s5
	v_add_f32_e32 v2, s0, v2
	v_add_f32_e32 v11, s4, v11
	v_add_f32_e32 v2, v2, v11
	v_fmac_f32_e32 v7, 0xbb000000, v2
	v_fmac_f32_e32 v6, 0xbb000000, v2
	v_mul_f32_e32 v7, v7, v7
	v_fmac_f32_e32 v8, 0xbb000000, v2
	v_fmac_f32_e32 v7, v6, v6
	v_fmac_f32_e32 v3, 0xbb000000, v2
	v_fmac_f32_e32 v7, v8, v8
	v_fmac_f32_e32 v9, 0xbb000000, v2
	v_fmac_f32_e32 v7, v3, v3
	v_fmac_f32_e32 v4, 0xbb000000, v2
	v_fmac_f32_e32 v7, v9, v9
	v_fmac_f32_e32 v10, 0xbb000000, v2
	v_fmac_f32_e32 v7, v4, v4
	v_fmac_f32_e32 v5, 0xbb000000, v2
	v_fmac_f32_e32 v7, v10, v10
	v_fmac_f32_e32 v7, v5, v5
	v_mov_b32_e32 v3, v7
	s_nop 1
	v_mov_b32_dpp v3, v3 quad_perm:[1,0,3,2] row_mask:0xf bank_mask:0xf
	v_add_f32_e32 v3, v7, v3
	v_mov_b32_e32 v4, v3
	s_nop 1
	v_mov_b32_dpp v4, v4 quad_perm:[2,3,0,1] row_mask:0xf bank_mask:0xf
	v_add_f32_e32 v3, v3, v4
	v_mov_b32_e32 v4, v3
	s_nop 1
	v_mov_b32_dpp v4, v4 row_half_mirror row_mask:0xf bank_mask:0xf
	v_add_f32_e32 v3, v3, v4
	v_mov_b32_e32 v4, v3
	s_nop 1
	v_mov_b32_dpp v4, v4 row_mirror row_mask:0xf bank_mask:0xf
	v_add_f32_e32 v3, v3, v4
	s_nop 0
	v_readlane_b32 s0, v3, 0
	v_readlane_b32 s26, v3, 16
	v_readlane_b32 s1, v3, 32
	v_readlane_b32 s27, v3, 48
	s_and_saveexec_b64 s[4:5], s[2:3]
	s_cbranch_execz .Lgst_0_2
; __device__ __forceinline__ void gmlp_mfma_unit(const Params& p, int l, bf16_t* Z, LAS unsigned char* lds, int nb) {
;     ...
;     for (int i = 0; i < 16; ++i) { const int tok = wave * 16 + i;
;         const u32x4 raw = *(const u32x4*)(Z + (size_t)(row0 + tok) * ZP + ZC_V + lane * 8);
;         const float x[8] = {bflo(raw.x), bfhi(raw.x), bflo(raw.y), bfhi(raw.y), bflo(raw.z), bfhi(raw.z), bflo(raw.w), bfhi(raw.w)};
;         float s = 0.f;
; #pragma unroll
;         for (int e = 0; e < 8; ++e) s += x[e];
;         const float mean = wave_sum(s) * (1.f / 512.f); float s2 = 0.f;
; #pragma unroll
;         for (int e = 0; e < 8; ++e) { const float d = x[e] - mean; s2 += d * d; }
;         const float rstd = 1.f / sqrtf(wave_sum(s2) * (1.f / 512.f) + 1e-5f);
;         if (lane == 0) { st[tok] = mean; st[128 + tok] = rstd; } }
	v_mov_b32_e32 v3, s26
	v_mov_b32_e32 v4, s27
	v_add_f32_e32 v3, s0, v3
	v_add_f32_e32 v4, s1, v4
	v_add_f32_e32 v3, v3, v4
	v_fmamk_f32 v3, v3, 0x3b000000, v59
	v_mul_f32_e32 v4, 0x4f800000, v3
	v_cmp_gt_f32_e32 vcc, s13, v3
	v_mul_f32_e32 v2, 0x3b000000, v2
	s_nop 0
	v_cndmask_b32_e32 v3, v3, v4, vcc
	v_sqrt_f32_e32 v4, v3
	s_nop 0
	v_add_u32_e32 v5, -1, v4
	v_fma_f32 v6, -v5, v4, v3
	v_cmp_ge_f32_e64 s[0:1], 0, v6
	v_add_u32_e32 v6, 1, v4
	s_nop 0
	v_cndmask_b32_e64 v5, v4, v5, s[0:1]
	v_fma_f32 v4, -v6, v4, v3
	v_cmp_lt_f32_e64 s[0:1], 0, v4
	s_nop 1
	v_cndmask_b32_e64 v4, v5, v6, s[0:1]
	v_mul_f32_e32 v5, 0x37800000, v4
	v_cndmask_b32_e32 v4, v4, v5, vcc
	v_cmp_class_f32_e32 vcc, v3, v60
	s_nop 1
	v_cndmask_b32_e32 v3, v4, v3, vcc
	v_div_scale_f32 v4, s[0:1], v3, v3, 1.0
	v_rcp_f32_e32 v5, v4
	s_add_i32 s0, s24, s25
	v_fma_f32 v6, -v4, v5, 1.0
	v_fmac_f32_e32 v5, v6, v5
	v_div_scale_f32 v6, vcc, 1.0, v3, 1.0
	v_mul_f32_e32 v7, v6, v5
	v_fma_f32 v8, -v4, v7, v6
	v_fmac_f32_e32 v7, v8, v5
	v_fma_f32 v4, -v4, v7, v6
	v_div_fmas_f32 v4, v4, v5, v7
	v_div_fixup_f32 v3, v4, v3, 1.0
	v_mov_b32_e32 v4, s0
	ds_write2st64_b32 v4, v2, v3 offset1:2
.Lgst_0_2:
	s_or_b64 exec, exec, s[4:5]
	s_add_i32 s25, s25, 4
	v_mov_b64_e32 v[2:3], v[108:109]
	v_mov_b64_e32 v[4:5], v[110:111]
	v_lshlrev_b32_e32 v6, 16, v2
	v_and_b32_e32 v7, 0xffff0000, v2
	v_add_f32_e32 v2, 0, v6
	v_lshlrev_b32_e32 v8, 16, v3
	v_add_f32_e32 v2, v2, v7
	v_and_b32_e32 v3, 0xffff0000, v3
	v_add_f32_e32 v2, v2, v8
	v_lshlrev_b32_e32 v9, 16, v4
	v_add_f32_e32 v2, v2, v3
	v_and_b32_e32 v4, 0xffff0000, v4
	v_add_f32_e32 v2, v2, v9
	v_lshlrev_b32_e32 v10, 16, v5
	v_add_f32_e32 v2, v2, v4
	v_and_b32_e32 v5, 0xffff0000, v5
	v_add_f32_e32 v2, v2, v10
	v_add_f32_e32 v2, v2, v5
	v_mov_b32_e32 v11, v2
	s_nop 1
	v_mov_b32_dpp v11, v11 quad_perm:[1,0,3,2] row_mask:0xf bank_mask:0xf
	v_add_f32_e32 v2, v2, v11
	v_mov_b32_e32 v11, v2
	s_nop 1
	v_mov_b32_dpp v11, v11 quad_perm:[2,3,0,1] row_mask:0xf bank_mask:0xf
	v_add_f32_e32 v2, v2, v11
	v_mov_b32_e32 v11, v2
	s_nop 1
	v_mov_b32_dpp v11, v11 row_half_mirror row_mask:0xf bank_mask:0xf
	v_add_f32_e32 v2, v2, v11
	v_mov_b32_e32 v11, v2
	s_nop 1
	v_mov_b32_dpp v11, v11 row_mirror row_mask:0xf bank_mask:0xf
	v_add_f32_e32 v2, v2, v11
	s_nop 0
	v_readlane_b32 s1, v2, 16
	v_readlane_b32 s5, v2, 48
	v_readlane_b32 s0, v2, 0
	v_readlane_b32 s4, v2, 32
	v_mov_b32_e32 v2, s1
	v_mov_b32_e32 v11, s5
	v_add_f32_e32 v2, s0, v2
	v_add_f32_e32 v11, s4, v11
	v_add_f32_e32 v2, v2, v11
	v_fmac_f32_e32 v7, 0xbb000000, v2
	v_fmac_f32_e32 v6, 0xbb000000, v2
	v_mul_f32_e32 v7, v7, v7
	v_fmac_f32_e32 v8, 0xbb000000, v2
	v_fmac_f32_e32 v7, v6, v6
	v_fmac_f32_e32 v3, 0xbb000000, v2
	v_fmac_f32_e32 v7, v8, v8
	v_fmac_f32_e32 v9, 0xbb000000, v2
	v_fmac_f32_e32 v7, v3, v3
	v_fmac_f32_e32 v4, 0xbb000000, v2
	v_fmac_f32_e32 v7, v9, v9
	v_fmac_f32_e32 v10, 0xbb000000, v2
	v_fmac_f32_e32 v7, v4, v4
	v_fmac_f32_e32 v5, 0xbb000000, v2
	v_fmac_f32_e32 v7, v10, v10
	v_fmac_f32_e32 v7, v5, v5
	v_mov_b32_e32 v3, v7
	s_nop 1
	v_mov_b32_dpp v3, v3 quad_perm:[1,0,3,2] row_mask:0xf bank_mask:0xf
	v_add_f32_e32 v3, v7, v3
	v_mov_b32_e32 v4, v3
	s_nop 1
	v_mov_b32_dpp v4, v4 quad_perm:[2,3,0,1] row_mask:0xf bank_mask:0xf
	v_add_f32_e32 v3, v3, v4
	v_mov_b32_e32 v4, v3
	s_nop 1
	v_mov_b32_dpp v4, v4 row_half_mirror row_mask:0xf bank_mask:0xf
	v_add_f32_e32 v3, v3, v4
	v_mov_b32_e32 v4, v3
	s_nop 1
	v_mov_b32_dpp v4, v4 row_mirror row_mask:0xf bank_mask:0xf
	v_add_f32_e32 v3, v3, v4
	s_nop 0
	v_readlane_b32 s0, v3, 0
	v_readlane_b32 s26, v3, 16
	v_readlane_b32 s1, v3, 32
	v_readlane_b32 s27, v3, 48
	s_and_saveexec_b64 s[4:5], s[2:3]
	s_cbranch_execz .Lgst_0_3
	v_mov_b32_e32 v3, s26
	v_mov_b32_e32 v4, s27
	v_add_f32_e32 v3, s0, v3
	v_add_f32_e32 v4, s1, v4
	v_add_f32_e32 v3, v3, v4
	v_fmamk_f32 v3, v3, 0x3b000000, v59
	v_mul_f32_e32 v4, 0x4f800000, v3
	v_cmp_gt_f32_e32 vcc, s13, v3
	v_mul_f32_e32 v2, 0x3b000000, v2
	s_nop 0
	v_cndmask_b32_e32 v3, v3, v4, vcc
	v_sqrt_f32_e32 v4, v3
	s_nop 0
	v_add_u32_e32 v5, -1, v4
	v_fma_f32 v6, -v5, v4, v3
	v_cmp_ge_f32_e64 s[0:1], 0, v6
	v_add_u32_e32 v6, 1, v4
	s_nop 0
	v_cndmask_b32_e64 v5, v4, v5, s[0:1]
	v_fma_f32 v4, -v6, v4, v3
	v_cmp_lt_f32_e64 s[0:1], 0, v4
	s_nop 1
	v_cndmask_b32_e64 v4, v5, v6, s[0:1]
	v_mul_f32_e32 v5, 0x37800000, v4
	v_cndmask_b32_e32 v4, v4, v5, vcc
	v_cmp_class_f32_e32 vcc, v3, v60
	s_nop 1
	v_cndmask_b32_e32 v3, v4, v3, vcc
	v_div_scale_f32 v4, s[0:1], v3, v3, 1.0
	v_rcp_f32_e32 v5, v4
	s_add_i32 s0, s24, s25
	v_fma_f32 v6, -v4, v5, 1.0
	v_fmac_f32_e32 v5, v6, v5
	v_div_scale_f32 v6, vcc, 1.0, v3, 1.0
	v_mul_f32_e32 v7, v6, v5
	v_fma_f32 v8, -v4, v7, v6
	v_fmac_f32_e32 v7, v8, v5
	v_fma_f32 v4, -v4, v7, v6
	v_div_fmas_f32 v4, v4, v5, v7
	v_div_fixup_f32 v3, v4, v3, 1.0
	v_mov_b32_e32 v4, s0
	ds_write2st64_b32 v4, v2, v3 offset1:2
; __device__ __forceinline__ void gmlp_mfma_unit(const Params& p, int l, bf16_t* Z, LAS unsigned char* lds, int nb) {
;     ...
;     for (int i = 0; i < 16; ++i) { const int tok = wave * 16 + i;
;         const u32x4 raw = *(const u32x4*)(Z + (size_t)(row0 + tok) * ZP + ZC_V + lane * 8);
;         const float x[8] = {bflo(raw.x), bfhi(raw.x), bflo(raw.y), bfhi(raw.y), bflo(raw.z), bfhi(raw.z), bflo(raw.w), bfhi(raw.w)};
;         float s = 0.f;
; #pragma unroll
;         for (int e = 0; e < 8; ++e) s += x[e];
;         const float mean = wave_sum(s) * (1.f / 512.f); float s2 = 0.f;
; #pragma unroll
;         for (int e = 0; e < 8; ++e) { const float d = x[e] - mean; s2 += d * d; }
;         const float rstd = 1.f / sqrtf(wave_sum(s2) * (1.f / 512.f) + 1e-5f);
;         if (lane == 0) { st[tok] = mean; st[128 + tok] = rstd; } }
.Lgst_0_3:
	s_or_b64 exec, exec, s[4:5]
	s_add_i32 s25, s25, 4
	v_mov_b64_e32 v[2:3], v[112:113]
	v_mov_b64_e32 v[4:5], v[114:115]
	v_lshlrev_b32_e32 v6, 16, v2
	v_and_b32_e32 v7, 0xffff0000, v2
	v_add_f32_e32 v2, 0, v6
	v_lshlrev_b32_e32 v8, 16, v3
	v_add_f32_e32 v2, v2, v7
	v_and_b32_e32 v3, 0xffff0000, v3
	v_add_f32_e32 v2, v2, v8
	v_lshlrev_b32_e32 v9, 16, v4
	v_add_f32_e32 v2, v2, v3
	v_and_b32_e32 v4, 0xffff0000, v4
	v_add_f32_e32 v2, v2, v9
	v_lshlrev_b32_e32 v10, 16, v5
	v_add_f32_e32 v2, v2, v4
	v_and_b32_e32 v5, 0xffff0000, v5
	v_add_f32_e32 v2, v2, v10
	v_add_f32_e32 v2, v2, v5
	v_mov_b32_e32 v11, v2
	s_nop 1
	v_mov_b32_dpp v11, v11 quad_perm:[1,0,3,2] row_mask:0xf bank_mask:0xf
	v_add_f32_e32 v2, v2, v11
	v_mov_b32_e32 v11, v2
	s_nop 1
	v_mov_b32_dpp v11, v11 quad_perm:[2,3,0,1] row_mask:0xf bank_mask:0xf
	v_add_f32_e32 v2, v2, v11
	v_mov_b32_e32 v11, v2
	s_nop 1
	v_mov_b32_dpp v11, v11 row_half_mirror row_mask:0xf bank_mask:0xf
	v_add_f32_e32 v2, v2, v11
	v_mov_b32_e32 v11, v2
	s_nop 1
	v_mov_b32_dpp v11, v11 row_mirror row_mask:0xf bank_mask:0xf
	v_add_f32_e32 v2, v2, v11
	s_nop 0
	v_readlane_b32 s1, v2, 16
	v_readlane_b32 s5, v2, 48
	v_readlane_b32 s0, v2, 0
	v_readlane_b32 s4, v2, 32
	v_mov_b32_e32 v2, s1
	v_mov_b32_e32 v11, s5
	v_add_f32_e32 v2, s0, v2
	v_add_f32_e32 v11, s4, v11
	v_add_f32_e32 v2, v2, v11
	v_fmac_f32_e32 v7, 0xbb000000, v2
	v_fmac_f32_e32 v6, 0xbb000000, v2
	v_mul_f32_e32 v7, v7, v7
	v_fmac_f32_e32 v8, 0xbb000000, v2
	v_fmac_f32_e32 v7, v6, v6
	v_fmac_f32_e32 v3, 0xbb000000, v2
	v_fmac_f32_e32 v7, v8, v8
	v_fmac_f32_e32 v9, 0xbb000000, v2
	v_fmac_f32_e32 v7, v3, v3
	v_fmac_f32_e32 v4, 0xbb000000, v2
	v_fmac_f32_e32 v7, v9, v9
	v_fmac_f32_e32 v10, 0xbb000000, v2
	v_fmac_f32_e32 v7, v4, v4
	v_fmac_f32_e32 v5, 0xbb000000, v2
	v_fmac_f32_e32 v7, v10, v10
	v_fmac_f32_e32 v7, v5, v5
	v_mov_b32_e32 v3, v7
	s_nop 1
	v_mov_b32_dpp v3, v3 quad_perm:[1,0,3,2] row_mask:0xf bank_mask:0xf
	v_add_f32_e32 v3, v7, v3
	v_mov_b32_e32 v4, v3
	s_nop 1
	v_mov_b32_dpp v4, v4 quad_perm:[2,3,0,1] row_mask:0xf bank_mask:0xf
	v_add_f32_e32 v3, v3, v4
	v_mov_b32_e32 v4, v3
	s_nop 1
	v_mov_b32_dpp v4, v4 row_half_mirror row_mask:0xf bank_mask:0xf
	v_add_f32_e32 v3, v3, v4
	v_mov_b32_e32 v4, v3
	s_nop 1
	v_mov_b32_dpp v4, v4 row_mirror row_mask:0xf bank_mask:0xf
	v_add_f32_e32 v3, v3, v4
	s_nop 0
	v_readlane_b32 s0, v3, 0
	v_readlane_b32 s26, v3, 16
	v_readlane_b32 s1, v3, 32
	v_readlane_b32 s27, v3, 48
	s_and_saveexec_b64 s[4:5], s[2:3]
	s_cbranch_execz .Lgst_0_4
	v_mov_b32_e32 v3, s26
	v_mov_b32_e32 v4, s27
	v_add_f32_e32 v3, s0, v3
	v_add_f32_e32 v4, s1, v4
	v_add_f32_e32 v3, v3, v4
	v_fmamk_f32 v3, v3, 0x3b000000, v59
	v_mul_f32_e32 v4, 0x4f800000, v3
	v_cmp_gt_f32_e32 vcc, s13, v3
	v_mul_f32_e32 v2, 0x3b000000, v2
	s_nop 0
	v_cndmask_b32_e32 v3, v3, v4, vcc
	v_sqrt_f32_e32 v4, v3
	s_nop 0
	v_add_u32_e32 v5, -1, v4
	v_fma_f32 v6, -v5, v4, v3
	v_cmp_ge_f32_e64 s[0:1], 0, v6
	v_add_u32_e32 v6, 1, v4
	s_nop 0
	v_cndmask_b32_e64 v5, v4, v5, s[0:1]
	v_fma_f32 v4, -v6, v4, v3
	v_cmp_lt_f32_e64 s[0:1], 0, v4
	s_nop 1
	v_cndmask_b32_e64 v4, v5, v6, s[0:1]
	v_mul_f32_e32 v5, 0x37800000, v4
	v_cndmask_b32_e32 v4, v4, v5, vcc
	v_cmp_class_f32_e32 vcc, v3, v60
	s_nop 1
	v_cndmask_b32_e32 v3, v4, v3, vcc
	v_div_scale_f32 v4, s[0:1], v3, v3, 1.0
	v_rcp_f32_e32 v5, v4
	s_add_i32 s0, s24, s25
	v_fma_f32 v6, -v4, v5, 1.0
	v_fmac_f32_e32 v5, v6, v5
	v_div_scale_f32 v6, vcc, 1.0, v3, 1.0
	v_mul_f32_e32 v7, v6, v5
	v_fma_f32 v8, -v4, v7, v6
	v_fmac_f32_e32 v7, v8, v5
	v_fma_f32 v4, -v4, v7, v6
	v_div_fmas_f32 v4, v4, v5, v7
	v_div_fixup_f32 v3, v4, v3, 1.0
	v_mov_b32_e32 v4, s0
	ds_write2st64_b32 v4, v2, v3 offset1:2
.Lgst_0_4:
	s_or_b64 exec, exec, s[4:5]
	s_add_i32 s25, s25, 4
	v_mov_b64_e32 v[2:3], v[116:117]
	v_mov_b64_e32 v[4:5], v[118:119]
	v_lshlrev_b32_e32 v6, 16, v2
	v_and_b32_e32 v7, 0xffff0000, v2
	v_add_f32_e32 v2, 0, v6
	v_lshlrev_b32_e32 v8, 16, v3
	v_add_f32_e32 v2, v2, v7
	v_and_b32_e32 v3, 0xffff0000, v3
	v_add_f32_e32 v2, v2, v8
	v_lshlrev_b32_e32 v9, 16, v4
	v_add_f32_e32 v2, v2, v3
	v_and_b32_e32 v4, 0xffff0000, v4
	v_add_f32_e32 v2, v2, v9
	v_lshlrev_b32_e32 v10, 16, v5
	v_add_f32_e32 v2, v2, v4
	v_and_b32_e32 v5, 0xffff0000, v5
	v_add_f32_e32 v2, v2, v10
	v_add_f32_e32 v2, v2, v5
	v_mov_b32_e32 v11, v2
	s_nop 1
	v_mov_b32_dpp v11, v11 quad_perm:[1,0,3,2] row_mask:0xf bank_mask:0xf
	v_add_f32_e32 v2, v2, v11
	v_mov_b32_e32 v11, v2
	s_nop 1
	v_mov_b32_dpp v11, v11 quad_perm:[2,3,0,1] row_mask:0xf bank_mask:0xf
	v_add_f32_e32 v2, v2, v11
	v_mov_b32_e32 v11, v2
	s_nop 1
	v_mov_b32_dpp v11, v11 row_half_mirror row_mask:0xf bank_mask:0xf
	v_add_f32_e32 v2, v2, v11
	v_mov_b32_e32 v11, v2
	s_nop 1
	v_mov_b32_dpp v11, v11 row_mirror row_mask:0xf bank_mask:0xf
	v_add_f32_e32 v2, v2, v11
	s_nop 0
	v_readlane_b32 s1, v2, 16
	v_readlane_b32 s5, v2, 48
	v_readlane_b32 s0, v2, 0
	v_readlane_b32 s4, v2, 32
	v_mov_b32_e32 v2, s1
	v_mov_b32_e32 v11, s5
	v_add_f32_e32 v2, s0, v2
	v_add_f32_e32 v11, s4, v11
	v_add_f32_e32 v2, v2, v11
	v_fmac_f32_e32 v7, 0xbb000000, v2
	v_fmac_f32_e32 v6, 0xbb000000, v2
	v_mul_f32_e32 v7, v7, v7
	v_fmac_f32_e32 v8, 0xbb000000, v2
	v_fmac_f32_e32 v7, v6, v6
	v_fmac_f32_e32 v3, 0xbb000000, v2
	v_fmac_f32_e32 v7, v8, v8
	v_fmac_f32_e32 v9, 0xbb000000, v2
	v_fmac_f32_e32 v7, v3, v3
	v_fmac_f32_e32 v4, 0xbb000000, v2
	v_fmac_f32_e32 v7, v9, v9
	v_fmac_f32_e32 v10, 0xbb000000, v2
	v_fmac_f32_e32 v7, v4, v4
	v_fmac_f32_e32 v5, 0xbb000000, v2
	v_fmac_f32_e32 v7, v10, v10
	v_fmac_f32_e32 v7, v5, v5
	v_mov_b32_e32 v3, v7
	s_nop 1
	v_mov_b32_dpp v3, v3 quad_perm:[1,0,3,2] row_mask:0xf bank_mask:0xf
	v_add_f32_e32 v3, v7, v3
	v_mov_b32_e32 v4, v3
	s_nop 1
	v_mov_b32_dpp v4, v4 quad_perm:[2,3,0,1] row_mask:0xf bank_mask:0xf
	v_add_f32_e32 v3, v3, v4
	v_mov_b32_e32 v4, v3
	s_nop 1
	v_mov_b32_dpp v4, v4 row_half_mirror row_mask:0xf bank_mask:0xf
	v_add_f32_e32 v3, v3, v4
	v_mov_b32_e32 v4, v3
	s_nop 1
	v_mov_b32_dpp v4, v4 row_mirror row_mask:0xf bank_mask:0xf
	v_add_f32_e32 v3, v3, v4
	s_nop 0
	v_readlane_b32 s0, v3, 0
	v_readlane_b32 s26, v3, 16
	v_readlane_b32 s1, v3, 32
	v_readlane_b32 s27, v3, 48
	s_and_saveexec_b64 s[4:5], s[2:3]
	s_cbranch_execz .Lgst_0_5
; __device__ __forceinline__ void gmlp_mfma_unit(const Params& p, int l, bf16_t* Z, LAS unsigned char* lds, int nb) {
;     ...
;     for (int i = 0; i < 16; ++i) { const int tok = wave * 16 + i;
;         const u32x4 raw = *(const u32x4*)(Z + (size_t)(row0 + tok) * ZP + ZC_V + lane * 8);
;         const float x[8] = {bflo(raw.x), bfhi(raw.x), bflo(raw.y), bfhi(raw.y), bflo(raw.z), bfhi(raw.z), bflo(raw.w), bfhi(raw.w)};
;         float s = 0.f;
; #pragma unroll
;         for (int e = 0; e < 8; ++e) s += x[e];
;         const float mean = wave_sum(s) * (1.f / 512.f); float s2 = 0.f;
; #pragma unroll
;         for (int e = 0; e < 8; ++e) { const float d = x[e] - mean; s2 += d * d; }
;         const float rstd = 1.f / sqrtf(wave_sum(s2) * (1.f / 512.f) + 1e-5f);
;         if (lane == 0) { st[tok] = mean; st[128 + tok] = rstd; } }
	v_mov_b32_e32 v3, s26
	v_mov_b32_e32 v4, s27
	v_add_f32_e32 v3, s0, v3
	v_add_f32_e32 v4, s1, v4
	v_add_f32_e32 v3, v3, v4
	v_fmamk_f32 v3, v3, 0x3b000000, v59
	v_mul_f32_e32 v4, 0x4f800000, v3
	v_cmp_gt_f32_e32 vcc, s13, v3
	v_mul_f32_e32 v2, 0x3b000000, v2
	s_nop 0
	v_cndmask_b32_e32 v3, v3, v4, vcc
	v_sqrt_f32_e32 v4, v3
	s_nop 0
	v_add_u32_e32 v5, -1, v4
	v_fma_f32 v6, -v5, v4, v3
	v_cmp_ge_f32_e64 s[0:1], 0, v6
	v_add_u32_e32 v6, 1, v4
	s_nop 0
	v_cndmask_b32_e64 v5, v4, v5, s[0:1]
	v_fma_f32 v4, -v6, v4, v3
	v_cmp_lt_f32_e64 s[0:1], 0, v4
	s_nop 1
	v_cndmask_b32_e64 v4, v5, v6, s[0:1]
	v_mul_f32_e32 v5, 0x37800000, v4
	v_cndmask_b32_e32 v4, v4, v5, vcc
	v_cmp_class_f32_e32 vcc, v3, v60
	s_nop 1
	v_cndmask_b32_e32 v3, v4, v3, vcc
	v_div_scale_f32 v4, s[0:1], v3, v3, 1.0
	v_rcp_f32_e32 v5, v4
	s_add_i32 s0, s24, s25
	v_fma_f32 v6, -v4, v5, 1.0
	v_fmac_f32_e32 v5, v6, v5
	v_div_scale_f32 v6, vcc, 1.0, v3, 1.0
	v_mul_f32_e32 v7, v6, v5
	v_fma_f32 v8, -v4, v7, v6
	v_fmac_f32_e32 v7, v8, v5
	v_fma_f32 v4, -v4, v7, v6
	v_div_fmas_f32 v4, v4, v5, v7
	v_div_fixup_f32 v3, v4, v3, 1.0
	v_mov_b32_e32 v4, s0
	ds_write2st64_b32 v4, v2, v3 offset1:2
.Lgst_0_5:
	s_or_b64 exec, exec, s[4:5]
	s_add_i32 s25, s25, 4
	v_mov_b64_e32 v[2:3], v[120:121]
	v_mov_b64_e32 v[4:5], v[122:123]
	v_lshlrev_b32_e32 v6, 16, v2
	v_and_b32_e32 v7, 0xffff0000, v2
	v_add_f32_e32 v2, 0, v6
	v_lshlrev_b32_e32 v8, 16, v3
	v_add_f32_e32 v2, v2, v7
	v_and_b32_e32 v3, 0xffff0000, v3
	v_add_f32_e32 v2, v2, v8
	v_lshlrev_b32_e32 v9, 16, v4
	v_add_f32_e32 v2, v2, v3
	v_and_b32_e32 v4, 0xffff0000, v4
	v_add_f32_e32 v2, v2, v9
	v_lshlrev_b32_e32 v10, 16, v5
	v_add_f32_e32 v2, v2, v4
	v_and_b32_e32 v5, 0xffff0000, v5
	v_add_f32_e32 v2, v2, v10
	v_add_f32_e32 v2, v2, v5
	v_mov_b32_e32 v11, v2
	s_nop 1
	v_mov_b32_dpp v11, v11 quad_perm:[1,0,3,2] row_mask:0xf bank_mask:0xf
	v_add_f32_e32 v2, v2, v11
	v_mov_b32_e32 v11, v2
	s_nop 1
	v_mov_b32_dpp v11, v11 quad_perm:[2,3,0,1] row_mask:0xf bank_mask:0xf
	v_add_f32_e32 v2, v2, v11
	v_mov_b32_e32 v11, v2
	s_nop 1
	v_mov_b32_dpp v11, v11 row_half_mirror row_mask:0xf bank_mask:0xf
	v_add_f32_e32 v2, v2, v11
	v_mov_b32_e32 v11, v2
	s_nop 1
	v_mov_b32_dpp v11, v11 row_mirror row_mask:0xf bank_mask:0xf
	v_add_f32_e32 v2, v2, v11
	s_nop 0
	v_readlane_b32 s1, v2, 16
	v_readlane_b32 s5, v2, 48
	v_readlane_b32 s0, v2, 0
	v_readlane_b32 s4, v2, 32
	v_mov_b32_e32 v2, s1
	v_mov_b32_e32 v11, s5
	v_add_f32_e32 v2, s0, v2
	v_add_f32_e32 v11, s4, v11
	v_add_f32_e32 v2, v2, v11
	v_fmac_f32_e32 v7, 0xbb000000, v2
	v_fmac_f32_e32 v6, 0xbb000000, v2
	v_mul_f32_e32 v7, v7, v7
	v_fmac_f32_e32 v8, 0xbb000000, v2
	v_fmac_f32_e32 v7, v6, v6
	v_fmac_f32_e32 v3, 0xbb000000, v2
	v_fmac_f32_e32 v7, v8, v8
	v_fmac_f32_e32 v9, 0xbb000000, v2
	v_fmac_f32_e32 v7, v3, v3
	v_fmac_f32_e32 v4, 0xbb000000, v2
	v_fmac_f32_e32 v7, v9, v9
	v_fmac_f32_e32 v10, 0xbb000000, v2
	v_fmac_f32_e32 v7, v4, v4
	v_fmac_f32_e32 v5, 0xbb000000, v2
	v_fmac_f32_e32 v7, v10, v10
	v_fmac_f32_e32 v7, v5, v5
	v_mov_b32_e32 v3, v7
	s_nop 1
	v_mov_b32_dpp v3, v3 quad_perm:[1,0,3,2] row_mask:0xf bank_mask:0xf
	v_add_f32_e32 v3, v7, v3
	v_mov_b32_e32 v4, v3
	s_nop 1
	v_mov_b32_dpp v4, v4 quad_perm:[2,3,0,1] row_mask:0xf bank_mask:0xf
	v_add_f32_e32 v3, v3, v4
	v_mov_b32_e32 v4, v3
	s_nop 1
	v_mov_b32_dpp v4, v4 row_half_mirror row_mask:0xf bank_mask:0xf
	v_add_f32_e32 v3, v3, v4
	v_mov_b32_e32 v4, v3
	s_nop 1
	v_mov_b32_dpp v4, v4 row_mirror row_mask:0xf bank_mask:0xf
	v_add_f32_e32 v3, v3, v4
	s_nop 0
	v_readlane_b32 s0, v3, 0
	v_readlane_b32 s26, v3, 16
	v_readlane_b32 s1, v3, 32
	v_readlane_b32 s27, v3, 48
	s_and_saveexec_b64 s[4:5], s[2:3]
	s_cbranch_execz .Lgst_0_6
	v_mov_b32_e32 v3, s26
	v_mov_b32_e32 v4, s27
	v_add_f32_e32 v3, s0, v3
	v_add_f32_e32 v4, s1, v4
	v_add_f32_e32 v3, v3, v4
	v_fmamk_f32 v3, v3, 0x3b000000, v59
	v_mul_f32_e32 v4, 0x4f800000, v3
	v_cmp_gt_f32_e32 vcc, s13, v3
	v_mul_f32_e32 v2, 0x3b000000, v2
	s_nop 0
	v_cndmask_b32_e32 v3, v3, v4, vcc
	v_sqrt_f32_e32 v4, v3
	s_nop 0
	v_add_u32_e32 v5, -1, v4
	v_fma_f32 v6, -v5, v4, v3
	v_cmp_ge_f32_e64 s[0:1], 0, v6
	v_add_u32_e32 v6, 1, v4
	s_nop 0
	v_cndmask_b32_e64 v5, v4, v5, s[0:1]
	v_fma_f32 v4, -v6, v4, v3
	v_cmp_lt_f32_e64 s[0:1], 0, v4
	s_nop 1
	v_cndmask_b32_e64 v4, v5, v6, s[0:1]
	v_mul_f32_e32 v5, 0x37800000, v4
	v_cndmask_b32_e32 v4, v4, v5, vcc
	v_cmp_class_f32_e32 vcc, v3, v60
	s_nop 1
	v_cndmask_b32_e32 v3, v4, v3, vcc
	v_div_scale_f32 v4, s[0:1], v3, v3, 1.0
	v_rcp_f32_e32 v5, v4
	s_add_i32 s0, s24, s25
	v_fma_f32 v6, -v4, v5, 1.0
	v_fmac_f32_e32 v5, v6, v5
	v_div_scale_f32 v6, vcc, 1.0, v3, 1.0
	v_mul_f32_e32 v7, v6, v5
	v_fma_f32 v8, -v4, v7, v6
	v_fmac_f32_e32 v7, v8, v5
	v_fma_f32 v4, -v4, v7, v6
	v_div_fmas_f32 v4, v4, v5, v7
	v_div_fixup_f32 v3, v4, v3, 1.0
	v_mov_b32_e32 v4, s0
	ds_write2st64_b32 v4, v2, v3 offset1:2
; __device__ __forceinline__ void gmlp_mfma_unit(const Params& p, int l, bf16_t* Z, LAS unsigned char* lds, int nb) {
;     ...
;     for (int i = 0; i < 16; ++i) { const int tok = wave * 16 + i;
;         const u32x4 raw = *(const u32x4*)(Z + (size_t)(row0 + tok) * ZP + ZC_V + lane * 8);
;         const float x[8] = {bflo(raw.x), bfhi(raw.x), bflo(raw.y), bfhi(raw.y), bflo(raw.z), bfhi(raw.z), bflo(raw.w), bfhi(raw.w)};
;         float s = 0.f;
; #pragma unroll
;         for (int e = 0; e < 8; ++e) s += x[e];
;         const float mean = wave_sum(s) * (1.f / 512.f); float s2 = 0.f;
; #pragma unroll
;         for (int e = 0; e < 8; ++e) { const float d = x[e] - mean; s2 += d * d; }
;         const float rstd = 1.f / sqrtf(wave_sum(s2) * (1.f / 512.f) + 1e-5f);
;         if (lane == 0) { st[tok] = mean; st[128 + tok] = rstd; } }
.Lgst_0_6:
	s_or_b64 exec, exec, s[4:5]
	s_add_i32 s25, s25, 4
	v_mov_b64_e32 v[2:3], v[124:125]
	v_mov_b64_e32 v[4:5], v[126:127]
	v_lshlrev_b32_e32 v6, 16, v2
	v_and_b32_e32 v7, 0xffff0000, v2
	v_add_f32_e32 v2, 0, v6
	v_lshlrev_b32_e32 v8, 16, v3
	v_add_f32_e32 v2, v2, v7
	v_and_b32_e32 v3, 0xffff0000, v3
	v_add_f32_e32 v2, v2, v8
	v_lshlrev_b32_e32 v9, 16, v4
	v_add_f32_e32 v2, v2, v3
	v_and_b32_e32 v4, 0xffff0000, v4
	v_add_f32_e32 v2, v2, v9
	v_lshlrev_b32_e32 v10, 16, v5
	v_add_f32_e32 v2, v2, v4
	v_and_b32_e32 v5, 0xffff0000, v5
	v_add_f32_e32 v2, v2, v10
	v_add_f32_e32 v2, v2, v5
	v_mov_b32_e32 v11, v2
	s_nop 1
	v_mov_b32_dpp v11, v11 quad_perm:[1,0,3,2] row_mask:0xf bank_mask:0xf
	v_add_f32_e32 v2, v2, v11
	v_mov_b32_e32 v11, v2
	s_nop 1
	v_mov_b32_dpp v11, v11 quad_perm:[2,3,0,1] row_mask:0xf bank_mask:0xf
	v_add_f32_e32 v2, v2, v11
	v_mov_b32_e32 v11, v2
	s_nop 1
	v_mov_b32_dpp v11, v11 row_half_mirror row_mask:0xf bank_mask:0xf
	v_add_f32_e32 v2, v2, v11
	v_mov_b32_e32 v11, v2
	s_nop 1
	v_mov_b32_dpp v11, v11 row_mirror row_mask:0xf bank_mask:0xf
	v_add_f32_e32 v2, v2, v11
	s_nop 0
	v_readlane_b32 s1, v2, 16
	v_readlane_b32 s5, v2, 48
	v_readlane_b32 s0, v2, 0
	v_readlane_b32 s4, v2, 32
	v_mov_b32_e32 v2, s1
	v_mov_b32_e32 v11, s5
	v_add_f32_e32 v2, s0, v2
	v_add_f32_e32 v11, s4, v11
	v_add_f32_e32 v2, v2, v11
	v_fmac_f32_e32 v7, 0xbb000000, v2
	v_fmac_f32_e32 v6, 0xbb000000, v2
	v_mul_f32_e32 v7, v7, v7
	v_fmac_f32_e32 v8, 0xbb000000, v2
	v_fmac_f32_e32 v7, v6, v6
	v_fmac_f32_e32 v3, 0xbb000000, v2
	v_fmac_f32_e32 v7, v8, v8
	v_fmac_f32_e32 v9, 0xbb000000, v2
	v_fmac_f32_e32 v7, v3, v3
	v_fmac_f32_e32 v4, 0xbb000000, v2
	v_fmac_f32_e32 v7, v9, v9
	v_fmac_f32_e32 v10, 0xbb000000, v2
	v_fmac_f32_e32 v7, v4, v4
	v_fmac_f32_e32 v5, 0xbb000000, v2
	v_fmac_f32_e32 v7, v10, v10
	v_fmac_f32_e32 v7, v5, v5
	v_mov_b32_e32 v3, v7
	s_nop 1
	v_mov_b32_dpp v3, v3 quad_perm:[1,0,3,2] row_mask:0xf bank_mask:0xf
	v_add_f32_e32 v3, v7, v3
	v_mov_b32_e32 v4, v3
	s_nop 1
	v_mov_b32_dpp v4, v4 quad_perm:[2,3,0,1] row_mask:0xf bank_mask:0xf
	v_add_f32_e32 v3, v3, v4
	v_mov_b32_e32 v4, v3
	s_nop 1
	v_mov_b32_dpp v4, v4 row_half_mirror row_mask:0xf bank_mask:0xf
	v_add_f32_e32 v3, v3, v4
	v_mov_b32_e32 v4, v3
	s_nop 1
	v_mov_b32_dpp v4, v4 row_mirror row_mask:0xf bank_mask:0xf
	v_add_f32_e32 v3, v3, v4
	s_nop 0
	v_readlane_b32 s0, v3, 0
	v_readlane_b32 s26, v3, 16
	v_readlane_b32 s1, v3, 32
	v_readlane_b32 s27, v3, 48
	s_and_saveexec_b64 s[4:5], s[2:3]
	s_cbranch_execz .Lgst_0_7
	v_mov_b32_e32 v3, s26
	v_mov_b32_e32 v4, s27
	v_add_f32_e32 v3, s0, v3
	v_add_f32_e32 v4, s1, v4
	v_add_f32_e32 v3, v3, v4
	v_fmamk_f32 v3, v3, 0x3b000000, v59
	v_mul_f32_e32 v4, 0x4f800000, v3
	v_cmp_gt_f32_e32 vcc, s13, v3
	v_mul_f32_e32 v2, 0x3b000000, v2
	s_nop 0
	v_cndmask_b32_e32 v3, v3, v4, vcc
	v_sqrt_f32_e32 v4, v3
	s_nop 0
	v_add_u32_e32 v5, -1, v4
	v_fma_f32 v6, -v5, v4, v3
	v_cmp_ge_f32_e64 s[0:1], 0, v6
	v_add_u32_e32 v6, 1, v4
	s_nop 0
	v_cndmask_b32_e64 v5, v4, v5, s[0:1]
	v_fma_f32 v4, -v6, v4, v3
	v_cmp_lt_f32_e64 s[0:1], 0, v4
	s_nop 1
	v_cndmask_b32_e64 v4, v5, v6, s[0:1]
	v_mul_f32_e32 v5, 0x37800000, v4
	v_cndmask_b32_e32 v4, v4, v5, vcc
	v_cmp_class_f32_e32 vcc, v3, v60
	s_nop 1
	v_cndmask_b32_e32 v3, v4, v3, vcc
	v_div_scale_f32 v4, s[0:1], v3, v3, 1.0
	v_rcp_f32_e32 v5, v4
	s_add_i32 s0, s24, s25
	v_fma_f32 v6, -v4, v5, 1.0
	v_fmac_f32_e32 v5, v6, v5
	v_div_scale_f32 v6, vcc, 1.0, v3, 1.0
	v_mul_f32_e32 v7, v6, v5
	v_fma_f32 v8, -v4, v7, v6
	v_fmac_f32_e32 v7, v8, v5
	v_fma_f32 v4, -v4, v7, v6
	v_div_fmas_f32 v4, v4, v5, v7
	v_div_fixup_f32 v3, v4, v3, 1.0
	v_mov_b32_e32 v4, s0
	ds_write2st64_b32 v4, v2, v3 offset1:2
.Lgst_0_7:
	s_or_b64 exec, exec, s[4:5]
	s_add_i32 s25, s25, 4
	v_mov_b64_e32 v[2:3], v[128:129]
	v_mov_b64_e32 v[4:5], v[130:131]
	v_lshlrev_b32_e32 v6, 16, v2
	v_and_b32_e32 v7, 0xffff0000, v2
	v_add_f32_e32 v2, 0, v6
	v_lshlrev_b32_e32 v8, 16, v3
	v_add_f32_e32 v2, v2, v7
	v_and_b32_e32 v3, 0xffff0000, v3
	v_add_f32_e32 v2, v2, v8
	v_lshlrev_b32_e32 v9, 16, v4
	v_add_f32_e32 v2, v2, v3
	v_and_b32_e32 v4, 0xffff0000, v4
	v_add_f32_e32 v2, v2, v9
	v_lshlrev_b32_e32 v10, 16, v5
	v_add_f32_e32 v2, v2, v4
	v_and_b32_e32 v5, 0xffff0000, v5
	v_add_f32_e32 v2, v2, v10
	v_add_f32_e32 v2, v2, v5
	v_mov_b32_e32 v11, v2
	s_nop 1
	v_mov_b32_dpp v11, v11 quad_perm:[1,0,3,2] row_mask:0xf bank_mask:0xf
	v_add_f32_e32 v2, v2, v11
	v_mov_b32_e32 v11, v2
	s_nop 1
	v_mov_b32_dpp v11, v11 quad_perm:[2,3,0,1] row_mask:0xf bank_mask:0xf
	v_add_f32_e32 v2, v2, v11
	v_mov_b32_e32 v11, v2
	s_nop 1
	v_mov_b32_dpp v11, v11 row_half_mirror row_mask:0xf bank_mask:0xf
	v_add_f32_e32 v2, v2, v11
	v_mov_b32_e32 v11, v2
	s_nop 1
	v_mov_b32_dpp v11, v11 row_mirror row_mask:0xf bank_mask:0xf
	v_add_f32_e32 v2, v2, v11
	s_nop 0
	v_readlane_b32 s1, v2, 16
	v_readlane_b32 s5, v2, 48
	v_readlane_b32 s0, v2, 0
	v_readlane_b32 s4, v2, 32
	v_mov_b32_e32 v2, s1
	v_mov_b32_e32 v11, s5
	v_add_f32_e32 v2, s0, v2
	v_add_f32_e32 v11, s4, v11
	v_add_f32_e32 v2, v2, v11
	v_fmac_f32_e32 v7, 0xbb000000, v2
	v_fmac_f32_e32 v6, 0xbb000000, v2
	v_mul_f32_e32 v7, v7, v7
	v_fmac_f32_e32 v8, 0xbb000000, v2
	v_fmac_f32_e32 v7, v6, v6
	v_fmac_f32_e32 v3, 0xbb000000, v2
	v_fmac_f32_e32 v7, v8, v8
	v_fmac_f32_e32 v9, 0xbb000000, v2
	v_fmac_f32_e32 v7, v3, v3
	v_fmac_f32_e32 v4, 0xbb000000, v2
	v_fmac_f32_e32 v7, v9, v9
	v_fmac_f32_e32 v10, 0xbb000000, v2
	v_fmac_f32_e32 v7, v4, v4
	v_fmac_f32_e32 v5, 0xbb000000, v2
	v_fmac_f32_e32 v7, v10, v10
	v_fmac_f32_e32 v7, v5, v5
	v_mov_b32_e32 v3, v7
	s_nop 1
	v_mov_b32_dpp v3, v3 quad_perm:[1,0,3,2] row_mask:0xf bank_mask:0xf
	v_add_f32_e32 v3, v7, v3
	v_mov_b32_e32 v4, v3
	s_nop 1
	v_mov_b32_dpp v4, v4 quad_perm:[2,3,0,1] row_mask:0xf bank_mask:0xf
	v_add_f32_e32 v3, v3, v4
	v_mov_b32_e32 v4, v3
	s_nop 1
	v_mov_b32_dpp v4, v4 row_half_mirror row_mask:0xf bank_mask:0xf
	v_add_f32_e32 v3, v3, v4
	v_mov_b32_e32 v4, v3
	s_nop 1
	v_mov_b32_dpp v4, v4 row_mirror row_mask:0xf bank_mask:0xf
	v_add_f32_e32 v3, v3, v4
	s_nop 0
	v_readlane_b32 s0, v3, 0
	v_readlane_b32 s26, v3, 16
	v_readlane_b32 s1, v3, 32
	v_readlane_b32 s27, v3, 48
	s_and_saveexec_b64 s[4:5], s[2:3]
	s_cbranch_execz .Lgst_0_8
; __device__ __forceinline__ void gmlp_mfma_unit(const Params& p, int l, bf16_t* Z, LAS unsigned char* lds, int nb) {
;     ...
;     for (int i = 0; i < 16; ++i) { const int tok = wave * 16 + i;
;         const u32x4 raw = *(const u32x4*)(Z + (size_t)(row0 + tok) * ZP + ZC_V + lane * 8);
;         const float x[8] = {bflo(raw.x), bfhi(raw.x), bflo(raw.y), bfhi(raw.y), bflo(raw.z), bfhi(raw.z), bflo(raw.w), bfhi(raw.w)};
;         float s = 0.f;
; #pragma unroll
;         for (int e = 0; e < 8; ++e) s += x[e];
;         const float mean = wave_sum(s) * (1.f / 512.f); float s2 = 0.f;
; #pragma unroll
;         for (int e = 0; e < 8; ++e) { const float d = x[e] - mean; s2 += d * d; }
;         const float rstd = 1.f / sqrtf(wave_sum(s2) * (1.f / 512.f) + 1e-5f);
;         if (lane == 0) { st[tok] = mean; st[128 + tok] = rstd; } }
	v_mov_b32_e32 v3, s26
	v_mov_b32_e32 v4, s27
	v_add_f32_e32 v3, s0, v3
	v_add_f32_e32 v4, s1, v4
	v_add_f32_e32 v3, v3, v4
	v_fmamk_f32 v3, v3, 0x3b000000, v59
	v_mul_f32_e32 v4, 0x4f800000, v3
	v_cmp_gt_f32_e32 vcc, s13, v3
	v_mul_f32_e32 v2, 0x3b000000, v2
	s_nop 0
	v_cndmask_b32_e32 v3, v3, v4, vcc
	v_sqrt_f32_e32 v4, v3
	s_nop 0
	v_add_u32_e32 v5, -1, v4
	v_fma_f32 v6, -v5, v4, v3
	v_cmp_ge_f32_e64 s[0:1], 0, v6
	v_add_u32_e32 v6, 1, v4
	s_nop 0
	v_cndmask_b32_e64 v5, v4, v5, s[0:1]
	v_fma_f32 v4, -v6, v4, v3
	v_cmp_lt_f32_e64 s[0:1], 0, v4
	s_nop 1
	v_cndmask_b32_e64 v4, v5, v6, s[0:1]
	v_mul_f32_e32 v5, 0x37800000, v4
	v_cndmask_b32_e32 v4, v4, v5, vcc
	v_cmp_class_f32_e32 vcc, v3, v60
	s_nop 1
	v_cndmask_b32_e32 v3, v4, v3, vcc
	v_div_scale_f32 v4, s[0:1], v3, v3, 1.0
	v_rcp_f32_e32 v5, v4
	s_add_i32 s0, s24, s25
	v_fma_f32 v6, -v4, v5, 1.0
	v_fmac_f32_e32 v5, v6, v5
	v_div_scale_f32 v6, vcc, 1.0, v3, 1.0
	v_mul_f32_e32 v7, v6, v5
	v_fma_f32 v8, -v4, v7, v6
	v_fmac_f32_e32 v7, v8, v5
	v_fma_f32 v4, -v4, v7, v6
	v_div_fmas_f32 v4, v4, v5, v7
	v_div_fixup_f32 v3, v4, v3, 1.0
	v_mov_b32_e32 v4, s0
	ds_write2st64_b32 v4, v2, v3 offset1:2
.Lgst_0_8:
	s_or_b64 exec, exec, s[4:5]
	s_add_i32 s25, s25, 4
	v_mov_b64_e32 v[2:3], v[132:133]
	v_mov_b64_e32 v[4:5], v[134:135]
	v_lshlrev_b32_e32 v6, 16, v2
	v_and_b32_e32 v7, 0xffff0000, v2
	v_add_f32_e32 v2, 0, v6
	v_lshlrev_b32_e32 v8, 16, v3
	v_add_f32_e32 v2, v2, v7
	v_and_b32_e32 v3, 0xffff0000, v3
	v_add_f32_e32 v2, v2, v8
	v_lshlrev_b32_e32 v9, 16, v4
	v_add_f32_e32 v2, v2, v3
	v_and_b32_e32 v4, 0xffff0000, v4
	v_add_f32_e32 v2, v2, v9
	v_lshlrev_b32_e32 v10, 16, v5
	v_add_f32_e32 v2, v2, v4
	v_and_b32_e32 v5, 0xffff0000, v5
	v_add_f32_e32 v2, v2, v10
	v_add_f32_e32 v2, v2, v5
	v_mov_b32_e32 v11, v2
	s_nop 1
	v_mov_b32_dpp v11, v11 quad_perm:[1,0,3,2] row_mask:0xf bank_mask:0xf
	v_add_f32_e32 v2, v2, v11
	v_mov_b32_e32 v11, v2
	s_nop 1
	v_mov_b32_dpp v11, v11 quad_perm:[2,3,0,1] row_mask:0xf bank_mask:0xf
	v_add_f32_e32 v2, v2, v11
	v_mov_b32_e32 v11, v2
	s_nop 1
	v_mov_b32_dpp v11, v11 row_half_mirror row_mask:0xf bank_mask:0xf
	v_add_f32_e32 v2, v2, v11
	v_mov_b32_e32 v11, v2
	s_nop 1
	v_mov_b32_dpp v11, v11 row_mirror row_mask:0xf bank_mask:0xf
	v_add_f32_e32 v2, v2, v11
	s_nop 0
	v_readlane_b32 s1, v2, 16
	v_readlane_b32 s5, v2, 48
	v_readlane_b32 s0, v2, 0
	v_readlane_b32 s4, v2, 32
	v_mov_b32_e32 v2, s1
	v_mov_b32_e32 v11, s5
	v_add_f32_e32 v2, s0, v2
	v_add_f32_e32 v11, s4, v11
	v_add_f32_e32 v2, v2, v11
	v_fmac_f32_e32 v7, 0xbb000000, v2
	v_fmac_f32_e32 v6, 0xbb000000, v2
	v_mul_f32_e32 v7, v7, v7
	v_fmac_f32_e32 v8, 0xbb000000, v2
	v_fmac_f32_e32 v7, v6, v6
	v_fmac_f32_e32 v3, 0xbb000000, v2
	v_fmac_f32_e32 v7, v8, v8
	v_fmac_f32_e32 v9, 0xbb000000, v2
	v_fmac_f32_e32 v7, v3, v3
	v_fmac_f32_e32 v4, 0xbb000000, v2
	v_fmac_f32_e32 v7, v9, v9
	v_fmac_f32_e32 v10, 0xbb000000, v2
	v_fmac_f32_e32 v7, v4, v4
	v_fmac_f32_e32 v5, 0xbb000000, v2
	v_fmac_f32_e32 v7, v10, v10
	v_fmac_f32_e32 v7, v5, v5
	v_mov_b32_e32 v3, v7
	s_nop 1
	v_mov_b32_dpp v3, v3 quad_perm:[1,0,3,2] row_mask:0xf bank_mask:0xf
	v_add_f32_e32 v3, v7, v3
	v_mov_b32_e32 v4, v3
	s_nop 1
	v_mov_b32_dpp v4, v4 quad_perm:[2,3,0,1] row_mask:0xf bank_mask:0xf
	v_add_f32_e32 v3, v3, v4
	v_mov_b32_e32 v4, v3
	s_nop 1
	v_mov_b32_dpp v4, v4 row_half_mirror row_mask:0xf bank_mask:0xf
	v_add_f32_e32 v3, v3, v4
	v_mov_b32_e32 v4, v3
	s_nop 1
	v_mov_b32_dpp v4, v4 row_mirror row_mask:0xf bank_mask:0xf
	v_add_f32_e32 v3, v3, v4
	s_nop 0
	v_readlane_b32 s0, v3, 0
	v_readlane_b32 s26, v3, 16
	v_readlane_b32 s1, v3, 32
	v_readlane_b32 s27, v3, 48
	s_and_saveexec_b64 s[4:5], s[2:3]
	s_cbranch_execz .Lgst_0_9
	v_mov_b32_e32 v3, s26
	v_mov_b32_e32 v4, s27
	v_add_f32_e32 v3, s0, v3
	v_add_f32_e32 v4, s1, v4
	v_add_f32_e32 v3, v3, v4
	v_fmamk_f32 v3, v3, 0x3b000000, v59
	v_mul_f32_e32 v4, 0x4f800000, v3
	v_cmp_gt_f32_e32 vcc, s13, v3
	v_mul_f32_e32 v2, 0x3b000000, v2
	s_nop 0
	v_cndmask_b32_e32 v3, v3, v4, vcc
	v_sqrt_f32_e32 v4, v3
	s_nop 0
	v_add_u32_e32 v5, -1, v4
	v_fma_f32 v6, -v5, v4, v3
	v_cmp_ge_f32_e64 s[0:1], 0, v6
	v_add_u32_e32 v6, 1, v4
	s_nop 0
	v_cndmask_b32_e64 v5, v4, v5, s[0:1]
	v_fma_f32 v4, -v6, v4, v3
	v_cmp_lt_f32_e64 s[0:1], 0, v4
	s_nop 1
	v_cndmask_b32_e64 v4, v5, v6, s[0:1]
	v_mul_f32_e32 v5, 0x37800000, v4
	v_cndmask_b32_e32 v4, v4, v5, vcc
	v_cmp_class_f32_e32 vcc, v3, v60
	s_nop 1
	v_cndmask_b32_e32 v3, v4, v3, vcc
	v_div_scale_f32 v4, s[0:1], v3, v3, 1.0
	v_rcp_f32_e32 v5, v4
	s_add_i32 s0, s24, s25
	v_fma_f32 v6, -v4, v5, 1.0
	v_fmac_f32_e32 v5, v6, v5
	v_div_scale_f32 v6, vcc, 1.0, v3, 1.0
	v_mul_f32_e32 v7, v6, v5
	v_fma_f32 v8, -v4, v7, v6
	v_fmac_f32_e32 v7, v8, v5
	v_fma_f32 v4, -v4, v7, v6
	v_div_fmas_f32 v4, v4, v5, v7
	v_div_fixup_f32 v3, v4, v3, 1.0
	v_mov_b32_e32 v4, s0
	ds_write2st64_b32 v4, v2, v3 offset1:2
; __device__ __forceinline__ void gmlp_mfma_unit(const Params& p, int l, bf16_t* Z, LAS unsigned char* lds, int nb) {
;     ...
;     for (int i = 0; i < 16; ++i) { const int tok = wave * 16 + i;
;         const u32x4 raw = *(const u32x4*)(Z + (size_t)(row0 + tok) * ZP + ZC_V + lane * 8);
;         const float x[8] = {bflo(raw.x), bfhi(raw.x), bflo(raw.y), bfhi(raw.y), bflo(raw.z), bfhi(raw.z), bflo(raw.w), bfhi(raw.w)};
;         float s = 0.f;
; #pragma unroll
;         for (int e = 0; e < 8; ++e) s += x[e];
;         const float mean = wave_sum(s) * (1.f / 512.f); float s2 = 0.f;
; #pragma unroll
;         for (int e = 0; e < 8; ++e) { const float d = x[e] - mean; s2 += d * d; }
;         const float rstd = 1.f / sqrtf(wave_sum(s2) * (1.f / 512.f) + 1e-5f);
;         if (lane == 0) { st[tok] = mean; st[128 + tok] = rstd; } }
.Lgst_0_9:
	s_or_b64 exec, exec, s[4:5]
	s_add_i32 s25, s25, 4
	v_mov_b64_e32 v[2:3], v[136:137]
	v_mov_b64_e32 v[4:5], v[138:139]
	v_lshlrev_b32_e32 v6, 16, v2
	v_and_b32_e32 v7, 0xffff0000, v2
	v_add_f32_e32 v2, 0, v6
	v_lshlrev_b32_e32 v8, 16, v3
	v_add_f32_e32 v2, v2, v7
	v_and_b32_e32 v3, 0xffff0000, v3
	v_add_f32_e32 v2, v2, v8
	v_lshlrev_b32_e32 v9, 16, v4
	v_add_f32_e32 v2, v2, v3
	v_and_b32_e32 v4, 0xffff0000, v4
	v_add_f32_e32 v2, v2, v9
	v_lshlrev_b32_e32 v10, 16, v5
	v_add_f32_e32 v2, v2, v4
	v_and_b32_e32 v5, 0xffff0000, v5
	v_add_f32_e32 v2, v2, v10
	v_add_f32_e32 v2, v2, v5
	v_mov_b32_e32 v11, v2
	s_nop 1
	v_mov_b32_dpp v11, v11 quad_perm:[1,0,3,2] row_mask:0xf bank_mask:0xf
	v_add_f32_e32 v2, v2, v11
	v_mov_b32_e32 v11, v2
	s_nop 1
	v_mov_b32_dpp v11, v11 quad_perm:[2,3,0,1] row_mask:0xf bank_mask:0xf
	v_add_f32_e32 v2, v2, v11
	v_mov_b32_e32 v11, v2
	s_nop 1
	v_mov_b32_dpp v11, v11 row_half_mirror row_mask:0xf bank_mask:0xf
	v_add_f32_e32 v2, v2, v11
	v_mov_b32_e32 v11, v2
	s_nop 1
	v_mov_b32_dpp v11, v11 row_mirror row_mask:0xf bank_mask:0xf
	v_add_f32_e32 v2, v2, v11
	s_nop 0
	v_readlane_b32 s1, v2, 16
	v_readlane_b32 s5, v2, 48
	v_readlane_b32 s0, v2, 0
	v_readlane_b32 s4, v2, 32
	v_mov_b32_e32 v2, s1
	v_mov_b32_e32 v11, s5
	v_add_f32_e32 v2, s0, v2
	v_add_f32_e32 v11, s4, v11
	v_add_f32_e32 v2, v2, v11
	v_fmac_f32_e32 v7, 0xbb000000, v2
	v_fmac_f32_e32 v6, 0xbb000000, v2
	v_mul_f32_e32 v7, v7, v7
	v_fmac_f32_e32 v8, 0xbb000000, v2
	v_fmac_f32_e32 v7, v6, v6
	v_fmac_f32_e32 v3, 0xbb000000, v2
	v_fmac_f32_e32 v7, v8, v8
	v_fmac_f32_e32 v9, 0xbb000000, v2
	v_fmac_f32_e32 v7, v3, v3
	v_fmac_f32_e32 v4, 0xbb000000, v2
	v_fmac_f32_e32 v7, v9, v9
	v_fmac_f32_e32 v10, 0xbb000000, v2
	v_fmac_f32_e32 v7, v4, v4
	v_fmac_f32_e32 v5, 0xbb000000, v2
	v_fmac_f32_e32 v7, v10, v10
	v_fmac_f32_e32 v7, v5, v5
	v_mov_b32_e32 v3, v7
	s_nop 1
	v_mov_b32_dpp v3, v3 quad_perm:[1,0,3,2] row_mask:0xf bank_mask:0xf
	v_add_f32_e32 v3, v7, v3
	v_mov_b32_e32 v4, v3
	s_nop 1
	v_mov_b32_dpp v4, v4 quad_perm:[2,3,0,1] row_mask:0xf bank_mask:0xf
	v_add_f32_e32 v3, v3, v4
	v_mov_b32_e32 v4, v3
	s_nop 1
	v_mov_b32_dpp v4, v4 row_half_mirror row_mask:0xf bank_mask:0xf
	v_add_f32_e32 v3, v3, v4
	v_mov_b32_e32 v4, v3
	s_nop 1
	v_mov_b32_dpp v4, v4 row_mirror row_mask:0xf bank_mask:0xf
	v_add_f32_e32 v3, v3, v4
	s_nop 0
	v_readlane_b32 s0, v3, 0
	v_readlane_b32 s26, v3, 16
	v_readlane_b32 s1, v3, 32
	v_readlane_b32 s27, v3, 48
	s_and_saveexec_b64 s[4:5], s[2:3]
	s_cbranch_execz .Lgst_0_10
	v_mov_b32_e32 v3, s26
	v_mov_b32_e32 v4, s27
	v_add_f32_e32 v3, s0, v3
	v_add_f32_e32 v4, s1, v4
	v_add_f32_e32 v3, v3, v4
	v_fmamk_f32 v3, v3, 0x3b000000, v59
	v_mul_f32_e32 v4, 0x4f800000, v3
	v_cmp_gt_f32_e32 vcc, s13, v3
	v_mul_f32_e32 v2, 0x3b000000, v2
	s_nop 0
	v_cndmask_b32_e32 v3, v3, v4, vcc
	v_sqrt_f32_e32 v4, v3
	s_nop 0
	v_add_u32_e32 v5, -1, v4
	v_fma_f32 v6, -v5, v4, v3
	v_cmp_ge_f32_e64 s[0:1], 0, v6
	v_add_u32_e32 v6, 1, v4
	s_nop 0
	v_cndmask_b32_e64 v5, v4, v5, s[0:1]
	v_fma_f32 v4, -v6, v4, v3
	v_cmp_lt_f32_e64 s[0:1], 0, v4
	s_nop 1
	v_cndmask_b32_e64 v4, v5, v6, s[0:1]
	v_mul_f32_e32 v5, 0x37800000, v4
	v_cndmask_b32_e32 v4, v4, v5, vcc
	v_cmp_class_f32_e32 vcc, v3, v60
	s_nop 1
	v_cndmask_b32_e32 v3, v4, v3, vcc
	v_div_scale_f32 v4, s[0:1], v3, v3, 1.0
	v_rcp_f32_e32 v5, v4
	s_add_i32 s0, s24, s25
	v_fma_f32 v6, -v4, v5, 1.0
	v_fmac_f32_e32 v5, v6, v5
	v_div_scale_f32 v6, vcc, 1.0, v3, 1.0
	v_mul_f32_e32 v7, v6, v5
	v_fma_f32 v8, -v4, v7, v6
	v_fmac_f32_e32 v7, v8, v5
	v_fma_f32 v4, -v4, v7, v6
	v_div_fmas_f32 v4, v4, v5, v7
	v_div_fixup_f32 v3, v4, v3, 1.0
	v_mov_b32_e32 v4, s0
	ds_write2st64_b32 v4, v2, v3 offset1:2
.Lgst_0_10:
	s_or_b64 exec, exec, s[4:5]
	s_add_i32 s25, s25, 4
	v_mov_b64_e32 v[2:3], v[140:141]
	v_mov_b64_e32 v[4:5], v[142:143]
	v_lshlrev_b32_e32 v6, 16, v2
	v_and_b32_e32 v7, 0xffff0000, v2
	v_add_f32_e32 v2, 0, v6
	v_lshlrev_b32_e32 v8, 16, v3
	v_add_f32_e32 v2, v2, v7
	v_and_b32_e32 v3, 0xffff0000, v3
	v_add_f32_e32 v2, v2, v8
	v_lshlrev_b32_e32 v9, 16, v4
	v_add_f32_e32 v2, v2, v3
	v_and_b32_e32 v4, 0xffff0000, v4
	v_add_f32_e32 v2, v2, v9
	v_lshlrev_b32_e32 v10, 16, v5
	v_add_f32_e32 v2, v2, v4
	v_and_b32_e32 v5, 0xffff0000, v5
	v_add_f32_e32 v2, v2, v10
	v_add_f32_e32 v2, v2, v5
	v_mov_b32_e32 v11, v2
	s_nop 1
	v_mov_b32_dpp v11, v11 quad_perm:[1,0,3,2] row_mask:0xf bank_mask:0xf
	v_add_f32_e32 v2, v2, v11
	v_mov_b32_e32 v11, v2
	s_nop 1
	v_mov_b32_dpp v11, v11 quad_perm:[2,3,0,1] row_mask:0xf bank_mask:0xf
	v_add_f32_e32 v2, v2, v11
	v_mov_b32_e32 v11, v2
	s_nop 1
	v_mov_b32_dpp v11, v11 row_half_mirror row_mask:0xf bank_mask:0xf
	v_add_f32_e32 v2, v2, v11
	v_mov_b32_e32 v11, v2
	s_nop 1
	v_mov_b32_dpp v11, v11 row_mirror row_mask:0xf bank_mask:0xf
	v_add_f32_e32 v2, v2, v11
	s_nop 0
	v_readlane_b32 s1, v2, 16
	v_readlane_b32 s5, v2, 48
	v_readlane_b32 s0, v2, 0
	v_readlane_b32 s4, v2, 32
	v_mov_b32_e32 v2, s1
	v_mov_b32_e32 v11, s5
	v_add_f32_e32 v2, s0, v2
	v_add_f32_e32 v11, s4, v11
	v_add_f32_e32 v2, v2, v11
	v_fmac_f32_e32 v7, 0xbb000000, v2
	v_fmac_f32_e32 v6, 0xbb000000, v2
	v_mul_f32_e32 v7, v7, v7
	v_fmac_f32_e32 v8, 0xbb000000, v2
	v_fmac_f32_e32 v7, v6, v6
	v_fmac_f32_e32 v3, 0xbb000000, v2
	v_fmac_f32_e32 v7, v8, v8
	v_fmac_f32_e32 v9, 0xbb000000, v2
	v_fmac_f32_e32 v7, v3, v3
	v_fmac_f32_e32 v4, 0xbb000000, v2
	v_fmac_f32_e32 v7, v9, v9
	v_fmac_f32_e32 v10, 0xbb000000, v2
	v_fmac_f32_e32 v7, v4, v4
	v_fmac_f32_e32 v5, 0xbb000000, v2
	v_fmac_f32_e32 v7, v10, v10
	v_fmac_f32_e32 v7, v5, v5
	v_mov_b32_e32 v3, v7
	s_nop 1
	v_mov_b32_dpp v3, v3 quad_perm:[1,0,3,2] row_mask:0xf bank_mask:0xf
	v_add_f32_e32 v3, v7, v3
	v_mov_b32_e32 v4, v3
	s_nop 1
	v_mov_b32_dpp v4, v4 quad_perm:[2,3,0,1] row_mask:0xf bank_mask:0xf
	v_add_f32_e32 v3, v3, v4
	v_mov_b32_e32 v4, v3
	s_nop 1
	v_mov_b32_dpp v4, v4 row_half_mirror row_mask:0xf bank_mask:0xf
	v_add_f32_e32 v3, v3, v4
	v_mov_b32_e32 v4, v3
	s_nop 1
	v_mov_b32_dpp v4, v4 row_mirror row_mask:0xf bank_mask:0xf
	v_add_f32_e32 v3, v3, v4
	s_nop 0
	v_readlane_b32 s0, v3, 0
	v_readlane_b32 s26, v3, 16
	v_readlane_b32 s1, v3, 32
	v_readlane_b32 s27, v3, 48
	s_and_saveexec_b64 s[4:5], s[2:3]
	s_cbranch_execz .Lgst_0_11
; __device__ __forceinline__ void gmlp_mfma_unit(const Params& p, int l, bf16_t* Z, LAS unsigned char* lds, int nb) {
;     ...
;     for (int i = 0; i < 16; ++i) { const int tok = wave * 16 + i;
;         const u32x4 raw = *(const u32x4*)(Z + (size_t)(row0 + tok) * ZP + ZC_V + lane * 8);
;         const float x[8] = {bflo(raw.x), bfhi(raw.x), bflo(raw.y), bfhi(raw.y), bflo(raw.z), bfhi(raw.z), bflo(raw.w), bfhi(raw.w)};
;         float s = 0.f;
; #pragma unroll
;         for (int e = 0; e < 8; ++e) s += x[e];
;         const float mean = wave_sum(s) * (1.f / 512.f); float s2 = 0.f;
; #pragma unroll
;         for (int e = 0; e < 8; ++e) { const float d = x[e] - mean; s2 += d * d; }
;         const float rstd = 1.f / sqrtf(wave_sum(s2) * (1.f / 512.f) + 1e-5f);
;         if (lane == 0) { st[tok] = mean; st[128 + tok] = rstd; } }
	v_mov_b32_e32 v3, s26
	v_mov_b32_e32 v4, s27
	v_add_f32_e32 v3, s0, v3
	v_add_f32_e32 v4, s1, v4
	v_add_f32_e32 v3, v3, v4
	v_fmamk_f32 v3, v3, 0x3b000000, v59
	v_mul_f32_e32 v4, 0x4f800000, v3
	v_cmp_gt_f32_e32 vcc, s13, v3
	v_mul_f32_e32 v2, 0x3b000000, v2
	s_nop 0
	v_cndmask_b32_e32 v3, v3, v4, vcc
	v_sqrt_f32_e32 v4, v3
	s_nop 0
	v_add_u32_e32 v5, -1, v4
	v_fma_f32 v6, -v5, v4, v3
	v_cmp_ge_f32_e64 s[0:1], 0, v6
	v_add_u32_e32 v6, 1, v4
	s_nop 0
	v_cndmask_b32_e64 v5, v4, v5, s[0:1]
	v_fma_f32 v4, -v6, v4, v3
	v_cmp_lt_f32_e64 s[0:1], 0, v4
	s_nop 1
	v_cndmask_b32_e64 v4, v5, v6, s[0:1]
	v_mul_f32_e32 v5, 0x37800000, v4
	v_cndmask_b32_e32 v4, v4, v5, vcc
	v_cmp_class_f32_e32 vcc, v3, v60
	s_nop 1
	v_cndmask_b32_e32 v3, v4, v3, vcc
	v_div_scale_f32 v4, s[0:1], v3, v3, 1.0
	v_rcp_f32_e32 v5, v4
	s_add_i32 s0, s24, s25
	v_fma_f32 v6, -v4, v5, 1.0
	v_fmac_f32_e32 v5, v6, v5
	v_div_scale_f32 v6, vcc, 1.0, v3, 1.0
	v_mul_f32_e32 v7, v6, v5
	v_fma_f32 v8, -v4, v7, v6
	v_fmac_f32_e32 v7, v8, v5
	v_fma_f32 v4, -v4, v7, v6
	v_div_fmas_f32 v4, v4, v5, v7
	v_div_fixup_f32 v3, v4, v3, 1.0
	v_mov_b32_e32 v4, s0
	ds_write2st64_b32 v4, v2, v3 offset1:2
.Lgst_0_11:
	s_or_b64 exec, exec, s[4:5]
	s_add_i32 s25, s25, 4
	v_mov_b64_e32 v[2:3], v[144:145]
	v_mov_b64_e32 v[4:5], v[146:147]
	v_lshlrev_b32_e32 v6, 16, v2
	v_and_b32_e32 v7, 0xffff0000, v2
	v_add_f32_e32 v2, 0, v6
	v_lshlrev_b32_e32 v8, 16, v3
	v_add_f32_e32 v2, v2, v7
	v_and_b32_e32 v3, 0xffff0000, v3
	v_add_f32_e32 v2, v2, v8
	v_lshlrev_b32_e32 v9, 16, v4
	v_add_f32_e32 v2, v2, v3
	v_and_b32_e32 v4, 0xffff0000, v4
	v_add_f32_e32 v2, v2, v9
	v_lshlrev_b32_e32 v10, 16, v5
	v_add_f32_e32 v2, v2, v4
	v_and_b32_e32 v5, 0xffff0000, v5
	v_add_f32_e32 v2, v2, v10
	v_add_f32_e32 v2, v2, v5
	v_mov_b32_e32 v11, v2
	s_nop 1
	v_mov_b32_dpp v11, v11 quad_perm:[1,0,3,2] row_mask:0xf bank_mask:0xf
	v_add_f32_e32 v2, v2, v11
	v_mov_b32_e32 v11, v2
	s_nop 1
	v_mov_b32_dpp v11, v11 quad_perm:[2,3,0,1] row_mask:0xf bank_mask:0xf
	v_add_f32_e32 v2, v2, v11
	v_mov_b32_e32 v11, v2
	s_nop 1
	v_mov_b32_dpp v11, v11 row_half_mirror row_mask:0xf bank_mask:0xf
	v_add_f32_e32 v2, v2, v11
	v_mov_b32_e32 v11, v2
	s_nop 1
	v_mov_b32_dpp v11, v11 row_mirror row_mask:0xf bank_mask:0xf
	v_add_f32_e32 v2, v2, v11
	s_nop 0
	v_readlane_b32 s1, v2, 16
	v_readlane_b32 s5, v2, 48
	v_readlane_b32 s0, v2, 0
	v_readlane_b32 s4, v2, 32
	v_mov_b32_e32 v2, s1
	v_mov_b32_e32 v11, s5
	v_add_f32_e32 v2, s0, v2
	v_add_f32_e32 v11, s4, v11
	v_add_f32_e32 v2, v2, v11
	v_fmac_f32_e32 v7, 0xbb000000, v2
	v_fmac_f32_e32 v6, 0xbb000000, v2
	v_mul_f32_e32 v7, v7, v7
	v_fmac_f32_e32 v8, 0xbb000000, v2
	v_fmac_f32_e32 v7, v6, v6
	v_fmac_f32_e32 v3, 0xbb000000, v2
	v_fmac_f32_e32 v7, v8, v8
	v_fmac_f32_e32 v9, 0xbb000000, v2
	v_fmac_f32_e32 v7, v3, v3
	v_fmac_f32_e32 v4, 0xbb000000, v2
	v_fmac_f32_e32 v7, v9, v9
	v_fmac_f32_e32 v10, 0xbb000000, v2
	v_fmac_f32_e32 v7, v4, v4
	v_fmac_f32_e32 v5, 0xbb000000, v2
	v_fmac_f32_e32 v7, v10, v10
	v_fmac_f32_e32 v7, v5, v5
	v_mov_b32_e32 v3, v7
	s_nop 1
	v_mov_b32_dpp v3, v3 quad_perm:[1,0,3,2] row_mask:0xf bank_mask:0xf
	v_add_f32_e32 v3, v7, v3
	v_mov_b32_e32 v4, v3
	s_nop 1
	v_mov_b32_dpp v4, v4 quad_perm:[2,3,0,1] row_mask:0xf bank_mask:0xf
	v_add_f32_e32 v3, v3, v4
	v_mov_b32_e32 v4, v3
	s_nop 1
	v_mov_b32_dpp v4, v4 row_half_mirror row_mask:0xf bank_mask:0xf
	v_add_f32_e32 v3, v3, v4
	v_mov_b32_e32 v4, v3
	s_nop 1
	v_mov_b32_dpp v4, v4 row_mirror row_mask:0xf bank_mask:0xf
	v_add_f32_e32 v3, v3, v4
	s_nop 0
	v_readlane_b32 s0, v3, 0
	v_readlane_b32 s26, v3, 16
	v_readlane_b32 s1, v3, 32
	v_readlane_b32 s27, v3, 48
	s_and_saveexec_b64 s[4:5], s[2:3]
	s_cbranch_execz .Lgst_0_12
	v_mov_b32_e32 v3, s26
	v_mov_b32_e32 v4, s27
	v_add_f32_e32 v3, s0, v3
	v_add_f32_e32 v4, s1, v4
	v_add_f32_e32 v3, v3, v4
	v_fmamk_f32 v3, v3, 0x3b000000, v59
	v_mul_f32_e32 v4, 0x4f800000, v3
	v_cmp_gt_f32_e32 vcc, s13, v3
	v_mul_f32_e32 v2, 0x3b000000, v2
	s_nop 0
	v_cndmask_b32_e32 v3, v3, v4, vcc
	v_sqrt_f32_e32 v4, v3
	s_nop 0
	v_add_u32_e32 v5, -1, v4
	v_fma_f32 v6, -v5, v4, v3
	v_cmp_ge_f32_e64 s[0:1], 0, v6
	v_add_u32_e32 v6, 1, v4
	s_nop 0
	v_cndmask_b32_e64 v5, v4, v5, s[0:1]
	v_fma_f32 v4, -v6, v4, v3
	v_cmp_lt_f32_e64 s[0:1], 0, v4
	s_nop 1
	v_cndmask_b32_e64 v4, v5, v6, s[0:1]
	v_mul_f32_e32 v5, 0x37800000, v4
	v_cndmask_b32_e32 v4, v4, v5, vcc
	v_cmp_class_f32_e32 vcc, v3, v60
	s_nop 1
	v_cndmask_b32_e32 v3, v4, v3, vcc
	v_div_scale_f32 v4, s[0:1], v3, v3, 1.0
	v_rcp_f32_e32 v5, v4
	s_add_i32 s0, s24, s25
	v_fma_f32 v6, -v4, v5, 1.0
	v_fmac_f32_e32 v5, v6, v5
	v_div_scale_f32 v6, vcc, 1.0, v3, 1.0
	v_mul_f32_e32 v7, v6, v5
	v_fma_f32 v8, -v4, v7, v6
	v_fmac_f32_e32 v7, v8, v5
	v_fma_f32 v4, -v4, v7, v6
	v_div_fmas_f32 v4, v4, v5, v7
	v_div_fixup_f32 v3, v4, v3, 1.0
	v_mov_b32_e32 v4, s0
	ds_write2st64_b32 v4, v2, v3 offset1:2
; __device__ __forceinline__ void gmlp_mfma_unit(const Params& p, int l, bf16_t* Z, LAS unsigned char* lds, int nb) {
;     ...
;     for (int i = 0; i < 16; ++i) { const int tok = wave * 16 + i;
;         const u32x4 raw = *(const u32x4*)(Z + (size_t)(row0 + tok) * ZP + ZC_V + lane * 8);
;         const float x[8] = {bflo(raw.x), bfhi(raw.x), bflo(raw.y), bfhi(raw.y), bflo(raw.z), bfhi(raw.z), bflo(raw.w), bfhi(raw.w)};
;         float s = 0.f;
; #pragma unroll
;         for (int e = 0; e < 8; ++e) s += x[e];
;         const float mean = wave_sum(s) * (1.f / 512.f); float s2 = 0.f;
; #pragma unroll
;         for (int e = 0; e < 8; ++e) { const float d = x[e] - mean; s2 += d * d; }
;         const float rstd = 1.f / sqrtf(wave_sum(s2) * (1.f / 512.f) + 1e-5f);
;         if (lane == 0) { st[tok] = mean; st[128 + tok] = rstd; } }
.Lgst_0_12:
	s_or_b64 exec, exec, s[4:5]
	s_add_i32 s25, s25, 4
	v_mov_b64_e32 v[2:3], v[148:149]
	v_mov_b64_e32 v[4:5], v[150:151]
	v_lshlrev_b32_e32 v6, 16, v2
	v_and_b32_e32 v7, 0xffff0000, v2
	v_add_f32_e32 v2, 0, v6
	v_lshlrev_b32_e32 v8, 16, v3
	v_add_f32_e32 v2, v2, v7
	v_and_b32_e32 v3, 0xffff0000, v3
	v_add_f32_e32 v2, v2, v8
	v_lshlrev_b32_e32 v9, 16, v4
	v_add_f32_e32 v2, v2, v3
	v_and_b32_e32 v4, 0xffff0000, v4
	v_add_f32_e32 v2, v2, v9
	v_lshlrev_b32_e32 v10, 16, v5
	v_add_f32_e32 v2, v2, v4
	v_and_b32_e32 v5, 0xffff0000, v5
	v_add_f32_e32 v2, v2, v10
	v_add_f32_e32 v2, v2, v5
	v_mov_b32_e32 v11, v2
	s_nop 1
	v_mov_b32_dpp v11, v11 quad_perm:[1,0,3,2] row_mask:0xf bank_mask:0xf
	v_add_f32_e32 v2, v2, v11
	v_mov_b32_e32 v11, v2
	s_nop 1
	v_mov_b32_dpp v11, v11 quad_perm:[2,3,0,1] row_mask:0xf bank_mask:0xf
	v_add_f32_e32 v2, v2, v11
	v_mov_b32_e32 v11, v2
	s_nop 1
	v_mov_b32_dpp v11, v11 row_half_mirror row_mask:0xf bank_mask:0xf
	v_add_f32_e32 v2, v2, v11
	v_mov_b32_e32 v11, v2
	s_nop 1
	v_mov_b32_dpp v11, v11 row_mirror row_mask:0xf bank_mask:0xf
	v_add_f32_e32 v2, v2, v11
	s_nop 0
	v_readlane_b32 s1, v2, 16
	v_readlane_b32 s5, v2, 48
	v_readlane_b32 s0, v2, 0
	v_readlane_b32 s4, v2, 32
	v_mov_b32_e32 v2, s1
	v_mov_b32_e32 v11, s5
	v_add_f32_e32 v2, s0, v2
	v_add_f32_e32 v11, s4, v11
	v_add_f32_e32 v2, v2, v11
	v_fmac_f32_e32 v7, 0xbb000000, v2
	v_fmac_f32_e32 v6, 0xbb000000, v2
	v_mul_f32_e32 v7, v7, v7
	v_fmac_f32_e32 v8, 0xbb000000, v2
	v_fmac_f32_e32 v7, v6, v6
	v_fmac_f32_e32 v3, 0xbb000000, v2
	v_fmac_f32_e32 v7, v8, v8
	v_fmac_f32_e32 v9, 0xbb000000, v2
	v_fmac_f32_e32 v7, v3, v3
	v_fmac_f32_e32 v4, 0xbb000000, v2
	v_fmac_f32_e32 v7, v9, v9
	v_fmac_f32_e32 v10, 0xbb000000, v2
	v_fmac_f32_e32 v7, v4, v4
	v_fmac_f32_e32 v5, 0xbb000000, v2
	v_fmac_f32_e32 v7, v10, v10
	v_fmac_f32_e32 v7, v5, v5
	v_mov_b32_e32 v3, v7
	s_nop 1
	v_mov_b32_dpp v3, v3 quad_perm:[1,0,3,2] row_mask:0xf bank_mask:0xf
	v_add_f32_e32 v3, v7, v3
	v_mov_b32_e32 v4, v3
	s_nop 1
	v_mov_b32_dpp v4, v4 quad_perm:[2,3,0,1] row_mask:0xf bank_mask:0xf
	v_add_f32_e32 v3, v3, v4
	v_mov_b32_e32 v4, v3
	s_nop 1
	v_mov_b32_dpp v4, v4 row_half_mirror row_mask:0xf bank_mask:0xf
	v_add_f32_e32 v3, v3, v4
	v_mov_b32_e32 v4, v3
	s_nop 1
	v_mov_b32_dpp v4, v4 row_mirror row_mask:0xf bank_mask:0xf
	v_add_f32_e32 v3, v3, v4
	s_nop 0
	v_readlane_b32 s0, v3, 0
	v_readlane_b32 s26, v3, 16
	v_readlane_b32 s1, v3, 32
	v_readlane_b32 s27, v3, 48
	s_and_saveexec_b64 s[4:5], s[2:3]
	s_cbranch_execz .Lgst_0_13
	v_mov_b32_e32 v3, s26
	v_mov_b32_e32 v4, s27
	v_add_f32_e32 v3, s0, v3
	v_add_f32_e32 v4, s1, v4
	v_add_f32_e32 v3, v3, v4
	v_fmamk_f32 v3, v3, 0x3b000000, v59
	v_mul_f32_e32 v4, 0x4f800000, v3
	v_cmp_gt_f32_e32 vcc, s13, v3
	v_mul_f32_e32 v2, 0x3b000000, v2
	s_nop 0
	v_cndmask_b32_e32 v3, v3, v4, vcc
	v_sqrt_f32_e32 v4, v3
	s_nop 0
	v_add_u32_e32 v5, -1, v4
	v_fma_f32 v6, -v5, v4, v3
	v_cmp_ge_f32_e64 s[0:1], 0, v6
	v_add_u32_e32 v6, 1, v4
	s_nop 0
	v_cndmask_b32_e64 v5, v4, v5, s[0:1]
	v_fma_f32 v4, -v6, v4, v3
	v_cmp_lt_f32_e64 s[0:1], 0, v4
	s_nop 1
	v_cndmask_b32_e64 v4, v5, v6, s[0:1]
	v_mul_f32_e32 v5, 0x37800000, v4
	v_cndmask_b32_e32 v4, v4, v5, vcc
	v_cmp_class_f32_e32 vcc, v3, v60
	s_nop 1
	v_cndmask_b32_e32 v3, v4, v3, vcc
	v_div_scale_f32 v4, s[0:1], v3, v3, 1.0
	v_rcp_f32_e32 v5, v4
	s_add_i32 s0, s24, s25
	v_fma_f32 v6, -v4, v5, 1.0
	v_fmac_f32_e32 v5, v6, v5
	v_div_scale_f32 v6, vcc, 1.0, v3, 1.0
	v_mul_f32_e32 v7, v6, v5
	v_fma_f32 v8, -v4, v7, v6
	v_fmac_f32_e32 v7, v8, v5
	v_fma_f32 v4, -v4, v7, v6
	v_div_fmas_f32 v4, v4, v5, v7
	v_div_fixup_f32 v3, v4, v3, 1.0
	v_mov_b32_e32 v4, s0
	ds_write2st64_b32 v4, v2, v3 offset1:2
.Lgst_0_13:
	s_or_b64 exec, exec, s[4:5]
	s_add_i32 s25, s25, 4
	v_mov_b64_e32 v[2:3], v[152:153]
	v_mov_b64_e32 v[4:5], v[154:155]
	v_lshlrev_b32_e32 v6, 16, v2
	v_and_b32_e32 v7, 0xffff0000, v2
	v_add_f32_e32 v2, 0, v6
	v_lshlrev_b32_e32 v8, 16, v3
	v_add_f32_e32 v2, v2, v7
	v_and_b32_e32 v3, 0xffff0000, v3
	v_add_f32_e32 v2, v2, v8
	v_lshlrev_b32_e32 v9, 16, v4
	v_add_f32_e32 v2, v2, v3
	v_and_b32_e32 v4, 0xffff0000, v4
	v_add_f32_e32 v2, v2, v9
	v_lshlrev_b32_e32 v10, 16, v5
	v_add_f32_e32 v2, v2, v4
	v_and_b32_e32 v5, 0xffff0000, v5
	v_add_f32_e32 v2, v2, v10
	v_add_f32_e32 v2, v2, v5
	v_mov_b32_e32 v11, v2
	s_nop 1
	v_mov_b32_dpp v11, v11 quad_perm:[1,0,3,2] row_mask:0xf bank_mask:0xf
	v_add_f32_e32 v2, v2, v11
	v_mov_b32_e32 v11, v2
	s_nop 1
	v_mov_b32_dpp v11, v11 quad_perm:[2,3,0,1] row_mask:0xf bank_mask:0xf
	v_add_f32_e32 v2, v2, v11
	v_mov_b32_e32 v11, v2
	s_nop 1
	v_mov_b32_dpp v11, v11 row_half_mirror row_mask:0xf bank_mask:0xf
	v_add_f32_e32 v2, v2, v11
	v_mov_b32_e32 v11, v2
	s_nop 1
	v_mov_b32_dpp v11, v11 row_mirror row_mask:0xf bank_mask:0xf
	v_add_f32_e32 v2, v2, v11
	s_nop 0
	v_readlane_b32 s1, v2, 16
	v_readlane_b32 s5, v2, 48
	v_readlane_b32 s0, v2, 0
	v_readlane_b32 s4, v2, 32
	v_mov_b32_e32 v2, s1
	v_mov_b32_e32 v11, s5
	v_add_f32_e32 v2, s0, v2
	v_add_f32_e32 v11, s4, v11
	v_add_f32_e32 v2, v2, v11
	v_fmac_f32_e32 v7, 0xbb000000, v2
	v_fmac_f32_e32 v6, 0xbb000000, v2
	v_mul_f32_e32 v7, v7, v7
	v_fmac_f32_e32 v8, 0xbb000000, v2
	v_fmac_f32_e32 v7, v6, v6
	v_fmac_f32_e32 v3, 0xbb000000, v2
	v_fmac_f32_e32 v7, v8, v8
	v_fmac_f32_e32 v9, 0xbb000000, v2
	v_fmac_f32_e32 v7, v3, v3
	v_fmac_f32_e32 v4, 0xbb000000, v2
	v_fmac_f32_e32 v7, v9, v9
	v_fmac_f32_e32 v10, 0xbb000000, v2
	v_fmac_f32_e32 v7, v4, v4
	v_fmac_f32_e32 v5, 0xbb000000, v2
	v_fmac_f32_e32 v7, v10, v10
	v_fmac_f32_e32 v7, v5, v5
	v_mov_b32_e32 v3, v7
	s_nop 1
	v_mov_b32_dpp v3, v3 quad_perm:[1,0,3,2] row_mask:0xf bank_mask:0xf
	v_add_f32_e32 v3, v7, v3
	v_mov_b32_e32 v4, v3
	s_nop 1
	v_mov_b32_dpp v4, v4 quad_perm:[2,3,0,1] row_mask:0xf bank_mask:0xf
	v_add_f32_e32 v3, v3, v4
	v_mov_b32_e32 v4, v3
	s_nop 1
	v_mov_b32_dpp v4, v4 row_half_mirror row_mask:0xf bank_mask:0xf
	v_add_f32_e32 v3, v3, v4
	v_mov_b32_e32 v4, v3
	s_nop 1
	v_mov_b32_dpp v4, v4 row_mirror row_mask:0xf bank_mask:0xf
	v_add_f32_e32 v3, v3, v4
	s_nop 0
	v_readlane_b32 s0, v3, 0
	v_readlane_b32 s26, v3, 16
	v_readlane_b32 s1, v3, 32
	v_readlane_b32 s27, v3, 48
	s_and_saveexec_b64 s[4:5], s[2:3]
	s_cbranch_execz .Lgst_0_14
; __device__ __forceinline__ void gmlp_mfma_unit(const Params& p, int l, bf16_t* Z, LAS unsigned char* lds, int nb) {
;     ...
;     for (int i = 0; i < 16; ++i) { const int tok = wave * 16 + i;
;         const u32x4 raw = *(const u32x4*)(Z + (size_t)(row0 + tok) * ZP + ZC_V + lane * 8);
;         const float x[8] = {bflo(raw.x), bfhi(raw.x), bflo(raw.y), bfhi(raw.y), bflo(raw.z), bfhi(raw.z), bflo(raw.w), bfhi(raw.w)};
;         float s = 0.f;
; #pragma unroll
;         for (int e = 0; e < 8; ++e) s += x[e];
;         const float mean = wave_sum(s) * (1.f / 512.f); float s2 = 0.f;
; #pragma unroll
;         for (int e = 0; e < 8; ++e) { const float d = x[e] - mean; s2 += d * d; }
;         const float rstd = 1.f / sqrtf(wave_sum(s2) * (1.f / 512.f) + 1e-5f);
;         if (lane == 0) { st[tok] = mean; st[128 + tok] = rstd; } }
;     __syncthreads();
;     const int nks = wave < 4 ? 2 : 4, irow = 16 * wave + l15;
	v_mov_b32_e32 v3, s26
	v_mov_b32_e32 v4, s27
	v_add_f32_e32 v3, s0, v3
	v_add_f32_e32 v4, s1, v4
	v_add_f32_e32 v3, v3, v4
	v_fmamk_f32 v3, v3, 0x3b000000, v59
	v_mul_f32_e32 v4, 0x4f800000, v3
	v_cmp_gt_f32_e32 vcc, s13, v3
	v_mul_f32_e32 v2, 0x3b000000, v2
	s_nop 0
	v_cndmask_b32_e32 v3, v3, v4, vcc
	v_sqrt_f32_e32 v4, v3
	s_nop 0
	v_add_u32_e32 v5, -1, v4
	v_fma_f32 v6, -v5, v4, v3
	v_cmp_ge_f32_e64 s[0:1], 0, v6
	v_add_u32_e32 v6, 1, v4
	s_nop 0
	v_cndmask_b32_e64 v5, v4, v5, s[0:1]
	v_fma_f32 v4, -v6, v4, v3
	v_cmp_lt_f32_e64 s[0:1], 0, v4
	s_nop 1
	v_cndmask_b32_e64 v4, v5, v6, s[0:1]
	v_mul_f32_e32 v5, 0x37800000, v4
	v_cndmask_b32_e32 v4, v4, v5, vcc
	v_cmp_class_f32_e32 vcc, v3, v60
	s_nop 1
	v_cndmask_b32_e32 v3, v4, v3, vcc
	v_div_scale_f32 v4, s[0:1], v3, v3, 1.0
	v_rcp_f32_e32 v5, v4
	s_add_i32 s0, s24, s25
	v_fma_f32 v6, -v4, v5, 1.0
	v_fmac_f32_e32 v5, v6, v5
	v_div_scale_f32 v6, vcc, 1.0, v3, 1.0
	v_mul_f32_e32 v7, v6, v5
	v_fma_f32 v8, -v4, v7, v6
	v_fmac_f32_e32 v7, v8, v5
	v_fma_f32 v4, -v4, v7, v6
	v_div_fmas_f32 v4, v4, v5, v7
	v_div_fixup_f32 v3, v4, v3, 1.0
	v_mov_b32_e32 v4, s0
	ds_write2st64_b32 v4, v2, v3 offset1:2
.Lgst_0_14:
	s_or_b64 exec, exec, s[4:5]
	s_add_i32 s25, s25, 4
	v_mov_b64_e32 v[2:3], v[156:157]
	v_mov_b64_e32 v[4:5], v[158:159]
	v_lshlrev_b32_e32 v6, 16, v2
	v_and_b32_e32 v7, 0xffff0000, v2
	v_add_f32_e32 v2, 0, v6
	v_lshlrev_b32_e32 v8, 16, v3
	v_add_f32_e32 v2, v2, v7
	v_and_b32_e32 v3, 0xffff0000, v3
	v_add_f32_e32 v2, v2, v8
	v_lshlrev_b32_e32 v9, 16, v4
	v_add_f32_e32 v2, v2, v3
	v_and_b32_e32 v4, 0xffff0000, v4
	v_add_f32_e32 v2, v2, v9
	v_lshlrev_b32_e32 v10, 16, v5
	v_add_f32_e32 v2, v2, v4
	v_and_b32_e32 v5, 0xffff0000, v5
	v_add_f32_e32 v2, v2, v10
	v_add_f32_e32 v2, v2, v5
	v_mov_b32_e32 v11, v2
	s_nop 1
	v_mov_b32_dpp v11, v11 quad_perm:[1,0,3,2] row_mask:0xf bank_mask:0xf
	v_add_f32_e32 v2, v2, v11
	v_mov_b32_e32 v11, v2
	s_nop 1
	v_mov_b32_dpp v11, v11 quad_perm:[2,3,0,1] row_mask:0xf bank_mask:0xf
	v_add_f32_e32 v2, v2, v11
	v_mov_b32_e32 v11, v2
	s_nop 1
	v_mov_b32_dpp v11, v11 row_half_mirror row_mask:0xf bank_mask:0xf
	v_add_f32_e32 v2, v2, v11
	v_mov_b32_e32 v11, v2
	s_nop 1
	v_mov_b32_dpp v11, v11 row_mirror row_mask:0xf bank_mask:0xf
	v_add_f32_e32 v2, v2, v11
	s_nop 0
	v_readlane_b32 s1, v2, 16
	v_readlane_b32 s5, v2, 48
	v_readlane_b32 s0, v2, 0
	v_readlane_b32 s4, v2, 32
	v_mov_b32_e32 v2, s1
	v_mov_b32_e32 v11, s5
	v_add_f32_e32 v2, s0, v2
	v_add_f32_e32 v11, s4, v11
	v_add_f32_e32 v2, v2, v11
	v_fmac_f32_e32 v7, 0xbb000000, v2
	v_fmac_f32_e32 v6, 0xbb000000, v2
	v_mul_f32_e32 v7, v7, v7
	v_fmac_f32_e32 v8, 0xbb000000, v2
	v_fmac_f32_e32 v7, v6, v6
	v_fmac_f32_e32 v3, 0xbb000000, v2
	v_fmac_f32_e32 v7, v8, v8
	v_fmac_f32_e32 v9, 0xbb000000, v2
	v_fmac_f32_e32 v7, v3, v3
	v_fmac_f32_e32 v4, 0xbb000000, v2
	v_fmac_f32_e32 v7, v9, v9
	v_fmac_f32_e32 v10, 0xbb000000, v2
	v_fmac_f32_e32 v7, v4, v4
	v_fmac_f32_e32 v5, 0xbb000000, v2
	v_fmac_f32_e32 v7, v10, v10
	v_fmac_f32_e32 v7, v5, v5
	v_mov_b32_e32 v3, v7
	s_nop 1
	v_mov_b32_dpp v3, v3 quad_perm:[1,0,3,2] row_mask:0xf bank_mask:0xf
	v_add_f32_e32 v3, v7, v3
	v_mov_b32_e32 v4, v3
	s_nop 1
	v_mov_b32_dpp v4, v4 quad_perm:[2,3,0,1] row_mask:0xf bank_mask:0xf
	v_add_f32_e32 v3, v3, v4
	v_mov_b32_e32 v4, v3
	s_nop 1
	v_mov_b32_dpp v4, v4 row_half_mirror row_mask:0xf bank_mask:0xf
	v_add_f32_e32 v3, v3, v4
	v_mov_b32_e32 v4, v3
	s_nop 1
	v_mov_b32_dpp v4, v4 row_mirror row_mask:0xf bank_mask:0xf
	v_add_f32_e32 v3, v3, v4
	s_nop 0
	v_readlane_b32 s0, v3, 0
	v_readlane_b32 s26, v3, 16
	v_readlane_b32 s1, v3, 32
	v_readlane_b32 s27, v3, 48
	s_and_saveexec_b64 s[4:5], s[2:3]
	s_cbranch_execz .Lgst_0_15
	v_mov_b32_e32 v3, s26
	v_mov_b32_e32 v4, s27
	v_add_f32_e32 v3, s0, v3
	v_add_f32_e32 v4, s1, v4
	v_add_f32_e32 v3, v3, v4
	v_fmamk_f32 v3, v3, 0x3b000000, v59
	v_mul_f32_e32 v4, 0x4f800000, v3
	v_cmp_gt_f32_e32 vcc, s13, v3
	v_mul_f32_e32 v2, 0x3b000000, v2
	s_nop 0
	v_cndmask_b32_e32 v3, v3, v4, vcc
	v_sqrt_f32_e32 v4, v3
	s_nop 0
	v_add_u32_e32 v5, -1, v4
	v_fma_f32 v6, -v5, v4, v3
	v_cmp_ge_f32_e64 s[0:1], 0, v6
	v_add_u32_e32 v6, 1, v4
	s_nop 0
	v_cndmask_b32_e64 v5, v4, v5, s[0:1]
	v_fma_f32 v4, -v6, v4, v3
	v_cmp_lt_f32_e64 s[0:1], 0, v4
	s_nop 1
	v_cndmask_b32_e64 v4, v5, v6, s[0:1]
	v_mul_f32_e32 v5, 0x37800000, v4
	v_cndmask_b32_e32 v4, v4, v5, vcc
	v_cmp_class_f32_e32 vcc, v3, v60
	s_nop 1
	v_cndmask_b32_e32 v3, v4, v3, vcc
	v_div_scale_f32 v4, s[0:1], v3, v3, 1.0
	v_rcp_f32_e32 v5, v4
	s_add_i32 s0, s24, s25
	v_fma_f32 v6, -v4, v5, 1.0
	v_fmac_f32_e32 v5, v6, v5
	v_div_scale_f32 v6, vcc, 1.0, v3, 1.0
	v_mul_f32_e32 v7, v6, v5
	v_fma_f32 v8, -v4, v7, v6
	v_fmac_f32_e32 v7, v8, v5
	v_fma_f32 v4, -v4, v7, v6
	v_div_fmas_f32 v4, v4, v5, v7
	v_div_fixup_f32 v3, v4, v3, 1.0
	v_mov_b32_e32 v4, s0
	ds_write2st64_b32 v4, v2, v3 offset1:2
.Lgst_0_15:
	s_or_b64 exec, exec, s[4:5]
	s_add_i32 s25, s25, 4
.LBB0_336:
	s_lshl_b32 s24, s23, 7
	v_or_b32_e32 v0, s24, v51
	v_mad_i64_i32 v[36:37], s[4:5], v0, s9, v[26:27]
	v_or_b32_e32 v0, s24, v53
	s_lshr_b32 s0, s16, 2
	v_mad_i64_i32 v[38:39], s[4:5], v0, s9, v[26:27]
	v_or_b32_e32 v0, s24, v55
	s_and_b32 s25, s0, 0x3ffffff0
	v_mad_i64_i32 v[40:41], s[4:5], v0, s9, v[26:27]
	v_add_u32_e32 v0, s24, v56
	s_cmpk_gt_u32 s16, 0xff
	v_mad_i64_i32 v[42:43], s[4:5], v0, s9, v[26:27]
	v_add_u32_e32 v0, s25, v58
	s_cselect_b64 s[0:1], -1, 0
	v_or_b32_e32 v67, s25, v50
	v_mad_i64_i32 v[44:45], s[4:5], v0, s9, v[34:35]
	s_mov_b32 s24, 0
	s_waitcnt lgkmcnt(0)
	s_barrier
	s_branch .LBB0_338

; #define LAS __attribute__((address_space(3)))
; __device__ __forceinline__ unsigned pk2(float lo, float hi) { return f2bf(lo) | (f2bf(hi) << 16); }
; __device__ __forceinline__ void gmlp_mfma_unit(const Params& p, int l, bf16_t* Z, LAS unsigned char* lds, int nb) {
;     ...
;         const float bsv = p.in[I_GMBS][(l * 4 + g) * 128 + irow];
;         bf16_t* up = Z + (size_t)(row0 + irow) * ZP + g * 128 + 4 * lq;
; #pragma unroll 2
;         for (int mt = 0; mt < 8; ++mt) {
;             f32x4 acc = (f32x4){0.f, 0.f, 0.f, 0.f};
;             const LAS bf16_t* ap = vnT + (mt * 16 + l15) * 136 + 8 * lq;
;             acc = __builtin_amdgcn_mfma_f32_16x16x32_bf16(*(const LAS bf16x8*)(ap), wf[0], acc, 0, 0, 0);
;             acc = __builtin_amdgcn_mfma_f32_16x16x32_bf16(*(const LAS bf16x8*)(ap + 32), wf[1], acc, 0, 0, 0);
;             if (nks == 4) { acc = __builtin_amdgcn_mfma_f32_16x16x32_bf16(*(const LAS bf16x8*)(ap + 64), wf[2], acc, 0, 0, 0);
;                             acc = __builtin_amdgcn_mfma_f32_16x16x32_bf16(*(const LAS bf16x8*)(ap + 96), wf[3], acc, 0, 0, 0); }
;             const u32x2 uu = *(const u32x2*)(up + mt * 16);
;             u32x2 o; o.x = pk2(bflo(uu.x) * (acc[0] + bsv), bfhi(uu.x) * (acc[1] + bsv)); o.y = pk2(bflo(uu.y) * (acc[2] + bsv), bfhi(uu.y) * (acc[3] + bsv));
;             *(u32x2*)(up + mt * 16) = o; }
.LBB0_343:
	v_lshl_add_u64 v[16:17], v[22:23], 2, s[38:39]
	global_load_dword v46, v[16:17], off
	global_load_dwordx2 v[96:97], v[44:45], off offset:-32
	global_load_dwordx2 v[98:99], v[44:45], off
	global_load_dwordx2 v[100:101], v[44:45], off offset:32
	global_load_dwordx2 v[102:103], v[44:45], off offset:64
	global_load_dwordx2 v[104:105], v[44:45], off offset:96
	global_load_dwordx2 v[106:107], v[44:45], off offset:128
	global_load_dwordx2 v[108:109], v[44:45], off offset:160
	global_load_dwordx2 v[110:111], v[44:45], off offset:192
	v_mov_b64_e32 v[48:49], v[44:45]
	s_waitcnt vmcnt(0)
	v_mov_b32_e32 v47, v46
	s_branch .LBB0_345
.LBB0_344:
	v_mov_b64_e32 v[68:69], v[98:99]
	s_nop 5
	v_mov_b32_e32 v70, v16
	v_mov_b32_e32 v71, v18
	v_mov_b32_e32 v18, v17
	v_pk_add_f32 v[16:17], v[46:47], v[70:71]
	v_pk_add_f32 v[18:19], v[46:47], v[18:19]
	s_addk_i32 s16, 0x2200
	s_cmpk_eq_u32 s16, 0x8800
	v_lshlrev_b32_e32 v71, 16, v69
	v_lshlrev_b32_e32 v70, 16, v68
	v_and_b32_e32 v69, 0xffff0000, v69
	v_and_b32_e32 v68, 0xffff0000, v68
	v_pk_mul_f32 v[18:19], v[18:19], v[68:69]
	v_pk_mul_f32 v[16:17], v[16:17], v[70:71]
	v_and_b32_sdwa v69, v19, v65 dst_sel:DWORD dst_unused:UNUSED_PAD src0_sel:WORD_1 src1_sel:DWORD
	v_and_b32_sdwa v70, v18, v65 dst_sel:DWORD dst_unused:UNUSED_PAD src0_sel:WORD_1 src1_sel:DWORD
	v_and_b32_sdwa v22, v17, v65 dst_sel:DWORD dst_unused:UNUSED_PAD src0_sel:WORD_1 src1_sel:DWORD
	v_and_b32_sdwa v68, v16, v65 dst_sel:DWORD dst_unused:UNUSED_PAD src0_sel:WORD_1 src1_sel:DWORD
	v_add3_u32 v19, v19, v69, s22
	v_add3_u32 v18, v18, v70, s22
	v_add3_u32 v16, v16, v68, s22
	v_add3_u32 v17, v17, v22, s22
	v_and_b32_e32 v19, 0xffff0000, v19
	v_and_b32_e32 v18, 0xffff0000, v18
	v_or_b32_sdwa v17, v19, v17 dst_sel:DWORD dst_unused:UNUSED_PAD src0_sel:DWORD src1_sel:WORD_1
	v_or_b32_sdwa v16, v18, v16 dst_sel:DWORD dst_unused:UNUSED_PAD src0_sel:DWORD src1_sel:WORD_1
	global_store_dwordx2 v[48:49], v[16:17], off
	v_lshl_add_u64 v[48:49], v[48:49], 0, 64
	v_mov_b64_e32 v[96:97], v[100:101]
	v_mov_b64_e32 v[98:99], v[102:103]
	v_mov_b64_e32 v[100:101], v[104:105]
	v_mov_b64_e32 v[102:103], v[106:107]
	v_mov_b64_e32 v[104:105], v[108:109]
	v_mov_b64_e32 v[106:107], v[110:111]
	s_cbranch_scc1 .LBB0_337

; #define LAS __attribute__((address_space(3)))
; __device__ __forceinline__ unsigned pk2(float lo, float hi) { return f2bf(lo) | (f2bf(hi) << 16); }
; __device__ __forceinline__ void gmlp_mfma_unit(const Params& p, int l, bf16_t* Z, LAS unsigned char* lds, int nb) {
;     ...
;         for (int mt = 0; mt < 8; ++mt) {
;             f32x4 acc = (f32x4){0.f, 0.f, 0.f, 0.f};
;             const LAS bf16_t* ap = vnT + (mt * 16 + l15) * 136 + 8 * lq;
;             acc = __builtin_amdgcn_mfma_f32_16x16x32_bf16(*(const LAS bf16x8*)(ap), wf[0], acc, 0, 0, 0);
;             acc = __builtin_amdgcn_mfma_f32_16x16x32_bf16(*(const LAS bf16x8*)(ap + 32), wf[1], acc, 0, 0, 0);
;             if (nks == 4) { acc = __builtin_amdgcn_mfma_f32_16x16x32_bf16(*(const LAS bf16x8*)(ap + 64), wf[2], acc, 0, 0, 0);
;                             acc = __builtin_amdgcn_mfma_f32_16x16x32_bf16(*(const LAS bf16x8*)(ap + 96), wf[3], acc, 0, 0, 0); }
;             const u32x2 uu = *(const u32x2*)(up + mt * 16);
;             u32x2 o; o.x = pk2(bflo(uu.x) * (acc[0] + bsv), bfhi(uu.x) * (acc[1] + bsv)); o.y = pk2(bflo(uu.y) * (acc[2] + bsv), bfhi(uu.y) * (acc[3] + bsv));
;             *(u32x2*)(up + mt * 16) = o; }
.LBB0_347:
	v_mov_b64_e32 v[76:77], v[96:97]
	ds_read_b128 v[68:71], v22 offset:4352
	ds_read_b128 v[72:75], v22 offset:4416
	s_nop 4
	v_mov_b32_e32 v79, v18
	v_mov_b32_e32 v18, v17
	v_mov_b32_e32 v78, v16
	v_pk_add_f32 v[80:81], v[46:47], v[18:19]
	v_pk_add_f32 v[78:79], v[46:47], v[78:79]
	s_and_b64 vcc, exec, s[4:5]
	s_waitcnt lgkmcnt(1)
	v_mfma_f32_16x16x32_bf16 v[16:19], v[68:71], v[0:3], 0
	v_and_b32_e32 v71, 0xffff0000, v77
	v_and_b32_e32 v70, 0xffff0000, v76
	v_lshlrev_b32_e32 v69, 16, v77
	v_lshlrev_b32_e32 v68, 16, v76
	v_pk_mul_f32 v[70:71], v[80:81], v[70:71]
	v_pk_mul_f32 v[68:69], v[78:79], v[68:69]
	v_and_b32_sdwa v78, v71, v65 dst_sel:DWORD dst_unused:UNUSED_PAD src0_sel:WORD_1 src1_sel:DWORD
	v_and_b32_sdwa v79, v70, v65 dst_sel:DWORD dst_unused:UNUSED_PAD src0_sel:WORD_1 src1_sel:DWORD
	s_waitcnt lgkmcnt(0)
	v_mfma_f32_16x16x32_bf16 v[16:19], v[72:75], v[4:7], v[16:19]
	v_and_b32_sdwa v76, v69, v65 dst_sel:DWORD dst_unused:UNUSED_PAD src0_sel:WORD_1 src1_sel:DWORD
	v_and_b32_sdwa v77, v68, v65 dst_sel:DWORD dst_unused:UNUSED_PAD src0_sel:WORD_1 src1_sel:DWORD
	v_add3_u32 v71, v71, v78, s22
	v_add3_u32 v70, v70, v79, s22
	v_add3_u32 v68, v68, v77, s22
	v_add3_u32 v69, v69, v76, s22
	v_and_b32_e32 v71, 0xffff0000, v71
	v_and_b32_e32 v70, 0xffff0000, v70
	v_or_b32_sdwa v69, v71, v69 dst_sel:DWORD dst_unused:UNUSED_PAD src0_sel:DWORD src1_sel:WORD_1
	v_or_b32_sdwa v68, v70, v68 dst_sel:DWORD dst_unused:UNUSED_PAD src0_sel:DWORD src1_sel:WORD_1
	global_store_dwordx2 v[48:49], v[68:69], off offset:-32
	s_cbranch_vccnz .LBB0_344
	ds_read_b128 v[68:71], v22 offset:4480
	ds_read_b128 v[72:75], v22 offset:4544
	s_waitcnt lgkmcnt(1)
	v_mfma_f32_16x16x32_bf16 v[16:19], v[68:71], v[8:11], v[16:19]
	s_waitcnt lgkmcnt(0)
	v_mfma_f32_16x16x32_bf16 v[16:19], v[72:75], v[12:15], v[16:19]
	s_branch .LBB0_344

; __device__ __forceinline__ unsigned pk2(float lo, float hi) { return f2bf(lo) | (f2bf(hi) << 16); }
; __device__ __forceinline__ void latent_pass(const Params& p, int l, bf16_t* Z, bf16_t* Hb) {
;     ...
;     for (int row = gw; row < T; row += ngw) {
;         bf16_t* z = Z + (size_t)row * ZP;
;         const u32x2 qa = *(const u32x2*)(z + ZC_QLAT + 4 * lane);
;         float q0 = bflo(qa.x), q1 = bfhi(qa.x), q2 = bflo(qa.y), q3 = bfhi(qa.y);
;         const float qr = 1.f / sqrtf(wave_sum(q0 * q0 + q1 * q1 + q2 * q2 + q3 * q3) * (1.f / 256.f) + 1e-6f);
;         const f32x4 g4 = *(const f32x4*)(qg + 4 * lane);
;         const unsigned ka = *(const unsigned*)(z + ZC_KVLAT + 2 * lane);
;         float k0 = bflo(ka), k1 = bfhi(ka);
;         const float kr = 1.f / sqrtf(wave_sum(k0 * k0 + k1 * k1) * (1.f / 128.f) + 1e-6f);
;         const float kg0 = kg[2 * lane], kg1 = kg[2 * lane + 1];
;         float x1 = 0.f, x2 = 0.f;
;         if (lane < 16) { x1 = bf2f(z[ZC_KROPE + lane]); x2 = bf2f(z[ZC_KROPE + 16 + lane]); }
;         u32x2 qo; qo.x = pk2(q0 * qr * g4.x, q1 * qr * g4.y); qo.y = pk2(q2 * qr * g4.z, q3 * qr * g4.w);
;         *(u32x2*)(z + ZC_QLAT + 4 * lane) = qo;
.LBB0_352:
	v_lshl_add_u64 v[16:17], s[96:97], 0, v[14:15]
	global_load_dwordx2 v[24:25], v[16:17], off
	v_lshl_add_u64 v[18:19], s[96:97], 0, v[12:13]
	global_load_dword v21, v[18:19], off
	global_load_dwordx4 v[0:3], v[4:5], off
	global_load_dwordx2 v[22:23], v[6:7], off
	v_lshl_add_u64 v[44:45], s[96:97], 0, v[10:11]
	v_add_co_u32_e32 v44, vcc, 0x8c00000, v44
	s_nop 1
	v_addc_co_u32_e32 v45, vcc, 0, v45, vcc
	global_load_ushort v46, v[44:45], off offset:2848
	global_load_ushort v47, v[44:45], off offset:2816
	v_and_or_b32 v48, v30, s28, v64
	v_lshlrev_b32_e32 v48, 2, v48
	global_load_dword v49, v48, s[18:19]
	global_load_dword v50, v48, s[16:17]
	v_mov_b32_e32 v20, 0
	s_waitcnt vmcnt(7)
	v_lshlrev_b32_e32 v27, 16, v25
	v_lshlrev_b32_e32 v26, 16, v24
	v_and_b32_e32 v29, 0xffff0000, v25
	v_and_b32_e32 v28, 0xffff0000, v24
	v_pk_mul_f32 v[36:37], v[26:27], v[26:27]
	v_pk_mul_f32 v[38:39], v[28:29], v[28:29]
	s_waitcnt vmcnt(6)
	v_lshlrev_b32_e32 v24, 16, v21
	v_and_b32_e32 v25, 0xffff0000, v21
	v_add_f32_e32 v21, v36, v38
	v_pk_mul_f32 v[40:41], v[24:25], v[24:25]
	v_add_f32_e32 v21, v37, v21
	v_add_f32_e32 v35, v40, v41
	v_add_f32_e32 v21, v39, v21
	v_mov_b32_e32 v36, v35
	v_mov_b32_e32 v37, v21
	s_nop 0
	v_mov_b32_dpp v36, v36 quad_perm:[1,0,3,2] row_mask:0xf bank_mask:0xf
	v_mov_b32_dpp v37, v37 quad_perm:[1,0,3,2] row_mask:0xf bank_mask:0xf
	v_add_f32_e32 v35, v35, v36
	v_add_f32_e32 v21, v21, v37
	v_mov_b32_e32 v36, v35
	v_mov_b32_e32 v37, v21
	s_nop 0
	v_mov_b32_dpp v36, v36 quad_perm:[2,3,0,1] row_mask:0xf bank_mask:0xf
	v_mov_b32_dpp v37, v37 quad_perm:[2,3,0,1] row_mask:0xf bank_mask:0xf
	v_add_f32_e32 v35, v35, v36
	v_add_f32_e32 v21, v21, v37
	v_mov_b32_e32 v36, v35
	v_mov_b32_e32 v37, v21
	s_nop 0
	v_mov_b32_dpp v36, v36 row_half_mirror row_mask:0xf bank_mask:0xf
	v_mov_b32_dpp v37, v37 row_half_mirror row_mask:0xf bank_mask:0xf
	v_add_f32_e32 v35, v35, v36
	v_add_f32_e32 v21, v21, v37
	v_mov_b32_e32 v36, v35
	v_mov_b32_e32 v37, v21
	s_nop 0
	v_mov_b32_dpp v36, v36 row_mirror row_mask:0xf bank_mask:0xf
	v_mov_b32_dpp v37, v37 row_mirror row_mask:0xf bank_mask:0xf
	v_add_f32_e32 v35, v35, v36
	v_add_f32_e32 v21, v21, v37
	v_readlane_b32 s4, v35, 0
	v_readlane_b32 s29, v35, 16
	v_readlane_b32 s5, v35, 32
	v_readlane_b32 s30, v35, 48
	v_readlane_b32 s31, v21, 0
	v_readlane_b32 s35, v21, 16
	v_readlane_b32 s34, v21, 32
	v_readlane_b32 s36, v21, 48
	v_mov_b32_e32 v21, 0
	s_and_saveexec_b64 s[0:1], s[2:3]
	s_cbranch_execz .LBB0_354
	s_waitcnt vmcnt(2)
	v_lshlrev_b32_e32 v20, 16, v46
	v_lshlrev_b32_e32 v21, 16, v47
; __device__ __forceinline__ unsigned pk2(float lo, float hi) { return f2bf(lo) | (f2bf(hi) << 16); }
; __device__ __forceinline__ void latent_pass(const Params& p, int l, bf16_t* Z, bf16_t* Hb) {
;     ...
;         const float qr = 1.f / sqrtf(wave_sum(q0 * q0 + q1 * q1 + q2 * q2 + q3 * q3) * (1.f / 256.f) + 1e-6f);
;         const f32x4 g4 = *(const f32x4*)(qg + 4 * lane);
;         const unsigned ka = *(const unsigned*)(z + ZC_KVLAT + 2 * lane);
;         float k0 = bflo(ka), k1 = bfhi(ka);
;         const float kr = 1.f / sqrtf(wave_sum(k0 * k0 + k1 * k1) * (1.f / 128.f) + 1e-6f);
;         const float kg0 = kg[2 * lane], kg1 = kg[2 * lane + 1];
;         float x1 = 0.f, x2 = 0.f;
;         if (lane < 16) { x1 = bf2f(z[ZC_KROPE + lane]); x2 = bf2f(z[ZC_KROPE + 16 + lane]); }
;         u32x2 qo; qo.x = pk2(q0 * qr * g4.x, q1 * qr * g4.y); qo.y = pk2(q2 * qr * g4.z, q3 * qr * g4.w);
;         *(u32x2*)(z + ZC_QLAT + 4 * lane) = qo;
;         *(unsigned*)(z + ZC_KVLAT + 2 * lane) = pk2(k0 * kr * kg0, k1 * kr * kg1);
;         if (lane < 16) { const int pos = row & (SEQ - 1); const float c = rc[pos * 16 + lane], s = rs[pos * 16 + lane];
;             *(unsigned*)(Hb + (size_t)row * 1024 + 768 + 2 * lane) = pk2(x1 * c - x2 * s, x2 * c + x1 * s); }
.LBB0_354:
	s_or_b64 exec, exec, s[0:1]
	v_mov_b32_e32 v35, s35
	v_mov_b32_e32 v36, s36
	v_add_f32_e32 v35, s31, v35
	v_add_f32_e32 v36, s34, v36
	v_add_f32_e32 v35, v35, v36
	v_fmamk_f32 v35, v35, 0x3b800000, v31
	v_mul_f32_e32 v36, 0x4f800000, v35
	v_cmp_gt_f32_e32 vcc, s26, v35
	v_mov_b32_e32 v40, s29
	v_mov_b32_e32 v41, s30
	v_cndmask_b32_e32 v35, v35, v36, vcc
	v_sqrt_f32_e32 v36, v35
	v_add_f32_e32 v40, s4, v40
	v_add_f32_e32 v41, s5, v41
	v_add_f32_e32 v40, v40, v41
	v_add_u32_e32 v37, -1, v36
	v_fma_f32 v38, -v37, v36, v35
	v_cmp_ge_f32_e64 s[0:1], 0, v38
	v_add_u32_e32 v38, 1, v36
	v_fmamk_f32 v40, v40, 0x3c000000, v31
	v_cndmask_b32_e64 v37, v36, v37, s[0:1]
	v_fma_f32 v36, -v38, v36, v35
	v_cmp_lt_f32_e64 s[0:1], 0, v36
	v_mul_f32_e32 v41, 0x4f800000, v40
	s_nop 0
	v_cndmask_b32_e64 v36, v37, v38, s[0:1]
	v_mul_f32_e32 v37, 0x37800000, v36
	v_cndmask_b32_e32 v36, v36, v37, vcc
	v_cmp_class_f32_e32 vcc, v35, v32
	s_nop 1
	v_cndmask_b32_e32 v35, v36, v35, vcc
	v_div_scale_f32 v36, s[0:1], v35, v35, 1.0
	v_rcp_f32_e32 v37, v36
	v_cmp_gt_f32_e64 s[0:1], s26, v40
	v_fma_f32 v38, -v36, v37, 1.0
	s_nop 0
	v_cndmask_b32_e64 v40, v40, v41, s[0:1]
	v_fmac_f32_e32 v37, v38, v37
	v_div_scale_f32 v38, vcc, 1.0, v35, 1.0
	v_sqrt_f32_e32 v41, v40
	v_mul_f32_e32 v39, v38, v37
	v_fma_f32 v42, -v36, v39, v38
	v_fmac_f32_e32 v39, v42, v37
	v_fma_f32 v36, -v36, v39, v38
	v_add_u32_e32 v38, -1, v41
	v_fma_f32 v42, -v38, v41, v40
	v_cmp_ge_f32_e64 s[4:5], 0, v42
	v_add_u32_e32 v42, 1, v41
	v_div_fmas_f32 v36, v36, v37, v39
	v_cndmask_b32_e64 v38, v41, v38, s[4:5]
	v_fma_f32 v41, -v42, v41, v40
	v_cmp_lt_f32_e64 s[4:5], 0, v41
	v_div_fixup_f32 v36, v36, v35, 1.0
	s_nop 0
	v_cndmask_b32_e64 v38, v38, v42, s[4:5]
	v_mul_f32_e32 v41, 0x37800000, v38
	v_cndmask_b32_e64 v38, v38, v41, s[0:1]
	v_cmp_class_f32_e64 s[0:1], v40, v32
	s_nop 1
	v_cndmask_b32_e64 v38, v38, v40, s[0:1]
	v_div_scale_f32 v40, s[0:1], v38, v38, 1.0
	v_rcp_f32_e32 v41, v40
	s_nop 0
	v_fma_f32 v35, -v40, v41, 1.0
	v_fmac_f32_e32 v41, v35, v41
	v_div_scale_f32 v35, vcc, 1.0, v38, 1.0
	v_mul_f32_e32 v37, v35, v41
	v_fma_f32 v39, -v40, v37, v35
	v_fmac_f32_e32 v37, v39, v41
	v_fma_f32 v35, -v40, v37, v35
	v_div_fmas_f32 v35, v35, v41, v37
	v_pk_mul_f32 v[26:27], v[36:37], v[26:27] op_sel_hi:[0,1]
	v_pk_mul_f32 v[28:29], v[36:37], v[28:29] op_sel_hi:[0,1]
	s_waitcnt vmcnt(2)
	v_mov_b32_e32 v36, v0
	v_mov_b32_e32 v37, v2
	v_pk_mul_f32 v[26:27], v[36:37], v[26:27]
	v_mov_b32_e32 v2, v1
	v_pk_mul_f32 v[0:1], v[2:3], v[28:29]
	v_and_b32_sdwa v2, v27, v33 dst_sel:DWORD dst_unused:UNUSED_PAD src0_sel:WORD_1 src1_sel:DWORD
	v_and_b32_sdwa v3, v26, v33 dst_sel:DWORD dst_unused:UNUSED_PAD src0_sel:WORD_1 src1_sel:DWORD
	v_add3_u32 v3, v26, v3, s27
	v_add3_u32 v2, v27, v2, s27
	v_and_b32_sdwa v26, v1, v33 dst_sel:DWORD dst_unused:UNUSED_PAD src0_sel:WORD_1 src1_sel:DWORD
	v_and_b32_sdwa v27, v0, v33 dst_sel:DWORD dst_unused:UNUSED_PAD src0_sel:WORD_1 src1_sel:DWORD
	v_add3_u32 v1, v1, v26, s27
	v_add3_u32 v0, v0, v27, s27
	v_and_b32_e32 v1, 0xffff0000, v1
	v_and_b32_e32 v0, 0xffff0000, v0
	v_div_fixup_f32 v38, v35, v38, 1.0
	v_or_b32_sdwa v1, v1, v2 dst_sel:DWORD dst_unused:UNUSED_PAD src0_sel:DWORD src1_sel:WORD_1
	v_or_b32_sdwa v0, v0, v3 dst_sel:DWORD dst_unused:UNUSED_PAD src0_sel:DWORD src1_sel:WORD_1
	global_store_dwordx2 v[16:17], v[0:1], off
	v_pk_mul_f32 v[0:1], v[38:39], v[24:25] op_sel_hi:[0,1]
	s_waitcnt vmcnt(3)
	v_pk_mul_f32 v[0:1], v[22:23], v[0:1]
	s_nop 0
	v_and_b32_sdwa v3, v0, v33 dst_sel:DWORD dst_unused:UNUSED_PAD src0_sel:WORD_1 src1_sel:DWORD
	v_and_b32_sdwa v2, v1, v33 dst_sel:DWORD dst_unused:UNUSED_PAD src0_sel:WORD_1 src1_sel:DWORD
	v_add3_u32 v0, v0, v3, s27
	v_add3_u32 v1, v1, v2, s27
	v_lshrrev_b32_e32 v0, 16, v0
	v_and_or_b32 v0, v1, s13, v0
	global_store_dword v[18:19], v0, off
	s_and_saveexec_b64 s[0:1], s[2:3]
	s_cbranch_execz .LBB0_351
	v_and_or_b32 v0, v30, s28, v64
	v_lshlrev_b32_e32 v1, 2, v0
	s_waitcnt vmcnt(3)
	v_mov_b32_e32 v0, v49
	v_pk_mul_f32 v[0:1], v[20:21], v[0:1] op_sel:[1,0] op_sel_hi:[0,0]
	s_waitcnt vmcnt(2)
	v_mov_b32_e32 v2, v50
	v_pk_fma_f32 v[16:17], v[20:21], v[2:3], v[0:1]
	v_pk_fma_f32 v[0:1], v[20:21], v[2:3], v[0:1] op_sel_hi:[1,0,1] neg_lo:[0,0,1] neg_hi:[0,0,1]
	v_and_b32_sdwa v2, v16, v33 dst_sel:DWORD dst_unused:UNUSED_PAD src0_sel:WORD_1 src1_sel:DWORD
	v_and_b32_sdwa v0, v1, v33 dst_sel:DWORD dst_unused:UNUSED_PAD src0_sel:WORD_1 src1_sel:DWORD
	v_add3_u32 v0, v1, v0, s27
	v_add3_u32 v2, v16, v2, s27
	v_lshrrev_b32_e32 v0, 16, v0
	v_and_or_b32 v2, v2, s13, v0
	v_lshl_add_u64 v[0:1], s[96:97], 0, v[8:9]
	global_store_dword v[0:1], v2, off
	s_branch .LBB0_351

; #define LAS __attribute__((address_space(3)))
; __device__ __forceinline__ unsigned cvtpk2(float lo, float hi) { const f32x2 v = {lo, hi}; const bf16x2_n b = __builtin_convertvector(v, bf16x2_n); return __builtin_bit_cast(unsigned, b); }
; __device__ __forceinline__ void a2_exp_pack(f32x16& st0, f32x16& st1, float& lsum, bf16x8 (&pf)[4]) {
;     float ps = 0.f;
; #pragma unroll
;     for (int r = 0; r < 16; ++r) { st0[r] = __builtin_amdgcn_exp2f(st0[r]); st1[r] = __builtin_amdgcn_exp2f(st1[r]); ps += st0[r] + st1[r]; }
;     lsum += ps;
;     u32x4 w;
;     w.x = cvtpk2(st0[0], st0[1]); w.y = cvtpk2(st0[2], st0[3]); w.z = cvtpk2(st0[4], st0[5]); w.w = cvtpk2(st0[6], st0[7]); pf[0] = __builtin_bit_cast(bf16x8, w);
;     w.x = cvtpk2(st0[8], st0[9]); w.y = cvtpk2(st0[10], st0[11]); w.z = cvtpk2(st0[12], st0[13]); w.w = cvtpk2(st0[14], st0[15]); pf[1] = __builtin_bit_cast(bf16x8, w);
;     w.x = cvtpk2(st1[0], st1[1]); w.y = cvtpk2(st1[2], st1[3]); w.z = cvtpk2(st1[4], st1[5]); w.w = cvtpk2(st1[6], st1[7]); pf[2] = __builtin_bit_cast(bf16x8, w);
;     w.x = cvtpk2(st1[8], st1[9]); w.y = cvtpk2(st1[10], st1[11]); w.z = cvtpk2(st1[12], st1[13]); w.w = cvtpk2(st1[14], st1[15]); pf[3] = __builtin_bit_cast(bf16x8, w);
; }
; __device__ __forceinline__ void a2_pv(const LAS unsigned char* vb, const bf16x8 (&pf)[4], f32x16& ot0, f32x16& ot1) {
; #pragma unroll
;     for (int s = 0; s < 4; ++s) {
;         const s16x4 a00 = __builtin_bit_cast(s16x4, __builtin_amdgcn_ds_read_tr16_b64_v4i16((LAS s16x4*)(vb + (16 * s) * 64)));
;         const s16x4 a01 = __builtin_bit_cast(s16x4, __builtin_amdgcn_ds_read_tr16_b64_v4i16((LAS s16x4*)(vb + (16 * s + 8) * 64)));
;         const s16x4 a10 = __builtin_bit_cast(s16x4, __builtin_amdgcn_ds_read_tr16_b64_v4i16((LAS s16x4*)(vb + 8192 + (16 * s) * 64)));
;         const s16x4 a11 = __builtin_bit_cast(s16x4, __builtin_amdgcn_ds_read_tr16_b64_v4i16((LAS s16x4*)(vb + 8192 + (16 * s + 8) * 64)));
;         const bf16x8 va0 = (bf16x8){a00[0], a00[1], a00[2], a00[3], a01[0], a01[1], a01[2], a01[3]};
;         const bf16x8 va1 = (bf16x8){a10[0], a10[1], a10[2], a10[3], a11[0], a11[1], a11[2], a11[3]};
;         ot0 = __builtin_amdgcn_mfma_f32_32x32x16_bf16(va0, pf[s], ot0, 0, 0, 0); ot1 = __builtin_amdgcn_mfma_f32_32x32x16_bf16(va1, pf[s], ot1, 0, 0, 0); }
; }
.LBB0_832:
	v_add_u32_e32 v0, v2, v218
	v_exp_f32_e32 v199, v112
	v_exp_f32_e32 v7, v96
	v_exp_f32_e32 v113, v113
	v_exp_f32_e32 v9, v97
	v_exp_f32_e32 v201, v114
	v_exp_f32_e32 v3, v98
	v_exp_f32_e32 v115, v115
	v_exp_f32_e32 v5, v99
	v_exp_f32_e32 v203, v116
	v_exp_f32_e32 v15, v117
	v_exp_f32_e32 v13, v118
	v_exp_f32_e32 v11, v119
	s_waitcnt vmcnt(0)
	ds_read_b64_tr_b16 v[96:97], v0 offset:26624
	ds_read_b64_tr_b16 v[98:99], v0 offset:27136
	ds_read_b64_tr_b16 v[214:215], v0 offset:34816
	ds_read_b64_tr_b16 v[216:217], v0 offset:35328
	ds_read_b64_tr_b16 v[224:225], v0 offset:27648
	ds_read_b64_tr_b16 v[226:227], v0 offset:28160
	v_cvt_pk_bf16_f32 v210, v199, v113
	v_cvt_pk_bf16_f32 v211, v201, v115
	v_cvt_pk_bf16_f32 v212, v203, v15
	v_cvt_pk_bf16_f32 v213, v13, v11
	v_exp_f32_e32 v209, v120
	v_exp_f32_e32 v207, v121
	s_waitcnt lgkmcnt(4)
	v_mfma_f32_32x32x16_bf16 v[16:31], v[96:99], v[210:213], v[16:31]
	v_exp_f32_e32 v205, v122
	v_exp_f32_e32 v121, v123
	v_exp_f32_e32 v117, v124
	ds_read_b64_tr_b16 v[228:229], v0 offset:35840
	ds_read_b64_tr_b16 v[230:231], v0 offset:36352
	v_exp_f32_e32 v119, v125
	v_exp_f32_e32 v99, v126
	v_exp_f32_e32 v97, v127
	s_waitcnt lgkmcnt(4)
	v_mfma_f32_32x32x16_bf16 v[32:47], v[214:217], v[210:213], v[32:47]
	v_cvt_pk_bf16_f32 v232, v209, v207
	v_cvt_pk_bf16_f32 v233, v205, v121
	v_cvt_pk_bf16_f32 v234, v117, v119
	v_cvt_pk_bf16_f32 v235, v99, v97
	v_exp_f32_e32 v125, v100
	v_exp_f32_e32 v213, v101
	v_exp_f32_e32 v211, v102
	s_waitcnt lgkmcnt(2)
	v_mfma_f32_32x32x16_bf16 v[16:31], v[224:227], v[232:235], v[16:31]
	v_exp_f32_e32 v217, v103
	ds_read_b64_tr_b16 v[224:225], v0 offset:28672
	ds_read_b64_tr_b16 v[226:227], v0 offset:29184
	v_cvt_pk_bf16_f32 v100, v7, v9
	v_cvt_pk_bf16_f32 v101, v3, v5
	v_cvt_pk_bf16_f32 v102, v125, v213
	v_cvt_pk_bf16_f32 v103, v211, v217
	v_exp_f32_e32 v123, v104
	s_waitcnt lgkmcnt(2)
	v_mfma_f32_32x32x16_bf16 v[32:47], v[228:231], v[232:235], v[32:47]
	ds_read_b64_tr_b16 v[228:229], v0 offset:36864
	ds_read_b64_tr_b16 v[230:231], v0 offset:37376
	ds_read_b64_tr_b16 v[232:233], v0 offset:29696
	ds_read_b64_tr_b16 v[234:235], v0 offset:30208
	v_exp_f32_e32 v127, v105
	v_exp_f32_e32 v105, v106
	v_exp_f32_e32 v215, v107
	v_exp_f32_e32 v107, v108
	v_exp_f32_e32 v109, v109
	v_exp_f32_e32 v198, v64
	s_waitcnt lgkmcnt(4)
	v_mfma_f32_32x32x16_bf16 v[16:31], v[224:227], v[100:103], v[16:31]
	ds_read_b64_tr_b16 v[224:225], v0 offset:37888
	ds_read_b64_tr_b16 v[226:227], v0 offset:38400
	v_exp_f32_e32 v6, v80
	v_exp_f32_e32 v112, v65
	v_exp_f32_e32 v8, v81
	v_exp_f32_e32 v200, v66
	v_exp_f32_e32 v2, v82
	v_exp_f32_e32 v114, v67
	s_waitcnt lgkmcnt(4)
	v_mfma_f32_32x32x16_bf16 v[32:47], v[228:231], v[100:103], v[32:47]
	v_exp_f32_e32 v103, v110
	v_exp_f32_e32 v101, v111
	v_exp_f32_e32 v4, v83
	v_cvt_pk_bf16_f32 v228, v123, v127
	v_cvt_pk_bf16_f32 v229, v105, v215
	v_cvt_pk_bf16_f32 v230, v107, v109
	v_cvt_pk_bf16_f32 v231, v103, v101
	v_pk_add_f32 v[64:65], v[6:7], v[198:199]
	v_pk_add_f32 v[66:67], v[8:9], v[112:113]
	s_waitcnt lgkmcnt(2)
	v_mfma_f32_32x32x16_bf16 v[16:31], v[232:235], v[228:231], v[16:31]
	v_add_f32_e64 v64, v64, 0
	v_add_f32_e64 v65, v65, 0
	v_exp_f32_e32 v202, v68
	v_pk_add_f32 v[64:65], v[66:67], v[64:65]
	v_pk_add_f32 v[66:67], v[2:3], v[200:201]
	v_exp_f32_e32 v14, v69
	v_pk_add_f32 v[64:65], v[66:67], v[64:65]
	v_pk_add_f32 v[66:67], v[4:5], v[114:115]
	s_waitcnt lgkmcnt(0)
	v_mfma_f32_32x32x16_bf16 v[32:47], v[224:227], v[228:231], v[32:47]
	v_add_f32_e64 v110, v66, v64
	v_add_f32_e64 v111, v67, v65
	v_exp_f32_e32 v12, v70
	v_exp_f32_e32 v10, v71
	ds_read_b64_tr_b16 v[64:65], v0 offset:30720
	ds_read_b64_tr_b16 v[66:67], v0 offset:31232
	v_exp_f32_e32 v124, v84
	v_exp_f32_e32 v208, v72
	v_exp_f32_e32 v206, v73
	v_exp_f32_e32 v204, v74
	v_exp_f32_e32 v120, v75
	ds_read_b64_tr_b16 v[72:73], v0 offset:38912
	ds_read_b64_tr_b16 v[74:75], v0 offset:39424
	ds_read_b64_tr_b16 v[80:81], v0 offset:31744
	ds_read_b64_tr_b16 v[82:83], v0 offset:32256
	v_exp_f32_e32 v212, v85
	v_cvt_pk_bf16_f32 v68, v198, v112
	v_cvt_pk_bf16_f32 v69, v200, v114
	v_cvt_pk_bf16_f32 v70, v202, v14
	v_cvt_pk_bf16_f32 v71, v12, v10
	v_pk_add_f32 v[220:221], v[124:125], v[202:203]
	v_exp_f32_e32 v210, v86
	s_waitcnt lgkmcnt(4)
	v_mfma_f32_32x32x16_bf16 v[16:31], v[64:67], v[68:71], v[16:31]
	v_add_f32_e64 v64, v220, v110
	v_add_f32_e64 v65, v221, v111
	v_add_f32_e64 v14, v212, v14
	v_add_f32_e64 v15, v213, v15
	v_exp_f32_e32 v216, v87
	v_exp_f32_e32 v116, v76
	v_exp_f32_e32 v118, v77
	v_exp_f32_e32 v98, v78
	v_exp_f32_e32 v96, v79
	s_waitcnt lgkmcnt(2)
; __device__ __forceinline__ void a2_pv(const LAS unsigned char* vb, const bf16x8 (&pf)[4], f32x16& ot0, f32x16& ot1) {
; #pragma unroll
;     for (int s = 0; s < 4; ++s) {
;         const s16x4 a00 = __builtin_bit_cast(s16x4, __builtin_amdgcn_ds_read_tr16_b64_v4i16((LAS s16x4*)(vb + (16 * s) * 64)));
;         const s16x4 a01 = __builtin_bit_cast(s16x4, __builtin_amdgcn_ds_read_tr16_b64_v4i16((LAS s16x4*)(vb + (16 * s + 8) * 64)));
;         const s16x4 a10 = __builtin_bit_cast(s16x4, __builtin_amdgcn_ds_read_tr16_b64_v4i16((LAS s16x4*)(vb + 8192 + (16 * s) * 64)));
;         const s16x4 a11 = __builtin_bit_cast(s16x4, __builtin_amdgcn_ds_read_tr16_b64_v4i16((LAS s16x4*)(vb + 8192 + (16 * s + 8) * 64)));
;         const bf16x8 va0 = (bf16x8){a00[0], a00[1], a00[2], a00[3], a01[0], a01[1], a01[2], a01[3]};
;         const bf16x8 va1 = (bf16x8){a10[0], a10[1], a10[2], a10[3], a11[0], a11[1], a11[2], a11[3]};
;         ot0 = __builtin_amdgcn_mfma_f32_32x32x16_bf16(va0, pf[s], ot0, 0, 0, 0); ot1 = __builtin_amdgcn_mfma_f32_32x32x16_bf16(va1, pf[s], ot1, 0, 0, 0); }
; }
; __device__ __forceinline__ void attn2_unit(bf16_t* Z, const bf16_t* Hb, const float* rc, const float* rs, LAS unsigned char* lds, int b, int h, int qblk) {
;     ...
;     for (int kp = 0; kp < npairs; ++kp) {
;         const int sb = (kp & 1) * A2_STAGE, sbn = A2_STAGE - sb;
;         const bool more = kp + 1 < npairs;
;         if (more) A2_STAGE_LOAD(sbn, kp + 1);
;         const LAS unsigned char* kb = lds + sb + kboff; const LAS unsigned char* vb = lds + sb + vboff;
;         if (2 * kp + 1 <= cw) {
;             f32x16 sa0, sa1, sb0, sb1; bf16x8 pa[4], pb[4];
;             __builtin_amdgcn_s_setprio(1);
;             a2_qk(kb, qf, cneg, sa0, sa1);
;             a2_qk(kb + 64 * AT_KROW, qf, cneg, sb0, sb1);
;             __builtin_amdgcn_s_setprio(0);
;             const float mt = fmaxf(a2_max(sa0, sa1), a2_max(sb0, sb1));
;             if (kp == 0 || __builtin_amdgcn_ballot_w64(mt > 8.f) != 0ull) {
;                 const float delta = (kp == 0) ? mt : fmaxf(mt, 0.f), alpha = (kp == 0) ? 0.f : __builtin_amdgcn_exp2f(-delta);
;                 mrun += delta; lsum *= alpha;
; #pragma unroll
;                 for (int r = 0; r < 16; ++r) { ot0[r] *= alpha; ot1[r] *= alpha; sa0[r] -= delta; sa1[r] -= delta; sb0[r] -= delta; sb1[r] -= delta; cneg[r] = -mrun; }
;             }
	v_mfma_f32_32x32x16_bf16 v[32:47], v[72:75], v[68:71], v[32:47]
	v_add_f32_e64 v14, v14, v64
	v_add_f32_e64 v15, v15, v65
	ds_read_b64_tr_b16 v[64:65], v0 offset:39936
	ds_read_b64_tr_b16 v[66:67], v0 offset:40448
	v_exp_f32_e32 v122, v88
	v_pk_add_f32 v[12:13], v[210:211], v[12:13]
	v_pk_add_f32 v[68:69], v[216:217], v[10:11]
	v_pk_add_f32 v[14:15], v[12:13], v[14:15]
	v_cvt_pk_bf16_f32 v10, v208, v206
	v_cvt_pk_bf16_f32 v11, v204, v120
	v_cvt_pk_bf16_f32 v12, v116, v118
	v_cvt_pk_bf16_f32 v13, v98, v96
	v_pk_add_f32 v[14:15], v[68:69], v[14:15]
	v_pk_add_f32 v[68:69], v[122:123], v[208:209]
	s_waitcnt lgkmcnt(2)
	v_mfma_f32_32x32x16_bf16 v[16:31], v[80:83], v[10:13], v[16:31]
	v_add_f32_e64 v14, v68, v14
	v_add_f32_e64 v15, v69, v15
	ds_read_b64_tr_b16 v[68:69], v0 offset:32768
	ds_read_b64_tr_b16 v[70:71], v0 offset:33280
	v_exp_f32_e32 v126, v89
	v_exp_f32_e32 v104, v90
	v_cvt_pk_bf16_f32 v7, v2, v4
	v_exp_f32_e32 v214, v91
	v_cvt_pk_bf16_f32 v6, v6, v8
	s_waitcnt lgkmcnt(2)
	v_mfma_f32_32x32x16_bf16 v[32:47], v[64:67], v[10:13], v[32:47]
	ds_read_b64_tr_b16 v[2:3], v0 offset:40960
	ds_read_b64_tr_b16 v[4:5], v0 offset:41472
	ds_read_b64_tr_b16 v[10:11], v0 offset:33792
	ds_read_b64_tr_b16 v[12:13], v0 offset:34304
	v_cvt_pk_bf16_f32 v8, v124, v212
	v_cvt_pk_bf16_f32 v9, v210, v216
	v_pk_add_f32 v[72:73], v[126:127], v[206:207]
	v_pk_add_f32 v[64:65], v[104:105], v[204:205]
	v_pk_add_f32 v[14:15], v[72:73], v[14:15]
	v_exp_f32_e32 v106, v92
	s_waitcnt lgkmcnt(4)
	v_mfma_f32_32x32x16_bf16 v[16:31], v[68:71], v[6:9], v[16:31]
	v_add_f32_e64 v14, v64, v14
	v_add_f32_e64 v15, v65, v15
	v_add_f32_e64 v64, v214, v120
	v_add_f32_e64 v65, v215, v121
	v_exp_f32_e32 v108, v93
	v_exp_f32_e32 v102, v94
	v_exp_f32_e32 v100, v95
	v_pk_add_f32 v[14:15], v[64:65], v[14:15]
	ds_read_b64_tr_b16 v[64:65], v0 offset:41984
	ds_read_b64_tr_b16 v[66:67], v0 offset:42496
	s_waitcnt lgkmcnt(4)
	v_mfma_f32_32x32x16_bf16 v[32:47], v[2:5], v[6:9], v[32:47]
	v_add_f32_e64 v2, v106, v116
	v_add_f32_e64 v3, v107, v117
	v_cvt_pk_bf16_f32 v4, v106, v108
	v_add_f32_e64 v6, v2, v14
	v_add_f32_e64 v7, v3, v15
	v_cvt_pk_bf16_f32 v2, v122, v126
	v_cvt_pk_bf16_f32 v3, v104, v214
	v_cvt_pk_bf16_f32 v5, v102, v100
	v_pk_add_f32 v[8:9], v[108:109], v[118:119]
	v_mov_b32_e32 v14, v55
	s_waitcnt lgkmcnt(2)
	v_mfma_f32_32x32x16_bf16 v[16:31], v[10:13], v[2:5], v[16:31]
	v_add_f32_e64 v6, v8, v6
	v_add_f32_e64 v7, v9, v7
	v_add_f32_e64 v8, v102, v98
	v_add_f32_e64 v9, v103, v99
	v_mov_b32_e32 v10, v59
	v_pk_add_f32 v[6:7], v[8:9], v[6:7]
	v_pk_add_f32 v[8:9], v[100:101], v[96:97]
	v_mov_b32_e32 v11, v58
	v_pk_add_f32 v[6:7], v[8:9], v[6:7]
	s_waitcnt lgkmcnt(0)
	v_mfma_f32_32x32x16_bf16 v[32:47], v[64:67], v[2:5], v[32:47]
	v_add_f32_e32 v0, v169, v7
	v_add_f32_e32 v0, v6, v0
	s_add_i32 s65, s65, 1
	s_add_i32 s69, s69, 2
	s_add_i32 s6, s43, s65
	v_lshl_add_u64 v[176:177], v[176:177], 0, v[174:175]
	v_lshl_add_u64 v[178:179], v[178:179], 0, s[20:21]
	v_lshl_add_u64 v[180:181], v[180:181], 0, s[20:21]
	v_lshl_add_u64 v[184:185], v[184:185], 0, v[182:183]
	v_lshl_add_u64 v[188:189], v[188:189], 0, v[186:187]
	s_cmp_lg_u32 s6, 1
	v_lshl_add_u64 v[196:197], v[196:197], 0, v[190:191]
	s_waitcnt vmcnt(0) lgkmcnt(0)
	s_barrier
	s_cbranch_scc0 .Lattn_exit_0
	v_mov_b32_e32 v169, v0
	s_bitcmp1_b32 s65, 0
	s_cselect_b32 s6, 0, 0xa800
	s_cmp_ge_u32 s65, s36
	s_cbranch_scc0 .LBB0_810
	s_branch .LBB0_813
.Lattn_exit_0:
	s_nop 7
	s_nop 7
	v_mov_b64_e32 v[110:111], v[30:31]
	v_mov_b32_e32 v6, v63
	v_mov_b32_e32 v7, v62
	v_mov_b32_e32 v8, v61
	v_mov_b32_e32 v9, v60
	v_mov_b64_e32 v[126:127], v[46:47]
	v_mov_b32_e32 v12, v57
	v_mov_b32_e32 v13, v56
	v_mov_b32_e32 v15, v54
	v_mov_b32_e32 v171, v53
	v_mov_b32_e32 v198, v52
	v_mov_b32_e32 v199, v51
	v_mov_b32_e32 v200, v50
	v_mov_b32_e32 v201, v49
	v_mov_b32_e32 v4, v48
	v_mov_b32_e32 v5, v165
	v_mov_b64_e32 v[108:109], v[28:29]
	v_mov_b64_e32 v[106:107], v[26:27]
	v_mov_b64_e32 v[104:105], v[24:25]
	v_mov_b64_e32 v[102:103], v[22:23]
	v_mov_b64_e32 v[100:101], v[20:21]
	v_mov_b64_e32 v[98:99], v[18:19]
	v_mov_b64_e32 v[96:97], v[16:17]
	v_mov_b64_e32 v[124:125], v[44:45]
	v_mov_b64_e32 v[122:123], v[42:43]
	v_mov_b64_e32 v[120:121], v[40:41]
	v_mov_b64_e32 v[118:119], v[38:39]
	v_mov_b64_e32 v[116:117], v[36:37]
	v_mov_b64_e32 v[114:115], v[34:35]
	v_mov_b64_e32 v[112:113], v[32:33]
	s_branch .LBB0_837

; #define LAS __attribute__((address_space(3)))
; __device__ __forceinline__ unsigned cvtpk2(float lo, float hi) { const f32x2 v = {lo, hi}; const bf16x2_n b = __builtin_convertvector(v, bf16x2_n); return __builtin_bit_cast(unsigned, b); }
; __device__ __forceinline__ void a2_exp_pack(f32x16& st0, f32x16& st1, float& lsum, bf16x8 (&pf)[4]) {
;     float ps = 0.f;
; #pragma unroll
;     for (int r = 0; r < 16; ++r) { st0[r] = __builtin_amdgcn_exp2f(st0[r]); st1[r] = __builtin_amdgcn_exp2f(st1[r]); ps += st0[r] + st1[r]; }
;     lsum += ps;
;     u32x4 w;
;     w.x = cvtpk2(st0[0], st0[1]); w.y = cvtpk2(st0[2], st0[3]); w.z = cvtpk2(st0[4], st0[5]); w.w = cvtpk2(st0[6], st0[7]); pf[0] = __builtin_bit_cast(bf16x8, w);
;     w.x = cvtpk2(st0[8], st0[9]); w.y = cvtpk2(st0[10], st0[11]); w.z = cvtpk2(st0[12], st0[13]); w.w = cvtpk2(st0[14], st0[15]); pf[1] = __builtin_bit_cast(bf16x8, w);
;     w.x = cvtpk2(st1[0], st1[1]); w.y = cvtpk2(st1[2], st1[3]); w.z = cvtpk2(st1[4], st1[5]); w.w = cvtpk2(st1[6], st1[7]); pf[2] = __builtin_bit_cast(bf16x8, w);
;     w.x = cvtpk2(st1[8], st1[9]); w.y = cvtpk2(st1[10], st1[11]); w.z = cvtpk2(st1[12], st1[13]); w.w = cvtpk2(st1[14], st1[15]); pf[3] = __builtin_bit_cast(bf16x8, w);
; }
; __device__ __forceinline__ void a2_pv(const LAS unsigned char* vb, const bf16x8 (&pf)[4], f32x16& ot0, f32x16& ot1) {
; #pragma unroll
;     for (int s = 0; s < 4; ++s) {
;         const s16x4 a00 = __builtin_bit_cast(s16x4, __builtin_amdgcn_ds_read_tr16_b64_v4i16((LAS s16x4*)(vb + (16 * s) * 64)));
;         const s16x4 a01 = __builtin_bit_cast(s16x4, __builtin_amdgcn_ds_read_tr16_b64_v4i16((LAS s16x4*)(vb + (16 * s + 8) * 64)));
;         const s16x4 a10 = __builtin_bit_cast(s16x4, __builtin_amdgcn_ds_read_tr16_b64_v4i16((LAS s16x4*)(vb + 8192 + (16 * s) * 64)));
;         const s16x4 a11 = __builtin_bit_cast(s16x4, __builtin_amdgcn_ds_read_tr16_b64_v4i16((LAS s16x4*)(vb + 8192 + (16 * s + 8) * 64)));
;         const bf16x8 va0 = (bf16x8){a00[0], a00[1], a00[2], a00[3], a01[0], a01[1], a01[2], a01[3]};
;         const bf16x8 va1 = (bf16x8){a10[0], a10[1], a10[2], a10[3], a11[0], a11[1], a11[2], a11[3]};
;         ot0 = __builtin_amdgcn_mfma_f32_32x32x16_bf16(va0, pf[s], ot0, 0, 0, 0); ot1 = __builtin_amdgcn_mfma_f32_32x32x16_bf16(va1, pf[s], ot1, 0, 0, 0); }
; }
.LBB0_878:
	v_add_u32_e32 v0, v2, v218
	v_exp_f32_e32 v197, v112
	v_exp_f32_e32 v7, v96
	v_exp_f32_e32 v113, v113
	v_exp_f32_e32 v9, v97
	v_exp_f32_e32 v199, v114
	v_exp_f32_e32 v3, v98
	v_exp_f32_e32 v115, v115
	v_exp_f32_e32 v5, v99
	v_exp_f32_e32 v201, v116
	v_exp_f32_e32 v15, v117
	v_exp_f32_e32 v13, v118
	v_exp_f32_e32 v11, v119
	s_waitcnt vmcnt(0)
	ds_read_b64_tr_b16 v[96:97], v0 offset:26624
	ds_read_b64_tr_b16 v[98:99], v0 offset:27136
	ds_read_b64_tr_b16 v[212:213], v0 offset:34816
	ds_read_b64_tr_b16 v[214:215], v0 offset:35328
	ds_read_b64_tr_b16 v[224:225], v0 offset:27648
	ds_read_b64_tr_b16 v[226:227], v0 offset:28160
	v_cvt_pk_bf16_f32 v208, v197, v113
	v_cvt_pk_bf16_f32 v209, v199, v115
	v_cvt_pk_bf16_f32 v210, v201, v15
	v_cvt_pk_bf16_f32 v211, v13, v11
	v_exp_f32_e32 v207, v120
	v_exp_f32_e32 v205, v121
	s_waitcnt lgkmcnt(4)
	v_mfma_f32_32x32x16_bf16 v[16:31], v[96:99], v[208:211], v[16:31]
	v_exp_f32_e32 v203, v122
	v_exp_f32_e32 v121, v123
	v_exp_f32_e32 v117, v124
	ds_read_b64_tr_b16 v[228:229], v0 offset:35840
	ds_read_b64_tr_b16 v[230:231], v0 offset:36352
	v_exp_f32_e32 v119, v125
	v_exp_f32_e32 v99, v126
	v_exp_f32_e32 v97, v127
	s_waitcnt lgkmcnt(4)
	v_mfma_f32_32x32x16_bf16 v[32:47], v[212:215], v[208:211], v[32:47]
	v_cvt_pk_bf16_f32 v232, v207, v205
	v_cvt_pk_bf16_f32 v233, v203, v121
	v_cvt_pk_bf16_f32 v234, v117, v119
	v_cvt_pk_bf16_f32 v235, v99, v97
	v_exp_f32_e32 v125, v100
	v_exp_f32_e32 v211, v101
	v_exp_f32_e32 v209, v102
	s_waitcnt lgkmcnt(2)
	v_mfma_f32_32x32x16_bf16 v[16:31], v[224:227], v[232:235], v[16:31]
	v_exp_f32_e32 v215, v103
	ds_read_b64_tr_b16 v[224:225], v0 offset:28672
	ds_read_b64_tr_b16 v[226:227], v0 offset:29184
	v_cvt_pk_bf16_f32 v100, v7, v9
	v_cvt_pk_bf16_f32 v101, v3, v5
	v_cvt_pk_bf16_f32 v102, v125, v211
	v_cvt_pk_bf16_f32 v103, v209, v215
	v_exp_f32_e32 v123, v104
	s_waitcnt lgkmcnt(2)
	v_mfma_f32_32x32x16_bf16 v[32:47], v[228:231], v[232:235], v[32:47]
	ds_read_b64_tr_b16 v[228:229], v0 offset:36864
	ds_read_b64_tr_b16 v[230:231], v0 offset:37376
	ds_read_b64_tr_b16 v[232:233], v0 offset:29696
	ds_read_b64_tr_b16 v[234:235], v0 offset:30208
	v_exp_f32_e32 v127, v105
	v_exp_f32_e32 v105, v106
	v_exp_f32_e32 v213, v107
	v_exp_f32_e32 v107, v108
	v_exp_f32_e32 v109, v109
	v_exp_f32_e32 v196, v64
	s_waitcnt lgkmcnt(4)
	v_mfma_f32_32x32x16_bf16 v[16:31], v[224:227], v[100:103], v[16:31]
	ds_read_b64_tr_b16 v[224:225], v0 offset:37888
	ds_read_b64_tr_b16 v[226:227], v0 offset:38400
	v_exp_f32_e32 v6, v80
	v_exp_f32_e32 v112, v65
	v_exp_f32_e32 v8, v81
	v_exp_f32_e32 v198, v66
	v_exp_f32_e32 v2, v82
	v_exp_f32_e32 v114, v67
	s_waitcnt lgkmcnt(4)
	v_mfma_f32_32x32x16_bf16 v[32:47], v[228:231], v[100:103], v[32:47]
	v_exp_f32_e32 v103, v110
	v_exp_f32_e32 v101, v111
	v_exp_f32_e32 v4, v83
	v_cvt_pk_bf16_f32 v228, v123, v127
	v_cvt_pk_bf16_f32 v229, v105, v213
	v_cvt_pk_bf16_f32 v230, v107, v109
	v_cvt_pk_bf16_f32 v231, v103, v101
	v_pk_add_f32 v[64:65], v[6:7], v[196:197]
	v_pk_add_f32 v[66:67], v[8:9], v[112:113]
	s_waitcnt lgkmcnt(2)
	v_mfma_f32_32x32x16_bf16 v[16:31], v[232:235], v[228:231], v[16:31]
	v_add_f32_e64 v64, v64, 0
	v_add_f32_e64 v65, v65, 0
	v_exp_f32_e32 v200, v68
	v_pk_add_f32 v[64:65], v[66:67], v[64:65]
	v_pk_add_f32 v[66:67], v[2:3], v[198:199]
	v_exp_f32_e32 v14, v69
	v_pk_add_f32 v[64:65], v[66:67], v[64:65]
	v_pk_add_f32 v[66:67], v[4:5], v[114:115]
	s_waitcnt lgkmcnt(0)
	v_mfma_f32_32x32x16_bf16 v[32:47], v[224:227], v[228:231], v[32:47]
	v_add_f32_e64 v110, v66, v64
	v_add_f32_e64 v111, v67, v65
	v_exp_f32_e32 v12, v70
	v_exp_f32_e32 v10, v71
	ds_read_b64_tr_b16 v[64:65], v0 offset:30720
	ds_read_b64_tr_b16 v[66:67], v0 offset:31232
	v_exp_f32_e32 v124, v84
	v_exp_f32_e32 v206, v72
	v_exp_f32_e32 v204, v73
	v_exp_f32_e32 v202, v74
	v_exp_f32_e32 v120, v75
	ds_read_b64_tr_b16 v[72:73], v0 offset:38912
	ds_read_b64_tr_b16 v[74:75], v0 offset:39424
	ds_read_b64_tr_b16 v[80:81], v0 offset:31744
	ds_read_b64_tr_b16 v[82:83], v0 offset:32256
	v_exp_f32_e32 v210, v85
	v_cvt_pk_bf16_f32 v68, v196, v112
	v_cvt_pk_bf16_f32 v69, v198, v114
	v_cvt_pk_bf16_f32 v70, v200, v14
	v_cvt_pk_bf16_f32 v71, v12, v10
	v_pk_add_f32 v[216:217], v[124:125], v[200:201]
	v_exp_f32_e32 v208, v86
	s_waitcnt lgkmcnt(4)
	v_mfma_f32_32x32x16_bf16 v[16:31], v[64:67], v[68:71], v[16:31]
	v_add_f32_e64 v64, v216, v110
	v_add_f32_e64 v65, v217, v111
	v_add_f32_e64 v14, v210, v14
	v_add_f32_e64 v15, v211, v15
	v_exp_f32_e32 v214, v87
	v_exp_f32_e32 v116, v76
	v_exp_f32_e32 v118, v77
	v_exp_f32_e32 v98, v78
	v_exp_f32_e32 v96, v79
	s_waitcnt lgkmcnt(2)
; __device__ __forceinline__ void a2_pv(const LAS unsigned char* vb, const bf16x8 (&pf)[4], f32x16& ot0, f32x16& ot1) {
; #pragma unroll
;     for (int s = 0; s < 4; ++s) {
;         const s16x4 a00 = __builtin_bit_cast(s16x4, __builtin_amdgcn_ds_read_tr16_b64_v4i16((LAS s16x4*)(vb + (16 * s) * 64)));
;         const s16x4 a01 = __builtin_bit_cast(s16x4, __builtin_amdgcn_ds_read_tr16_b64_v4i16((LAS s16x4*)(vb + (16 * s + 8) * 64)));
;         const s16x4 a10 = __builtin_bit_cast(s16x4, __builtin_amdgcn_ds_read_tr16_b64_v4i16((LAS s16x4*)(vb + 8192 + (16 * s) * 64)));
;         const s16x4 a11 = __builtin_bit_cast(s16x4, __builtin_amdgcn_ds_read_tr16_b64_v4i16((LAS s16x4*)(vb + 8192 + (16 * s + 8) * 64)));
;         const bf16x8 va0 = (bf16x8){a00[0], a00[1], a00[2], a00[3], a01[0], a01[1], a01[2], a01[3]};
;         const bf16x8 va1 = (bf16x8){a10[0], a10[1], a10[2], a10[3], a11[0], a11[1], a11[2], a11[3]};
;         ot0 = __builtin_amdgcn_mfma_f32_32x32x16_bf16(va0, pf[s], ot0, 0, 0, 0); ot1 = __builtin_amdgcn_mfma_f32_32x32x16_bf16(va1, pf[s], ot1, 0, 0, 0); }
; }
; __device__ __forceinline__ void attn2_unit(bf16_t* Z, const bf16_t* Hb, const float* rc, const float* rs, LAS unsigned char* lds, int b, int h, int qblk) {
;     ...
;     for (int kp = 0; kp < npairs; ++kp) {
;         const int sb = (kp & 1) * A2_STAGE, sbn = A2_STAGE - sb;
;         const bool more = kp + 1 < npairs;
;         if (more) A2_STAGE_LOAD(sbn, kp + 1);
;         const LAS unsigned char* kb = lds + sb + kboff; const LAS unsigned char* vb = lds + sb + vboff;
;         if (2 * kp + 1 <= cw) {
;             f32x16 sa0, sa1, sb0, sb1; bf16x8 pa[4], pb[4];
;             __builtin_amdgcn_s_setprio(1);
;             a2_qk(kb, qf, cneg, sa0, sa1);
;             a2_qk(kb + 64 * AT_KROW, qf, cneg, sb0, sb1);
;             __builtin_amdgcn_s_setprio(0);
;             const float mt = fmaxf(a2_max(sa0, sa1), a2_max(sb0, sb1));
;             if (kp == 0 || __builtin_amdgcn_ballot_w64(mt > 8.f) != 0ull) {
;                 const float delta = (kp == 0) ? mt : fmaxf(mt, 0.f), alpha = (kp == 0) ? 0.f : __builtin_amdgcn_exp2f(-delta);
;                 mrun += delta; lsum *= alpha;
; #pragma unroll
;                 for (int r = 0; r < 16; ++r) { ot0[r] *= alpha; ot1[r] *= alpha; sa0[r] -= delta; sa1[r] -= delta; sb0[r] -= delta; sb1[r] -= delta; cneg[r] = -mrun; }
;             }
	v_mfma_f32_32x32x16_bf16 v[32:47], v[72:75], v[68:71], v[32:47]
	v_add_f32_e64 v14, v14, v64
	v_add_f32_e64 v15, v15, v65
	ds_read_b64_tr_b16 v[64:65], v0 offset:39936
	ds_read_b64_tr_b16 v[66:67], v0 offset:40448
	v_exp_f32_e32 v122, v88
	v_pk_add_f32 v[12:13], v[208:209], v[12:13]
	v_pk_add_f32 v[68:69], v[214:215], v[10:11]
	v_pk_add_f32 v[14:15], v[12:13], v[14:15]
	v_cvt_pk_bf16_f32 v10, v206, v204
	v_cvt_pk_bf16_f32 v11, v202, v120
	v_cvt_pk_bf16_f32 v12, v116, v118
	v_cvt_pk_bf16_f32 v13, v98, v96
	v_pk_add_f32 v[14:15], v[68:69], v[14:15]
	v_pk_add_f32 v[68:69], v[122:123], v[206:207]
	s_waitcnt lgkmcnt(2)
	v_mfma_f32_32x32x16_bf16 v[16:31], v[80:83], v[10:13], v[16:31]
	v_add_f32_e64 v14, v68, v14
	v_add_f32_e64 v15, v69, v15
	ds_read_b64_tr_b16 v[68:69], v0 offset:32768
	ds_read_b64_tr_b16 v[70:71], v0 offset:33280
	v_exp_f32_e32 v126, v89
	v_exp_f32_e32 v104, v90
	v_cvt_pk_bf16_f32 v7, v2, v4
	v_exp_f32_e32 v212, v91
	v_cvt_pk_bf16_f32 v6, v6, v8
	s_waitcnt lgkmcnt(2)
	v_mfma_f32_32x32x16_bf16 v[32:47], v[64:67], v[10:13], v[32:47]
	ds_read_b64_tr_b16 v[2:3], v0 offset:40960
	ds_read_b64_tr_b16 v[4:5], v0 offset:41472
	ds_read_b64_tr_b16 v[10:11], v0 offset:33792
	ds_read_b64_tr_b16 v[12:13], v0 offset:34304
	v_cvt_pk_bf16_f32 v8, v124, v210
	v_cvt_pk_bf16_f32 v9, v208, v214
	v_pk_add_f32 v[72:73], v[126:127], v[204:205]
	v_pk_add_f32 v[64:65], v[104:105], v[202:203]
	v_pk_add_f32 v[14:15], v[72:73], v[14:15]
	v_exp_f32_e32 v106, v92
	s_waitcnt lgkmcnt(4)
	v_mfma_f32_32x32x16_bf16 v[16:31], v[68:71], v[6:9], v[16:31]
	v_add_f32_e64 v14, v64, v14
	v_add_f32_e64 v15, v65, v15
	v_add_f32_e64 v64, v212, v120
	v_add_f32_e64 v65, v213, v121
	v_exp_f32_e32 v108, v93
	v_exp_f32_e32 v102, v94
	v_exp_f32_e32 v100, v95
	v_pk_add_f32 v[14:15], v[64:65], v[14:15]
	ds_read_b64_tr_b16 v[64:65], v0 offset:41984
	ds_read_b64_tr_b16 v[66:67], v0 offset:42496
	s_waitcnt lgkmcnt(4)
	v_mfma_f32_32x32x16_bf16 v[32:47], v[2:5], v[6:9], v[32:47]
	v_add_f32_e64 v2, v106, v116
	v_add_f32_e64 v3, v107, v117
	v_cvt_pk_bf16_f32 v4, v106, v108
	v_add_f32_e64 v6, v2, v14
	v_add_f32_e64 v7, v3, v15
	v_cvt_pk_bf16_f32 v2, v122, v126
	v_cvt_pk_bf16_f32 v3, v104, v212
	v_cvt_pk_bf16_f32 v5, v102, v100
	v_pk_add_f32 v[8:9], v[108:109], v[118:119]
	v_mov_b32_e32 v14, v55
	s_waitcnt lgkmcnt(2)
	v_mfma_f32_32x32x16_bf16 v[16:31], v[10:13], v[2:5], v[16:31]
	v_add_f32_e64 v6, v8, v6
	v_add_f32_e64 v7, v9, v7
	v_add_f32_e64 v8, v102, v98
	v_add_f32_e64 v9, v103, v99
	v_mov_b32_e32 v10, v59
	v_pk_add_f32 v[6:7], v[8:9], v[6:7]
	v_pk_add_f32 v[8:9], v[100:101], v[96:97]
	v_mov_b32_e32 v11, v58
	v_pk_add_f32 v[6:7], v[8:9], v[6:7]
	s_waitcnt lgkmcnt(0)
	v_mfma_f32_32x32x16_bf16 v[32:47], v[64:67], v[2:5], v[32:47]
	v_add_f32_e32 v0, v169, v7
	v_add_f32_e32 v0, v6, v0
	s_add_i32 s35, s35, 1
	s_add_i32 s56, s56, 2
	s_add_i32 s6, s46, s35
	v_lshl_add_u64 v[174:175], v[174:175], 0, v[170:171]
	v_lshl_add_u64 v[176:177], v[176:177], 0, s[20:21]
	v_lshl_add_u64 v[178:179], v[178:179], 0, s[20:21]
	v_lshl_add_u64 v[182:183], v[182:183], 0, v[180:181]
	v_lshl_add_u64 v[186:187], v[186:187], 0, v[184:185]
	s_cmp_lg_u32 s6, 1
	v_lshl_add_u64 v[190:191], v[190:191], 0, v[188:189]
	s_waitcnt vmcnt(0) lgkmcnt(0)
	s_barrier
	s_cbranch_scc0 .Lattn_exit_1
	v_mov_b32_e32 v169, v0
	s_bitcmp1_b32 s35, 0
	s_cselect_b32 s6, 0, 0xa800
	s_cmp_ge_u32 s35, s42
	s_cbranch_scc0 .LBB0_856
	s_branch .LBB0_859
.Lattn_exit_1:
	s_nop 7
	s_nop 7
	v_mov_b64_e32 v[110:111], v[30:31]
	v_mov_b32_e32 v6, v63
	v_mov_b32_e32 v7, v62
	v_mov_b32_e32 v8, v61
	v_mov_b32_e32 v9, v60
	v_mov_b64_e32 v[126:127], v[46:47]
	v_mov_b32_e32 v12, v57
	v_mov_b32_e32 v13, v56
	v_mov_b32_e32 v15, v54
	v_mov_b32_e32 v196, v53
	v_mov_b32_e32 v197, v52
	v_mov_b32_e32 v198, v51
	v_mov_b32_e32 v199, v50
	v_mov_b32_e32 v200, v49
	v_mov_b32_e32 v4, v48
	v_mov_b32_e32 v5, v165
	v_mov_b64_e32 v[108:109], v[28:29]
	v_mov_b64_e32 v[106:107], v[26:27]
	v_mov_b64_e32 v[104:105], v[24:25]
	v_mov_b64_e32 v[102:103], v[22:23]
	v_mov_b64_e32 v[100:101], v[20:21]
	v_mov_b64_e32 v[98:99], v[18:19]
	v_mov_b64_e32 v[96:97], v[16:17]
	v_mov_b64_e32 v[124:125], v[44:45]
	v_mov_b64_e32 v[122:123], v[42:43]
	v_mov_b64_e32 v[120:121], v[40:41]
	v_mov_b64_e32 v[118:119], v[38:39]
	v_mov_b64_e32 v[116:117], v[36:37]
	v_mov_b64_e32 v[114:115], v[34:35]
	v_mov_b64_e32 v[112:113], v[32:33]
	s_branch .LBB0_790

; __device__ __forceinline__ unsigned cvt_pk_bf16(float lo, float hi) { unsigned r; asm volatile("v_cvt_pk_bf16_f32 %0, %1, %2" : "=v"(r) : "v"(lo), "v"(hi)); return r; }
;     __device__ __forceinline__ void operator()(const f32x4 (&acc)[2][2][4][2], const Unit& u, int wr, int wc, int fr, int fq) const {
;         EPI_LOOP_BEGIN
;             const int col = u.pn * BM + cl;
;             v0 = v0 + *(const f32x4*)(bias + col); v1 = v1 + *(const f32x4*)(bias + col + 4);
; #pragma unroll
;             for (int e = 0; e < 4; ++e) { const float a = fmaxf(v0[e], 0.f), b = fmaxf(v1[e], 0.f); v0[e] = a * a; v1[e] = b * b; }
;             u32x4 w; w.x = cvt_pk_bf16(v0[0], v0[1]); w.y = cvt_pk_bf16(v0[2], v0[3]); w.z = cvt_pk_bf16(v1[0], v1[1]); w.w = cvt_pk_bf16(v1[2], v1[3]);
;             *(u32x4*)(F1 + (size_t)row * ZP + col) = w;
;         EPI_LOOP_END
.LBB0_1323:
	v_lshl_or_b32 v148, s65, 8, v152
	v_readlane_b32 s72, v246, 0
	v_ashrrev_i32_e32 v149, 31, v148
	v_readlane_b32 s73, v246, 1
	v_lshl_add_u32 v156, s28, 8, v150
	v_mov_b64_e32 v[146:147], s[4:5]
	v_lshl_add_u64 v[144:145], v[148:149], 2, s[72:73]
	global_load_dwordx4 v[200:203], v[144:145], off
	global_load_dwordx4 v[204:207], v[144:145], off offset:16
	global_load_dwordx4 v[208:211], v[144:145], off offset:512
	global_load_dwordx4 v[212:215], v[144:145], off offset:528
	v_mad_i64_i32 v[166:167], s[6:7], v156, s64, v[146:147]
	v_lshlrev_b64 v[148:149], 1, v[148:149]
	v_lshl_add_u64 v[166:167], v[166:167], 0, v[148:149]
	s_andn2_b64 vcc, exec, s[2:3]
	s_mov_b64 s[2:3], -1
	v_readlane_b32 s74, v246, 2
	v_readlane_b32 s75, v246, 3
	v_readlane_b32 s76, v246, 4
	v_readlane_b32 s77, v246, 5
	v_readlane_b32 s78, v246, 6
	v_readlane_b32 s79, v246, 7
	s_waitcnt vmcnt(0)
	v_pk_add_f32 v[126:127], v[126:127], v[202:203]
	v_pk_add_f32 v[124:125], v[124:125], v[200:201]
	v_pk_add_f32 v[122:123], v[122:123], v[206:207]
	v_pk_add_f32 v[120:121], v[120:121], v[204:205]
	v_max_f32_e32 v125, 0, v125
	v_max_f32_e32 v120, 0, v120
	v_max_f32_e32 v121, 0, v121
	v_max_f32_e32 v126, 0, v126
	v_max_f32_e32 v122, 0, v122
	v_max_f32_e32 v127, 0, v127
	v_max_f32_e32 v123, 0, v123
	v_max_f32_e32 v124, 0, v124
	v_mul_f32_e32 v157, v120, v120
	v_mul_f32_e32 v120, v125, v125
	v_mul_f32_e32 v125, v121, v121
	v_mul_f32_e32 v121, v126, v126
	v_mul_f32_e32 v126, v122, v122
	v_mul_f32_e32 v122, v127, v127
	v_mul_f32_e32 v123, v123, v123
	v_mul_f32_e32 v124, v124, v124
	v_cvt_pk_bf16_f32 v120, v124, v120
	v_cvt_pk_bf16_f32 v121, v121, v122
	v_cvt_pk_bf16_f32 v122, v157, v125
	v_cvt_pk_bf16_f32 v123, v126, v123
	global_store_dwordx4 v[166:167], v[120:123], off
	v_pk_add_f32 v[118:119], v[118:119], v[210:211]
	v_pk_add_f32 v[116:117], v[116:117], v[208:209]
	v_pk_add_f32 v[114:115], v[114:115], v[214:215]
	v_pk_add_f32 v[112:113], v[112:113], v[212:213]
	v_max_f32_e32 v117, 0, v117
	v_max_f32_e32 v112, 0, v112
	v_max_f32_e32 v113, 0, v113
	v_max_f32_e32 v118, 0, v118
	v_max_f32_e32 v114, 0, v114
	v_max_f32_e32 v119, 0, v119
	v_max_f32_e32 v115, 0, v115
	v_max_f32_e32 v116, 0, v116
	v_mul_f32_e32 v120, v112, v112
	v_mul_f32_e32 v112, v117, v117
	v_mul_f32_e32 v117, v113, v113
	v_mul_f32_e32 v113, v118, v118
	v_mul_f32_e32 v118, v114, v114
	v_mul_f32_e32 v114, v119, v119
	v_mul_f32_e32 v115, v115, v115
	v_mul_f32_e32 v116, v116, v116
	v_cvt_pk_bf16_f32 v112, v116, v112
	v_cvt_pk_bf16_f32 v113, v113, v114
	v_cvt_pk_bf16_f32 v114, v120, v117
	v_cvt_pk_bf16_f32 v115, v118, v115
	global_store_dwordx4 v[166:167], v[112:115], off offset:256
	v_or_b32_e32 v120, 16, v156
	v_mad_i64_i32 v[120:121], s[6:7], v120, s64, v[146:147]
	v_lshl_add_u64 v[120:121], v[120:121], 0, v[148:149]
	v_pk_add_f32 v[110:111], v[110:111], v[202:203]
	v_pk_add_f32 v[108:109], v[108:109], v[200:201]
	v_pk_add_f32 v[106:107], v[106:107], v[206:207]
	v_pk_add_f32 v[104:105], v[104:105], v[204:205]
	v_max_f32_e32 v109, 0, v109
	v_max_f32_e32 v104, 0, v104
	v_max_f32_e32 v105, 0, v105
	v_max_f32_e32 v110, 0, v110
	v_max_f32_e32 v106, 0, v106
	v_max_f32_e32 v111, 0, v111
	v_max_f32_e32 v107, 0, v107
	v_max_f32_e32 v108, 0, v108
	v_mul_f32_e32 v112, v104, v104
	v_mul_f32_e32 v104, v109, v109
	v_mul_f32_e32 v109, v105, v105
	v_mul_f32_e32 v105, v110, v110
	v_mul_f32_e32 v110, v106, v106
	v_mul_f32_e32 v106, v111, v111
	v_mul_f32_e32 v107, v107, v107
	v_mul_f32_e32 v108, v108, v108
	v_cvt_pk_bf16_f32 v104, v108, v104
	v_cvt_pk_bf16_f32 v105, v105, v106
	v_cvt_pk_bf16_f32 v106, v112, v109
	v_cvt_pk_bf16_f32 v107, v110, v107
	global_store_dwordx4 v[120:121], v[104:107], off
	v_pk_add_f32 v[102:103], v[102:103], v[210:211]
	v_pk_add_f32 v[100:101], v[100:101], v[208:209]
	v_pk_add_f32 v[98:99], v[98:99], v[214:215]
	v_pk_add_f32 v[96:97], v[96:97], v[212:213]
	v_max_f32_e32 v101, 0, v101
	v_max_f32_e32 v96, 0, v96
	v_max_f32_e32 v97, 0, v97
	v_max_f32_e32 v102, 0, v102
	v_max_f32_e32 v98, 0, v98
	v_max_f32_e32 v103, 0, v103
	v_max_f32_e32 v99, 0, v99
	v_max_f32_e32 v100, 0, v100
	v_mul_f32_e32 v104, v96, v96
	v_mul_f32_e32 v96, v101, v101
	v_mul_f32_e32 v101, v97, v97
	v_mul_f32_e32 v97, v102, v102
	v_mul_f32_e32 v102, v98, v98
	v_mul_f32_e32 v98, v103, v103
	v_mul_f32_e32 v99, v99, v99
	v_mul_f32_e32 v100, v100, v100
	v_cvt_pk_bf16_f32 v96, v100, v96
	v_cvt_pk_bf16_f32 v97, v97, v98
	v_cvt_pk_bf16_f32 v98, v104, v101
	v_cvt_pk_bf16_f32 v99, v102, v99
	global_store_dwordx4 v[120:121], v[96:99], off offset:256
	v_or_b32_e32 v104, 32, v156
	v_mad_i64_i32 v[104:105], s[6:7], v104, s64, v[146:147]
	v_lshl_add_u64 v[104:105], v[104:105], 0, v[148:149]
	v_pk_add_f32 v[94:95], v[94:95], v[202:203]
	v_pk_add_f32 v[92:93], v[92:93], v[200:201]
	v_pk_add_f32 v[90:91], v[90:91], v[206:207]
	v_pk_add_f32 v[88:89], v[88:89], v[204:205]
	v_max_f32_e32 v93, 0, v93
	v_max_f32_e32 v88, 0, v88
	v_max_f32_e32 v89, 0, v89
	v_max_f32_e32 v94, 0, v94
	v_max_f32_e32 v90, 0, v90
	v_max_f32_e32 v95, 0, v95
	v_max_f32_e32 v91, 0, v91
	v_max_f32_e32 v92, 0, v92
	v_mul_f32_e32 v96, v88, v88
	v_mul_f32_e32 v88, v93, v93
	v_mul_f32_e32 v93, v89, v89
	v_mul_f32_e32 v89, v94, v94
	v_mul_f32_e32 v94, v90, v90
	v_mul_f32_e32 v90, v95, v95
	v_mul_f32_e32 v91, v91, v91
	v_mul_f32_e32 v92, v92, v92
	v_cvt_pk_bf16_f32 v88, v92, v88
	v_cvt_pk_bf16_f32 v89, v89, v90
	v_cvt_pk_bf16_f32 v90, v96, v93
	v_cvt_pk_bf16_f32 v91, v94, v91
	global_store_dwordx4 v[104:105], v[88:91], off
	v_pk_add_f32 v[86:87], v[86:87], v[210:211]
	v_pk_add_f32 v[84:85], v[84:85], v[208:209]
	v_pk_add_f32 v[82:83], v[82:83], v[214:215]
	v_pk_add_f32 v[80:81], v[80:81], v[212:213]
; __device__ __forceinline__ unsigned cvt_pk_bf16(float lo, float hi) { unsigned r; asm volatile("v_cvt_pk_bf16_f32 %0, %1, %2" : "=v"(r) : "v"(lo), "v"(hi)); return r; }
;     __device__ __forceinline__ void operator()(const f32x4 (&acc)[2][2][4][2], const Unit& u, int wr, int wc, int fr, int fq) const {
;         EPI_LOOP_BEGIN
;             const int col = u.pn * BM + cl;
;             v0 = v0 + *(const f32x4*)(bias + col); v1 = v1 + *(const f32x4*)(bias + col + 4);
; #pragma unroll
;             for (int e = 0; e < 4; ++e) { const float a = fmaxf(v0[e], 0.f), b = fmaxf(v1[e], 0.f); v0[e] = a * a; v1[e] = b * b; }
;             u32x4 w; w.x = cvt_pk_bf16(v0[0], v0[1]); w.y = cvt_pk_bf16(v0[2], v0[3]); w.z = cvt_pk_bf16(v1[0], v1[1]); w.w = cvt_pk_bf16(v1[2], v1[3]);
;             *(u32x4*)(F1 + (size_t)row * ZP + col) = w;
;         EPI_LOOP_END
	v_max_f32_e32 v85, 0, v85
	v_max_f32_e32 v80, 0, v80
	v_max_f32_e32 v81, 0, v81
	v_max_f32_e32 v86, 0, v86
	v_max_f32_e32 v82, 0, v82
	v_max_f32_e32 v87, 0, v87
	v_max_f32_e32 v83, 0, v83
	v_max_f32_e32 v84, 0, v84
	v_mul_f32_e32 v88, v80, v80
	v_mul_f32_e32 v80, v85, v85
	v_mul_f32_e32 v85, v81, v81
	v_mul_f32_e32 v81, v86, v86
	v_mul_f32_e32 v86, v82, v82
	v_mul_f32_e32 v82, v87, v87
	v_mul_f32_e32 v83, v83, v83
	v_mul_f32_e32 v84, v84, v84
	v_cvt_pk_bf16_f32 v80, v84, v80
	v_cvt_pk_bf16_f32 v81, v81, v82
	v_cvt_pk_bf16_f32 v82, v88, v85
	v_cvt_pk_bf16_f32 v83, v86, v83
	global_store_dwordx4 v[104:105], v[80:83], off offset:256
	v_or_b32_e32 v88, 48, v156
	v_mad_i64_i32 v[88:89], s[6:7], v88, s64, v[146:147]
	v_lshl_add_u64 v[88:89], v[88:89], 0, v[148:149]
	v_pk_add_f32 v[78:79], v[78:79], v[202:203]
	v_pk_add_f32 v[76:77], v[76:77], v[200:201]
	v_pk_add_f32 v[74:75], v[74:75], v[206:207]
	v_pk_add_f32 v[72:73], v[72:73], v[204:205]
	v_max_f32_e32 v77, 0, v77
	v_max_f32_e32 v72, 0, v72
	v_max_f32_e32 v73, 0, v73
	v_max_f32_e32 v78, 0, v78
	v_max_f32_e32 v74, 0, v74
	v_max_f32_e32 v79, 0, v79
	v_max_f32_e32 v75, 0, v75
	v_max_f32_e32 v76, 0, v76
	v_mul_f32_e32 v80, v72, v72
	v_mul_f32_e32 v72, v77, v77
	v_mul_f32_e32 v77, v73, v73
	v_mul_f32_e32 v73, v78, v78
	v_mul_f32_e32 v78, v74, v74
	v_mul_f32_e32 v74, v79, v79
	v_mul_f32_e32 v75, v75, v75
	v_mul_f32_e32 v76, v76, v76
	v_cvt_pk_bf16_f32 v72, v76, v72
	v_cvt_pk_bf16_f32 v73, v73, v74
	v_cvt_pk_bf16_f32 v74, v80, v77
	v_cvt_pk_bf16_f32 v75, v78, v75
	global_store_dwordx4 v[88:89], v[72:75], off
	v_pk_add_f32 v[70:71], v[70:71], v[210:211]
	v_pk_add_f32 v[68:69], v[68:69], v[208:209]
	v_pk_add_f32 v[66:67], v[66:67], v[214:215]
	v_pk_add_f32 v[64:65], v[64:65], v[212:213]
	v_max_f32_e32 v69, 0, v69
	v_max_f32_e32 v64, 0, v64
	v_max_f32_e32 v65, 0, v65
	v_max_f32_e32 v70, 0, v70
	v_max_f32_e32 v66, 0, v66
	v_max_f32_e32 v71, 0, v71
	v_max_f32_e32 v67, 0, v67
	v_max_f32_e32 v68, 0, v68
	v_mul_f32_e32 v72, v64, v64
	v_mul_f32_e32 v64, v69, v69
	v_mul_f32_e32 v69, v65, v65
	v_mul_f32_e32 v65, v70, v70
	v_mul_f32_e32 v70, v66, v66
	v_mul_f32_e32 v66, v71, v71
	v_mul_f32_e32 v67, v67, v67
	v_mul_f32_e32 v68, v68, v68
	v_cvt_pk_bf16_f32 v64, v68, v64
	v_cvt_pk_bf16_f32 v65, v65, v66
	v_cvt_pk_bf16_f32 v66, v72, v69
	v_cvt_pk_bf16_f32 v67, v70, v67
	global_store_dwordx4 v[88:89], v[64:67], off offset:256
	v_add_u32_e32 v72, 0x80, v156
	v_mad_i64_i32 v[72:73], s[6:7], v72, s64, v[146:147]
	v_lshl_add_u64 v[72:73], v[72:73], 0, v[148:149]
	v_pk_add_f32 v[62:63], v[62:63], v[202:203]
	v_pk_add_f32 v[60:61], v[60:61], v[200:201]
	v_pk_add_f32 v[58:59], v[58:59], v[206:207]
	v_pk_add_f32 v[56:57], v[56:57], v[204:205]
	v_max_f32_e32 v61, 0, v61
	v_max_f32_e32 v56, 0, v56
	v_max_f32_e32 v57, 0, v57
	v_max_f32_e32 v62, 0, v62
	v_max_f32_e32 v58, 0, v58
	v_max_f32_e32 v63, 0, v63
	v_max_f32_e32 v59, 0, v59
	v_max_f32_e32 v60, 0, v60
	v_mul_f32_e32 v64, v56, v56
	v_mul_f32_e32 v56, v61, v61
	v_mul_f32_e32 v61, v57, v57
	v_mul_f32_e32 v57, v62, v62
	v_mul_f32_e32 v62, v58, v58
	v_mul_f32_e32 v58, v63, v63
	v_mul_f32_e32 v59, v59, v59
	v_mul_f32_e32 v60, v60, v60
	v_cvt_pk_bf16_f32 v56, v60, v56
	v_cvt_pk_bf16_f32 v57, v57, v58
	v_cvt_pk_bf16_f32 v58, v64, v61
	v_cvt_pk_bf16_f32 v59, v62, v59
	global_store_dwordx4 v[72:73], v[56:59], off
	v_pk_add_f32 v[54:55], v[54:55], v[210:211]
	v_pk_add_f32 v[52:53], v[52:53], v[208:209]
	v_pk_add_f32 v[50:51], v[50:51], v[214:215]
	v_pk_add_f32 v[48:49], v[48:49], v[212:213]
	v_max_f32_e32 v53, 0, v53
	v_max_f32_e32 v48, 0, v48
	v_max_f32_e32 v49, 0, v49
	v_max_f32_e32 v54, 0, v54
	v_max_f32_e32 v50, 0, v50
	v_max_f32_e32 v55, 0, v55
	v_max_f32_e32 v51, 0, v51
	v_max_f32_e32 v52, 0, v52
	v_mul_f32_e32 v56, v48, v48
	v_mul_f32_e32 v48, v53, v53
	v_mul_f32_e32 v53, v49, v49
	v_mul_f32_e32 v49, v54, v54
	v_mul_f32_e32 v54, v50, v50
	v_mul_f32_e32 v50, v55, v55
	v_mul_f32_e32 v51, v51, v51
	v_mul_f32_e32 v52, v52, v52
	v_cvt_pk_bf16_f32 v48, v52, v48
	v_cvt_pk_bf16_f32 v49, v49, v50
	v_cvt_pk_bf16_f32 v50, v56, v53
	v_cvt_pk_bf16_f32 v51, v54, v51
	global_store_dwordx4 v[72:73], v[48:51], off offset:256
	v_add_u32_e32 v56, 0x90, v156
	v_mad_i64_i32 v[56:57], s[6:7], v56, s64, v[146:147]
	v_lshl_add_u64 v[56:57], v[56:57], 0, v[148:149]
	v_pk_add_f32 v[46:47], v[46:47], v[202:203]
	v_pk_add_f32 v[44:45], v[44:45], v[200:201]
	v_pk_add_f32 v[42:43], v[42:43], v[206:207]
	v_pk_add_f32 v[40:41], v[40:41], v[204:205]
	v_max_f32_e32 v45, 0, v45
	v_max_f32_e32 v40, 0, v40
	v_max_f32_e32 v41, 0, v41
	v_max_f32_e32 v46, 0, v46
	v_max_f32_e32 v42, 0, v42
	v_max_f32_e32 v47, 0, v47
	v_max_f32_e32 v43, 0, v43
	v_max_f32_e32 v44, 0, v44
	v_mul_f32_e32 v48, v40, v40
	v_mul_f32_e32 v40, v45, v45
; __device__ __forceinline__ unsigned cvt_pk_bf16(float lo, float hi) { unsigned r; asm volatile("v_cvt_pk_bf16_f32 %0, %1, %2" : "=v"(r) : "v"(lo), "v"(hi)); return r; }
; #define PG8_BAR __builtin_amdgcn_s_barrier()
;     __device__ __forceinline__ void operator()(const f32x4 (&acc)[2][2][4][2], const Unit& u, int wr, int wc, int fr, int fq) const {
;         EPI_LOOP_BEGIN
;             const int col = u.pn * BM + cl;
;             v0 = v0 + *(const f32x4*)(bias + col); v1 = v1 + *(const f32x4*)(bias + col + 4);
; #pragma unroll
;             for (int e = 0; e < 4; ++e) { const float a = fmaxf(v0[e], 0.f), b = fmaxf(v1[e], 0.f); v0[e] = a * a; v1[e] = b * b; }
;             u32x4 w; w.x = cvt_pk_bf16(v0[0], v0[1]); w.y = cvt_pk_bf16(v0[2], v0[3]); w.z = cvt_pk_bf16(v1[0], v1[1]); w.w = cvt_pk_bf16(v1[2], v1[3]);
;             *(u32x4*)(F1 + (size_t)row * ZP + col) = w;
;         EPI_LOOP_END
; template <class Epi, class Sched>
; __device__ __forceinline__ void gemm_phase(LAS unsigned char* lds, const Gemm g, const Sched& S, const Epi& E) {
;     ...
;         if (!has_next) break;
; #pragma unroll
;         for (int a = 0; a < 2; ++a)
; #pragma unroll
;             for (int b = 0; b < 2; ++b)
; #pragma unroll
;                 for (int m = 0; m < 4; ++m)
; #pragma unroll
;                     for (int n = 0; n < 2; ++n) acc[a][b][m][n] = (f32x4){0.f, 0.f, 0.f, 0.f};
;         cur = nxt; cA = nA; cB = nB; ++ui;
;         if (wr == 1) PG8_BAR;
	v_mul_f32_e32 v45, v41, v41
	v_mul_f32_e32 v41, v46, v46
	v_mul_f32_e32 v46, v42, v42
	v_mul_f32_e32 v42, v47, v47
	v_mul_f32_e32 v43, v43, v43
	v_mul_f32_e32 v44, v44, v44
	v_cvt_pk_bf16_f32 v40, v44, v40
	v_cvt_pk_bf16_f32 v41, v41, v42
	v_cvt_pk_bf16_f32 v42, v48, v45
	v_cvt_pk_bf16_f32 v43, v46, v43
	global_store_dwordx4 v[56:57], v[40:43], off
	v_pk_add_f32 v[38:39], v[38:39], v[210:211]
	v_pk_add_f32 v[36:37], v[36:37], v[208:209]
	v_pk_add_f32 v[34:35], v[34:35], v[214:215]
	v_pk_add_f32 v[32:33], v[32:33], v[212:213]
	v_max_f32_e32 v37, 0, v37
	v_max_f32_e32 v32, 0, v32
	v_max_f32_e32 v33, 0, v33
	v_max_f32_e32 v38, 0, v38
	v_max_f32_e32 v34, 0, v34
	v_max_f32_e32 v39, 0, v39
	v_max_f32_e32 v35, 0, v35
	v_max_f32_e32 v36, 0, v36
	v_mul_f32_e32 v40, v32, v32
	v_mul_f32_e32 v32, v37, v37
	v_mul_f32_e32 v37, v33, v33
	v_mul_f32_e32 v33, v38, v38
	v_mul_f32_e32 v38, v34, v34
	v_mul_f32_e32 v34, v39, v39
	v_mul_f32_e32 v35, v35, v35
	v_mul_f32_e32 v36, v36, v36
	v_cvt_pk_bf16_f32 v32, v36, v32
	v_cvt_pk_bf16_f32 v33, v33, v34
	v_cvt_pk_bf16_f32 v34, v40, v37
	v_cvt_pk_bf16_f32 v35, v38, v35
	global_store_dwordx4 v[56:57], v[32:35], off offset:256
	v_add_u32_e32 v40, 0xa0, v156
	v_mad_i64_i32 v[40:41], s[6:7], v40, s64, v[146:147]
	v_lshl_add_u64 v[40:41], v[40:41], 0, v[148:149]
	v_pk_add_f32 v[30:31], v[30:31], v[202:203]
	v_pk_add_f32 v[28:29], v[28:29], v[200:201]
	v_pk_add_f32 v[26:27], v[26:27], v[206:207]
	v_pk_add_f32 v[24:25], v[24:25], v[204:205]
	v_max_f32_e32 v29, 0, v29
	v_max_f32_e32 v24, 0, v24
	v_max_f32_e32 v25, 0, v25
	v_max_f32_e32 v30, 0, v30
	v_max_f32_e32 v26, 0, v26
	v_max_f32_e32 v31, 0, v31
	v_max_f32_e32 v27, 0, v27
	v_max_f32_e32 v28, 0, v28
	v_mul_f32_e32 v32, v24, v24
	v_mul_f32_e32 v24, v29, v29
	v_mul_f32_e32 v29, v25, v25
	v_mul_f32_e32 v25, v30, v30
	v_mul_f32_e32 v30, v26, v26
	v_mul_f32_e32 v26, v31, v31
	v_mul_f32_e32 v27, v27, v27
	v_mul_f32_e32 v28, v28, v28
	v_cvt_pk_bf16_f32 v24, v28, v24
	v_cvt_pk_bf16_f32 v25, v25, v26
	v_cvt_pk_bf16_f32 v26, v32, v29
	v_cvt_pk_bf16_f32 v27, v30, v27
	global_store_dwordx4 v[40:41], v[24:27], off
	v_pk_add_f32 v[22:23], v[22:23], v[210:211]
	v_pk_add_f32 v[20:21], v[20:21], v[208:209]
	v_pk_add_f32 v[18:19], v[18:19], v[214:215]
	v_pk_add_f32 v[16:17], v[16:17], v[212:213]
	v_max_f32_e32 v21, 0, v21
	v_max_f32_e32 v16, 0, v16
	v_max_f32_e32 v17, 0, v17
	v_max_f32_e32 v22, 0, v22
	v_max_f32_e32 v18, 0, v18
	v_max_f32_e32 v23, 0, v23
	v_max_f32_e32 v19, 0, v19
	v_max_f32_e32 v20, 0, v20
	v_mul_f32_e32 v24, v16, v16
	v_mul_f32_e32 v16, v21, v21
	v_mul_f32_e32 v21, v17, v17
	v_mul_f32_e32 v17, v22, v22
	v_mul_f32_e32 v22, v18, v18
	v_mul_f32_e32 v18, v23, v23
	v_mul_f32_e32 v19, v19, v19
	v_mul_f32_e32 v20, v20, v20
	v_cvt_pk_bf16_f32 v16, v20, v16
	v_cvt_pk_bf16_f32 v17, v17, v18
	v_cvt_pk_bf16_f32 v18, v24, v21
	v_cvt_pk_bf16_f32 v19, v22, v19
	global_store_dwordx4 v[40:41], v[16:19], off offset:256
	v_add_u32_e32 v24, 0xb0, v156
	v_mad_i64_i32 v[24:25], s[6:7], v24, s64, v[146:147]
	v_lshl_add_u64 v[24:25], v[24:25], 0, v[148:149]
	v_pk_add_f32 v[14:15], v[14:15], v[202:203]
	v_pk_add_f32 v[12:13], v[12:13], v[200:201]
	v_pk_add_f32 v[10:11], v[10:11], v[206:207]
	v_pk_add_f32 v[8:9], v[8:9], v[204:205]
	v_max_f32_e32 v13, 0, v13
	v_max_f32_e32 v8, 0, v8
	v_max_f32_e32 v9, 0, v9
	v_max_f32_e32 v14, 0, v14
	v_max_f32_e32 v10, 0, v10
	v_max_f32_e32 v15, 0, v15
	v_max_f32_e32 v11, 0, v11
	v_max_f32_e32 v12, 0, v12
	v_mul_f32_e32 v16, v8, v8
	v_mul_f32_e32 v8, v13, v13
	v_mul_f32_e32 v13, v9, v9
	v_mul_f32_e32 v9, v14, v14
	v_mul_f32_e32 v14, v10, v10
	v_mul_f32_e32 v10, v15, v15
	v_mul_f32_e32 v11, v11, v11
	v_mul_f32_e32 v12, v12, v12
	v_cvt_pk_bf16_f32 v8, v12, v8
	v_cvt_pk_bf16_f32 v9, v9, v10
	v_cvt_pk_bf16_f32 v10, v16, v13
	v_cvt_pk_bf16_f32 v11, v14, v11
	global_store_dwordx4 v[24:25], v[8:11], off
	v_pk_add_f32 v[6:7], v[6:7], v[210:211]
	v_pk_add_f32 v[4:5], v[4:5], v[208:209]
	v_pk_add_f32 v[2:3], v[2:3], v[214:215]
	v_pk_add_f32 v[0:1], v[0:1], v[212:213]
	v_max_f32_e32 v5, 0, v5
	v_max_f32_e32 v0, 0, v0
	v_max_f32_e32 v1, 0, v1
	v_max_f32_e32 v6, 0, v6
	v_max_f32_e32 v2, 0, v2
	v_max_f32_e32 v7, 0, v7
	v_max_f32_e32 v3, 0, v3
	v_max_f32_e32 v4, 0, v4
	v_mul_f32_e32 v8, v0, v0
	v_mul_f32_e32 v0, v5, v5
	v_mul_f32_e32 v5, v1, v1
	v_mul_f32_e32 v1, v6, v6
	v_mul_f32_e32 v6, v2, v2
	v_mul_f32_e32 v2, v7, v7
	v_mul_f32_e32 v3, v3, v3
	v_mul_f32_e32 v4, v4, v4
	v_cvt_pk_bf16_f32 v0, v4, v0
	v_cvt_pk_bf16_f32 v1, v1, v2
	v_cvt_pk_bf16_f32 v2, v8, v5
	v_cvt_pk_bf16_f32 v3, v6, v3
	global_store_dwordx4 v[24:25], v[0:3], off offset:256
	s_cbranch_vccnz .LBB0_1312
	s_andn2_b64 vcc, exec, s[0:1]
	s_cbranch_vccnz .LBB0_1311
	s_barrier
	s_branch .LBB0_1311

; __device__ __forceinline__ float sigmoidf_(float x) { return __builtin_amdgcn_rcpf(1.f + __builtin_amdgcn_exp2f(-1.4426950408889634f * x)); }
; __device__ __forceinline__ float gelu_t(float x) { const float u = x * (-2.3022081986f - 0.1029432404f * x * x); return x * __builtin_amdgcn_rcpf(1.f + __builtin_amdgcn_exp2f(u)); }
;     __device__ __forceinline__ void operator()(const f32x4 (&acc)[2][2][4][2], const Unit& u, int wr, int wc, int fr, int fq) const {
;         const int pn = u.pn; const int act = (pn < 4 || pn == 8 || pn == 9) ? 1 : (pn >= 10 ? 2 : 0);
;         EPI_LOOP_BEGIN
;             const int col = pn * BM + cl; const f32x4 b0 = *(const f32x4*)(bias + col), b1 = *(const f32x4*)(bias + col + 4);
;             v0 = v0 + b0; v1 = v1 + b1;
;             if (act == 1) {
; #pragma unroll
;                 for (int e = 0; e < 4; ++e) { v0[e] = gelu_t(v0[e]); v1[e] = gelu_t(v1[e]); }
;             } else if (act == 2) {
; #pragma unroll
;                 for (int e = 0; e < 4; ++e) { v0[e] = sigmoidf_(v0[e]); v1[e] = sigmoidf_(v1[e]); }
.LBB0_1630:
	v_lshl_or_b32 v144, s34, 8, v150
	v_ashrrev_i32_e32 v145, 31, v144
	v_lshl_add_u64 v[146:147], v[144:145], 2, s[14:15]
	global_load_dwordx4 v[200:203], v[146:147], off
	global_load_dwordx4 v[204:207], v[146:147], off offset:16
	global_load_dwordx4 v[208:211], v[146:147], off offset:512
	global_load_dwordx4 v[212:215], v[146:147], off offset:528
	s_cmp_lt_i32 s34, 4
	s_cselect_b64 s[6:7], -1, 0
	s_and_b32 s21, s34, -2
	s_cmp_eq_u32 s21, 8
	s_cselect_b64 s[24:25], -1, 0
	s_or_b64 s[6:7], s[6:7], s[24:25]
	s_cmp_gt_i32 s34, 9
	s_cselect_b32 s21, 2, 0
	s_and_b64 s[6:7], s[6:7], exec
	s_cselect_b32 s21, 1, s21
	s_cmp_gt_i32 s21, 1
	s_mov_b64 s[6:7], -1
	s_waitcnt vmcnt(0)
	v_pk_add_f32 v[126:127], v[126:127], v[202:203]
	v_pk_add_f32 v[124:125], v[124:125], v[200:201]
	v_pk_add_f32 v[122:123], v[122:123], v[206:207]
	v_pk_add_f32 v[120:121], v[120:121], v[204:205]
	s_cbranch_scc0 .LBB0_1632
	v_mul_f32_e32 v160, 0xbfb8aa3b, v127
	v_mul_f32_e32 v154, 0xbfb8aa3b, v124
	v_mul_f32_e32 v155, 0xbfb8aa3b, v120
	v_mul_f32_e32 v156, 0xbfb8aa3b, v125
	v_mul_f32_e32 v157, 0xbfb8aa3b, v121
	v_mul_f32_e32 v158, 0xbfb8aa3b, v126
	v_mul_f32_e32 v159, 0xbfb8aa3b, v122
	v_exp_f32_e32 v160, v160
	v_mul_f32_e32 v161, 0xbfb8aa3b, v123
	v_exp_f32_e32 v154, v154
	v_exp_f32_e32 v155, v155
	v_exp_f32_e32 v156, v156
	v_exp_f32_e32 v157, v157
	v_exp_f32_e32 v158, v158
	v_exp_f32_e32 v159, v159
	v_exp_f32_e32 v162, v161
	v_add_f32_e32 v160, 1.0, v160
	v_add_f32_e32 v154, 1.0, v154
	v_add_f32_e32 v155, 1.0, v155
	v_add_f32_e32 v156, 1.0, v156
	v_add_f32_e32 v157, 1.0, v157
	v_add_f32_e32 v158, 1.0, v158
	v_add_f32_e32 v159, 1.0, v159
	v_rcp_f32_e32 v161, v160
	v_add_f32_e32 v160, 1.0, v162
	v_rcp_f32_e32 v154, v154
	v_rcp_f32_e32 v155, v155
	v_rcp_f32_e32 v156, v156
	v_rcp_f32_e32 v157, v157
	v_rcp_f32_e32 v158, v158
	v_rcp_f32_e32 v159, v159
	v_rcp_f32_e32 v160, v160
	s_mov_b64 s[6:7], 0

; __device__ __forceinline__ float sigmoidf_(float x) { return __builtin_amdgcn_rcpf(1.f + __builtin_amdgcn_exp2f(-1.4426950408889634f * x)); }
; __device__ __forceinline__ float gelu_t(float x) { const float u = x * (-2.3022081986f - 0.1029432404f * x * x); return x * __builtin_amdgcn_rcpf(1.f + __builtin_amdgcn_exp2f(u)); }
; __device__ __forceinline__ unsigned cvt_pk_bf16(float lo, float hi) { unsigned r; asm volatile("v_cvt_pk_bf16_f32 %0, %1, %2" : "=v"(r) : "v"(lo), "v"(hi)); return r; }
;     __device__ __forceinline__ void operator()(const f32x4 (&acc)[2][2][4][2], const Unit& u, int wr, int wc, int fr, int fq) const {
;     ...
;             const int col = pn * BM + cl; const f32x4 b0 = *(const f32x4*)(bias + col), b1 = *(const f32x4*)(bias + col + 4);
;             v0 = v0 + b0; v1 = v1 + b1;
;             if (act == 1) {
; #pragma unroll
;                 for (int e = 0; e < 4; ++e) { v0[e] = gelu_t(v0[e]); v1[e] = gelu_t(v1[e]); }
;             } else if (act == 2) {
; #pragma unroll
;                 for (int e = 0; e < 4; ++e) { v0[e] = sigmoidf_(v0[e]); v1[e] = sigmoidf_(v1[e]); }
;             }
;             u32x4 w; w.x = cvt_pk_bf16(v0[0], v0[1]); w.y = cvt_pk_bf16(v0[2], v0[3]); w.z = cvt_pk_bf16(v1[0], v1[1]); w.w = cvt_pk_bf16(v1[2], v1[3]);
;             *(u32x4*)(Z + (size_t)row * ZP + col) = w;
.LBB0_1636:
	v_lshl_add_u32 v124, s30, 8, v148
	v_mov_b64_e32 v[120:121], s[4:5]
	v_mad_i64_i32 v[120:121], s[6:7], v124, s71, v[120:121]
	v_lshl_add_u64 v[122:123], v[144:145], 1, v[120:121]
	v_or_b32_e32 v120, 0x80, v144
	v_ashrrev_i32_e32 v121, 31, v120
	v_cvt_pk_bf16_f32 v162, v154, v156
	v_cvt_pk_bf16_f32 v163, v158, v161
	v_cvt_pk_bf16_f32 v164, v155, v157
	v_cvt_pk_bf16_f32 v165, v159, v160
	global_store_dwordx4 v[122:123], v[162:165], off
	v_lshl_add_u64 v[120:121], v[120:121], 2, s[14:15]
	s_cmp_gt_i32 s21, 1
	s_mov_b64 s[6:7], -1
	v_pk_add_f32 v[118:119], v[118:119], v[210:211]
	v_pk_add_f32 v[116:117], v[116:117], v[208:209]
	v_pk_add_f32 v[114:115], v[114:115], v[214:215]
	v_pk_add_f32 v[112:113], v[112:113], v[212:213]
	s_cbranch_scc0 .LBB0_1638
	v_mul_f32_e32 v157, 0xbfb8aa3b, v119
	v_mul_f32_e32 v125, 0xbfb8aa3b, v116
	v_mul_f32_e32 v126, 0xbfb8aa3b, v112
	v_mul_f32_e32 v127, 0xbfb8aa3b, v117
	v_mul_f32_e32 v154, 0xbfb8aa3b, v113
	v_mul_f32_e32 v155, 0xbfb8aa3b, v118
	v_mul_f32_e32 v156, 0xbfb8aa3b, v114
	v_exp_f32_e32 v157, v157
	v_mul_f32_e32 v158, 0xbfb8aa3b, v115
	v_exp_f32_e32 v125, v125
	v_exp_f32_e32 v126, v126
	v_exp_f32_e32 v127, v127
	v_exp_f32_e32 v154, v154
	v_exp_f32_e32 v155, v155
	v_exp_f32_e32 v156, v156
	v_exp_f32_e32 v159, v158
	v_add_f32_e32 v157, 1.0, v157
	v_add_f32_e32 v125, 1.0, v125
	v_add_f32_e32 v126, 1.0, v126
	v_add_f32_e32 v127, 1.0, v127
	v_add_f32_e32 v154, 1.0, v154
	v_add_f32_e32 v155, 1.0, v155
	v_add_f32_e32 v156, 1.0, v156
	v_rcp_f32_e32 v158, v157
	v_add_f32_e32 v157, 1.0, v159
	v_rcp_f32_e32 v125, v125
	v_rcp_f32_e32 v126, v126
	v_rcp_f32_e32 v127, v127
	v_rcp_f32_e32 v154, v154
	v_rcp_f32_e32 v155, v155
	v_rcp_f32_e32 v156, v156
	v_rcp_f32_e32 v157, v157
	s_mov_b64 s[6:7], 0

; __device__ __forceinline__ float sigmoidf_(float x) { return __builtin_amdgcn_rcpf(1.f + __builtin_amdgcn_exp2f(-1.4426950408889634f * x)); }
; __device__ __forceinline__ float gelu_t(float x) { const float u = x * (-2.3022081986f - 0.1029432404f * x * x); return x * __builtin_amdgcn_rcpf(1.f + __builtin_amdgcn_exp2f(u)); }
; __device__ __forceinline__ unsigned cvt_pk_bf16(float lo, float hi) { unsigned r; asm volatile("v_cvt_pk_bf16_f32 %0, %1, %2" : "=v"(r) : "v"(lo), "v"(hi)); return r; }
;     __device__ __forceinline__ void operator()(const f32x4 (&acc)[2][2][4][2], const Unit& u, int wr, int wc, int fr, int fq) const {
;     ...
;             const int col = pn * BM + cl; const f32x4 b0 = *(const f32x4*)(bias + col), b1 = *(const f32x4*)(bias + col + 4);
;             v0 = v0 + b0; v1 = v1 + b1;
;             if (act == 1) {
; #pragma unroll
;                 for (int e = 0; e < 4; ++e) { v0[e] = gelu_t(v0[e]); v1[e] = gelu_t(v1[e]); }
;             } else if (act == 2) {
; #pragma unroll
;                 for (int e = 0; e < 4; ++e) { v0[e] = sigmoidf_(v0[e]); v1[e] = sigmoidf_(v1[e]); }
;             }
;             u32x4 w; w.x = cvt_pk_bf16(v0[0], v0[1]); w.y = cvt_pk_bf16(v0[2], v0[3]); w.z = cvt_pk_bf16(v1[0], v1[1]); w.w = cvt_pk_bf16(v1[2], v1[3]);
;             *(u32x4*)(Z + (size_t)row * ZP + col) = w;
.LBB0_1642:
	v_cvt_pk_bf16_f32 v112, v125, v127
	v_cvt_pk_bf16_f32 v113, v155, v158
	v_cvt_pk_bf16_f32 v114, v126, v154
	v_cvt_pk_bf16_f32 v115, v156, v157
	global_store_dwordx4 v[122:123], v[112:115], off offset:256
	s_cmp_gt_i32 s21, 1
	s_mov_b64 s[6:7], -1
	v_pk_add_f32 v[110:111], v[110:111], v[202:203]
	v_pk_add_f32 v[108:109], v[108:109], v[200:201]
	v_pk_add_f32 v[106:107], v[106:107], v[206:207]
	v_pk_add_f32 v[104:105], v[104:105], v[204:205]
	s_cbranch_scc0 .LBB0_1644
	v_mul_f32_e32 v118, 0xbfb8aa3b, v111
	v_mul_f32_e32 v112, 0xbfb8aa3b, v108
	v_mul_f32_e32 v113, 0xbfb8aa3b, v104
	v_mul_f32_e32 v114, 0xbfb8aa3b, v109
	v_mul_f32_e32 v115, 0xbfb8aa3b, v105
	v_mul_f32_e32 v116, 0xbfb8aa3b, v110
	v_mul_f32_e32 v117, 0xbfb8aa3b, v106
	v_exp_f32_e32 v118, v118
	v_mul_f32_e32 v119, 0xbfb8aa3b, v107
	v_exp_f32_e32 v112, v112
	v_exp_f32_e32 v113, v113
	v_exp_f32_e32 v114, v114
	v_exp_f32_e32 v115, v115
	v_exp_f32_e32 v116, v116
	v_exp_f32_e32 v117, v117
	v_exp_f32_e32 v122, v119
	v_add_f32_e32 v118, 1.0, v118
	v_add_f32_e32 v112, 1.0, v112
	v_add_f32_e32 v113, 1.0, v113
	v_add_f32_e32 v114, 1.0, v114
	v_add_f32_e32 v115, 1.0, v115
	v_add_f32_e32 v116, 1.0, v116
	v_add_f32_e32 v117, 1.0, v117
	v_rcp_f32_e32 v119, v118
	v_add_f32_e32 v118, 1.0, v122
	v_rcp_f32_e32 v112, v112
	v_rcp_f32_e32 v113, v113
	v_rcp_f32_e32 v114, v114
	v_rcp_f32_e32 v115, v115
	v_rcp_f32_e32 v116, v116
	v_rcp_f32_e32 v117, v117
	v_rcp_f32_e32 v118, v118
	s_mov_b64 s[6:7], 0

; __device__ __forceinline__ float sigmoidf_(float x) { return __builtin_amdgcn_rcpf(1.f + __builtin_amdgcn_exp2f(-1.4426950408889634f * x)); }
; __device__ __forceinline__ float gelu_t(float x) { const float u = x * (-2.3022081986f - 0.1029432404f * x * x); return x * __builtin_amdgcn_rcpf(1.f + __builtin_amdgcn_exp2f(u)); }
; __device__ __forceinline__ unsigned cvt_pk_bf16(float lo, float hi) { unsigned r; asm volatile("v_cvt_pk_bf16_f32 %0, %1, %2" : "=v"(r) : "v"(lo), "v"(hi)); return r; }
;     __device__ __forceinline__ void operator()(const f32x4 (&acc)[2][2][4][2], const Unit& u, int wr, int wc, int fr, int fq) const {
;     ...
;             const int col = pn * BM + cl; const f32x4 b0 = *(const f32x4*)(bias + col), b1 = *(const f32x4*)(bias + col + 4);
;             v0 = v0 + b0; v1 = v1 + b1;
;             if (act == 1) {
; #pragma unroll
;                 for (int e = 0; e < 4; ++e) { v0[e] = gelu_t(v0[e]); v1[e] = gelu_t(v1[e]); }
;             } else if (act == 2) {
; #pragma unroll
;                 for (int e = 0; e < 4; ++e) { v0[e] = sigmoidf_(v0[e]); v1[e] = sigmoidf_(v1[e]); }
;             }
;             u32x4 w; w.x = cvt_pk_bf16(v0[0], v0[1]); w.y = cvt_pk_bf16(v0[2], v0[3]); w.z = cvt_pk_bf16(v1[0], v1[1]); w.w = cvt_pk_bf16(v1[2], v1[3]);
;             *(u32x4*)(Z + (size_t)row * ZP + col) = w;
.LBB0_1648:
	v_or_b32_e32 v110, 16, v124
	v_mov_b64_e32 v[104:105], s[4:5]
	v_mad_i64_i32 v[104:105], s[6:7], v110, s71, v[104:105]
	v_lshl_add_u64 v[104:105], v[144:145], 1, v[104:105]
	v_cvt_pk_bf16_f32 v106, v112, v114
	v_cvt_pk_bf16_f32 v107, v116, v119
	v_cvt_pk_bf16_f32 v108, v113, v115
	v_cvt_pk_bf16_f32 v109, v117, v118
	global_store_dwordx4 v[104:105], v[106:109], off
	s_cmp_gt_i32 s21, 1
	s_mov_b64 s[6:7], -1
	v_pk_add_f32 v[102:103], v[102:103], v[210:211]
	v_pk_add_f32 v[100:101], v[100:101], v[208:209]
	v_pk_add_f32 v[98:99], v[98:99], v[214:215]
	v_pk_add_f32 v[96:97], v[96:97], v[212:213]
	s_cbranch_scc0 .LBB0_1650
	v_mul_f32_e32 v112, 0xbfb8aa3b, v103
	v_mul_f32_e32 v106, 0xbfb8aa3b, v100
	v_mul_f32_e32 v107, 0xbfb8aa3b, v96
	v_mul_f32_e32 v108, 0xbfb8aa3b, v101
	v_mul_f32_e32 v109, 0xbfb8aa3b, v97
	v_mul_f32_e32 v110, 0xbfb8aa3b, v102
	v_mul_f32_e32 v111, 0xbfb8aa3b, v98
	v_exp_f32_e32 v112, v112
	v_mul_f32_e32 v113, 0xbfb8aa3b, v99
	v_exp_f32_e32 v106, v106
	v_exp_f32_e32 v107, v107
	v_exp_f32_e32 v108, v108
	v_exp_f32_e32 v109, v109
	v_exp_f32_e32 v110, v110
	v_exp_f32_e32 v111, v111
	v_exp_f32_e32 v114, v113
	v_add_f32_e32 v112, 1.0, v112
	v_add_f32_e32 v106, 1.0, v106
	v_add_f32_e32 v107, 1.0, v107
	v_add_f32_e32 v108, 1.0, v108
	v_add_f32_e32 v109, 1.0, v109
	v_add_f32_e32 v110, 1.0, v110
	v_add_f32_e32 v111, 1.0, v111
	v_rcp_f32_e32 v113, v112
	v_add_f32_e32 v112, 1.0, v114
	v_rcp_f32_e32 v106, v106
	v_rcp_f32_e32 v107, v107
	v_rcp_f32_e32 v108, v108
	v_rcp_f32_e32 v109, v109
	v_rcp_f32_e32 v110, v110
	v_rcp_f32_e32 v111, v111
	v_rcp_f32_e32 v112, v112
	s_mov_b64 s[6:7], 0

; __device__ __forceinline__ float sigmoidf_(float x) { return __builtin_amdgcn_rcpf(1.f + __builtin_amdgcn_exp2f(-1.4426950408889634f * x)); }
; __device__ __forceinline__ float gelu_t(float x) { const float u = x * (-2.3022081986f - 0.1029432404f * x * x); return x * __builtin_amdgcn_rcpf(1.f + __builtin_amdgcn_exp2f(u)); }
; __device__ __forceinline__ unsigned cvt_pk_bf16(float lo, float hi) { unsigned r; asm volatile("v_cvt_pk_bf16_f32 %0, %1, %2" : "=v"(r) : "v"(lo), "v"(hi)); return r; }
;     __device__ __forceinline__ void operator()(const f32x4 (&acc)[2][2][4][2], const Unit& u, int wr, int wc, int fr, int fq) const {
;     ...
;             const int col = pn * BM + cl; const f32x4 b0 = *(const f32x4*)(bias + col), b1 = *(const f32x4*)(bias + col + 4);
;             v0 = v0 + b0; v1 = v1 + b1;
;             if (act == 1) {
; #pragma unroll
;                 for (int e = 0; e < 4; ++e) { v0[e] = gelu_t(v0[e]); v1[e] = gelu_t(v1[e]); }
;             } else if (act == 2) {
; #pragma unroll
;                 for (int e = 0; e < 4; ++e) { v0[e] = sigmoidf_(v0[e]); v1[e] = sigmoidf_(v1[e]); }
;             }
;             u32x4 w; w.x = cvt_pk_bf16(v0[0], v0[1]); w.y = cvt_pk_bf16(v0[2], v0[3]); w.z = cvt_pk_bf16(v1[0], v1[1]); w.w = cvt_pk_bf16(v1[2], v1[3]);
;             *(u32x4*)(Z + (size_t)row * ZP + col) = w;
.LBB0_1654:
	v_cvt_pk_bf16_f32 v96, v106, v108
	v_cvt_pk_bf16_f32 v97, v110, v113
	v_cvt_pk_bf16_f32 v98, v107, v109
	v_cvt_pk_bf16_f32 v99, v111, v112
	global_store_dwordx4 v[104:105], v[96:99], off offset:256
	s_cmp_gt_i32 s21, 1
	s_mov_b64 s[6:7], -1
	v_pk_add_f32 v[94:95], v[94:95], v[202:203]
	v_pk_add_f32 v[92:93], v[92:93], v[200:201]
	v_pk_add_f32 v[90:91], v[90:91], v[206:207]
	v_pk_add_f32 v[88:89], v[88:89], v[204:205]
	s_cbranch_scc0 .LBB0_1656
	v_mul_f32_e32 v102, 0xbfb8aa3b, v95
	v_mul_f32_e32 v96, 0xbfb8aa3b, v92
	v_mul_f32_e32 v97, 0xbfb8aa3b, v88
	v_mul_f32_e32 v98, 0xbfb8aa3b, v93
	v_mul_f32_e32 v99, 0xbfb8aa3b, v89
	v_mul_f32_e32 v100, 0xbfb8aa3b, v94
	v_mul_f32_e32 v101, 0xbfb8aa3b, v90
	v_exp_f32_e32 v102, v102
	v_mul_f32_e32 v103, 0xbfb8aa3b, v91
	v_exp_f32_e32 v96, v96
	v_exp_f32_e32 v97, v97
	v_exp_f32_e32 v98, v98
	v_exp_f32_e32 v99, v99
	v_exp_f32_e32 v100, v100
	v_exp_f32_e32 v101, v101
	v_exp_f32_e32 v104, v103
	v_add_f32_e32 v102, 1.0, v102
	v_add_f32_e32 v96, 1.0, v96
	v_add_f32_e32 v97, 1.0, v97
	v_add_f32_e32 v98, 1.0, v98
	v_add_f32_e32 v99, 1.0, v99
	v_add_f32_e32 v100, 1.0, v100
	v_add_f32_e32 v101, 1.0, v101
	v_rcp_f32_e32 v103, v102
	v_add_f32_e32 v102, 1.0, v104
	v_rcp_f32_e32 v96, v96
	v_rcp_f32_e32 v97, v97
	v_rcp_f32_e32 v98, v98
	v_rcp_f32_e32 v99, v99
	v_rcp_f32_e32 v100, v100
	v_rcp_f32_e32 v101, v101
	v_rcp_f32_e32 v102, v102
	s_mov_b64 s[6:7], 0

; __device__ __forceinline__ float sigmoidf_(float x) { return __builtin_amdgcn_rcpf(1.f + __builtin_amdgcn_exp2f(-1.4426950408889634f * x)); }
; __device__ __forceinline__ float gelu_t(float x) { const float u = x * (-2.3022081986f - 0.1029432404f * x * x); return x * __builtin_amdgcn_rcpf(1.f + __builtin_amdgcn_exp2f(u)); }
; __device__ __forceinline__ unsigned cvt_pk_bf16(float lo, float hi) { unsigned r; asm volatile("v_cvt_pk_bf16_f32 %0, %1, %2" : "=v"(r) : "v"(lo), "v"(hi)); return r; }
;     __device__ __forceinline__ void operator()(const f32x4 (&acc)[2][2][4][2], const Unit& u, int wr, int wc, int fr, int fq) const {
;     ...
;             const int col = pn * BM + cl; const f32x4 b0 = *(const f32x4*)(bias + col), b1 = *(const f32x4*)(bias + col + 4);
;             v0 = v0 + b0; v1 = v1 + b1;
;             if (act == 1) {
; #pragma unroll
;                 for (int e = 0; e < 4; ++e) { v0[e] = gelu_t(v0[e]); v1[e] = gelu_t(v1[e]); }
;             } else if (act == 2) {
; #pragma unroll
;                 for (int e = 0; e < 4; ++e) { v0[e] = sigmoidf_(v0[e]); v1[e] = sigmoidf_(v1[e]); }
;             }
;             u32x4 w; w.x = cvt_pk_bf16(v0[0], v0[1]); w.y = cvt_pk_bf16(v0[2], v0[3]); w.z = cvt_pk_bf16(v1[0], v1[1]); w.w = cvt_pk_bf16(v1[2], v1[3]);
;             *(u32x4*)(Z + (size_t)row * ZP + col) = w;
.LBB0_1660:
	v_or_b32_e32 v94, 32, v124
	v_mov_b64_e32 v[88:89], s[4:5]
	v_mad_i64_i32 v[88:89], s[6:7], v94, s71, v[88:89]
	v_lshl_add_u64 v[88:89], v[144:145], 1, v[88:89]
	v_cvt_pk_bf16_f32 v90, v96, v98
	v_cvt_pk_bf16_f32 v91, v100, v103
	v_cvt_pk_bf16_f32 v92, v97, v99
	v_cvt_pk_bf16_f32 v93, v101, v102
	global_store_dwordx4 v[88:89], v[90:93], off
	s_cmp_gt_i32 s21, 1
	s_mov_b64 s[6:7], -1
	v_pk_add_f32 v[86:87], v[86:87], v[210:211]
	v_pk_add_f32 v[84:85], v[84:85], v[208:209]
	v_pk_add_f32 v[82:83], v[82:83], v[214:215]
	v_pk_add_f32 v[80:81], v[80:81], v[212:213]
	s_cbranch_scc0 .LBB0_1662
	v_mul_f32_e32 v96, 0xbfb8aa3b, v87
	v_mul_f32_e32 v90, 0xbfb8aa3b, v84
	v_mul_f32_e32 v91, 0xbfb8aa3b, v80
	v_mul_f32_e32 v92, 0xbfb8aa3b, v85
	v_mul_f32_e32 v93, 0xbfb8aa3b, v81
	v_mul_f32_e32 v94, 0xbfb8aa3b, v86
	v_mul_f32_e32 v95, 0xbfb8aa3b, v82
	v_exp_f32_e32 v96, v96
	v_mul_f32_e32 v97, 0xbfb8aa3b, v83
	v_exp_f32_e32 v90, v90
	v_exp_f32_e32 v91, v91
	v_exp_f32_e32 v92, v92
	v_exp_f32_e32 v93, v93
	v_exp_f32_e32 v94, v94
	v_exp_f32_e32 v95, v95
	v_exp_f32_e32 v98, v97
	v_add_f32_e32 v96, 1.0, v96
	v_add_f32_e32 v90, 1.0, v90
	v_add_f32_e32 v91, 1.0, v91
	v_add_f32_e32 v92, 1.0, v92
	v_add_f32_e32 v93, 1.0, v93
	v_add_f32_e32 v94, 1.0, v94
	v_add_f32_e32 v95, 1.0, v95
	v_rcp_f32_e32 v97, v96
	v_add_f32_e32 v96, 1.0, v98
	v_rcp_f32_e32 v90, v90
	v_rcp_f32_e32 v91, v91
	v_rcp_f32_e32 v92, v92
	v_rcp_f32_e32 v93, v93
	v_rcp_f32_e32 v94, v94
	v_rcp_f32_e32 v95, v95
	v_rcp_f32_e32 v96, v96
	s_mov_b64 s[6:7], 0

; __device__ __forceinline__ float sigmoidf_(float x) { return __builtin_amdgcn_rcpf(1.f + __builtin_amdgcn_exp2f(-1.4426950408889634f * x)); }
; __device__ __forceinline__ float gelu_t(float x) { const float u = x * (-2.3022081986f - 0.1029432404f * x * x); return x * __builtin_amdgcn_rcpf(1.f + __builtin_amdgcn_exp2f(u)); }
; __device__ __forceinline__ unsigned cvt_pk_bf16(float lo, float hi) { unsigned r; asm volatile("v_cvt_pk_bf16_f32 %0, %1, %2" : "=v"(r) : "v"(lo), "v"(hi)); return r; }
;     __device__ __forceinline__ void operator()(const f32x4 (&acc)[2][2][4][2], const Unit& u, int wr, int wc, int fr, int fq) const {
;     ...
;             const int col = pn * BM + cl; const f32x4 b0 = *(const f32x4*)(bias + col), b1 = *(const f32x4*)(bias + col + 4);
;             v0 = v0 + b0; v1 = v1 + b1;
;             if (act == 1) {
; #pragma unroll
;                 for (int e = 0; e < 4; ++e) { v0[e] = gelu_t(v0[e]); v1[e] = gelu_t(v1[e]); }
;             } else if (act == 2) {
; #pragma unroll
;                 for (int e = 0; e < 4; ++e) { v0[e] = sigmoidf_(v0[e]); v1[e] = sigmoidf_(v1[e]); }
;             }
;             u32x4 w; w.x = cvt_pk_bf16(v0[0], v0[1]); w.y = cvt_pk_bf16(v0[2], v0[3]); w.z = cvt_pk_bf16(v1[0], v1[1]); w.w = cvt_pk_bf16(v1[2], v1[3]);
;             *(u32x4*)(Z + (size_t)row * ZP + col) = w;
.LBB0_1666:
	v_cvt_pk_bf16_f32 v80, v90, v92
	v_cvt_pk_bf16_f32 v81, v94, v97
	v_cvt_pk_bf16_f32 v82, v91, v93
	v_cvt_pk_bf16_f32 v83, v95, v96
	global_store_dwordx4 v[88:89], v[80:83], off offset:256
	s_cmp_gt_i32 s21, 1
	s_mov_b64 s[6:7], -1
	v_pk_add_f32 v[78:79], v[78:79], v[202:203]
	v_pk_add_f32 v[76:77], v[76:77], v[200:201]
	v_pk_add_f32 v[74:75], v[74:75], v[206:207]
	v_pk_add_f32 v[72:73], v[72:73], v[204:205]
	s_cbranch_scc0 .LBB0_1668
	v_mul_f32_e32 v86, 0xbfb8aa3b, v79
	v_mul_f32_e32 v80, 0xbfb8aa3b, v76
	v_mul_f32_e32 v81, 0xbfb8aa3b, v72
	v_mul_f32_e32 v82, 0xbfb8aa3b, v77
	v_mul_f32_e32 v83, 0xbfb8aa3b, v73
	v_mul_f32_e32 v84, 0xbfb8aa3b, v78
	v_mul_f32_e32 v85, 0xbfb8aa3b, v74
	v_exp_f32_e32 v86, v86
	v_mul_f32_e32 v87, 0xbfb8aa3b, v75
	v_exp_f32_e32 v80, v80
	v_exp_f32_e32 v81, v81
	v_exp_f32_e32 v82, v82
	v_exp_f32_e32 v83, v83
	v_exp_f32_e32 v84, v84
	v_exp_f32_e32 v85, v85
	v_exp_f32_e32 v88, v87
	v_add_f32_e32 v86, 1.0, v86
	v_add_f32_e32 v80, 1.0, v80
	v_add_f32_e32 v81, 1.0, v81
	v_add_f32_e32 v82, 1.0, v82
	v_add_f32_e32 v83, 1.0, v83
	v_add_f32_e32 v84, 1.0, v84
	v_add_f32_e32 v85, 1.0, v85
	v_rcp_f32_e32 v87, v86
	v_add_f32_e32 v86, 1.0, v88
	v_rcp_f32_e32 v80, v80
	v_rcp_f32_e32 v81, v81
	v_rcp_f32_e32 v82, v82
	v_rcp_f32_e32 v83, v83
	v_rcp_f32_e32 v84, v84
	v_rcp_f32_e32 v85, v85
	v_rcp_f32_e32 v86, v86
	s_mov_b64 s[6:7], 0

; __device__ __forceinline__ float sigmoidf_(float x) { return __builtin_amdgcn_rcpf(1.f + __builtin_amdgcn_exp2f(-1.4426950408889634f * x)); }
; __device__ __forceinline__ float gelu_t(float x) { const float u = x * (-2.3022081986f - 0.1029432404f * x * x); return x * __builtin_amdgcn_rcpf(1.f + __builtin_amdgcn_exp2f(u)); }
; __device__ __forceinline__ unsigned cvt_pk_bf16(float lo, float hi) { unsigned r; asm volatile("v_cvt_pk_bf16_f32 %0, %1, %2" : "=v"(r) : "v"(lo), "v"(hi)); return r; }
;     __device__ __forceinline__ void operator()(const f32x4 (&acc)[2][2][4][2], const Unit& u, int wr, int wc, int fr, int fq) const {
;     ...
;             const int col = pn * BM + cl; const f32x4 b0 = *(const f32x4*)(bias + col), b1 = *(const f32x4*)(bias + col + 4);
;             v0 = v0 + b0; v1 = v1 + b1;
;             if (act == 1) {
; #pragma unroll
;                 for (int e = 0; e < 4; ++e) { v0[e] = gelu_t(v0[e]); v1[e] = gelu_t(v1[e]); }
;             } else if (act == 2) {
; #pragma unroll
;                 for (int e = 0; e < 4; ++e) { v0[e] = sigmoidf_(v0[e]); v1[e] = sigmoidf_(v1[e]); }
;             }
;             u32x4 w; w.x = cvt_pk_bf16(v0[0], v0[1]); w.y = cvt_pk_bf16(v0[2], v0[3]); w.z = cvt_pk_bf16(v1[0], v1[1]); w.w = cvt_pk_bf16(v1[2], v1[3]);
;             *(u32x4*)(Z + (size_t)row * ZP + col) = w;
.LBB0_1672:
	v_or_b32_e32 v78, 48, v124
	v_mov_b64_e32 v[72:73], s[4:5]
	v_mad_i64_i32 v[72:73], s[6:7], v78, s71, v[72:73]
	v_lshl_add_u64 v[72:73], v[144:145], 1, v[72:73]
	v_cvt_pk_bf16_f32 v74, v80, v82
	v_cvt_pk_bf16_f32 v75, v84, v87
	v_cvt_pk_bf16_f32 v76, v81, v83
	v_cvt_pk_bf16_f32 v77, v85, v86
	global_store_dwordx4 v[72:73], v[74:77], off
	s_cmp_gt_i32 s21, 1
	s_mov_b64 s[6:7], -1
	v_pk_add_f32 v[70:71], v[70:71], v[210:211]
	v_pk_add_f32 v[68:69], v[68:69], v[208:209]
	v_pk_add_f32 v[66:67], v[66:67], v[214:215]
	v_pk_add_f32 v[64:65], v[64:65], v[212:213]
	s_cbranch_scc0 .LBB0_1674
	v_mul_f32_e32 v80, 0xbfb8aa3b, v71
	v_mul_f32_e32 v74, 0xbfb8aa3b, v68
	v_mul_f32_e32 v75, 0xbfb8aa3b, v64
	v_mul_f32_e32 v76, 0xbfb8aa3b, v69
	v_mul_f32_e32 v77, 0xbfb8aa3b, v65
	v_mul_f32_e32 v78, 0xbfb8aa3b, v70
	v_mul_f32_e32 v79, 0xbfb8aa3b, v66
	v_exp_f32_e32 v80, v80
	v_mul_f32_e32 v81, 0xbfb8aa3b, v67
	v_exp_f32_e32 v74, v74
	v_exp_f32_e32 v75, v75
	v_exp_f32_e32 v76, v76
	v_exp_f32_e32 v77, v77
	v_exp_f32_e32 v78, v78
	v_exp_f32_e32 v79, v79
	v_exp_f32_e32 v82, v81
	v_add_f32_e32 v80, 1.0, v80
	v_add_f32_e32 v74, 1.0, v74
	v_add_f32_e32 v75, 1.0, v75
	v_add_f32_e32 v76, 1.0, v76
	v_add_f32_e32 v77, 1.0, v77
	v_add_f32_e32 v78, 1.0, v78
	v_add_f32_e32 v79, 1.0, v79
	v_rcp_f32_e32 v81, v80
	v_add_f32_e32 v80, 1.0, v82
	v_rcp_f32_e32 v74, v74
	v_rcp_f32_e32 v75, v75
	v_rcp_f32_e32 v76, v76
	v_rcp_f32_e32 v77, v77
	v_rcp_f32_e32 v78, v78
	v_rcp_f32_e32 v79, v79
	v_rcp_f32_e32 v80, v80
	s_mov_b64 s[6:7], 0

; __device__ __forceinline__ float sigmoidf_(float x) { return __builtin_amdgcn_rcpf(1.f + __builtin_amdgcn_exp2f(-1.4426950408889634f * x)); }
; __device__ __forceinline__ float gelu_t(float x) { const float u = x * (-2.3022081986f - 0.1029432404f * x * x); return x * __builtin_amdgcn_rcpf(1.f + __builtin_amdgcn_exp2f(u)); }
; __device__ __forceinline__ unsigned cvt_pk_bf16(float lo, float hi) { unsigned r; asm volatile("v_cvt_pk_bf16_f32 %0, %1, %2" : "=v"(r) : "v"(lo), "v"(hi)); return r; }
;     __device__ __forceinline__ void operator()(const f32x4 (&acc)[2][2][4][2], const Unit& u, int wr, int wc, int fr, int fq) const {
;     ...
;             const int col = pn * BM + cl; const f32x4 b0 = *(const f32x4*)(bias + col), b1 = *(const f32x4*)(bias + col + 4);
;             v0 = v0 + b0; v1 = v1 + b1;
;             if (act == 1) {
; #pragma unroll
;                 for (int e = 0; e < 4; ++e) { v0[e] = gelu_t(v0[e]); v1[e] = gelu_t(v1[e]); }
;             } else if (act == 2) {
; #pragma unroll
;                 for (int e = 0; e < 4; ++e) { v0[e] = sigmoidf_(v0[e]); v1[e] = sigmoidf_(v1[e]); }
;             }
;             u32x4 w; w.x = cvt_pk_bf16(v0[0], v0[1]); w.y = cvt_pk_bf16(v0[2], v0[3]); w.z = cvt_pk_bf16(v1[0], v1[1]); w.w = cvt_pk_bf16(v1[2], v1[3]);
;             *(u32x4*)(Z + (size_t)row * ZP + col) = w;
.LBB0_1678:
	v_cvt_pk_bf16_f32 v64, v74, v76
	v_cvt_pk_bf16_f32 v65, v78, v81
	v_cvt_pk_bf16_f32 v66, v75, v77
	v_cvt_pk_bf16_f32 v67, v79, v80
	global_store_dwordx4 v[72:73], v[64:67], off offset:256
	s_cmp_gt_i32 s21, 1
	s_mov_b64 s[6:7], -1
	v_pk_add_f32 v[62:63], v[62:63], v[202:203]
	v_pk_add_f32 v[60:61], v[60:61], v[200:201]
	v_pk_add_f32 v[58:59], v[58:59], v[206:207]
	v_pk_add_f32 v[56:57], v[56:57], v[204:205]
	s_cbranch_scc0 .LBB0_1680
	v_mul_f32_e32 v70, 0xbfb8aa3b, v63
	v_mul_f32_e32 v64, 0xbfb8aa3b, v60
	v_mul_f32_e32 v65, 0xbfb8aa3b, v56
	v_mul_f32_e32 v66, 0xbfb8aa3b, v61
	v_mul_f32_e32 v67, 0xbfb8aa3b, v57
	v_mul_f32_e32 v68, 0xbfb8aa3b, v62
	v_mul_f32_e32 v69, 0xbfb8aa3b, v58
	v_exp_f32_e32 v70, v70
	v_mul_f32_e32 v71, 0xbfb8aa3b, v59
	v_exp_f32_e32 v64, v64
	v_exp_f32_e32 v65, v65
	v_exp_f32_e32 v66, v66
	v_exp_f32_e32 v67, v67
	v_exp_f32_e32 v68, v68
	v_exp_f32_e32 v69, v69
	v_exp_f32_e32 v72, v71
	v_add_f32_e32 v70, 1.0, v70
	v_add_f32_e32 v64, 1.0, v64
	v_add_f32_e32 v65, 1.0, v65
	v_add_f32_e32 v66, 1.0, v66
	v_add_f32_e32 v67, 1.0, v67
	v_add_f32_e32 v68, 1.0, v68
	v_add_f32_e32 v69, 1.0, v69
	v_rcp_f32_e32 v71, v70
	v_add_f32_e32 v70, 1.0, v72
	v_rcp_f32_e32 v64, v64
	v_rcp_f32_e32 v65, v65
	v_rcp_f32_e32 v66, v66
	v_rcp_f32_e32 v67, v67
	v_rcp_f32_e32 v68, v68
	v_rcp_f32_e32 v69, v69
	v_rcp_f32_e32 v70, v70
	s_mov_b64 s[6:7], 0

; __device__ __forceinline__ float sigmoidf_(float x) { return __builtin_amdgcn_rcpf(1.f + __builtin_amdgcn_exp2f(-1.4426950408889634f * x)); }
; __device__ __forceinline__ float gelu_t(float x) { const float u = x * (-2.3022081986f - 0.1029432404f * x * x); return x * __builtin_amdgcn_rcpf(1.f + __builtin_amdgcn_exp2f(u)); }
; __device__ __forceinline__ unsigned cvt_pk_bf16(float lo, float hi) { unsigned r; asm volatile("v_cvt_pk_bf16_f32 %0, %1, %2" : "=v"(r) : "v"(lo), "v"(hi)); return r; }
;     __device__ __forceinline__ void operator()(const f32x4 (&acc)[2][2][4][2], const Unit& u, int wr, int wc, int fr, int fq) const {
;     ...
;             const int col = pn * BM + cl; const f32x4 b0 = *(const f32x4*)(bias + col), b1 = *(const f32x4*)(bias + col + 4);
;             v0 = v0 + b0; v1 = v1 + b1;
;             if (act == 1) {
; #pragma unroll
;                 for (int e = 0; e < 4; ++e) { v0[e] = gelu_t(v0[e]); v1[e] = gelu_t(v1[e]); }
;             } else if (act == 2) {
; #pragma unroll
;                 for (int e = 0; e < 4; ++e) { v0[e] = sigmoidf_(v0[e]); v1[e] = sigmoidf_(v1[e]); }
;             }
;             u32x4 w; w.x = cvt_pk_bf16(v0[0], v0[1]); w.y = cvt_pk_bf16(v0[2], v0[3]); w.z = cvt_pk_bf16(v1[0], v1[1]); w.w = cvt_pk_bf16(v1[2], v1[3]);
;             *(u32x4*)(Z + (size_t)row * ZP + col) = w;
.LBB0_1684:
	v_add_u32_e32 v62, 0x80, v124
	v_mov_b64_e32 v[56:57], s[4:5]
	v_mad_i64_i32 v[56:57], s[6:7], v62, s71, v[56:57]
	v_lshl_add_u64 v[56:57], v[144:145], 1, v[56:57]
	v_cvt_pk_bf16_f32 v58, v64, v66
	v_cvt_pk_bf16_f32 v59, v68, v71
	v_cvt_pk_bf16_f32 v60, v65, v67
	v_cvt_pk_bf16_f32 v61, v69, v70
	global_store_dwordx4 v[56:57], v[58:61], off
	s_cmp_gt_i32 s21, 1
	s_mov_b64 s[6:7], -1
	v_pk_add_f32 v[54:55], v[54:55], v[210:211]
	v_pk_add_f32 v[52:53], v[52:53], v[208:209]
	v_pk_add_f32 v[50:51], v[50:51], v[214:215]
	v_pk_add_f32 v[48:49], v[48:49], v[212:213]
	s_cbranch_scc0 .LBB0_1686
	v_mul_f32_e32 v64, 0xbfb8aa3b, v55
	v_mul_f32_e32 v58, 0xbfb8aa3b, v52
	v_mul_f32_e32 v59, 0xbfb8aa3b, v48
	v_mul_f32_e32 v60, 0xbfb8aa3b, v53
	v_mul_f32_e32 v61, 0xbfb8aa3b, v49
	v_mul_f32_e32 v62, 0xbfb8aa3b, v54
	v_mul_f32_e32 v63, 0xbfb8aa3b, v50
	v_exp_f32_e32 v64, v64
	v_mul_f32_e32 v65, 0xbfb8aa3b, v51
	v_exp_f32_e32 v58, v58
	v_exp_f32_e32 v59, v59
	v_exp_f32_e32 v60, v60
	v_exp_f32_e32 v61, v61
	v_exp_f32_e32 v62, v62
	v_exp_f32_e32 v63, v63
	v_exp_f32_e32 v66, v65
	v_add_f32_e32 v64, 1.0, v64
	v_add_f32_e32 v58, 1.0, v58
	v_add_f32_e32 v59, 1.0, v59
	v_add_f32_e32 v60, 1.0, v60
	v_add_f32_e32 v61, 1.0, v61
	v_add_f32_e32 v62, 1.0, v62
	v_add_f32_e32 v63, 1.0, v63
	v_rcp_f32_e32 v65, v64
	v_add_f32_e32 v64, 1.0, v66
	v_rcp_f32_e32 v58, v58
	v_rcp_f32_e32 v59, v59
	v_rcp_f32_e32 v60, v60
	v_rcp_f32_e32 v61, v61
	v_rcp_f32_e32 v62, v62
	v_rcp_f32_e32 v63, v63
	v_rcp_f32_e32 v64, v64
	s_mov_b64 s[6:7], 0

; __device__ __forceinline__ float sigmoidf_(float x) { return __builtin_amdgcn_rcpf(1.f + __builtin_amdgcn_exp2f(-1.4426950408889634f * x)); }
; __device__ __forceinline__ float gelu_t(float x) { const float u = x * (-2.3022081986f - 0.1029432404f * x * x); return x * __builtin_amdgcn_rcpf(1.f + __builtin_amdgcn_exp2f(u)); }
; __device__ __forceinline__ unsigned cvt_pk_bf16(float lo, float hi) { unsigned r; asm volatile("v_cvt_pk_bf16_f32 %0, %1, %2" : "=v"(r) : "v"(lo), "v"(hi)); return r; }
;     __device__ __forceinline__ void operator()(const f32x4 (&acc)[2][2][4][2], const Unit& u, int wr, int wc, int fr, int fq) const {
;     ...
;             const int col = pn * BM + cl; const f32x4 b0 = *(const f32x4*)(bias + col), b1 = *(const f32x4*)(bias + col + 4);
;             v0 = v0 + b0; v1 = v1 + b1;
;             if (act == 1) {
; #pragma unroll
;                 for (int e = 0; e < 4; ++e) { v0[e] = gelu_t(v0[e]); v1[e] = gelu_t(v1[e]); }
;             } else if (act == 2) {
; #pragma unroll
;                 for (int e = 0; e < 4; ++e) { v0[e] = sigmoidf_(v0[e]); v1[e] = sigmoidf_(v1[e]); }
;             }
;             u32x4 w; w.x = cvt_pk_bf16(v0[0], v0[1]); w.y = cvt_pk_bf16(v0[2], v0[3]); w.z = cvt_pk_bf16(v1[0], v1[1]); w.w = cvt_pk_bf16(v1[2], v1[3]);
;             *(u32x4*)(Z + (size_t)row * ZP + col) = w;
.LBB0_1690:
	v_cvt_pk_bf16_f32 v48, v58, v60
	v_cvt_pk_bf16_f32 v49, v62, v65
	v_cvt_pk_bf16_f32 v50, v59, v61
	v_cvt_pk_bf16_f32 v51, v63, v64
	global_store_dwordx4 v[56:57], v[48:51], off offset:256
	s_cmp_gt_i32 s21, 1
	s_mov_b64 s[6:7], -1
	v_pk_add_f32 v[46:47], v[46:47], v[202:203]
	v_pk_add_f32 v[44:45], v[44:45], v[200:201]
	v_pk_add_f32 v[42:43], v[42:43], v[206:207]
	v_pk_add_f32 v[40:41], v[40:41], v[204:205]
	s_cbranch_scc0 .LBB0_1692
	v_mul_f32_e32 v54, 0xbfb8aa3b, v47
	v_mul_f32_e32 v48, 0xbfb8aa3b, v44
	v_mul_f32_e32 v49, 0xbfb8aa3b, v40
	v_mul_f32_e32 v50, 0xbfb8aa3b, v45
	v_mul_f32_e32 v51, 0xbfb8aa3b, v41
	v_mul_f32_e32 v52, 0xbfb8aa3b, v46
	v_mul_f32_e32 v53, 0xbfb8aa3b, v42
	v_exp_f32_e32 v54, v54
	v_mul_f32_e32 v55, 0xbfb8aa3b, v43
	v_exp_f32_e32 v48, v48
	v_exp_f32_e32 v49, v49
	v_exp_f32_e32 v50, v50
	v_exp_f32_e32 v51, v51
	v_exp_f32_e32 v52, v52
	v_exp_f32_e32 v53, v53
	v_exp_f32_e32 v56, v55
	v_add_f32_e32 v54, 1.0, v54
	v_add_f32_e32 v48, 1.0, v48
	v_add_f32_e32 v49, 1.0, v49
	v_add_f32_e32 v50, 1.0, v50
	v_add_f32_e32 v51, 1.0, v51
	v_add_f32_e32 v52, 1.0, v52
	v_add_f32_e32 v53, 1.0, v53
	v_rcp_f32_e32 v55, v54
	v_add_f32_e32 v54, 1.0, v56
	v_rcp_f32_e32 v48, v48
	v_rcp_f32_e32 v49, v49
	v_rcp_f32_e32 v50, v50
	v_rcp_f32_e32 v51, v51
	v_rcp_f32_e32 v52, v52
	v_rcp_f32_e32 v53, v53
	v_rcp_f32_e32 v54, v54
	s_mov_b64 s[6:7], 0

; __device__ __forceinline__ float sigmoidf_(float x) { return __builtin_amdgcn_rcpf(1.f + __builtin_amdgcn_exp2f(-1.4426950408889634f * x)); }
; __device__ __forceinline__ float gelu_t(float x) { const float u = x * (-2.3022081986f - 0.1029432404f * x * x); return x * __builtin_amdgcn_rcpf(1.f + __builtin_amdgcn_exp2f(u)); }
; __device__ __forceinline__ unsigned cvt_pk_bf16(float lo, float hi) { unsigned r; asm volatile("v_cvt_pk_bf16_f32 %0, %1, %2" : "=v"(r) : "v"(lo), "v"(hi)); return r; }
;     __device__ __forceinline__ void operator()(const f32x4 (&acc)[2][2][4][2], const Unit& u, int wr, int wc, int fr, int fq) const {
;     ...
;             const int col = pn * BM + cl; const f32x4 b0 = *(const f32x4*)(bias + col), b1 = *(const f32x4*)(bias + col + 4);
;             v0 = v0 + b0; v1 = v1 + b1;
;             if (act == 1) {
; #pragma unroll
;                 for (int e = 0; e < 4; ++e) { v0[e] = gelu_t(v0[e]); v1[e] = gelu_t(v1[e]); }
;             } else if (act == 2) {
; #pragma unroll
;                 for (int e = 0; e < 4; ++e) { v0[e] = sigmoidf_(v0[e]); v1[e] = sigmoidf_(v1[e]); }
;             }
;             u32x4 w; w.x = cvt_pk_bf16(v0[0], v0[1]); w.y = cvt_pk_bf16(v0[2], v0[3]); w.z = cvt_pk_bf16(v1[0], v1[1]); w.w = cvt_pk_bf16(v1[2], v1[3]);
;             *(u32x4*)(Z + (size_t)row * ZP + col) = w;
.LBB0_1696:
	v_add_u32_e32 v46, 0x90, v124
	v_mov_b64_e32 v[40:41], s[4:5]
	v_mad_i64_i32 v[40:41], s[6:7], v46, s71, v[40:41]
	v_lshl_add_u64 v[40:41], v[144:145], 1, v[40:41]
	v_cvt_pk_bf16_f32 v42, v48, v50
	v_cvt_pk_bf16_f32 v43, v52, v55
	v_cvt_pk_bf16_f32 v44, v49, v51
	v_cvt_pk_bf16_f32 v45, v53, v54
	global_store_dwordx4 v[40:41], v[42:45], off
	s_cmp_gt_i32 s21, 1
	s_mov_b64 s[6:7], -1
	v_pk_add_f32 v[38:39], v[38:39], v[210:211]
	v_pk_add_f32 v[36:37], v[36:37], v[208:209]
	v_pk_add_f32 v[34:35], v[34:35], v[214:215]
	v_pk_add_f32 v[32:33], v[32:33], v[212:213]
	s_cbranch_scc0 .LBB0_1698
	v_mul_f32_e32 v48, 0xbfb8aa3b, v39
	v_mul_f32_e32 v42, 0xbfb8aa3b, v36
	v_mul_f32_e32 v43, 0xbfb8aa3b, v32
	v_mul_f32_e32 v44, 0xbfb8aa3b, v37
	v_mul_f32_e32 v45, 0xbfb8aa3b, v33
	v_mul_f32_e32 v46, 0xbfb8aa3b, v38
	v_mul_f32_e32 v47, 0xbfb8aa3b, v34
	v_exp_f32_e32 v48, v48
	v_mul_f32_e32 v49, 0xbfb8aa3b, v35
	v_exp_f32_e32 v42, v42
	v_exp_f32_e32 v43, v43
	v_exp_f32_e32 v44, v44
	v_exp_f32_e32 v45, v45
	v_exp_f32_e32 v46, v46
	v_exp_f32_e32 v47, v47
	v_exp_f32_e32 v50, v49
	v_add_f32_e32 v48, 1.0, v48
	v_add_f32_e32 v42, 1.0, v42
	v_add_f32_e32 v43, 1.0, v43
	v_add_f32_e32 v44, 1.0, v44
	v_add_f32_e32 v45, 1.0, v45
	v_add_f32_e32 v46, 1.0, v46
	v_add_f32_e32 v47, 1.0, v47
	v_rcp_f32_e32 v49, v48
	v_add_f32_e32 v48, 1.0, v50
	v_rcp_f32_e32 v42, v42
	v_rcp_f32_e32 v43, v43
	v_rcp_f32_e32 v44, v44
	v_rcp_f32_e32 v45, v45
	v_rcp_f32_e32 v46, v46
	v_rcp_f32_e32 v47, v47
	v_rcp_f32_e32 v48, v48
	s_mov_b64 s[6:7], 0

; __device__ __forceinline__ float sigmoidf_(float x) { return __builtin_amdgcn_rcpf(1.f + __builtin_amdgcn_exp2f(-1.4426950408889634f * x)); }
; __device__ __forceinline__ float gelu_t(float x) { const float u = x * (-2.3022081986f - 0.1029432404f * x * x); return x * __builtin_amdgcn_rcpf(1.f + __builtin_amdgcn_exp2f(u)); }
; __device__ __forceinline__ unsigned cvt_pk_bf16(float lo, float hi) { unsigned r; asm volatile("v_cvt_pk_bf16_f32 %0, %1, %2" : "=v"(r) : "v"(lo), "v"(hi)); return r; }
;     __device__ __forceinline__ void operator()(const f32x4 (&acc)[2][2][4][2], const Unit& u, int wr, int wc, int fr, int fq) const {
;     ...
;             const int col = pn * BM + cl; const f32x4 b0 = *(const f32x4*)(bias + col), b1 = *(const f32x4*)(bias + col + 4);
;             v0 = v0 + b0; v1 = v1 + b1;
;             if (act == 1) {
; #pragma unroll
;                 for (int e = 0; e < 4; ++e) { v0[e] = gelu_t(v0[e]); v1[e] = gelu_t(v1[e]); }
;             } else if (act == 2) {
; #pragma unroll
;                 for (int e = 0; e < 4; ++e) { v0[e] = sigmoidf_(v0[e]); v1[e] = sigmoidf_(v1[e]); }
;             }
;             u32x4 w; w.x = cvt_pk_bf16(v0[0], v0[1]); w.y = cvt_pk_bf16(v0[2], v0[3]); w.z = cvt_pk_bf16(v1[0], v1[1]); w.w = cvt_pk_bf16(v1[2], v1[3]);
;             *(u32x4*)(Z + (size_t)row * ZP + col) = w;
.LBB0_1702:
	v_cvt_pk_bf16_f32 v32, v42, v44
	v_cvt_pk_bf16_f32 v33, v46, v49
	v_cvt_pk_bf16_f32 v34, v43, v45
	v_cvt_pk_bf16_f32 v35, v47, v48
	global_store_dwordx4 v[40:41], v[32:35], off offset:256
	s_cmp_gt_i32 s21, 1
	s_mov_b64 s[6:7], -1
	v_pk_add_f32 v[30:31], v[30:31], v[202:203]
	v_pk_add_f32 v[28:29], v[28:29], v[200:201]
	v_pk_add_f32 v[26:27], v[26:27], v[206:207]
	v_pk_add_f32 v[24:25], v[24:25], v[204:205]
	s_cbranch_scc0 .LBB0_1704
	v_mul_f32_e32 v38, 0xbfb8aa3b, v31
	v_mul_f32_e32 v32, 0xbfb8aa3b, v28
	v_mul_f32_e32 v33, 0xbfb8aa3b, v24
	v_mul_f32_e32 v34, 0xbfb8aa3b, v29
	v_mul_f32_e32 v35, 0xbfb8aa3b, v25
	v_mul_f32_e32 v36, 0xbfb8aa3b, v30
	v_mul_f32_e32 v37, 0xbfb8aa3b, v26
	v_exp_f32_e32 v38, v38
	v_mul_f32_e32 v39, 0xbfb8aa3b, v27
	v_exp_f32_e32 v32, v32
	v_exp_f32_e32 v33, v33
	v_exp_f32_e32 v34, v34
	v_exp_f32_e32 v35, v35
	v_exp_f32_e32 v36, v36
	v_exp_f32_e32 v37, v37
	v_exp_f32_e32 v40, v39
	v_add_f32_e32 v38, 1.0, v38
	v_add_f32_e32 v32, 1.0, v32
	v_add_f32_e32 v33, 1.0, v33
	v_add_f32_e32 v34, 1.0, v34
	v_add_f32_e32 v35, 1.0, v35
	v_add_f32_e32 v36, 1.0, v36
	v_add_f32_e32 v37, 1.0, v37
	v_rcp_f32_e32 v39, v38
	v_add_f32_e32 v38, 1.0, v40
	v_rcp_f32_e32 v32, v32
	v_rcp_f32_e32 v33, v33
	v_rcp_f32_e32 v34, v34
	v_rcp_f32_e32 v35, v35
	v_rcp_f32_e32 v36, v36
	v_rcp_f32_e32 v37, v37
	v_rcp_f32_e32 v38, v38
	s_mov_b64 s[6:7], 0

; __device__ __forceinline__ float sigmoidf_(float x) { return __builtin_amdgcn_rcpf(1.f + __builtin_amdgcn_exp2f(-1.4426950408889634f * x)); }
; __device__ __forceinline__ float gelu_t(float x) { const float u = x * (-2.3022081986f - 0.1029432404f * x * x); return x * __builtin_amdgcn_rcpf(1.f + __builtin_amdgcn_exp2f(u)); }
; __device__ __forceinline__ unsigned cvt_pk_bf16(float lo, float hi) { unsigned r; asm volatile("v_cvt_pk_bf16_f32 %0, %1, %2" : "=v"(r) : "v"(lo), "v"(hi)); return r; }
;     __device__ __forceinline__ void operator()(const f32x4 (&acc)[2][2][4][2], const Unit& u, int wr, int wc, int fr, int fq) const {
;     ...
;             const int col = pn * BM + cl; const f32x4 b0 = *(const f32x4*)(bias + col), b1 = *(const f32x4*)(bias + col + 4);
;             v0 = v0 + b0; v1 = v1 + b1;
;             if (act == 1) {
; #pragma unroll
;                 for (int e = 0; e < 4; ++e) { v0[e] = gelu_t(v0[e]); v1[e] = gelu_t(v1[e]); }
;             } else if (act == 2) {
; #pragma unroll
;                 for (int e = 0; e < 4; ++e) { v0[e] = sigmoidf_(v0[e]); v1[e] = sigmoidf_(v1[e]); }
;             }
;             u32x4 w; w.x = cvt_pk_bf16(v0[0], v0[1]); w.y = cvt_pk_bf16(v0[2], v0[3]); w.z = cvt_pk_bf16(v1[0], v1[1]); w.w = cvt_pk_bf16(v1[2], v1[3]);
;             *(u32x4*)(Z + (size_t)row * ZP + col) = w;
.LBB0_1708:
	v_add_u32_e32 v30, 0xa0, v124
	v_mov_b64_e32 v[24:25], s[4:5]
	v_mad_i64_i32 v[24:25], s[6:7], v30, s71, v[24:25]
	v_lshl_add_u64 v[24:25], v[144:145], 1, v[24:25]
	v_cvt_pk_bf16_f32 v26, v32, v34
	v_cvt_pk_bf16_f32 v27, v36, v39
	v_cvt_pk_bf16_f32 v28, v33, v35
	v_cvt_pk_bf16_f32 v29, v37, v38
	global_store_dwordx4 v[24:25], v[26:29], off
	s_cmp_gt_i32 s21, 1
	s_mov_b64 s[6:7], -1
	v_pk_add_f32 v[22:23], v[22:23], v[210:211]
	v_pk_add_f32 v[20:21], v[20:21], v[208:209]
	v_pk_add_f32 v[18:19], v[18:19], v[214:215]
	v_pk_add_f32 v[16:17], v[16:17], v[212:213]
	s_cbranch_scc0 .LBB0_1710
	v_mul_f32_e32 v32, 0xbfb8aa3b, v23
	v_mul_f32_e32 v26, 0xbfb8aa3b, v20
	v_mul_f32_e32 v27, 0xbfb8aa3b, v16
	v_mul_f32_e32 v28, 0xbfb8aa3b, v21
	v_mul_f32_e32 v29, 0xbfb8aa3b, v17
	v_mul_f32_e32 v30, 0xbfb8aa3b, v22
	v_mul_f32_e32 v31, 0xbfb8aa3b, v18
	v_exp_f32_e32 v32, v32
	v_mul_f32_e32 v33, 0xbfb8aa3b, v19
	v_exp_f32_e32 v26, v26
	v_exp_f32_e32 v27, v27
	v_exp_f32_e32 v28, v28
	v_exp_f32_e32 v29, v29
	v_exp_f32_e32 v30, v30
	v_exp_f32_e32 v31, v31
	v_exp_f32_e32 v34, v33
	v_add_f32_e32 v32, 1.0, v32
	v_add_f32_e32 v26, 1.0, v26
	v_add_f32_e32 v27, 1.0, v27
	v_add_f32_e32 v28, 1.0, v28
	v_add_f32_e32 v29, 1.0, v29
	v_add_f32_e32 v30, 1.0, v30
	v_add_f32_e32 v31, 1.0, v31
	v_rcp_f32_e32 v33, v32
	v_add_f32_e32 v32, 1.0, v34
	v_rcp_f32_e32 v26, v26
	v_rcp_f32_e32 v27, v27
	v_rcp_f32_e32 v28, v28
	v_rcp_f32_e32 v29, v29
	v_rcp_f32_e32 v30, v30
	v_rcp_f32_e32 v31, v31
	v_rcp_f32_e32 v32, v32
	s_mov_b64 s[6:7], 0

; __device__ __forceinline__ float sigmoidf_(float x) { return __builtin_amdgcn_rcpf(1.f + __builtin_amdgcn_exp2f(-1.4426950408889634f * x)); }
; __device__ __forceinline__ float gelu_t(float x) { const float u = x * (-2.3022081986f - 0.1029432404f * x * x); return x * __builtin_amdgcn_rcpf(1.f + __builtin_amdgcn_exp2f(u)); }
; __device__ __forceinline__ unsigned cvt_pk_bf16(float lo, float hi) { unsigned r; asm volatile("v_cvt_pk_bf16_f32 %0, %1, %2" : "=v"(r) : "v"(lo), "v"(hi)); return r; }
;     __device__ __forceinline__ void operator()(const f32x4 (&acc)[2][2][4][2], const Unit& u, int wr, int wc, int fr, int fq) const {
;     ...
;             const int col = pn * BM + cl; const f32x4 b0 = *(const f32x4*)(bias + col), b1 = *(const f32x4*)(bias + col + 4);
;             v0 = v0 + b0; v1 = v1 + b1;
;             if (act == 1) {
; #pragma unroll
;                 for (int e = 0; e < 4; ++e) { v0[e] = gelu_t(v0[e]); v1[e] = gelu_t(v1[e]); }
;             } else if (act == 2) {
; #pragma unroll
;                 for (int e = 0; e < 4; ++e) { v0[e] = sigmoidf_(v0[e]); v1[e] = sigmoidf_(v1[e]); }
;             }
;             u32x4 w; w.x = cvt_pk_bf16(v0[0], v0[1]); w.y = cvt_pk_bf16(v0[2], v0[3]); w.z = cvt_pk_bf16(v1[0], v1[1]); w.w = cvt_pk_bf16(v1[2], v1[3]);
;             *(u32x4*)(Z + (size_t)row * ZP + col) = w;
.LBB0_1714:
	v_cvt_pk_bf16_f32 v16, v26, v28
	v_cvt_pk_bf16_f32 v17, v30, v33
	v_cvt_pk_bf16_f32 v18, v27, v29
	v_cvt_pk_bf16_f32 v19, v31, v32
	global_store_dwordx4 v[24:25], v[16:19], off offset:256
	s_cmp_gt_i32 s21, 1
	s_mov_b64 s[6:7], -1
	v_pk_add_f32 v[14:15], v[14:15], v[202:203]
	v_pk_add_f32 v[12:13], v[12:13], v[200:201]
	v_pk_add_f32 v[10:11], v[10:11], v[206:207]
	v_pk_add_f32 v[8:9], v[8:9], v[204:205]
	s_cbranch_scc0 .LBB0_1716
	v_mul_f32_e32 v22, 0xbfb8aa3b, v15
	v_mul_f32_e32 v16, 0xbfb8aa3b, v12
	v_mul_f32_e32 v17, 0xbfb8aa3b, v8
	v_mul_f32_e32 v18, 0xbfb8aa3b, v13
	v_mul_f32_e32 v19, 0xbfb8aa3b, v9
	v_mul_f32_e32 v20, 0xbfb8aa3b, v14
	v_mul_f32_e32 v21, 0xbfb8aa3b, v10
	v_exp_f32_e32 v22, v22
	v_mul_f32_e32 v23, 0xbfb8aa3b, v11
	v_exp_f32_e32 v16, v16
	v_exp_f32_e32 v17, v17
	v_exp_f32_e32 v18, v18
	v_exp_f32_e32 v19, v19
	v_exp_f32_e32 v20, v20
	v_exp_f32_e32 v21, v21
	v_exp_f32_e32 v24, v23
	v_add_f32_e32 v22, 1.0, v22
	v_add_f32_e32 v16, 1.0, v16
	v_add_f32_e32 v17, 1.0, v17
	v_add_f32_e32 v18, 1.0, v18
	v_add_f32_e32 v19, 1.0, v19
	v_add_f32_e32 v20, 1.0, v20
	v_add_f32_e32 v21, 1.0, v21
	v_rcp_f32_e32 v23, v22
	v_add_f32_e32 v22, 1.0, v24
	v_rcp_f32_e32 v16, v16
	v_rcp_f32_e32 v17, v17
	v_rcp_f32_e32 v18, v18
	v_rcp_f32_e32 v19, v19
	v_rcp_f32_e32 v20, v20
	v_rcp_f32_e32 v21, v21
	v_rcp_f32_e32 v22, v22
	s_mov_b64 s[6:7], 0

; __device__ __forceinline__ float sigmoidf_(float x) { return __builtin_amdgcn_rcpf(1.f + __builtin_amdgcn_exp2f(-1.4426950408889634f * x)); }
; __device__ __forceinline__ float gelu_t(float x) { const float u = x * (-2.3022081986f - 0.1029432404f * x * x); return x * __builtin_amdgcn_rcpf(1.f + __builtin_amdgcn_exp2f(u)); }
; __device__ __forceinline__ unsigned cvt_pk_bf16(float lo, float hi) { unsigned r; asm volatile("v_cvt_pk_bf16_f32 %0, %1, %2" : "=v"(r) : "v"(lo), "v"(hi)); return r; }
;     __device__ __forceinline__ void operator()(const f32x4 (&acc)[2][2][4][2], const Unit& u, int wr, int wc, int fr, int fq) const {
;     ...
;             const int col = pn * BM + cl; const f32x4 b0 = *(const f32x4*)(bias + col), b1 = *(const f32x4*)(bias + col + 4);
;             v0 = v0 + b0; v1 = v1 + b1;
;             if (act == 1) {
; #pragma unroll
;                 for (int e = 0; e < 4; ++e) { v0[e] = gelu_t(v0[e]); v1[e] = gelu_t(v1[e]); }
;             } else if (act == 2) {
; #pragma unroll
;                 for (int e = 0; e < 4; ++e) { v0[e] = sigmoidf_(v0[e]); v1[e] = sigmoidf_(v1[e]); }
;             }
;             u32x4 w; w.x = cvt_pk_bf16(v0[0], v0[1]); w.y = cvt_pk_bf16(v0[2], v0[3]); w.z = cvt_pk_bf16(v1[0], v1[1]); w.w = cvt_pk_bf16(v1[2], v1[3]);
;             *(u32x4*)(Z + (size_t)row * ZP + col) = w;
.LBB0_1720:
	v_add_u32_e32 v14, 0xb0, v124
	v_mov_b64_e32 v[8:9], s[4:5]
	v_mad_i64_i32 v[8:9], s[6:7], v14, s71, v[8:9]
	v_lshl_add_u64 v[8:9], v[144:145], 1, v[8:9]
	v_cvt_pk_bf16_f32 v10, v16, v18
	v_cvt_pk_bf16_f32 v11, v20, v23
	v_cvt_pk_bf16_f32 v12, v17, v19
	v_cvt_pk_bf16_f32 v13, v21, v22
	global_store_dwordx4 v[8:9], v[10:13], off
	s_cmp_gt_i32 s21, 1
	s_mov_b64 s[6:7], -1
	v_pk_add_f32 v[6:7], v[6:7], v[210:211]
	v_pk_add_f32 v[4:5], v[4:5], v[208:209]
	v_pk_add_f32 v[2:3], v[2:3], v[214:215]
	v_pk_add_f32 v[0:1], v[0:1], v[212:213]
	s_cbranch_scc0 .LBB0_1722
	v_mul_f32_e32 v16, 0xbfb8aa3b, v7
	v_mul_f32_e32 v10, 0xbfb8aa3b, v4
	v_mul_f32_e32 v11, 0xbfb8aa3b, v0
	v_mul_f32_e32 v12, 0xbfb8aa3b, v5
	v_mul_f32_e32 v13, 0xbfb8aa3b, v1
	v_mul_f32_e32 v14, 0xbfb8aa3b, v6
	v_mul_f32_e32 v15, 0xbfb8aa3b, v2
	v_exp_f32_e32 v16, v16
	v_mul_f32_e32 v17, 0xbfb8aa3b, v3
	v_exp_f32_e32 v10, v10
	v_exp_f32_e32 v11, v11
	v_exp_f32_e32 v12, v12
	v_exp_f32_e32 v13, v13
	v_exp_f32_e32 v14, v14
	v_exp_f32_e32 v15, v15
	v_exp_f32_e32 v18, v17
	v_add_f32_e32 v16, 1.0, v16
	v_add_f32_e32 v10, 1.0, v10
	v_add_f32_e32 v11, 1.0, v11
	v_add_f32_e32 v12, 1.0, v12
	v_add_f32_e32 v13, 1.0, v13
	v_add_f32_e32 v14, 1.0, v14
	v_add_f32_e32 v15, 1.0, v15
	v_rcp_f32_e32 v17, v16
	v_add_f32_e32 v16, 1.0, v18
	v_rcp_f32_e32 v10, v10
	v_rcp_f32_e32 v11, v11
	v_rcp_f32_e32 v12, v12
	v_rcp_f32_e32 v13, v13
	v_rcp_f32_e32 v14, v14
	v_rcp_f32_e32 v15, v15
	v_rcp_f32_e32 v16, v16
	s_mov_b64 s[6:7], 0

; __device__ __forceinline__ void gmlp_mfma_unit(const Params& p, int l, bf16_t* Z, LAS unsigned char* lds, int nb) {
;     ...
;         if (lane == 0) { st[tok] = mean; st[128 + tok] = rstd; } }
;     __syncthreads();
;     const int nks = wave < 4 ? 2 : 4, irow = 16 * wave + l15;
;     for (int g = 0; g < 4; ++g) {
;         const float* lng = p.in[I_GMLNG] + l * 512 + g * 128; const float* lnb = p.in[I_GMLNB] + l * 512 + g * 128;
; #pragma unroll
;         for (int j = 0; j < 4; ++j) { const int idx = tid + NTHREADS * j, tok = idx >> 4, c8 = (idx & 15) * 8;
.Lgst_1_15:
	s_or_b64 exec, exec, s[4:5]
	s_add_i32 s25, s25, 4
.LBB0_1792:
	s_lshl_b32 s24, s23, 7
	v_or_b32_e32 v0, s24, v51
	v_mad_i64_i32 v[36:37], s[4:5], v0, s9, v[26:27]
	v_or_b32_e32 v0, s24, v53
	s_lshr_b32 s0, s16, 2
	v_mad_i64_i32 v[38:39], s[4:5], v0, s9, v[26:27]
	v_or_b32_e32 v0, s24, v55
	s_and_b32 s25, s0, 0x3ffffff0
	v_mad_i64_i32 v[40:41], s[4:5], v0, s9, v[26:27]
	v_add_u32_e32 v0, s24, v56
	s_cmpk_gt_u32 s16, 0xff
	v_or_b32_e32 v67, s25, v50
	v_mad_i64_i32 v[42:43], s[4:5], v0, s9, v[26:27]
	v_add_u32_e32 v0, s25, v58
	s_cselect_b64 s[0:1], -1, 0
	v_add_u32_e32 v68, 0x200, v67
	v_mad_i64_i32 v[44:45], s[4:5], v0, s9, v[34:35]
	s_mov_b32 s24, 0
	s_waitcnt lgkmcnt(0)
	s_barrier
	s_branch .LBB0_1794

; #define LAS __attribute__((address_space(3)))
; __device__ __forceinline__ unsigned pk2(float lo, float hi) { return f2bf(lo) | (f2bf(hi) << 16); }
; __device__ __forceinline__ void gmlp_mfma_unit(const Params& p, int l, bf16_t* Z, LAS unsigned char* lds, int nb) {
;     ...
;         bf16x8 wf[4];
;         const bf16_t* wp = (const bf16_t*)(p.ws + WS_GMW) + ((size_t)(l * 4 + g) * 128 + irow) * 128 + 8 * lq;
; #pragma unroll
;         for (int ks = 0; ks < 4; ++ks) wf[ks] = (ks < nks) ? *(const bf16x8*)(wp + ks * 32) : (bf16x8){0, 0, 0, 0, 0, 0, 0, 0};
;         const float bsv = p.in[I_GMBS][(l * 4 + g) * 128 + irow];
;         bf16_t* up = Z + (size_t)(row0 + irow) * ZP + g * 128 + 4 * lq;
; #pragma unroll 2
;         for (int mt = 0; mt < 8; ++mt) {
;             f32x4 acc = (f32x4){0.f, 0.f, 0.f, 0.f};
;             const LAS bf16_t* ap = vnT + (mt * 16 + l15) * 136 + 8 * lq;
;             acc = __builtin_amdgcn_mfma_f32_16x16x32_bf16(*(const LAS bf16x8*)(ap), wf[0], acc, 0, 0, 0);
;             acc = __builtin_amdgcn_mfma_f32_16x16x32_bf16(*(const LAS bf16x8*)(ap + 32), wf[1], acc, 0, 0, 0);
;             if (nks == 4) { acc = __builtin_amdgcn_mfma_f32_16x16x32_bf16(*(const LAS bf16x8*)(ap + 64), wf[2], acc, 0, 0, 0);
;                             acc = __builtin_amdgcn_mfma_f32_16x16x32_bf16(*(const LAS bf16x8*)(ap + 96), wf[3], acc, 0, 0, 0); }
;             const u32x2 uu = *(const u32x2*)(up + mt * 16);
;             u32x2 o; o.x = pk2(bflo(uu.x) * (acc[0] + bsv), bfhi(uu.x) * (acc[1] + bsv)); o.y = pk2(bflo(uu.y) * (acc[2] + bsv), bfhi(uu.y) * (acc[3] + bsv));
;             *(u32x2*)(up + mt * 16) = o; }
.LBB0_1799:
	v_add_u32_e32 v22, s16, v67
	v_lshl_add_u64 v[16:17], v[22:23], 2, s[38:39]
	global_load_dword v46, v[16:17], off offset:2048
	global_load_dwordx2 v[96:97], v[44:45], off offset:-32
	global_load_dwordx2 v[98:99], v[44:45], off
	global_load_dwordx2 v[100:101], v[44:45], off offset:32
	global_load_dwordx2 v[102:103], v[44:45], off offset:64
	global_load_dwordx2 v[104:105], v[44:45], off offset:96
	global_load_dwordx2 v[106:107], v[44:45], off offset:128
	global_load_dwordx2 v[108:109], v[44:45], off offset:160
	global_load_dwordx2 v[110:111], v[44:45], off offset:192
	v_mov_b64_e32 v[48:49], v[44:45]
	s_waitcnt vmcnt(0)
	v_mov_b32_e32 v47, v46
	s_branch .LBB0_1801
.LBB0_1800:
	v_mov_b64_e32 v[70:71], v[98:99]
	s_nop 5
	v_mov_b32_e32 v72, v16
	v_mov_b32_e32 v73, v18
	v_mov_b32_e32 v18, v17
	v_pk_add_f32 v[16:17], v[46:47], v[72:73]
	v_pk_add_f32 v[18:19], v[46:47], v[18:19]
	s_addk_i32 s25, 0x2200
	s_cmpk_eq_u32 s25, 0x8800
	v_lshlrev_b32_e32 v73, 16, v71
	v_lshlrev_b32_e32 v72, 16, v70
	v_and_b32_e32 v71, 0xffff0000, v71
	v_and_b32_e32 v70, 0xffff0000, v70
	v_pk_mul_f32 v[18:19], v[18:19], v[70:71]
	v_pk_mul_f32 v[16:17], v[16:17], v[72:73]
	v_and_b32_sdwa v70, v19, v65 dst_sel:DWORD dst_unused:UNUSED_PAD src0_sel:WORD_1 src1_sel:DWORD
	v_and_b32_sdwa v71, v18, v65 dst_sel:DWORD dst_unused:UNUSED_PAD src0_sel:WORD_1 src1_sel:DWORD
	v_and_b32_sdwa v22, v17, v65 dst_sel:DWORD dst_unused:UNUSED_PAD src0_sel:WORD_1 src1_sel:DWORD
	v_and_b32_sdwa v69, v16, v65 dst_sel:DWORD dst_unused:UNUSED_PAD src0_sel:WORD_1 src1_sel:DWORD
	v_add3_u32 v19, v19, v70, s22
	v_add3_u32 v18, v18, v71, s22
	v_add3_u32 v16, v16, v69, s22
	v_add3_u32 v17, v17, v22, s22
	v_and_b32_e32 v19, 0xffff0000, v19
	v_and_b32_e32 v18, 0xffff0000, v18
	v_or_b32_sdwa v17, v19, v17 dst_sel:DWORD dst_unused:UNUSED_PAD src0_sel:DWORD src1_sel:WORD_1
	v_or_b32_sdwa v16, v18, v16 dst_sel:DWORD dst_unused:UNUSED_PAD src0_sel:DWORD src1_sel:WORD_1
	global_store_dwordx2 v[48:49], v[16:17], off
	v_lshl_add_u64 v[48:49], v[48:49], 0, 64
	v_mov_b64_e32 v[96:97], v[100:101]
	v_mov_b64_e32 v[98:99], v[102:103]
	v_mov_b64_e32 v[100:101], v[104:105]
	v_mov_b64_e32 v[102:103], v[106:107]
	v_mov_b64_e32 v[104:105], v[108:109]
	v_mov_b64_e32 v[106:107], v[110:111]
	s_cbranch_scc1 .LBB0_1793

; #define LAS __attribute__((address_space(3)))
; __device__ __forceinline__ unsigned pk2(float lo, float hi) { return f2bf(lo) | (f2bf(hi) << 16); }
; __device__ __forceinline__ void gmlp_mfma_unit(const Params& p, int l, bf16_t* Z, LAS unsigned char* lds, int nb) {
;     ...
; #pragma unroll 2
;         for (int mt = 0; mt < 8; ++mt) {
;             f32x4 acc = (f32x4){0.f, 0.f, 0.f, 0.f};
;             const LAS bf16_t* ap = vnT + (mt * 16 + l15) * 136 + 8 * lq;
;             acc = __builtin_amdgcn_mfma_f32_16x16x32_bf16(*(const LAS bf16x8*)(ap), wf[0], acc, 0, 0, 0);
;             acc = __builtin_amdgcn_mfma_f32_16x16x32_bf16(*(const LAS bf16x8*)(ap + 32), wf[1], acc, 0, 0, 0);
;             if (nks == 4) { acc = __builtin_amdgcn_mfma_f32_16x16x32_bf16(*(const LAS bf16x8*)(ap + 64), wf[2], acc, 0, 0, 0);
;                             acc = __builtin_amdgcn_mfma_f32_16x16x32_bf16(*(const LAS bf16x8*)(ap + 96), wf[3], acc, 0, 0, 0); }
;             const u32x2 uu = *(const u32x2*)(up + mt * 16);
;             u32x2 o; o.x = pk2(bflo(uu.x) * (acc[0] + bsv), bfhi(uu.x) * (acc[1] + bsv)); o.y = pk2(bflo(uu.y) * (acc[2] + bsv), bfhi(uu.y) * (acc[3] + bsv));
;             *(u32x2*)(up + mt * 16) = o; }
.LBB0_1803:
	v_mov_b64_e32 v[78:79], v[96:97]
	ds_read_b128 v[70:73], v22 offset:4352
	ds_read_b128 v[74:77], v22 offset:4416
	s_nop 4
	v_mov_b32_e32 v81, v18
	v_mov_b32_e32 v18, v17
	v_mov_b32_e32 v80, v16
	v_pk_add_f32 v[82:83], v[46:47], v[18:19]
	v_pk_add_f32 v[80:81], v[46:47], v[80:81]
	s_and_b64 vcc, exec, s[4:5]
	s_waitcnt lgkmcnt(1)
	v_mfma_f32_16x16x32_bf16 v[16:19], v[70:73], v[0:3], 0
	v_lshlrev_b32_e32 v71, 16, v79
	v_lshlrev_b32_e32 v70, 16, v78
	v_and_b32_e32 v73, 0xffff0000, v79
	v_and_b32_e32 v72, 0xffff0000, v78
	v_pk_mul_f32 v[70:71], v[80:81], v[70:71]
	v_pk_mul_f32 v[72:73], v[82:83], v[72:73]
	v_and_b32_sdwa v69, v71, v65 dst_sel:DWORD dst_unused:UNUSED_PAD src0_sel:WORD_1 src1_sel:DWORD
	v_and_b32_sdwa v79, v73, v65 dst_sel:DWORD dst_unused:UNUSED_PAD src0_sel:WORD_1 src1_sel:DWORD
	v_and_b32_sdwa v80, v72, v65 dst_sel:DWORD dst_unused:UNUSED_PAD src0_sel:WORD_1 src1_sel:DWORD
	s_waitcnt lgkmcnt(0)
	v_mfma_f32_16x16x32_bf16 v[16:19], v[74:77], v[4:7], v[16:19]
	v_and_b32_sdwa v78, v70, v65 dst_sel:DWORD dst_unused:UNUSED_PAD src0_sel:WORD_1 src1_sel:DWORD
	v_add3_u32 v69, v71, v69, s22
	v_add3_u32 v71, v73, v79, s22
	v_add3_u32 v72, v72, v80, s22
	v_add3_u32 v70, v70, v78, s22
	v_and_b32_e32 v71, 0xffff0000, v71
	v_and_b32_e32 v72, 0xffff0000, v72
	v_or_b32_sdwa v71, v71, v69 dst_sel:DWORD dst_unused:UNUSED_PAD src0_sel:DWORD src1_sel:WORD_1
	v_or_b32_sdwa v70, v72, v70 dst_sel:DWORD dst_unused:UNUSED_PAD src0_sel:DWORD src1_sel:WORD_1
	global_store_dwordx2 v[48:49], v[70:71], off offset:-32
	s_cbranch_vccnz .LBB0_1800
	ds_read_b128 v[70:73], v22 offset:4480
	ds_read_b128 v[74:77], v22 offset:4544
	s_waitcnt lgkmcnt(1)
	v_mfma_f32_16x16x32_bf16 v[16:19], v[70:73], v[8:11], v[16:19]
	s_waitcnt lgkmcnt(0)
	v_mfma_f32_16x16x32_bf16 v[16:19], v[74:77], v[12:15], v[16:19]
	s_branch .LBB0_1800

; __device__ __forceinline__ void latent_pass(const Params& p, int l, bf16_t* Z, bf16_t* Hb) {
;     ...
;         bf16_t* z = Z + (size_t)row * ZP;
;         const u32x2 qa = *(const u32x2*)(z + ZC_QLAT + 4 * lane);
;         float q0 = bflo(qa.x), q1 = bfhi(qa.x), q2 = bflo(qa.y), q3 = bfhi(qa.y);
;         const float qr = 1.f / sqrtf(wave_sum(q0 * q0 + q1 * q1 + q2 * q2 + q3 * q3) * (1.f / 256.f) + 1e-6f);
;         const f32x4 g4 = *(const f32x4*)(qg + 4 * lane);
;         const unsigned ka = *(const unsigned*)(z + ZC_KVLAT + 2 * lane);
;         float k0 = bflo(ka), k1 = bfhi(ka);
;         const float kr = 1.f / sqrtf(wave_sum(k0 * k0 + k1 * k1) * (1.f / 128.f) + 1e-6f);
;         const float kg0 = kg[2 * lane], kg1 = kg[2 * lane + 1];
;         float x1 = 0.f, x2 = 0.f;
;         if (lane < 16) { x1 = bf2f(z[ZC_KROPE + lane]); x2 = bf2f(z[ZC_KROPE + 16 + lane]); }
.LBB0_1808:
	v_lshl_add_u64 v[16:17], s[96:97], 0, v[14:15]
	global_load_dwordx2 v[24:25], v[16:17], off
	v_lshl_add_u64 v[18:19], s[96:97], 0, v[12:13]
	global_load_dword v21, v[18:19], off
	global_load_dwordx4 v[0:3], v[4:5], off offset:1024
	global_load_dwordx2 v[22:23], v[6:7], off offset:512
	v_lshl_add_u64 v[44:45], s[96:97], 0, v[10:11]
	v_add_co_u32_e32 v44, vcc, 0x8c00000, v44
	s_nop 1
	v_addc_co_u32_e32 v45, vcc, 0, v45, vcc
	global_load_ushort v46, v[44:45], off offset:2848
	global_load_ushort v47, v[44:45], off offset:2816
	v_and_or_b32 v48, v30, s28, v64
	v_lshlrev_b32_e32 v48, 2, v48
	global_load_dword v49, v48, s[18:19]
	global_load_dword v50, v48, s[16:17]
	v_mov_b32_e32 v20, 0
	s_waitcnt vmcnt(4)
	v_lshlrev_b32_e32 v27, 16, v25
	v_lshlrev_b32_e32 v26, 16, v24
	v_and_b32_e32 v29, 0xffff0000, v25
	v_and_b32_e32 v28, 0xffff0000, v24
	v_pk_mul_f32 v[34:35], v[26:27], v[26:27]
	v_pk_mul_f32 v[36:37], v[28:29], v[28:29]
	v_lshlrev_b32_e32 v24, 16, v21
	v_and_b32_e32 v25, 0xffff0000, v21
	v_add_f32_e32 v21, v34, v36
	v_pk_mul_f32 v[38:39], v[24:25], v[24:25]
	v_add_f32_e32 v21, v35, v21
	v_add_f32_e32 v34, v38, v39
	v_add_f32_e32 v21, v37, v21
	v_mov_b32_e32 v35, v34
	v_mov_b32_e32 v36, v21
	s_nop 0
	v_mov_b32_dpp v35, v35 quad_perm:[1,0,3,2] row_mask:0xf bank_mask:0xf
	v_mov_b32_dpp v36, v36 quad_perm:[1,0,3,2] row_mask:0xf bank_mask:0xf
	v_add_f32_e32 v34, v34, v35
	v_add_f32_e32 v21, v21, v36
	v_mov_b32_e32 v35, v34
	v_mov_b32_e32 v36, v21
	s_nop 0
	v_mov_b32_dpp v35, v35 quad_perm:[2,3,0,1] row_mask:0xf bank_mask:0xf
	v_mov_b32_dpp v36, v36 quad_perm:[2,3,0,1] row_mask:0xf bank_mask:0xf
	v_add_f32_e32 v34, v34, v35
	v_add_f32_e32 v21, v21, v36
	v_mov_b32_e32 v35, v34
	v_mov_b32_e32 v36, v21
	s_nop 0
	v_mov_b32_dpp v35, v35 row_half_mirror row_mask:0xf bank_mask:0xf
	v_mov_b32_dpp v36, v36 row_half_mirror row_mask:0xf bank_mask:0xf
	v_add_f32_e32 v34, v34, v35
	v_add_f32_e32 v21, v21, v36
	v_mov_b32_e32 v35, v34
	v_mov_b32_e32 v36, v21
	s_nop 0
	v_mov_b32_dpp v35, v35 row_mirror row_mask:0xf bank_mask:0xf
	v_mov_b32_dpp v36, v36 row_mirror row_mask:0xf bank_mask:0xf
	v_add_f32_e32 v34, v34, v35
	v_add_f32_e32 v21, v21, v36
	v_readlane_b32 s4, v34, 0
	v_readlane_b32 s29, v34, 16
	v_readlane_b32 s5, v34, 32
	v_readlane_b32 s30, v34, 48
	v_readlane_b32 s31, v21, 0
	v_readlane_b32 s34, v21, 16
	v_readlane_b32 s33, v21, 32
	v_readlane_b32 s35, v21, 48
	v_mov_b32_e32 v21, 0
	s_and_saveexec_b64 s[0:1], s[2:3]
	s_cbranch_execz .LBB0_1810
	s_waitcnt vmcnt(2)
	v_lshlrev_b32_e32 v20, 16, v46
	v_lshlrev_b32_e32 v21, 16, v47
; __device__ __forceinline__ unsigned pk2(float lo, float hi) { return f2bf(lo) | (f2bf(hi) << 16); }
; __device__ __forceinline__ void latent_pass(const Params& p, int l, bf16_t* Z, bf16_t* Hb) {
;     ...
;         const float qr = 1.f / sqrtf(wave_sum(q0 * q0 + q1 * q1 + q2 * q2 + q3 * q3) * (1.f / 256.f) + 1e-6f);
;         const f32x4 g4 = *(const f32x4*)(qg + 4 * lane);
;         const unsigned ka = *(const unsigned*)(z + ZC_KVLAT + 2 * lane);
;         float k0 = bflo(ka), k1 = bfhi(ka);
;         const float kr = 1.f / sqrtf(wave_sum(k0 * k0 + k1 * k1) * (1.f / 128.f) + 1e-6f);
;         const float kg0 = kg[2 * lane], kg1 = kg[2 * lane + 1];
;         float x1 = 0.f, x2 = 0.f;
;         if (lane < 16) { x1 = bf2f(z[ZC_KROPE + lane]); x2 = bf2f(z[ZC_KROPE + 16 + lane]); }
;         u32x2 qo; qo.x = pk2(q0 * qr * g4.x, q1 * qr * g4.y); qo.y = pk2(q2 * qr * g4.z, q3 * qr * g4.w);
;         *(u32x2*)(z + ZC_QLAT + 4 * lane) = qo;
;         *(unsigned*)(z + ZC_KVLAT + 2 * lane) = pk2(k0 * kr * kg0, k1 * kr * kg1);
;         if (lane < 16) { const int pos = row & (SEQ - 1); const float c = rc[pos * 16 + lane], s = rs[pos * 16 + lane];
;             *(unsigned*)(Hb + (size_t)row * 1024 + 768 + 2 * lane) = pk2(x1 * c - x2 * s, x2 * c + x1 * s); }
.LBB0_1810:
	s_or_b64 exec, exec, s[0:1]
	v_mov_b32_e32 v34, s34
	v_mov_b32_e32 v35, s35
	v_add_f32_e32 v34, s31, v34
	v_add_f32_e32 v35, s33, v35
	v_add_f32_e32 v34, v34, v35
	v_fmamk_f32 v34, v34, 0x3b800000, v31
	v_mul_f32_e32 v35, 0x4f800000, v34
	v_cmp_gt_f32_e32 vcc, s26, v34
	v_mov_b32_e32 v39, s29
	v_mov_b32_e32 v40, s30
	v_cndmask_b32_e32 v34, v34, v35, vcc
	v_sqrt_f32_e32 v35, v34
	v_add_f32_e32 v39, s4, v39
	v_add_f32_e32 v40, s5, v40
	v_add_f32_e32 v39, v39, v40
	v_add_u32_e32 v36, -1, v35
	v_fma_f32 v37, -v36, v35, v34
	v_cmp_ge_f32_e64 s[0:1], 0, v37
	v_add_u32_e32 v37, 1, v35
	v_fmamk_f32 v39, v39, 0x3c000000, v31
	v_cndmask_b32_e64 v36, v35, v36, s[0:1]
	v_fma_f32 v35, -v37, v35, v34
	v_cmp_lt_f32_e64 s[0:1], 0, v35
	v_mul_f32_e32 v40, 0x4f800000, v39
	s_nop 0
	v_cndmask_b32_e64 v35, v36, v37, s[0:1]
	v_mul_f32_e32 v36, 0x37800000, v35
	v_cndmask_b32_e32 v35, v35, v36, vcc
	v_cmp_class_f32_e32 vcc, v34, v32
	s_nop 1
	v_cndmask_b32_e32 v34, v35, v34, vcc
	v_div_scale_f32 v35, s[0:1], v34, v34, 1.0
	v_rcp_f32_e32 v36, v35
	v_cmp_gt_f32_e64 s[0:1], s26, v39
	v_fma_f32 v37, -v35, v36, 1.0
	s_nop 0
	v_cndmask_b32_e64 v39, v39, v40, s[0:1]
	v_fmac_f32_e32 v36, v37, v36
	v_div_scale_f32 v37, vcc, 1.0, v34, 1.0
	v_sqrt_f32_e32 v40, v39
	v_mul_f32_e32 v38, v37, v36
	v_fma_f32 v41, -v35, v38, v37
	v_fmac_f32_e32 v38, v41, v36
	v_fma_f32 v35, -v35, v38, v37
	v_add_u32_e32 v37, -1, v40
	v_fma_f32 v41, -v37, v40, v39
	v_cmp_ge_f32_e64 s[4:5], 0, v41
	v_add_u32_e32 v41, 1, v40
	v_div_fmas_f32 v35, v35, v36, v38
	v_cndmask_b32_e64 v37, v40, v37, s[4:5]
	v_fma_f32 v40, -v41, v40, v39
	v_cmp_lt_f32_e64 s[4:5], 0, v40
	v_div_fixup_f32 v34, v35, v34, 1.0
	s_nop 0
	v_cndmask_b32_e64 v37, v37, v41, s[4:5]
	v_mul_f32_e32 v40, 0x37800000, v37
	v_cndmask_b32_e64 v37, v37, v40, s[0:1]
	v_cmp_class_f32_e64 s[0:1], v39, v32
	s_nop 1
	v_cndmask_b32_e64 v37, v37, v39, s[0:1]
	v_div_scale_f32 v39, s[0:1], v37, v37, 1.0
	v_rcp_f32_e32 v40, v39
	s_nop 0
	v_fma_f32 v35, -v39, v40, 1.0
	v_fmac_f32_e32 v40, v35, v40
	v_div_scale_f32 v35, vcc, 1.0, v37, 1.0
	v_mul_f32_e32 v36, v35, v40
	v_fma_f32 v38, -v39, v36, v35
	v_fmac_f32_e32 v36, v38, v40
	v_fma_f32 v35, -v39, v36, v35
	v_div_fmas_f32 v35, v35, v40, v36
	v_div_fixup_f32 v36, v35, v37, 1.0
	v_pk_mul_f32 v[26:27], v[34:35], v[26:27] op_sel_hi:[0,1]
	v_pk_mul_f32 v[28:29], v[34:35], v[28:29] op_sel_hi:[0,1]
	v_mov_b32_e32 v34, v0
	v_mov_b32_e32 v35, v2
	v_pk_mul_f32 v[26:27], v[34:35], v[26:27]
	v_mov_b32_e32 v2, v1
	v_pk_mul_f32 v[0:1], v[2:3], v[28:29]
	v_and_b32_sdwa v2, v27, v33 dst_sel:DWORD dst_unused:UNUSED_PAD src0_sel:WORD_1 src1_sel:DWORD
	v_and_b32_sdwa v3, v26, v33 dst_sel:DWORD dst_unused:UNUSED_PAD src0_sel:WORD_1 src1_sel:DWORD
	v_add3_u32 v3, v26, v3, s27
	v_add3_u32 v2, v27, v2, s27
	v_and_b32_sdwa v26, v1, v33 dst_sel:DWORD dst_unused:UNUSED_PAD src0_sel:WORD_1 src1_sel:DWORD
	v_and_b32_sdwa v27, v0, v33 dst_sel:DWORD dst_unused:UNUSED_PAD src0_sel:WORD_1 src1_sel:DWORD
	v_add3_u32 v1, v1, v26, s27
	v_add3_u32 v0, v0, v27, s27
	v_and_b32_e32 v1, 0xffff0000, v1
	v_and_b32_e32 v0, 0xffff0000, v0
	v_or_b32_sdwa v1, v1, v2 dst_sel:DWORD dst_unused:UNUSED_PAD src0_sel:DWORD src1_sel:WORD_1
	v_or_b32_sdwa v0, v0, v3 dst_sel:DWORD dst_unused:UNUSED_PAD src0_sel:DWORD src1_sel:WORD_1
	global_store_dwordx2 v[16:17], v[0:1], off
	v_pk_mul_f32 v[0:1], v[36:37], v[24:25] op_sel_hi:[0,1]
	v_pk_mul_f32 v[0:1], v[22:23], v[0:1]
	s_nop 0
	v_and_b32_sdwa v3, v0, v33 dst_sel:DWORD dst_unused:UNUSED_PAD src0_sel:WORD_1 src1_sel:DWORD
	v_and_b32_sdwa v2, v1, v33 dst_sel:DWORD dst_unused:UNUSED_PAD src0_sel:WORD_1 src1_sel:DWORD
	v_add3_u32 v0, v0, v3, s27
	v_add3_u32 v1, v1, v2, s27
	v_lshrrev_b32_e32 v0, 16, v0
	v_and_or_b32 v0, v1, s13, v0
	global_store_dword v[18:19], v0, off
	s_and_saveexec_b64 s[0:1], s[2:3]
	s_cbranch_execz .LBB0_1807
	v_and_or_b32 v0, v30, s28, v64
	v_lshlrev_b32_e32 v1, 2, v0
	s_waitcnt vmcnt(3)
	v_mov_b32_e32 v0, v49
	v_pk_mul_f32 v[0:1], v[20:21], v[0:1] op_sel:[1,0] op_sel_hi:[0,0]
	s_waitcnt vmcnt(2)
	v_mov_b32_e32 v2, v50
	v_pk_fma_f32 v[16:17], v[20:21], v[2:3], v[0:1]
	v_pk_fma_f32 v[0:1], v[20:21], v[2:3], v[0:1] op_sel_hi:[1,0,1] neg_lo:[0,0,1] neg_hi:[0,0,1]
	v_and_b32_sdwa v2, v16, v33 dst_sel:DWORD dst_unused:UNUSED_PAD src0_sel:WORD_1 src1_sel:DWORD
	v_and_b32_sdwa v0, v1, v33 dst_sel:DWORD dst_unused:UNUSED_PAD src0_sel:WORD_1 src1_sel:DWORD
	v_add3_u32 v0, v1, v0, s27
	v_add3_u32 v2, v16, v2, s27
	v_lshrrev_b32_e32 v0, 16, v0
	v_and_or_b32 v2, v2, s13, v0
	v_lshl_add_u64 v[0:1], s[96:97], 0, v[8:9]
	global_store_dword v[0:1], v2, off
	s_branch .LBB0_1807

; #define LAS __attribute__((address_space(3)))
; __device__ __forceinline__ unsigned cvtpk2(float lo, float hi) { const f32x2 v = {lo, hi}; const bf16x2_n b = __builtin_convertvector(v, bf16x2_n); return __builtin_bit_cast(unsigned, b); }
; __device__ __forceinline__ void a2_exp_pack(f32x16& st0, f32x16& st1, float& lsum, bf16x8 (&pf)[4]) {
;     float ps = 0.f;
; #pragma unroll
;     for (int r = 0; r < 16; ++r) { st0[r] = __builtin_amdgcn_exp2f(st0[r]); st1[r] = __builtin_amdgcn_exp2f(st1[r]); ps += st0[r] + st1[r]; }
;     lsum += ps;
;     u32x4 w;
;     w.x = cvtpk2(st0[0], st0[1]); w.y = cvtpk2(st0[2], st0[3]); w.z = cvtpk2(st0[4], st0[5]); w.w = cvtpk2(st0[6], st0[7]); pf[0] = __builtin_bit_cast(bf16x8, w);
;     w.x = cvtpk2(st0[8], st0[9]); w.y = cvtpk2(st0[10], st0[11]); w.z = cvtpk2(st0[12], st0[13]); w.w = cvtpk2(st0[14], st0[15]); pf[1] = __builtin_bit_cast(bf16x8, w);
;     w.x = cvtpk2(st1[0], st1[1]); w.y = cvtpk2(st1[2], st1[3]); w.z = cvtpk2(st1[4], st1[5]); w.w = cvtpk2(st1[6], st1[7]); pf[2] = __builtin_bit_cast(bf16x8, w);
;     w.x = cvtpk2(st1[8], st1[9]); w.y = cvtpk2(st1[10], st1[11]); w.z = cvtpk2(st1[12], st1[13]); w.w = cvtpk2(st1[14], st1[15]); pf[3] = __builtin_bit_cast(bf16x8, w);
; }
; __device__ __forceinline__ void a2_pv(const LAS unsigned char* vb, const bf16x8 (&pf)[4], f32x16& ot0, f32x16& ot1) {
; #pragma unroll
;     for (int s = 0; s < 4; ++s) {
;         const s16x4 a00 = __builtin_bit_cast(s16x4, __builtin_amdgcn_ds_read_tr16_b64_v4i16((LAS s16x4*)(vb + (16 * s) * 64)));
;         const s16x4 a01 = __builtin_bit_cast(s16x4, __builtin_amdgcn_ds_read_tr16_b64_v4i16((LAS s16x4*)(vb + (16 * s + 8) * 64)));
;         const s16x4 a10 = __builtin_bit_cast(s16x4, __builtin_amdgcn_ds_read_tr16_b64_v4i16((LAS s16x4*)(vb + 8192 + (16 * s) * 64)));
;         const s16x4 a11 = __builtin_bit_cast(s16x4, __builtin_amdgcn_ds_read_tr16_b64_v4i16((LAS s16x4*)(vb + 8192 + (16 * s + 8) * 64)));
;         const bf16x8 va0 = (bf16x8){a00[0], a00[1], a00[2], a00[3], a01[0], a01[1], a01[2], a01[3]};
;         const bf16x8 va1 = (bf16x8){a10[0], a10[1], a10[2], a10[3], a11[0], a11[1], a11[2], a11[3]};
;         ot0 = __builtin_amdgcn_mfma_f32_32x32x16_bf16(va0, pf[s], ot0, 0, 0, 0); ot1 = __builtin_amdgcn_mfma_f32_32x32x16_bf16(va1, pf[s], ot1, 0, 0, 0); }
; }
.LBB0_2243:
	v_add_u32_e32 v0, v2, v218
	v_exp_f32_e32 v199, v112
	v_exp_f32_e32 v7, v96
	v_exp_f32_e32 v113, v113
	v_exp_f32_e32 v9, v97
	v_exp_f32_e32 v201, v114
	v_exp_f32_e32 v3, v98
	v_exp_f32_e32 v115, v115
	v_exp_f32_e32 v5, v99
	v_exp_f32_e32 v203, v116
	v_exp_f32_e32 v15, v117
	v_exp_f32_e32 v13, v118
	v_exp_f32_e32 v11, v119
	s_waitcnt vmcnt(0)
	ds_read_b64_tr_b16 v[96:97], v0 offset:26624
	ds_read_b64_tr_b16 v[98:99], v0 offset:27136
	ds_read_b64_tr_b16 v[214:215], v0 offset:34816
	ds_read_b64_tr_b16 v[216:217], v0 offset:35328
	ds_read_b64_tr_b16 v[220:221], v0 offset:27648
	ds_read_b64_tr_b16 v[222:223], v0 offset:28160
	v_cvt_pk_bf16_f32 v210, v199, v113
	v_cvt_pk_bf16_f32 v211, v201, v115
	v_cvt_pk_bf16_f32 v212, v203, v15
	v_cvt_pk_bf16_f32 v213, v13, v11
	v_exp_f32_e32 v209, v120
	v_exp_f32_e32 v207, v121
	s_waitcnt lgkmcnt(4)
	v_mfma_f32_32x32x16_bf16 v[16:31], v[96:99], v[210:213], v[16:31]
	v_exp_f32_e32 v205, v122
	v_exp_f32_e32 v121, v123
	v_exp_f32_e32 v117, v124
	ds_read_b64_tr_b16 v[224:225], v0 offset:35840
	ds_read_b64_tr_b16 v[226:227], v0 offset:36352
	v_exp_f32_e32 v119, v125
	v_exp_f32_e32 v99, v126
	v_exp_f32_e32 v97, v127
	s_waitcnt lgkmcnt(4)
	v_mfma_f32_32x32x16_bf16 v[32:47], v[214:217], v[210:213], v[32:47]
	v_cvt_pk_bf16_f32 v228, v209, v207
	v_cvt_pk_bf16_f32 v229, v205, v121
	v_cvt_pk_bf16_f32 v230, v117, v119
	v_cvt_pk_bf16_f32 v231, v99, v97
	v_exp_f32_e32 v125, v100
	v_exp_f32_e32 v213, v101
	v_exp_f32_e32 v211, v102
	s_waitcnt lgkmcnt(2)
	v_mfma_f32_32x32x16_bf16 v[16:31], v[220:223], v[228:231], v[16:31]
	v_exp_f32_e32 v217, v103
	ds_read_b64_tr_b16 v[220:221], v0 offset:28672
	ds_read_b64_tr_b16 v[222:223], v0 offset:29184
	v_cvt_pk_bf16_f32 v100, v7, v9
	v_cvt_pk_bf16_f32 v101, v3, v5
	v_cvt_pk_bf16_f32 v102, v125, v213
	v_cvt_pk_bf16_f32 v103, v211, v217
	v_exp_f32_e32 v123, v104
	s_waitcnt lgkmcnt(2)
	v_mfma_f32_32x32x16_bf16 v[32:47], v[224:227], v[228:231], v[32:47]
	ds_read_b64_tr_b16 v[224:225], v0 offset:36864
	ds_read_b64_tr_b16 v[226:227], v0 offset:37376
	ds_read_b64_tr_b16 v[228:229], v0 offset:29696
	ds_read_b64_tr_b16 v[230:231], v0 offset:30208
	v_exp_f32_e32 v127, v105
	v_exp_f32_e32 v105, v106
	v_exp_f32_e32 v215, v107
	v_exp_f32_e32 v107, v108
	v_exp_f32_e32 v109, v109
	v_exp_f32_e32 v198, v64
	s_waitcnt lgkmcnt(4)
	v_mfma_f32_32x32x16_bf16 v[16:31], v[220:223], v[100:103], v[16:31]
	ds_read_b64_tr_b16 v[220:221], v0 offset:37888
	ds_read_b64_tr_b16 v[222:223], v0 offset:38400
	v_exp_f32_e32 v6, v80
	v_exp_f32_e32 v112, v65
	v_exp_f32_e32 v8, v81
	v_exp_f32_e32 v200, v66
	v_exp_f32_e32 v2, v82
	v_exp_f32_e32 v114, v67
	s_waitcnt lgkmcnt(4)
	v_mfma_f32_32x32x16_bf16 v[32:47], v[224:227], v[100:103], v[32:47]
	v_exp_f32_e32 v103, v110
	v_exp_f32_e32 v101, v111
	v_exp_f32_e32 v4, v83
	v_cvt_pk_bf16_f32 v224, v123, v127
	v_cvt_pk_bf16_f32 v225, v105, v215
	v_cvt_pk_bf16_f32 v226, v107, v109
	v_cvt_pk_bf16_f32 v227, v103, v101
	v_pk_add_f32 v[64:65], v[6:7], v[198:199]
	v_pk_add_f32 v[66:67], v[8:9], v[112:113]
	s_waitcnt lgkmcnt(2)
	v_mfma_f32_32x32x16_bf16 v[16:31], v[228:231], v[224:227], v[16:31]
	v_add_f32_e64 v64, v64, 0
	v_add_f32_e64 v65, v65, 0
	v_exp_f32_e32 v202, v68
	v_pk_add_f32 v[64:65], v[66:67], v[64:65]
	v_pk_add_f32 v[66:67], v[2:3], v[200:201]
	v_exp_f32_e32 v14, v69
	v_pk_add_f32 v[64:65], v[66:67], v[64:65]
	v_pk_add_f32 v[66:67], v[4:5], v[114:115]
	s_waitcnt lgkmcnt(0)
	v_mfma_f32_32x32x16_bf16 v[32:47], v[220:223], v[224:227], v[32:47]
	v_add_f32_e64 v110, v66, v64
	v_add_f32_e64 v111, v67, v65
	v_exp_f32_e32 v12, v70
	v_exp_f32_e32 v10, v71
	ds_read_b64_tr_b16 v[64:65], v0 offset:30720
	ds_read_b64_tr_b16 v[66:67], v0 offset:31232
	v_exp_f32_e32 v124, v84
	v_exp_f32_e32 v208, v72
	v_exp_f32_e32 v206, v73
	v_exp_f32_e32 v204, v74
	v_exp_f32_e32 v120, v75
	ds_read_b64_tr_b16 v[72:73], v0 offset:38912
	ds_read_b64_tr_b16 v[74:75], v0 offset:39424
	ds_read_b64_tr_b16 v[80:81], v0 offset:31744
	ds_read_b64_tr_b16 v[82:83], v0 offset:32256
	v_exp_f32_e32 v212, v85
	v_cvt_pk_bf16_f32 v68, v198, v112
	v_cvt_pk_bf16_f32 v69, v200, v114
	v_cvt_pk_bf16_f32 v70, v202, v14
	v_cvt_pk_bf16_f32 v71, v12, v10
	v_pk_add_f32 v[220:221], v[124:125], v[202:203]
	v_exp_f32_e32 v210, v86
	s_waitcnt lgkmcnt(4)
; __device__ __forceinline__ void a2_pv(const LAS unsigned char* vb, const bf16x8 (&pf)[4], f32x16& ot0, f32x16& ot1) {
; #pragma unroll
;     for (int s = 0; s < 4; ++s) {
;         const s16x4 a00 = __builtin_bit_cast(s16x4, __builtin_amdgcn_ds_read_tr16_b64_v4i16((LAS s16x4*)(vb + (16 * s) * 64)));
;         const s16x4 a01 = __builtin_bit_cast(s16x4, __builtin_amdgcn_ds_read_tr16_b64_v4i16((LAS s16x4*)(vb + (16 * s + 8) * 64)));
;         const s16x4 a10 = __builtin_bit_cast(s16x4, __builtin_amdgcn_ds_read_tr16_b64_v4i16((LAS s16x4*)(vb + 8192 + (16 * s) * 64)));
;         const s16x4 a11 = __builtin_bit_cast(s16x4, __builtin_amdgcn_ds_read_tr16_b64_v4i16((LAS s16x4*)(vb + 8192 + (16 * s + 8) * 64)));
;         const bf16x8 va0 = (bf16x8){a00[0], a00[1], a00[2], a00[3], a01[0], a01[1], a01[2], a01[3]};
;         const bf16x8 va1 = (bf16x8){a10[0], a10[1], a10[2], a10[3], a11[0], a11[1], a11[2], a11[3]};
;         ot0 = __builtin_amdgcn_mfma_f32_32x32x16_bf16(va0, pf[s], ot0, 0, 0, 0); ot1 = __builtin_amdgcn_mfma_f32_32x32x16_bf16(va1, pf[s], ot1, 0, 0, 0); }
; }
; __device__ __forceinline__ void attn2_unit(bf16_t* Z, const bf16_t* Hb, const float* rc, const float* rs, LAS unsigned char* lds, int b, int h, int qblk) {
;     ...
;     for (int kp = 0; kp < npairs; ++kp) {
;         const int sb = (kp & 1) * A2_STAGE, sbn = A2_STAGE - sb;
;         const bool more = kp + 1 < npairs;
;         if (more) A2_STAGE_LOAD(sbn, kp + 1);
;         const LAS unsigned char* kb = lds + sb + kboff; const LAS unsigned char* vb = lds + sb + vboff;
;         if (2 * kp + 1 <= cw) {
;             f32x16 sa0, sa1, sb0, sb1; bf16x8 pa[4], pb[4];
;             __builtin_amdgcn_s_setprio(1);
;             a2_qk(kb, qf, cneg, sa0, sa1);
;             a2_qk(kb + 64 * AT_KROW, qf, cneg, sb0, sb1);
;             __builtin_amdgcn_s_setprio(0);
;             const float mt = fmaxf(a2_max(sa0, sa1), a2_max(sb0, sb1));
;             if (kp == 0 || __builtin_amdgcn_ballot_w64(mt > 8.f) != 0ull) {
;                 const float delta = (kp == 0) ? mt : fmaxf(mt, 0.f), alpha = (kp == 0) ? 0.f : __builtin_amdgcn_exp2f(-delta);
;                 mrun += delta; lsum *= alpha;
; #pragma unroll
;                 for (int r = 0; r < 16; ++r) { ot0[r] *= alpha; ot1[r] *= alpha; sa0[r] -= delta; sa1[r] -= delta; sb0[r] -= delta; sb1[r] -= delta; cneg[r] = -mrun; }
;             }
	v_mfma_f32_32x32x16_bf16 v[16:31], v[64:67], v[68:71], v[16:31]
	v_add_f32_e64 v64, v220, v110
	v_add_f32_e64 v65, v221, v111
	v_add_f32_e64 v14, v212, v14
	v_add_f32_e64 v15, v213, v15
	v_exp_f32_e32 v216, v87
	v_exp_f32_e32 v116, v76
	v_exp_f32_e32 v118, v77
	v_exp_f32_e32 v98, v78
	v_exp_f32_e32 v96, v79
	s_waitcnt lgkmcnt(2)
	v_mfma_f32_32x32x16_bf16 v[32:47], v[72:75], v[68:71], v[32:47]
	v_add_f32_e64 v14, v14, v64
	v_add_f32_e64 v15, v15, v65
	ds_read_b64_tr_b16 v[64:65], v0 offset:39936
	ds_read_b64_tr_b16 v[66:67], v0 offset:40448
	v_exp_f32_e32 v122, v88
	v_pk_add_f32 v[12:13], v[210:211], v[12:13]
	v_pk_add_f32 v[68:69], v[216:217], v[10:11]
	v_pk_add_f32 v[14:15], v[12:13], v[14:15]
	v_cvt_pk_bf16_f32 v10, v208, v206
	v_cvt_pk_bf16_f32 v11, v204, v120
	v_cvt_pk_bf16_f32 v12, v116, v118
	v_cvt_pk_bf16_f32 v13, v98, v96
	v_pk_add_f32 v[14:15], v[68:69], v[14:15]
	v_pk_add_f32 v[68:69], v[122:123], v[208:209]
	s_waitcnt lgkmcnt(2)
	v_mfma_f32_32x32x16_bf16 v[16:31], v[80:83], v[10:13], v[16:31]
	v_add_f32_e64 v14, v68, v14
	v_add_f32_e64 v15, v69, v15
	ds_read_b64_tr_b16 v[68:69], v0 offset:32768
	ds_read_b64_tr_b16 v[70:71], v0 offset:33280
	v_exp_f32_e32 v126, v89
	v_exp_f32_e32 v104, v90
	v_cvt_pk_bf16_f32 v7, v2, v4
	v_exp_f32_e32 v214, v91
	v_cvt_pk_bf16_f32 v6, v6, v8
	s_waitcnt lgkmcnt(2)
	v_mfma_f32_32x32x16_bf16 v[32:47], v[64:67], v[10:13], v[32:47]
	ds_read_b64_tr_b16 v[2:3], v0 offset:40960
	ds_read_b64_tr_b16 v[4:5], v0 offset:41472
	ds_read_b64_tr_b16 v[10:11], v0 offset:33792
	ds_read_b64_tr_b16 v[12:13], v0 offset:34304
	v_cvt_pk_bf16_f32 v8, v124, v212
	v_cvt_pk_bf16_f32 v9, v210, v216
	v_pk_add_f32 v[72:73], v[126:127], v[206:207]
	v_pk_add_f32 v[64:65], v[104:105], v[204:205]
	v_pk_add_f32 v[14:15], v[72:73], v[14:15]
	v_exp_f32_e32 v106, v92
	s_waitcnt lgkmcnt(4)
	v_mfma_f32_32x32x16_bf16 v[16:31], v[68:71], v[6:9], v[16:31]
	v_add_f32_e64 v14, v64, v14
	v_add_f32_e64 v15, v65, v15
	v_add_f32_e64 v64, v214, v120
	v_add_f32_e64 v65, v215, v121
	v_exp_f32_e32 v108, v93
	v_exp_f32_e32 v102, v94
	v_exp_f32_e32 v100, v95
	v_pk_add_f32 v[14:15], v[64:65], v[14:15]
	ds_read_b64_tr_b16 v[64:65], v0 offset:41984
	ds_read_b64_tr_b16 v[66:67], v0 offset:42496
	s_waitcnt lgkmcnt(4)
	v_mfma_f32_32x32x16_bf16 v[32:47], v[2:5], v[6:9], v[32:47]
	v_add_f32_e64 v2, v106, v116
	v_add_f32_e64 v3, v107, v117
	v_cvt_pk_bf16_f32 v4, v106, v108
	v_add_f32_e64 v6, v2, v14
	v_add_f32_e64 v7, v3, v15
	v_cvt_pk_bf16_f32 v2, v122, v126
	v_cvt_pk_bf16_f32 v3, v104, v214
	v_cvt_pk_bf16_f32 v5, v102, v100
	v_pk_add_f32 v[8:9], v[108:109], v[118:119]
	v_mov_b32_e32 v14, v55
	s_waitcnt lgkmcnt(2)
	v_mfma_f32_32x32x16_bf16 v[16:31], v[10:13], v[2:5], v[16:31]
	v_add_f32_e64 v6, v8, v6
	v_add_f32_e64 v7, v9, v7
	v_add_f32_e64 v8, v102, v98
	v_add_f32_e64 v9, v103, v99
	v_mov_b32_e32 v10, v59
	v_pk_add_f32 v[6:7], v[8:9], v[6:7]
	v_pk_add_f32 v[8:9], v[100:101], v[96:97]
	v_mov_b32_e32 v11, v58
	v_pk_add_f32 v[6:7], v[8:9], v[6:7]
	s_waitcnt lgkmcnt(0)
	v_mfma_f32_32x32x16_bf16 v[32:47], v[64:67], v[2:5], v[32:47]
	v_add_f32_e32 v0, v169, v7
	v_add_f32_e32 v0, v6, v0
	s_add_i32 s47, s47, 1
	s_add_i32 s48, s48, 2
	s_add_i32 s6, s37, s47
	v_lshl_add_u64 v[176:177], v[176:177], 0, v[174:175]
	v_lshl_add_u64 v[178:179], v[178:179], 0, s[18:19]
	v_lshl_add_u64 v[180:181], v[180:181], 0, s[18:19]
	v_lshl_add_u64 v[184:185], v[184:185], 0, v[182:183]
	v_lshl_add_u64 v[188:189], v[188:189], 0, v[186:187]
	s_cmp_lg_u32 s6, 1
	v_lshl_add_u64 v[194:195], v[194:195], 0, v[190:191]
	s_waitcnt vmcnt(0) lgkmcnt(0)
	s_barrier
	s_cbranch_scc0 .Lattn_exit_2
	v_mov_b32_e32 v169, v0
	s_bitcmp1_b32 s47, 0
	s_cselect_b32 s6, 0, 0xa800
	s_cmp_ge_u32 s47, s34
	s_cbranch_scc0 .LBB0_2221
	s_branch .LBB0_2224

; #define LAS __attribute__((address_space(3)))
; __device__ __forceinline__ unsigned cvtpk2(float lo, float hi) { const f32x2 v = {lo, hi}; const bf16x2_n b = __builtin_convertvector(v, bf16x2_n); return __builtin_bit_cast(unsigned, b); }
; __device__ __forceinline__ void a2_exp_pack(f32x16& st0, f32x16& st1, float& lsum, bf16x8 (&pf)[4]) {
;     float ps = 0.f;
; #pragma unroll
;     for (int r = 0; r < 16; ++r) { st0[r] = __builtin_amdgcn_exp2f(st0[r]); st1[r] = __builtin_amdgcn_exp2f(st1[r]); ps += st0[r] + st1[r]; }
;     lsum += ps;
;     u32x4 w;
;     w.x = cvtpk2(st0[0], st0[1]); w.y = cvtpk2(st0[2], st0[3]); w.z = cvtpk2(st0[4], st0[5]); w.w = cvtpk2(st0[6], st0[7]); pf[0] = __builtin_bit_cast(bf16x8, w);
;     w.x = cvtpk2(st0[8], st0[9]); w.y = cvtpk2(st0[10], st0[11]); w.z = cvtpk2(st0[12], st0[13]); w.w = cvtpk2(st0[14], st0[15]); pf[1] = __builtin_bit_cast(bf16x8, w);
;     w.x = cvtpk2(st1[0], st1[1]); w.y = cvtpk2(st1[2], st1[3]); w.z = cvtpk2(st1[4], st1[5]); w.w = cvtpk2(st1[6], st1[7]); pf[2] = __builtin_bit_cast(bf16x8, w);
;     w.x = cvtpk2(st1[8], st1[9]); w.y = cvtpk2(st1[10], st1[11]); w.z = cvtpk2(st1[12], st1[13]); w.w = cvtpk2(st1[14], st1[15]); pf[3] = __builtin_bit_cast(bf16x8, w);
; }
; __device__ __forceinline__ void a2_pv(const LAS unsigned char* vb, const bf16x8 (&pf)[4], f32x16& ot0, f32x16& ot1) {
; #pragma unroll
;     for (int s = 0; s < 4; ++s) {
;         const s16x4 a00 = __builtin_bit_cast(s16x4, __builtin_amdgcn_ds_read_tr16_b64_v4i16((LAS s16x4*)(vb + (16 * s) * 64)));
;         const s16x4 a01 = __builtin_bit_cast(s16x4, __builtin_amdgcn_ds_read_tr16_b64_v4i16((LAS s16x4*)(vb + (16 * s + 8) * 64)));
;         const s16x4 a10 = __builtin_bit_cast(s16x4, __builtin_amdgcn_ds_read_tr16_b64_v4i16((LAS s16x4*)(vb + 8192 + (16 * s) * 64)));
;         const s16x4 a11 = __builtin_bit_cast(s16x4, __builtin_amdgcn_ds_read_tr16_b64_v4i16((LAS s16x4*)(vb + 8192 + (16 * s + 8) * 64)));
;         const bf16x8 va0 = (bf16x8){a00[0], a00[1], a00[2], a00[3], a01[0], a01[1], a01[2], a01[3]};
;         const bf16x8 va1 = (bf16x8){a10[0], a10[1], a10[2], a10[3], a11[0], a11[1], a11[2], a11[3]};
;         ot0 = __builtin_amdgcn_mfma_f32_32x32x16_bf16(va0, pf[s], ot0, 0, 0, 0); ot1 = __builtin_amdgcn_mfma_f32_32x32x16_bf16(va1, pf[s], ot1, 0, 0, 0); }
; }
.LBB0_2289:
	v_add_u32_e32 v0, v2, v218
	v_exp_f32_e32 v195, v112
	v_exp_f32_e32 v7, v96
	v_exp_f32_e32 v113, v113
	v_exp_f32_e32 v9, v97
	v_exp_f32_e32 v199, v114
	v_exp_f32_e32 v3, v98
	v_exp_f32_e32 v115, v115
	v_exp_f32_e32 v5, v99
	v_exp_f32_e32 v201, v116
	v_exp_f32_e32 v15, v117
	v_exp_f32_e32 v13, v118
	v_exp_f32_e32 v11, v119
	s_waitcnt vmcnt(0)
	ds_read_b64_tr_b16 v[96:97], v0 offset:26624
	ds_read_b64_tr_b16 v[98:99], v0 offset:27136
	ds_read_b64_tr_b16 v[212:213], v0 offset:34816
	ds_read_b64_tr_b16 v[214:215], v0 offset:35328
	ds_read_b64_tr_b16 v[220:221], v0 offset:27648
	ds_read_b64_tr_b16 v[222:223], v0 offset:28160
	v_cvt_pk_bf16_f32 v208, v195, v113
	v_cvt_pk_bf16_f32 v209, v199, v115
	v_cvt_pk_bf16_f32 v210, v201, v15
	v_cvt_pk_bf16_f32 v211, v13, v11
	v_exp_f32_e32 v207, v120
	v_exp_f32_e32 v205, v121
	s_waitcnt lgkmcnt(4)
	v_mfma_f32_32x32x16_bf16 v[16:31], v[96:99], v[208:211], v[16:31]
	v_exp_f32_e32 v203, v122
	v_exp_f32_e32 v121, v123
	v_exp_f32_e32 v117, v124
	ds_read_b64_tr_b16 v[224:225], v0 offset:35840
	ds_read_b64_tr_b16 v[226:227], v0 offset:36352
	v_exp_f32_e32 v119, v125
	v_exp_f32_e32 v99, v126
	v_exp_f32_e32 v97, v127
	s_waitcnt lgkmcnt(4)
	v_mfma_f32_32x32x16_bf16 v[32:47], v[212:215], v[208:211], v[32:47]
	v_cvt_pk_bf16_f32 v228, v207, v205
	v_cvt_pk_bf16_f32 v229, v203, v121
	v_cvt_pk_bf16_f32 v230, v117, v119
	v_cvt_pk_bf16_f32 v231, v99, v97
	v_exp_f32_e32 v125, v100
	v_exp_f32_e32 v211, v101
	v_exp_f32_e32 v209, v102
	s_waitcnt lgkmcnt(2)
	v_mfma_f32_32x32x16_bf16 v[16:31], v[220:223], v[228:231], v[16:31]
	v_exp_f32_e32 v215, v103
	ds_read_b64_tr_b16 v[220:221], v0 offset:28672
	ds_read_b64_tr_b16 v[222:223], v0 offset:29184
	v_cvt_pk_bf16_f32 v100, v7, v9
	v_cvt_pk_bf16_f32 v101, v3, v5
	v_cvt_pk_bf16_f32 v102, v125, v211
	v_cvt_pk_bf16_f32 v103, v209, v215
	v_exp_f32_e32 v123, v104
	s_waitcnt lgkmcnt(2)
	v_mfma_f32_32x32x16_bf16 v[32:47], v[224:227], v[228:231], v[32:47]
	ds_read_b64_tr_b16 v[224:225], v0 offset:36864
	ds_read_b64_tr_b16 v[226:227], v0 offset:37376
	ds_read_b64_tr_b16 v[228:229], v0 offset:29696
	ds_read_b64_tr_b16 v[230:231], v0 offset:30208
	v_exp_f32_e32 v127, v105
	v_exp_f32_e32 v105, v106
	v_exp_f32_e32 v213, v107
	v_exp_f32_e32 v107, v108
	v_exp_f32_e32 v109, v109
	v_exp_f32_e32 v194, v64
	s_waitcnt lgkmcnt(4)
	v_mfma_f32_32x32x16_bf16 v[16:31], v[220:223], v[100:103], v[16:31]
	ds_read_b64_tr_b16 v[220:221], v0 offset:37888
	ds_read_b64_tr_b16 v[222:223], v0 offset:38400
	v_exp_f32_e32 v6, v80
	v_exp_f32_e32 v112, v65
	v_exp_f32_e32 v8, v81
	v_exp_f32_e32 v198, v66
	v_exp_f32_e32 v2, v82
	v_exp_f32_e32 v114, v67
	s_waitcnt lgkmcnt(4)
	v_mfma_f32_32x32x16_bf16 v[32:47], v[224:227], v[100:103], v[32:47]
	v_exp_f32_e32 v103, v110
	v_exp_f32_e32 v101, v111
	v_exp_f32_e32 v4, v83
	v_cvt_pk_bf16_f32 v224, v123, v127
	v_cvt_pk_bf16_f32 v225, v105, v213
	v_cvt_pk_bf16_f32 v226, v107, v109
	v_cvt_pk_bf16_f32 v227, v103, v101
	v_pk_add_f32 v[64:65], v[6:7], v[194:195]
	v_pk_add_f32 v[66:67], v[8:9], v[112:113]
	s_waitcnt lgkmcnt(2)
	v_mfma_f32_32x32x16_bf16 v[16:31], v[228:231], v[224:227], v[16:31]
	v_add_f32_e64 v64, v64, 0
	v_add_f32_e64 v65, v65, 0
	v_exp_f32_e32 v200, v68
	v_pk_add_f32 v[64:65], v[66:67], v[64:65]
	v_pk_add_f32 v[66:67], v[2:3], v[198:199]
	v_exp_f32_e32 v14, v69
	v_pk_add_f32 v[64:65], v[66:67], v[64:65]
	v_pk_add_f32 v[66:67], v[4:5], v[114:115]
	s_waitcnt lgkmcnt(0)
	v_mfma_f32_32x32x16_bf16 v[32:47], v[220:223], v[224:227], v[32:47]
	v_add_f32_e64 v110, v66, v64
	v_add_f32_e64 v111, v67, v65
	v_exp_f32_e32 v12, v70
	v_exp_f32_e32 v10, v71
	ds_read_b64_tr_b16 v[64:65], v0 offset:30720
	ds_read_b64_tr_b16 v[66:67], v0 offset:31232
	v_exp_f32_e32 v124, v84
	v_exp_f32_e32 v206, v72
	v_exp_f32_e32 v204, v73
	v_exp_f32_e32 v202, v74
	v_exp_f32_e32 v120, v75
	ds_read_b64_tr_b16 v[72:73], v0 offset:38912
	ds_read_b64_tr_b16 v[74:75], v0 offset:39424
	ds_read_b64_tr_b16 v[80:81], v0 offset:31744
	ds_read_b64_tr_b16 v[82:83], v0 offset:32256
	v_exp_f32_e32 v210, v85
	v_cvt_pk_bf16_f32 v68, v194, v112
	v_cvt_pk_bf16_f32 v69, v198, v114
	v_cvt_pk_bf16_f32 v70, v200, v14
	v_cvt_pk_bf16_f32 v71, v12, v10
	v_pk_add_f32 v[216:217], v[124:125], v[200:201]
	v_exp_f32_e32 v208, v86
	s_waitcnt lgkmcnt(4)
	v_mfma_f32_32x32x16_bf16 v[16:31], v[64:67], v[68:71], v[16:31]
	v_add_f32_e64 v64, v216, v110
	v_add_f32_e64 v65, v217, v111
	v_add_f32_e64 v14, v210, v14
	v_add_f32_e64 v15, v211, v15
	v_exp_f32_e32 v214, v87
	v_exp_f32_e32 v116, v76
	v_exp_f32_e32 v118, v77
	v_exp_f32_e32 v98, v78
	v_exp_f32_e32 v96, v79
	s_waitcnt lgkmcnt(2)
; __device__ __forceinline__ void a2_pv(const LAS unsigned char* vb, const bf16x8 (&pf)[4], f32x16& ot0, f32x16& ot1) {
; #pragma unroll
;     for (int s = 0; s < 4; ++s) {
;         const s16x4 a00 = __builtin_bit_cast(s16x4, __builtin_amdgcn_ds_read_tr16_b64_v4i16((LAS s16x4*)(vb + (16 * s) * 64)));
;         const s16x4 a01 = __builtin_bit_cast(s16x4, __builtin_amdgcn_ds_read_tr16_b64_v4i16((LAS s16x4*)(vb + (16 * s + 8) * 64)));
;         const s16x4 a10 = __builtin_bit_cast(s16x4, __builtin_amdgcn_ds_read_tr16_b64_v4i16((LAS s16x4*)(vb + 8192 + (16 * s) * 64)));
;         const s16x4 a11 = __builtin_bit_cast(s16x4, __builtin_amdgcn_ds_read_tr16_b64_v4i16((LAS s16x4*)(vb + 8192 + (16 * s + 8) * 64)));
;         const bf16x8 va0 = (bf16x8){a00[0], a00[1], a00[2], a00[3], a01[0], a01[1], a01[2], a01[3]};
;         const bf16x8 va1 = (bf16x8){a10[0], a10[1], a10[2], a10[3], a11[0], a11[1], a11[2], a11[3]};
;         ot0 = __builtin_amdgcn_mfma_f32_32x32x16_bf16(va0, pf[s], ot0, 0, 0, 0); ot1 = __builtin_amdgcn_mfma_f32_32x32x16_bf16(va1, pf[s], ot1, 0, 0, 0); }
; }
; __device__ __forceinline__ void attn2_unit(bf16_t* Z, const bf16_t* Hb, const float* rc, const float* rs, LAS unsigned char* lds, int b, int h, int qblk) {
;     ...
;     for (int kp = 0; kp < npairs; ++kp) {
;         const int sb = (kp & 1) * A2_STAGE, sbn = A2_STAGE - sb;
;         const bool more = kp + 1 < npairs;
;         if (more) A2_STAGE_LOAD(sbn, kp + 1);
;         const LAS unsigned char* kb = lds + sb + kboff; const LAS unsigned char* vb = lds + sb + vboff;
;         if (2 * kp + 1 <= cw) {
;             f32x16 sa0, sa1, sb0, sb1; bf16x8 pa[4], pb[4];
;             __builtin_amdgcn_s_setprio(1);
;             a2_qk(kb, qf, cneg, sa0, sa1);
;             a2_qk(kb + 64 * AT_KROW, qf, cneg, sb0, sb1);
;             __builtin_amdgcn_s_setprio(0);
;             const float mt = fmaxf(a2_max(sa0, sa1), a2_max(sb0, sb1));
;             if (kp == 0 || __builtin_amdgcn_ballot_w64(mt > 8.f) != 0ull) {
;                 const float delta = (kp == 0) ? mt : fmaxf(mt, 0.f), alpha = (kp == 0) ? 0.f : __builtin_amdgcn_exp2f(-delta);
;                 mrun += delta; lsum *= alpha;
; #pragma unroll
;                 for (int r = 0; r < 16; ++r) { ot0[r] *= alpha; ot1[r] *= alpha; sa0[r] -= delta; sa1[r] -= delta; sb0[r] -= delta; sb1[r] -= delta; cneg[r] = -mrun; }
;             }
	v_mfma_f32_32x32x16_bf16 v[32:47], v[72:75], v[68:71], v[32:47]
	v_add_f32_e64 v14, v14, v64
	v_add_f32_e64 v15, v15, v65
	ds_read_b64_tr_b16 v[64:65], v0 offset:39936
	ds_read_b64_tr_b16 v[66:67], v0 offset:40448
	v_exp_f32_e32 v122, v88
	v_pk_add_f32 v[12:13], v[208:209], v[12:13]
	v_pk_add_f32 v[68:69], v[214:215], v[10:11]
	v_pk_add_f32 v[14:15], v[12:13], v[14:15]
	v_cvt_pk_bf16_f32 v10, v206, v204
	v_cvt_pk_bf16_f32 v11, v202, v120
	v_cvt_pk_bf16_f32 v12, v116, v118
	v_cvt_pk_bf16_f32 v13, v98, v96
	v_pk_add_f32 v[14:15], v[68:69], v[14:15]
	v_pk_add_f32 v[68:69], v[122:123], v[206:207]
	s_waitcnt lgkmcnt(2)
	v_mfma_f32_32x32x16_bf16 v[16:31], v[80:83], v[10:13], v[16:31]
	v_add_f32_e64 v14, v68, v14
	v_add_f32_e64 v15, v69, v15
	ds_read_b64_tr_b16 v[68:69], v0 offset:32768
	ds_read_b64_tr_b16 v[70:71], v0 offset:33280
	v_exp_f32_e32 v126, v89
	v_exp_f32_e32 v104, v90
	v_cvt_pk_bf16_f32 v7, v2, v4
	v_exp_f32_e32 v212, v91
	v_cvt_pk_bf16_f32 v6, v6, v8
	s_waitcnt lgkmcnt(2)
	v_mfma_f32_32x32x16_bf16 v[32:47], v[64:67], v[10:13], v[32:47]
	ds_read_b64_tr_b16 v[2:3], v0 offset:40960
	ds_read_b64_tr_b16 v[4:5], v0 offset:41472
	ds_read_b64_tr_b16 v[10:11], v0 offset:33792
	ds_read_b64_tr_b16 v[12:13], v0 offset:34304
	v_cvt_pk_bf16_f32 v8, v124, v210
	v_cvt_pk_bf16_f32 v9, v208, v214
	v_pk_add_f32 v[72:73], v[126:127], v[204:205]
	v_pk_add_f32 v[64:65], v[104:105], v[202:203]
	v_pk_add_f32 v[14:15], v[72:73], v[14:15]
	v_exp_f32_e32 v106, v92
	s_waitcnt lgkmcnt(4)
	v_mfma_f32_32x32x16_bf16 v[16:31], v[68:71], v[6:9], v[16:31]
	v_add_f32_e64 v14, v64, v14
	v_add_f32_e64 v15, v65, v15
	v_add_f32_e64 v64, v212, v120
	v_add_f32_e64 v65, v213, v121
	v_exp_f32_e32 v108, v93
	v_exp_f32_e32 v102, v94
	v_exp_f32_e32 v100, v95
	v_pk_add_f32 v[14:15], v[64:65], v[14:15]
	ds_read_b64_tr_b16 v[64:65], v0 offset:41984
	ds_read_b64_tr_b16 v[66:67], v0 offset:42496
	s_waitcnt lgkmcnt(4)
	v_mfma_f32_32x32x16_bf16 v[32:47], v[2:5], v[6:9], v[32:47]
	v_add_f32_e64 v2, v106, v116
	v_add_f32_e64 v3, v107, v117
	v_cvt_pk_bf16_f32 v4, v106, v108
	v_add_f32_e64 v6, v2, v14
	v_add_f32_e64 v7, v3, v15
	v_cvt_pk_bf16_f32 v2, v122, v126
	v_cvt_pk_bf16_f32 v3, v104, v212
	v_cvt_pk_bf16_f32 v5, v102, v100
	v_pk_add_f32 v[8:9], v[108:109], v[118:119]
	v_mov_b32_e32 v14, v55
	s_waitcnt lgkmcnt(2)
	v_mfma_f32_32x32x16_bf16 v[16:31], v[10:13], v[2:5], v[16:31]
	v_add_f32_e64 v6, v8, v6
	v_add_f32_e64 v7, v9, v7
	v_add_f32_e64 v8, v102, v98
	v_add_f32_e64 v9, v103, v99
	v_mov_b32_e32 v10, v59
	v_pk_add_f32 v[6:7], v[8:9], v[6:7]
	v_pk_add_f32 v[8:9], v[100:101], v[96:97]
	v_mov_b32_e32 v11, v58
	v_pk_add_f32 v[6:7], v[8:9], v[6:7]
	s_waitcnt lgkmcnt(0)
	v_mfma_f32_32x32x16_bf16 v[32:47], v[64:67], v[2:5], v[32:47]
	v_add_f32_e32 v0, v169, v7
	v_add_f32_e32 v0, v6, v0
	s_add_i32 s31, s31, 1
	s_add_i32 s42, s42, 2
	s_add_i32 s6, s38, s31
	v_lshl_add_u64 v[174:175], v[174:175], 0, v[170:171]
	v_lshl_add_u64 v[176:177], v[176:177], 0, s[18:19]
	v_lshl_add_u64 v[178:179], v[178:179], 0, s[18:19]
	v_lshl_add_u64 v[182:183], v[182:183], 0, v[180:181]
	v_lshl_add_u64 v[186:187], v[186:187], 0, v[184:185]
	s_cmp_lg_u32 s6, 1
	v_lshl_add_u64 v[190:191], v[190:191], 0, v[188:189]
	s_waitcnt vmcnt(0) lgkmcnt(0)
	s_barrier
	s_cbranch_scc0 .Lattn_exit_3
	v_mov_b32_e32 v169, v0
	s_bitcmp1_b32 s31, 0
	s_cselect_b32 s6, 0, 0xa800
	s_cmp_ge_u32 s31, s36
	s_cbranch_scc0 .LBB0_2267
	s_branch .LBB0_2270
.Lattn_exit_3:
	s_nop 7
	s_nop 7
	v_mov_b64_e32 v[110:111], v[30:31]
	v_mov_b32_e32 v6, v63
	v_mov_b32_e32 v7, v62
	v_mov_b32_e32 v8, v61
	v_mov_b32_e32 v9, v60
	v_mov_b64_e32 v[126:127], v[46:47]
	v_mov_b32_e32 v12, v57
	v_mov_b32_e32 v13, v56
	v_mov_b32_e32 v15, v54
	v_mov_b32_e32 v194, v53
	v_mov_b32_e32 v195, v52
	v_mov_b32_e32 v198, v51
	v_mov_b32_e32 v199, v50
	v_mov_b32_e32 v200, v49
	v_mov_b32_e32 v4, v48
	v_mov_b32_e32 v5, v165
	v_mov_b64_e32 v[108:109], v[28:29]
	v_mov_b64_e32 v[106:107], v[26:27]
	v_mov_b64_e32 v[104:105], v[24:25]
	v_mov_b64_e32 v[102:103], v[22:23]
	v_mov_b64_e32 v[100:101], v[20:21]
	v_mov_b64_e32 v[98:99], v[18:19]
	v_mov_b64_e32 v[96:97], v[16:17]
	v_mov_b64_e32 v[124:125], v[44:45]
	v_mov_b64_e32 v[122:123], v[42:43]
	v_mov_b64_e32 v[120:121], v[40:41]
	v_mov_b64_e32 v[118:119], v[38:39]
	v_mov_b64_e32 v[116:117], v[36:37]
	v_mov_b64_e32 v[114:115], v[34:35]
	v_mov_b64_e32 v[112:113], v[32:33]
	s_branch .LBB0_2201

; __device__ __forceinline__ unsigned cvt_pk_bf16(float lo, float hi) { unsigned r; asm volatile("v_cvt_pk_bf16_f32 %0, %1, %2" : "=v"(r) : "v"(lo), "v"(hi)); return r; }
;     __device__ __forceinline__ void operator()(const f32x4 (&acc)[2][2][4][2], const Unit& u, int wr, int wc, int fr, int fq) const {
;         EPI_LOOP_BEGIN
;             const int col = u.pn * BM + cl;
;             v0 = v0 + *(const f32x4*)(bias + col); v1 = v1 + *(const f32x4*)(bias + col + 4);
; #pragma unroll
;             for (int e = 0; e < 4; ++e) { const float a = fmaxf(v0[e], 0.f), b = fmaxf(v1[e], 0.f); v0[e] = a * a; v1[e] = b * b; }
;             u32x4 w; w.x = cvt_pk_bf16(v0[0], v0[1]); w.y = cvt_pk_bf16(v0[2], v0[3]); w.z = cvt_pk_bf16(v1[0], v1[1]); w.w = cvt_pk_bf16(v1[2], v1[3]);
;             *(u32x4*)(F1 + (size_t)row * ZP + col) = w;
;         EPI_LOOP_END
.LBB0_2732:
	v_lshl_or_b32 v144, s49, 8, v154
	v_ashrrev_i32_e32 v145, 31, v144
	v_lshl_add_u64 v[146:147], v[144:145], 2, s[12:13]
	global_load_dwordx4 v[200:203], v[146:147], off
	global_load_dwordx4 v[204:207], v[146:147], off offset:16
	global_load_dwordx4 v[208:211], v[146:147], off offset:512
	global_load_dwordx4 v[212:215], v[146:147], off offset:528
	v_lshl_add_u32 v158, s28, 8, v152
	v_mov_b64_e32 v[148:149], s[4:5]
	v_mad_i64_i32 v[168:169], s[6:7], v158, s48, v[148:149]
	v_or_b32_e32 v170, 0x80, v144
	v_lshlrev_b64 v[150:151], 1, v[144:145]
	v_ashrrev_i32_e32 v171, 31, v170
	v_lshl_add_u64 v[168:169], v[168:169], 0, v[150:151]
	v_lshl_add_u64 v[144:145], v[170:171], 2, s[12:13]
	s_andn2_b64 vcc, exec, s[2:3]
	s_mov_b64 s[2:3], -1
	s_waitcnt vmcnt(0)
	v_pk_add_f32 v[126:127], v[126:127], v[202:203]
	v_pk_add_f32 v[124:125], v[124:125], v[200:201]
	v_pk_add_f32 v[122:123], v[122:123], v[206:207]
	v_pk_add_f32 v[120:121], v[120:121], v[204:205]
	v_max_f32_e32 v125, 0, v125
	v_max_f32_e32 v120, 0, v120
	v_max_f32_e32 v121, 0, v121
	v_max_f32_e32 v126, 0, v126
	v_max_f32_e32 v122, 0, v122
	v_max_f32_e32 v127, 0, v127
	v_max_f32_e32 v123, 0, v123
	v_max_f32_e32 v124, 0, v124
	v_mul_f32_e32 v159, v120, v120
	v_mul_f32_e32 v120, v125, v125
	v_mul_f32_e32 v125, v121, v121
	v_mul_f32_e32 v121, v126, v126
	v_mul_f32_e32 v126, v122, v122
	v_mul_f32_e32 v122, v127, v127
	v_mul_f32_e32 v123, v123, v123
	v_mul_f32_e32 v124, v124, v124
	v_cvt_pk_bf16_f32 v120, v124, v120
	v_cvt_pk_bf16_f32 v121, v121, v122
	v_cvt_pk_bf16_f32 v122, v159, v125
	v_cvt_pk_bf16_f32 v123, v126, v123
	global_store_dwordx4 v[168:169], v[120:123], off
	v_pk_add_f32 v[118:119], v[118:119], v[210:211]
	v_pk_add_f32 v[116:117], v[116:117], v[208:209]
	v_pk_add_f32 v[114:115], v[114:115], v[214:215]
	v_pk_add_f32 v[112:113], v[112:113], v[212:213]
	v_max_f32_e32 v117, 0, v117
	v_max_f32_e32 v112, 0, v112
	v_max_f32_e32 v113, 0, v113
	v_max_f32_e32 v118, 0, v118
	v_max_f32_e32 v114, 0, v114
	v_max_f32_e32 v119, 0, v119
	v_max_f32_e32 v115, 0, v115
	v_max_f32_e32 v116, 0, v116
	v_mul_f32_e32 v120, v112, v112
	v_mul_f32_e32 v112, v117, v117
	v_mul_f32_e32 v117, v113, v113
	v_mul_f32_e32 v113, v118, v118
	v_mul_f32_e32 v118, v114, v114
	v_mul_f32_e32 v114, v119, v119
	v_mul_f32_e32 v115, v115, v115
	v_mul_f32_e32 v116, v116, v116
	v_cvt_pk_bf16_f32 v112, v116, v112
	v_cvt_pk_bf16_f32 v113, v113, v114
	v_cvt_pk_bf16_f32 v114, v120, v117
	v_cvt_pk_bf16_f32 v115, v118, v115
	global_store_dwordx4 v[168:169], v[112:115], off offset:256
	v_or_b32_e32 v120, 16, v158
	v_mad_i64_i32 v[120:121], s[6:7], v120, s48, v[148:149]
	v_lshl_add_u64 v[120:121], v[120:121], 0, v[150:151]
	v_pk_add_f32 v[110:111], v[110:111], v[202:203]
	v_pk_add_f32 v[108:109], v[108:109], v[200:201]
	v_pk_add_f32 v[106:107], v[106:107], v[206:207]
	v_pk_add_f32 v[104:105], v[104:105], v[204:205]
	v_max_f32_e32 v109, 0, v109
	v_max_f32_e32 v104, 0, v104
	v_max_f32_e32 v105, 0, v105
	v_max_f32_e32 v110, 0, v110
	v_max_f32_e32 v106, 0, v106
	v_max_f32_e32 v111, 0, v111
	v_max_f32_e32 v107, 0, v107
	v_max_f32_e32 v108, 0, v108
	v_mul_f32_e32 v112, v104, v104
	v_mul_f32_e32 v104, v109, v109
	v_mul_f32_e32 v109, v105, v105
	v_mul_f32_e32 v105, v110, v110
	v_mul_f32_e32 v110, v106, v106
	v_mul_f32_e32 v106, v111, v111
	v_mul_f32_e32 v107, v107, v107
	v_mul_f32_e32 v108, v108, v108
	v_cvt_pk_bf16_f32 v104, v108, v104
	v_cvt_pk_bf16_f32 v105, v105, v106
	v_cvt_pk_bf16_f32 v106, v112, v109
	v_cvt_pk_bf16_f32 v107, v110, v107
	global_store_dwordx4 v[120:121], v[104:107], off
	v_pk_add_f32 v[102:103], v[102:103], v[210:211]
	v_pk_add_f32 v[100:101], v[100:101], v[208:209]
	v_pk_add_f32 v[98:99], v[98:99], v[214:215]
	v_pk_add_f32 v[96:97], v[96:97], v[212:213]
	v_max_f32_e32 v101, 0, v101
	v_max_f32_e32 v96, 0, v96
	v_max_f32_e32 v97, 0, v97
	v_max_f32_e32 v102, 0, v102
	v_max_f32_e32 v98, 0, v98
	v_max_f32_e32 v103, 0, v103
	v_max_f32_e32 v99, 0, v99
	v_max_f32_e32 v100, 0, v100
	v_mul_f32_e32 v104, v96, v96
	v_mul_f32_e32 v96, v101, v101
	v_mul_f32_e32 v101, v97, v97
	v_mul_f32_e32 v97, v102, v102
	v_mul_f32_e32 v102, v98, v98
	v_mul_f32_e32 v98, v103, v103
	v_mul_f32_e32 v99, v99, v99
	v_mul_f32_e32 v100, v100, v100
	v_cvt_pk_bf16_f32 v96, v100, v96
	v_cvt_pk_bf16_f32 v97, v97, v98
	v_cvt_pk_bf16_f32 v98, v104, v101
	v_cvt_pk_bf16_f32 v99, v102, v99
	global_store_dwordx4 v[120:121], v[96:99], off offset:256
	v_or_b32_e32 v104, 32, v158
	v_mad_i64_i32 v[104:105], s[6:7], v104, s48, v[148:149]
	v_lshl_add_u64 v[104:105], v[104:105], 0, v[150:151]
	v_pk_add_f32 v[94:95], v[94:95], v[202:203]
	v_pk_add_f32 v[92:93], v[92:93], v[200:201]
	v_pk_add_f32 v[90:91], v[90:91], v[206:207]
	v_pk_add_f32 v[88:89], v[88:89], v[204:205]
	v_max_f32_e32 v93, 0, v93
	v_max_f32_e32 v88, 0, v88
	v_max_f32_e32 v89, 0, v89
	v_max_f32_e32 v94, 0, v94
	v_max_f32_e32 v90, 0, v90
	v_max_f32_e32 v95, 0, v95
	v_max_f32_e32 v91, 0, v91
	v_max_f32_e32 v92, 0, v92
	v_mul_f32_e32 v96, v88, v88
	v_mul_f32_e32 v88, v93, v93
	v_mul_f32_e32 v93, v89, v89
	v_mul_f32_e32 v89, v94, v94
	v_mul_f32_e32 v94, v90, v90
	v_mul_f32_e32 v90, v95, v95
	v_mul_f32_e32 v91, v91, v91
	v_mul_f32_e32 v92, v92, v92
	v_cvt_pk_bf16_f32 v88, v92, v88
	v_cvt_pk_bf16_f32 v89, v89, v90
	v_cvt_pk_bf16_f32 v90, v96, v93
	v_cvt_pk_bf16_f32 v91, v94, v91
	global_store_dwordx4 v[104:105], v[88:91], off
	v_pk_add_f32 v[86:87], v[86:87], v[210:211]
	v_pk_add_f32 v[84:85], v[84:85], v[208:209]
	v_pk_add_f32 v[82:83], v[82:83], v[214:215]
	v_pk_add_f32 v[80:81], v[80:81], v[212:213]
	v_max_f32_e32 v85, 0, v85
	v_max_f32_e32 v80, 0, v80
	v_max_f32_e32 v81, 0, v81
	v_max_f32_e32 v86, 0, v86
; __device__ __forceinline__ unsigned cvt_pk_bf16(float lo, float hi) { unsigned r; asm volatile("v_cvt_pk_bf16_f32 %0, %1, %2" : "=v"(r) : "v"(lo), "v"(hi)); return r; }
;     __device__ __forceinline__ void operator()(const f32x4 (&acc)[2][2][4][2], const Unit& u, int wr, int wc, int fr, int fq) const {
;         EPI_LOOP_BEGIN
;             const int col = u.pn * BM + cl;
;             v0 = v0 + *(const f32x4*)(bias + col); v1 = v1 + *(const f32x4*)(bias + col + 4);
; #pragma unroll
;             for (int e = 0; e < 4; ++e) { const float a = fmaxf(v0[e], 0.f), b = fmaxf(v1[e], 0.f); v0[e] = a * a; v1[e] = b * b; }
;             u32x4 w; w.x = cvt_pk_bf16(v0[0], v0[1]); w.y = cvt_pk_bf16(v0[2], v0[3]); w.z = cvt_pk_bf16(v1[0], v1[1]); w.w = cvt_pk_bf16(v1[2], v1[3]);
;             *(u32x4*)(F1 + (size_t)row * ZP + col) = w;
;         EPI_LOOP_END
	v_max_f32_e32 v82, 0, v82
	v_max_f32_e32 v87, 0, v87
	v_max_f32_e32 v83, 0, v83
	v_max_f32_e32 v84, 0, v84
	v_mul_f32_e32 v88, v80, v80
	v_mul_f32_e32 v80, v85, v85
	v_mul_f32_e32 v85, v81, v81
	v_mul_f32_e32 v81, v86, v86
	v_mul_f32_e32 v86, v82, v82
	v_mul_f32_e32 v82, v87, v87
	v_mul_f32_e32 v83, v83, v83
	v_mul_f32_e32 v84, v84, v84
	v_cvt_pk_bf16_f32 v80, v84, v80
	v_cvt_pk_bf16_f32 v81, v81, v82
	v_cvt_pk_bf16_f32 v82, v88, v85
	v_cvt_pk_bf16_f32 v83, v86, v83
	global_store_dwordx4 v[104:105], v[80:83], off offset:256
	v_or_b32_e32 v88, 48, v158
	v_mad_i64_i32 v[88:89], s[6:7], v88, s48, v[148:149]
	v_lshl_add_u64 v[88:89], v[88:89], 0, v[150:151]
	v_pk_add_f32 v[78:79], v[78:79], v[202:203]
	v_pk_add_f32 v[76:77], v[76:77], v[200:201]
	v_pk_add_f32 v[74:75], v[74:75], v[206:207]
	v_pk_add_f32 v[72:73], v[72:73], v[204:205]
	v_max_f32_e32 v77, 0, v77
	v_max_f32_e32 v72, 0, v72
	v_max_f32_e32 v73, 0, v73
	v_max_f32_e32 v78, 0, v78
	v_max_f32_e32 v74, 0, v74
	v_max_f32_e32 v79, 0, v79
	v_max_f32_e32 v75, 0, v75
	v_max_f32_e32 v76, 0, v76
	v_mul_f32_e32 v80, v72, v72
	v_mul_f32_e32 v72, v77, v77
	v_mul_f32_e32 v77, v73, v73
	v_mul_f32_e32 v73, v78, v78
	v_mul_f32_e32 v78, v74, v74
	v_mul_f32_e32 v74, v79, v79
	v_mul_f32_e32 v75, v75, v75
	v_mul_f32_e32 v76, v76, v76
	v_cvt_pk_bf16_f32 v72, v76, v72
	v_cvt_pk_bf16_f32 v73, v73, v74
	v_cvt_pk_bf16_f32 v74, v80, v77
	v_cvt_pk_bf16_f32 v75, v78, v75
	global_store_dwordx4 v[88:89], v[72:75], off
	v_pk_add_f32 v[70:71], v[70:71], v[210:211]
	v_pk_add_f32 v[68:69], v[68:69], v[208:209]
	v_pk_add_f32 v[66:67], v[66:67], v[214:215]
	v_pk_add_f32 v[64:65], v[64:65], v[212:213]
	v_max_f32_e32 v69, 0, v69
	v_max_f32_e32 v64, 0, v64
	v_max_f32_e32 v65, 0, v65
	v_max_f32_e32 v70, 0, v70
	v_max_f32_e32 v66, 0, v66
	v_max_f32_e32 v71, 0, v71
	v_max_f32_e32 v67, 0, v67
	v_max_f32_e32 v68, 0, v68
	v_mul_f32_e32 v72, v64, v64
	v_mul_f32_e32 v64, v69, v69
	v_mul_f32_e32 v69, v65, v65
	v_mul_f32_e32 v65, v70, v70
	v_mul_f32_e32 v70, v66, v66
	v_mul_f32_e32 v66, v71, v71
	v_mul_f32_e32 v67, v67, v67
	v_mul_f32_e32 v68, v68, v68
	v_cvt_pk_bf16_f32 v64, v68, v64
	v_cvt_pk_bf16_f32 v65, v65, v66
	v_cvt_pk_bf16_f32 v66, v72, v69
	v_cvt_pk_bf16_f32 v67, v70, v67
	global_store_dwordx4 v[88:89], v[64:67], off offset:256
	v_add_u32_e32 v72, 0x80, v158
	v_mad_i64_i32 v[72:73], s[6:7], v72, s48, v[148:149]
	v_lshl_add_u64 v[72:73], v[72:73], 0, v[150:151]
	v_pk_add_f32 v[62:63], v[62:63], v[202:203]
	v_pk_add_f32 v[60:61], v[60:61], v[200:201]
	v_pk_add_f32 v[58:59], v[58:59], v[206:207]
	v_pk_add_f32 v[56:57], v[56:57], v[204:205]
	v_max_f32_e32 v61, 0, v61
	v_max_f32_e32 v56, 0, v56
	v_max_f32_e32 v57, 0, v57
	v_max_f32_e32 v62, 0, v62
	v_max_f32_e32 v58, 0, v58
	v_max_f32_e32 v63, 0, v63
	v_max_f32_e32 v59, 0, v59
	v_max_f32_e32 v60, 0, v60
	v_mul_f32_e32 v64, v56, v56
	v_mul_f32_e32 v56, v61, v61
	v_mul_f32_e32 v61, v57, v57
	v_mul_f32_e32 v57, v62, v62
	v_mul_f32_e32 v62, v58, v58
	v_mul_f32_e32 v58, v63, v63
	v_mul_f32_e32 v59, v59, v59
	v_mul_f32_e32 v60, v60, v60
	v_cvt_pk_bf16_f32 v56, v60, v56
	v_cvt_pk_bf16_f32 v57, v57, v58
	v_cvt_pk_bf16_f32 v58, v64, v61
	v_cvt_pk_bf16_f32 v59, v62, v59
	global_store_dwordx4 v[72:73], v[56:59], off
	v_pk_add_f32 v[54:55], v[54:55], v[210:211]
	v_pk_add_f32 v[52:53], v[52:53], v[208:209]
	v_pk_add_f32 v[50:51], v[50:51], v[214:215]
	v_pk_add_f32 v[48:49], v[48:49], v[212:213]
	v_max_f32_e32 v53, 0, v53
	v_max_f32_e32 v48, 0, v48
	v_max_f32_e32 v49, 0, v49
	v_max_f32_e32 v54, 0, v54
	v_max_f32_e32 v50, 0, v50
	v_max_f32_e32 v55, 0, v55
	v_max_f32_e32 v51, 0, v51
	v_max_f32_e32 v52, 0, v52
	v_mul_f32_e32 v56, v48, v48
	v_mul_f32_e32 v48, v53, v53
	v_mul_f32_e32 v53, v49, v49
	v_mul_f32_e32 v49, v54, v54
	v_mul_f32_e32 v54, v50, v50
	v_mul_f32_e32 v50, v55, v55
	v_mul_f32_e32 v51, v51, v51
	v_mul_f32_e32 v52, v52, v52
	v_cvt_pk_bf16_f32 v48, v52, v48
	v_cvt_pk_bf16_f32 v49, v49, v50
	v_cvt_pk_bf16_f32 v50, v56, v53
	v_cvt_pk_bf16_f32 v51, v54, v51
	global_store_dwordx4 v[72:73], v[48:51], off offset:256
	v_add_u32_e32 v56, 0x90, v158
	v_mad_i64_i32 v[56:57], s[6:7], v56, s48, v[148:149]
	v_lshl_add_u64 v[56:57], v[56:57], 0, v[150:151]
	v_pk_add_f32 v[46:47], v[46:47], v[202:203]
	v_pk_add_f32 v[44:45], v[44:45], v[200:201]
	v_pk_add_f32 v[42:43], v[42:43], v[206:207]
	v_pk_add_f32 v[40:41], v[40:41], v[204:205]
	v_max_f32_e32 v45, 0, v45
	v_max_f32_e32 v40, 0, v40
	v_max_f32_e32 v41, 0, v41
	v_max_f32_e32 v46, 0, v46
	v_max_f32_e32 v42, 0, v42
	v_max_f32_e32 v47, 0, v47
	v_max_f32_e32 v43, 0, v43
	v_max_f32_e32 v44, 0, v44
	v_mul_f32_e32 v48, v40, v40
	v_mul_f32_e32 v40, v45, v45
	v_mul_f32_e32 v45, v41, v41
; __device__ __forceinline__ unsigned cvt_pk_bf16(float lo, float hi) { unsigned r; asm volatile("v_cvt_pk_bf16_f32 %0, %1, %2" : "=v"(r) : "v"(lo), "v"(hi)); return r; }
; #define PG8_BAR __builtin_amdgcn_s_barrier()
;     __device__ __forceinline__ void operator()(const f32x4 (&acc)[2][2][4][2], const Unit& u, int wr, int wc, int fr, int fq) const {
;         EPI_LOOP_BEGIN
;             const int col = u.pn * BM + cl;
;             v0 = v0 + *(const f32x4*)(bias + col); v1 = v1 + *(const f32x4*)(bias + col + 4);
; #pragma unroll
;             for (int e = 0; e < 4; ++e) { const float a = fmaxf(v0[e], 0.f), b = fmaxf(v1[e], 0.f); v0[e] = a * a; v1[e] = b * b; }
;             u32x4 w; w.x = cvt_pk_bf16(v0[0], v0[1]); w.y = cvt_pk_bf16(v0[2], v0[3]); w.z = cvt_pk_bf16(v1[0], v1[1]); w.w = cvt_pk_bf16(v1[2], v1[3]);
;             *(u32x4*)(F1 + (size_t)row * ZP + col) = w;
;         EPI_LOOP_END
; template <class Epi, class Sched>
; __device__ __forceinline__ void gemm_phase(LAS unsigned char* lds, const Gemm g, const Sched& S, const Epi& E) {
;     ...
;         if (!has_next) break;
; #pragma unroll
;         for (int a = 0; a < 2; ++a)
; #pragma unroll
;             for (int b = 0; b < 2; ++b)
; #pragma unroll
;                 for (int m = 0; m < 4; ++m)
; #pragma unroll
;                     for (int n = 0; n < 2; ++n) acc[a][b][m][n] = (f32x4){0.f, 0.f, 0.f, 0.f};
;         cur = nxt; cA = nA; cB = nB; ++ui;
;         if (wr == 1) PG8_BAR;
	v_mul_f32_e32 v41, v46, v46
	v_mul_f32_e32 v46, v42, v42
	v_mul_f32_e32 v42, v47, v47
	v_mul_f32_e32 v43, v43, v43
	v_mul_f32_e32 v44, v44, v44
	v_cvt_pk_bf16_f32 v40, v44, v40
	v_cvt_pk_bf16_f32 v41, v41, v42
	v_cvt_pk_bf16_f32 v42, v48, v45
	v_cvt_pk_bf16_f32 v43, v46, v43
	global_store_dwordx4 v[56:57], v[40:43], off
	v_pk_add_f32 v[38:39], v[38:39], v[210:211]
	v_pk_add_f32 v[36:37], v[36:37], v[208:209]
	v_pk_add_f32 v[34:35], v[34:35], v[214:215]
	v_pk_add_f32 v[32:33], v[32:33], v[212:213]
	v_max_f32_e32 v37, 0, v37
	v_max_f32_e32 v32, 0, v32
	v_max_f32_e32 v33, 0, v33
	v_max_f32_e32 v38, 0, v38
	v_max_f32_e32 v34, 0, v34
	v_max_f32_e32 v39, 0, v39
	v_max_f32_e32 v35, 0, v35
	v_max_f32_e32 v36, 0, v36
	v_mul_f32_e32 v40, v32, v32
	v_mul_f32_e32 v32, v37, v37
	v_mul_f32_e32 v37, v33, v33
	v_mul_f32_e32 v33, v38, v38
	v_mul_f32_e32 v38, v34, v34
	v_mul_f32_e32 v34, v39, v39
	v_mul_f32_e32 v35, v35, v35
	v_mul_f32_e32 v36, v36, v36
	v_cvt_pk_bf16_f32 v32, v36, v32
	v_cvt_pk_bf16_f32 v33, v33, v34
	v_cvt_pk_bf16_f32 v34, v40, v37
	v_cvt_pk_bf16_f32 v35, v38, v35
	global_store_dwordx4 v[56:57], v[32:35], off offset:256
	v_add_u32_e32 v40, 0xa0, v158
	v_mad_i64_i32 v[40:41], s[6:7], v40, s48, v[148:149]
	v_lshl_add_u64 v[40:41], v[40:41], 0, v[150:151]
	v_pk_add_f32 v[30:31], v[30:31], v[202:203]
	v_pk_add_f32 v[28:29], v[28:29], v[200:201]
	v_pk_add_f32 v[26:27], v[26:27], v[206:207]
	v_pk_add_f32 v[24:25], v[24:25], v[204:205]
	v_max_f32_e32 v29, 0, v29
	v_max_f32_e32 v24, 0, v24
	v_max_f32_e32 v25, 0, v25
	v_max_f32_e32 v30, 0, v30
	v_max_f32_e32 v26, 0, v26
	v_max_f32_e32 v31, 0, v31
	v_max_f32_e32 v27, 0, v27
	v_max_f32_e32 v28, 0, v28
	v_mul_f32_e32 v32, v24, v24
	v_mul_f32_e32 v24, v29, v29
	v_mul_f32_e32 v29, v25, v25
	v_mul_f32_e32 v25, v30, v30
	v_mul_f32_e32 v30, v26, v26
	v_mul_f32_e32 v26, v31, v31
	v_mul_f32_e32 v27, v27, v27
	v_mul_f32_e32 v28, v28, v28
	v_cvt_pk_bf16_f32 v24, v28, v24
	v_cvt_pk_bf16_f32 v25, v25, v26
	v_cvt_pk_bf16_f32 v26, v32, v29
	v_cvt_pk_bf16_f32 v27, v30, v27
	global_store_dwordx4 v[40:41], v[24:27], off
	v_pk_add_f32 v[22:23], v[22:23], v[210:211]
	v_pk_add_f32 v[20:21], v[20:21], v[208:209]
	v_pk_add_f32 v[18:19], v[18:19], v[214:215]
	v_pk_add_f32 v[16:17], v[16:17], v[212:213]
	v_max_f32_e32 v21, 0, v21
	v_max_f32_e32 v16, 0, v16
	v_max_f32_e32 v17, 0, v17
	v_max_f32_e32 v22, 0, v22
	v_max_f32_e32 v18, 0, v18
	v_max_f32_e32 v23, 0, v23
	v_max_f32_e32 v19, 0, v19
	v_max_f32_e32 v20, 0, v20
	v_mul_f32_e32 v24, v16, v16
	v_mul_f32_e32 v16, v21, v21
	v_mul_f32_e32 v21, v17, v17
	v_mul_f32_e32 v17, v22, v22
	v_mul_f32_e32 v22, v18, v18
	v_mul_f32_e32 v18, v23, v23
	v_mul_f32_e32 v19, v19, v19
	v_mul_f32_e32 v20, v20, v20
	v_cvt_pk_bf16_f32 v16, v20, v16
	v_cvt_pk_bf16_f32 v17, v17, v18
	v_cvt_pk_bf16_f32 v18, v24, v21
	v_cvt_pk_bf16_f32 v19, v22, v19
	global_store_dwordx4 v[40:41], v[16:19], off offset:256
	v_add_u32_e32 v24, 0xb0, v158
	v_mad_i64_i32 v[24:25], s[6:7], v24, s48, v[148:149]
	v_lshl_add_u64 v[24:25], v[24:25], 0, v[150:151]
	v_pk_add_f32 v[14:15], v[14:15], v[202:203]
	v_pk_add_f32 v[12:13], v[12:13], v[200:201]
	v_pk_add_f32 v[10:11], v[10:11], v[206:207]
	v_pk_add_f32 v[8:9], v[8:9], v[204:205]
	v_max_f32_e32 v13, 0, v13
	v_max_f32_e32 v8, 0, v8
	v_max_f32_e32 v9, 0, v9
	v_max_f32_e32 v14, 0, v14
	v_max_f32_e32 v10, 0, v10
	v_max_f32_e32 v15, 0, v15
	v_max_f32_e32 v11, 0, v11
	v_max_f32_e32 v12, 0, v12
	v_mul_f32_e32 v16, v8, v8
	v_mul_f32_e32 v8, v13, v13
	v_mul_f32_e32 v13, v9, v9
	v_mul_f32_e32 v9, v14, v14
	v_mul_f32_e32 v14, v10, v10
	v_mul_f32_e32 v10, v15, v15
	v_mul_f32_e32 v11, v11, v11
	v_mul_f32_e32 v12, v12, v12
	v_cvt_pk_bf16_f32 v8, v12, v8
	v_cvt_pk_bf16_f32 v9, v9, v10
	v_cvt_pk_bf16_f32 v10, v16, v13
	v_cvt_pk_bf16_f32 v11, v14, v11
	global_store_dwordx4 v[24:25], v[8:11], off
	v_pk_add_f32 v[6:7], v[6:7], v[210:211]
	v_pk_add_f32 v[4:5], v[4:5], v[208:209]
	v_pk_add_f32 v[2:3], v[2:3], v[214:215]
	v_pk_add_f32 v[0:1], v[0:1], v[212:213]
	v_max_f32_e32 v5, 0, v5
	v_max_f32_e32 v0, 0, v0
	v_max_f32_e32 v1, 0, v1
	v_max_f32_e32 v6, 0, v6
	v_max_f32_e32 v2, 0, v2
	v_max_f32_e32 v7, 0, v7
	v_max_f32_e32 v3, 0, v3
	v_max_f32_e32 v4, 0, v4
	v_mul_f32_e32 v8, v0, v0
	v_mul_f32_e32 v0, v5, v5
	v_mul_f32_e32 v5, v1, v1
	v_mul_f32_e32 v1, v6, v6
	v_mul_f32_e32 v6, v2, v2
	v_mul_f32_e32 v2, v7, v7
	v_mul_f32_e32 v3, v3, v3
	v_mul_f32_e32 v4, v4, v4
	v_cvt_pk_bf16_f32 v0, v4, v0
	v_cvt_pk_bf16_f32 v1, v1, v2
	v_cvt_pk_bf16_f32 v2, v8, v5
	v_cvt_pk_bf16_f32 v3, v6, v3
	global_store_dwordx4 v[24:25], v[0:3], off offset:256
	s_cbranch_vccnz .LBB0_2721
	s_andn2_b64 vcc, exec, s[0:1]
	s_cbranch_vccnz .LBB0_2720
	s_barrier
	s_branch .LBB0_2720
